# baseline (speedup 1.0000x reference)
; #define PG8_STAGE(bufoff, gbase, voff) do { _Pragma("unroll") for (int _i = 0; _i < 2; ++_i) \
;         __builtin_amdgcn_global_load_lds((const unsigned*)((const char*)(gbase) + (voff)[_i]), (LAS unsigned*)(lds + (bufoff) + ldsw + _i * 8192), 16, 0, 0); } while (0)
; #define PG8_LDA(dst, b, h) do { _Pragma("unroll") for (int m = 0; m < 4; ++m) _Pragma("unroll") for (int k = 0; k < 2; ++k) dst[m][k] = *(const LAS bf16x8*)(lds + PG8_SA(b, h) + aoff + m * 2048 + k * 1024); } while (0)
; #define PG8_LDB(dst, b, h) do { _Pragma("unroll") for (int n = 0; n < 2; ++n) _Pragma("unroll") for (int k = 0; k < 2; ++k) dst[n][k] = *(const LAS bf16x8*)(lds + PG8_SB(b, h) + boff + n * 2048 + k * 1024); } while (0)
; #define PG8_MMA(ai, bj, At, Bt) do { __builtin_amdgcn_s_setprio(1); _Pragma("unroll") for (int m = 0; m < 4; ++m) _Pragma("unroll") for (int n = 0; n < 2; ++n) _Pragma("unroll") for (int k = 0; k < 2; ++k) \
;         acc[ai][bj][m][n] = __builtin_amdgcn_mfma_f32_16x16x32_bf16(Bt[n][k], At[m][k], acc[ai][bj][m][n], 0, 0, 0); __builtin_amdgcn_s_setprio(0); } while (0)
; #define PG8_WAIT_V(n) asm volatile("s_waitcnt vmcnt(" #n ")" ::: "memory")
; #define PG8_WAIT_L(n) asm volatile("s_waitcnt lgkmcnt(" #n ")" ::: "memory")
; #define PG8_BAR __builtin_amdgcn_s_barrier()
; #define PG8_SCHED __builtin_amdgcn_sched_barrier(0)
; template <class Epi>
; DEV void gemm_phase(LAS unsigned char* lds, const Gemm g, const StaticOrder& S, const Epi& E) {
;     ...
;             PG8_LDB(B0, 0, 0); PG8_SCHED; PG8_LDA(At, 0, 0); PG8_STAGE(PG8_SA(1, 1), a1 + hstep, voffA);
;             PG8_WAIT_L(8); PG8_BAR; PG8_WAIT_L(0); PG8_MMA(0, 0, At, B0); PG8_BAR; PG8_SCHED;
;             PG8_LDB(B1, 0, 1); PG8_STAGE(PG8_SB(0, 0), b2, voffB);
;             PG8_BAR; PG8_WAIT_L(0); PG8_MMA(0, 1, At, B1); PG8_BAR;
;             PG8_LDA(At, 0, 1); PG8_STAGE(PG8_SA(0, 0), a2, voffA);
;             PG8_BAR; PG8_WAIT_L(0); PG8_MMA(1, 0, At, B0); PG8_BAR; PG8_SCHED;
;             PG8_STAGE(PG8_SB(0, 1), b2 + hstep, voffB);
;             PG8_WAIT_V(6); PG8_BAR; PG8_MMA(1, 1, At, B1); PG8_BAR;
;             PG8_LDB(B0, 1, 0); PG8_SCHED; PG8_LDA(At, 1, 0); PG8_STAGE(PG8_SA(0, 1), a2 + hstep, voffA);
.LBB0_61:
	s_add_u32 s28, s26, 0xfff80080
	s_addc_u32 s29, s27, -1
	s_add_i32 s49, 0, 0x10000
	v_add_u32_e32 v140, s49, v178
	ds_read_b128 v[128:131], v140
	ds_read_b128 v[132:135], v140 offset:1024
	ds_read_b128 v[136:139], v140 offset:2048
	ds_read_b128 v[140:143], v140 offset:3072
	s_cmp_eq_u32 s48, 28
	s_cselect_b32 s31, s15, s29
	s_cselect_b32 s30, s19, s28
	s_cselect_b32 s29, s17, s47
	s_cselect_b32 s28, s25, s46
	s_add_i32 m0, s37, 0xc000
	ds_read_b128 v[154:157], v181
	ds_read_b128 v[174:177], v181 offset:1024
	ds_read_b128 v[182:185], v181 offset:2048
	ds_read_b128 v[186:189], v181 offset:3072
	ds_read_b128 v[190:193], v181 offset:4096
	ds_read_b128 v[194:197], v181 offset:5120
	ds_read_b128 v[214:217], v181 offset:6144
	ds_read_b128 v[218:221], v181 offset:7168
	global_load_lds_dwordx4 v150, s[26:27]
	s_add_i32 m0, s37, 0xe000
	s_nop 0
	global_load_lds_dwordx4 v152, s[26:27]
	s_waitcnt lgkmcnt(8)
	s_waitcnt vmcnt(10)
	s_barrier
	s_waitcnt lgkmcnt(0)
	v_mfma_f32_16x16x32_bf16 v[124:127], v[128:131], v[154:157], v[124:127]
	v_mfma_f32_16x16x32_bf16 v[120:123], v[136:139], v[154:157], v[120:123]
	v_mfma_f32_16x16x32_bf16 v[108:111], v[128:131], v[182:185], v[108:111]
	v_mfma_f32_16x16x32_bf16 v[104:107], v[136:139], v[182:185], v[104:107]
	v_mfma_f32_16x16x32_bf16 v[92:95], v[128:131], v[190:193], v[92:95]
	v_mfma_f32_16x16x32_bf16 v[88:91], v[136:139], v[190:193], v[88:91]
	v_mfma_f32_16x16x32_bf16 v[76:79], v[128:131], v[214:217], v[76:79]
	v_mfma_f32_16x16x32_bf16 v[72:75], v[136:139], v[214:217], v[72:75]
	v_mfma_f32_16x16x32_bf16 v[124:127], v[132:135], v[174:177], v[124:127]
	v_mfma_f32_16x16x32_bf16 v[120:123], v[140:143], v[174:177], v[120:123]
	v_mfma_f32_16x16x32_bf16 v[108:111], v[132:135], v[186:189], v[108:111]
	v_mfma_f32_16x16x32_bf16 v[104:107], v[140:143], v[186:189], v[104:107]
	v_mfma_f32_16x16x32_bf16 v[92:95], v[132:135], v[194:197], v[92:95]
	v_mfma_f32_16x16x32_bf16 v[88:91], v[140:143], v[194:197], v[88:91]
	v_mfma_f32_16x16x32_bf16 v[76:79], v[132:135], v[218:221], v[76:79]
	v_mfma_f32_16x16x32_bf16 v[72:75], v[140:143], v[218:221], v[72:75]
	s_barrier
	s_add_i32 s52, 0, 0x14000
	v_add_u32_e32 v158, s52, v178
	s_add_i32 s49, s49, s36
	ds_read_b128 v[222:225], v158
	ds_read_b128 v[226:229], v158 offset:1024
	ds_read_b128 v[230:233], v158 offset:2048
	ds_read_b128 v[234:237], v158 offset:3072
	v_lshl_add_u64 v[158:159], s[28:29], 0, v[160:161]
	s_mov_b32 m0, s49
	v_lshl_add_u64 v[238:239], s[28:29], 0, v[148:149]
	global_load_lds_dwordx4 v160, s[28:29]
	s_add_i32 m0, s49, 0x2000
	s_nop 0
	global_load_lds_dwordx4 v148, s[28:29]
	s_waitcnt vmcnt(10)
	s_barrier
	s_waitcnt lgkmcnt(0)
	v_mfma_f32_16x16x32_bf16 v[116:119], v[222:225], v[154:157], v[116:119]
	v_mfma_f32_16x16x32_bf16 v[112:115], v[230:233], v[154:157], v[112:115]
	v_mfma_f32_16x16x32_bf16 v[100:103], v[222:225], v[182:185], v[100:103]
	v_mfma_f32_16x16x32_bf16 v[96:99], v[230:233], v[182:185], v[96:99]
	v_mfma_f32_16x16x32_bf16 v[84:87], v[222:225], v[190:193], v[84:87]
	v_mfma_f32_16x16x32_bf16 v[80:83], v[230:233], v[190:193], v[80:83]
	v_mfma_f32_16x16x32_bf16 v[68:71], v[222:225], v[214:217], v[68:71]
	v_mfma_f32_16x16x32_bf16 v[64:67], v[230:233], v[214:217], v[64:67]
	v_mfma_f32_16x16x32_bf16 v[116:119], v[226:229], v[174:177], v[116:119]
	v_mfma_f32_16x16x32_bf16 v[112:115], v[234:237], v[174:177], v[112:115]
	v_mfma_f32_16x16x32_bf16 v[100:103], v[226:229], v[186:189], v[100:103]
	v_mfma_f32_16x16x32_bf16 v[96:99], v[234:237], v[186:189], v[96:99]
	v_mfma_f32_16x16x32_bf16 v[84:87], v[226:229], v[194:197], v[84:87]
	v_mfma_f32_16x16x32_bf16 v[80:83], v[234:237], v[194:197], v[80:83]
	v_mfma_f32_16x16x32_bf16 v[68:71], v[226:229], v[218:221], v[68:71]
	v_mfma_f32_16x16x32_bf16 v[64:67], v[234:237], v[218:221], v[64:67]
	s_mov_b32 m0, s37
	v_lshl_add_u64 v[240:241], s[30:31], 0, v[144:145]
	s_barrier
	ds_read_b128 v[154:157], v181 offset:16384
	ds_read_b128 v[174:177], v181 offset:17408
	ds_read_b128 v[182:185], v181 offset:18432
	ds_read_b128 v[186:189], v181 offset:19456
	ds_read_b128 v[190:193], v181 offset:20480
	ds_read_b128 v[194:197], v181 offset:21504
	ds_read_b128 v[214:217], v181 offset:22528
	ds_read_b128 v[218:221], v181 offset:23552
	global_load_lds_dwordx4 v144, s[30:31]
	v_lshl_add_u64 v[242:243], s[30:31], 0, v[146:147]
	s_mov_b32 m0, s38
	s_nop 0
	global_load_lds_dwordx4 v146, s[30:31]
	s_barrier
	s_waitcnt lgkmcnt(0)
	v_mfma_f32_16x16x32_bf16 v[60:63], v[128:131], v[154:157], v[60:63]
	v_mfma_f32_16x16x32_bf16 v[56:59], v[136:139], v[154:157], v[56:59]
	v_mfma_f32_16x16x32_bf16 v[44:47], v[128:131], v[182:185], v[44:47]
	v_mfma_f32_16x16x32_bf16 v[40:43], v[136:139], v[182:185], v[40:43]
	v_mfma_f32_16x16x32_bf16 v[28:31], v[128:131], v[190:193], v[28:31]
	v_mfma_f32_16x16x32_bf16 v[24:27], v[136:139], v[190:193], v[24:27]
	v_mfma_f32_16x16x32_bf16 v[12:15], v[128:131], v[214:217], v[12:15]
	v_mfma_f32_16x16x32_bf16 v[8:11], v[136:139], v[214:217], v[8:11]
	v_mfma_f32_16x16x32_bf16 v[60:63], v[132:135], v[174:177], v[60:63]
	v_mfma_f32_16x16x32_bf16 v[56:59], v[140:143], v[174:177], v[56:59]
	v_mfma_f32_16x16x32_bf16 v[44:47], v[132:135], v[186:189], v[44:47]
	v_mfma_f32_16x16x32_bf16 v[40:43], v[140:143], v[186:189], v[40:43]
	v_mfma_f32_16x16x32_bf16 v[28:31], v[132:135], v[194:197], v[28:31]
	v_mfma_f32_16x16x32_bf16 v[24:27], v[140:143], v[194:197], v[24:27]
	v_mfma_f32_16x16x32_bf16 v[12:15], v[132:135], v[218:221], v[12:15]
	v_mfma_f32_16x16x32_bf16 v[8:11], v[140:143], v[218:221], v[8:11]
	s_barrier
; #define PG8_STAGE(bufoff, gbase, voff) do { _Pragma("unroll") for (int _i = 0; _i < 2; ++_i) \
;         __builtin_amdgcn_global_load_lds((const unsigned*)((const char*)(gbase) + (voff)[_i]), (LAS unsigned*)(lds + (bufoff) + ldsw + _i * 8192), 16, 0, 0); } while (0)
; #define PG8_LDA(dst, b, h) do { _Pragma("unroll") for (int m = 0; m < 4; ++m) _Pragma("unroll") for (int k = 0; k < 2; ++k) dst[m][k] = *(const LAS bf16x8*)(lds + PG8_SA(b, h) + aoff + m * 2048 + k * 1024); } while (0)
; #define PG8_LDB(dst, b, h) do { _Pragma("unroll") for (int n = 0; n < 2; ++n) _Pragma("unroll") for (int k = 0; k < 2; ++k) dst[n][k] = *(const LAS bf16x8*)(lds + PG8_SB(b, h) + boff + n * 2048 + k * 1024); } while (0)
; #define PG8_MMA(ai, bj, At, Bt) do { __builtin_amdgcn_s_setprio(1); _Pragma("unroll") for (int m = 0; m < 4; ++m) _Pragma("unroll") for (int n = 0; n < 2; ++n) _Pragma("unroll") for (int k = 0; k < 2; ++k) \
;         acc[ai][bj][m][n] = __builtin_amdgcn_mfma_f32_16x16x32_bf16(Bt[n][k], At[m][k], acc[ai][bj][m][n], 0, 0, 0); __builtin_amdgcn_s_setprio(0); } while (0)
; #define PG8_WAIT_V(n) asm volatile("s_waitcnt vmcnt(" #n ")" ::: "memory")
; #define PG8_WAIT_L(n) asm volatile("s_waitcnt lgkmcnt(" #n ")" ::: "memory")
; #define PG8_BAR __builtin_amdgcn_s_barrier()
; #define PG8_SCHED __builtin_amdgcn_sched_barrier(0)
; template <class Epi>
; DEV void gemm_phase(LAS unsigned char* lds, const Gemm g, const StaticOrder& S, const Epi& E) {
;     ...
;             PG8_WAIT_V(6); PG8_BAR; PG8_MMA(1, 1, At, B1); PG8_BAR;
;             PG8_LDB(B0, 1, 0); PG8_SCHED; PG8_LDA(At, 1, 0); PG8_STAGE(PG8_SA(0, 1), a2 + hstep, voffA);
;             PG8_WAIT_L(8); PG8_BAR; PG8_WAIT_L(0); PG8_MMA(0, 0, At, B0); PG8_BAR; PG8_SCHED;
;             PG8_LDB(B1, 1, 1); PG8_STAGE(PG8_SB(1, 0), b3, voffB);
;             PG8_BAR; PG8_WAIT_L(0); PG8_MMA(0, 1, At, B1); PG8_BAR;
;             PG8_LDA(At, 1, 1); PG8_STAGE(PG8_SA(1, 0), a3, voffA);
	s_add_u32 s50, s28, 0x80000
	s_addc_u32 s51, s29, 0
	s_add_i32 s49, s52, s36
	s_mov_b32 m0, s49
	s_nop 0
	global_load_lds_dwordx4 v160, s[50:51]
	s_add_i32 m0, s49, 0x2000
	s_nop 0
	global_load_lds_dwordx4 v148, s[50:51]
	s_waitcnt vmcnt(10)
	s_barrier
	v_mfma_f32_16x16x32_bf16 v[52:55], v[222:225], v[154:157], v[52:55]
	v_mfma_f32_16x16x32_bf16 v[48:51], v[230:233], v[154:157], v[48:51]
	v_mfma_f32_16x16x32_bf16 v[36:39], v[222:225], v[182:185], v[36:39]
	v_mfma_f32_16x16x32_bf16 v[32:35], v[230:233], v[182:185], v[32:35]
	v_mfma_f32_16x16x32_bf16 v[20:23], v[222:225], v[190:193], v[20:23]
	v_mfma_f32_16x16x32_bf16 v[16:19], v[230:233], v[190:193], v[16:19]
	v_mfma_f32_16x16x32_bf16 v[4:7], v[222:225], v[214:217], v[4:7]
	v_mfma_f32_16x16x32_bf16 v[0:3], v[230:233], v[214:217], v[0:3]
	v_mfma_f32_16x16x32_bf16 v[52:55], v[226:229], v[174:177], v[52:55]
	v_mfma_f32_16x16x32_bf16 v[48:51], v[234:237], v[174:177], v[48:51]
	v_mfma_f32_16x16x32_bf16 v[36:39], v[226:229], v[186:189], v[36:39]
	v_mfma_f32_16x16x32_bf16 v[32:35], v[234:237], v[186:189], v[32:35]
	v_mfma_f32_16x16x32_bf16 v[20:23], v[226:229], v[194:197], v[20:23]
	v_mfma_f32_16x16x32_bf16 v[16:19], v[234:237], v[194:197], v[16:19]
	v_mfma_f32_16x16x32_bf16 v[4:7], v[226:229], v[218:221], v[4:7]
	v_mfma_f32_16x16x32_bf16 v[0:3], v[234:237], v[218:221], v[0:3]
	s_add_i32 s49, 0, 0x18000
	v_add_u32_e32 v140, s49, v178
	s_barrier
	ds_read_b128 v[128:131], v140
	ds_read_b128 v[132:135], v140 offset:1024
	ds_read_b128 v[136:139], v140 offset:2048
	ds_read_b128 v[140:143], v140 offset:3072
	s_add_u32 s30, s30, 0x80000
	s_addc_u32 s31, s31, 0
	s_mov_b32 m0, s39
	ds_read_b128 v[154:157], v181 offset:32768
	ds_read_b128 v[174:177], v181 offset:33792
	ds_read_b128 v[182:185], v181 offset:34816
	ds_read_b128 v[186:189], v181 offset:35840
	ds_read_b128 v[190:193], v181 offset:36864
	ds_read_b128 v[194:197], v181 offset:37888
	ds_read_b128 v[214:217], v181 offset:38912
	ds_read_b128 v[218:221], v181 offset:39936
	global_load_lds_dwordx4 v144, s[30:31]
	s_mov_b32 m0, s40
	s_nop 0
	global_load_lds_dwordx4 v146, s[30:31]
	s_waitcnt lgkmcnt(8)
	s_waitcnt vmcnt(10)
	s_barrier
	s_waitcnt lgkmcnt(0)
	v_mfma_f32_16x16x32_bf16 v[124:127], v[128:131], v[154:157], v[124:127]
	v_mfma_f32_16x16x32_bf16 v[120:123], v[136:139], v[154:157], v[120:123]
	v_mfma_f32_16x16x32_bf16 v[108:111], v[128:131], v[182:185], v[108:111]
	v_mfma_f32_16x16x32_bf16 v[104:107], v[136:139], v[182:185], v[104:107]
	v_mfma_f32_16x16x32_bf16 v[92:95], v[128:131], v[190:193], v[92:95]
	v_mfma_f32_16x16x32_bf16 v[88:91], v[136:139], v[190:193], v[88:91]
	v_mfma_f32_16x16x32_bf16 v[76:79], v[128:131], v[214:217], v[76:79]
	v_mfma_f32_16x16x32_bf16 v[72:75], v[136:139], v[214:217], v[72:75]
	v_mfma_f32_16x16x32_bf16 v[124:127], v[132:135], v[174:177], v[124:127]
	v_mfma_f32_16x16x32_bf16 v[120:123], v[140:143], v[174:177], v[120:123]
	v_mfma_f32_16x16x32_bf16 v[108:111], v[132:135], v[186:189], v[108:111]
	v_mfma_f32_16x16x32_bf16 v[104:107], v[140:143], v[186:189], v[104:107]
	v_mfma_f32_16x16x32_bf16 v[92:95], v[132:135], v[194:197], v[92:95]
	v_mfma_f32_16x16x32_bf16 v[88:91], v[140:143], v[194:197], v[88:91]
	v_mfma_f32_16x16x32_bf16 v[76:79], v[132:135], v[218:221], v[76:79]
	v_mfma_f32_16x16x32_bf16 v[72:75], v[140:143], v[218:221], v[72:75]
	s_barrier
	s_add_i32 s30, 0, 0x1c000
	s_add_i32 s31, s49, s36
	v_add_u32_e32 v234, s30, v178
	v_lshl_add_u64 v[158:159], v[158:159], 0, s[2:3]
	s_mov_b32 m0, s31
	ds_read_b128 v[222:225], v234
	ds_read_b128 v[226:229], v234 offset:1024
	ds_read_b128 v[230:233], v234 offset:2048
	ds_read_b128 v[234:237], v234 offset:3072
	global_load_lds_dwordx4 v[158:159], off
	v_lshl_add_u64 v[158:159], v[238:239], 0, s[2:3]
	s_add_i32 m0, s31, 0x2000
	s_nop 0
	global_load_lds_dwordx4 v[158:159], off
	s_waitcnt vmcnt(10)
	s_barrier
	s_waitcnt lgkmcnt(0)
	v_mfma_f32_16x16x32_bf16 v[116:119], v[222:225], v[154:157], v[116:119]
	v_mfma_f32_16x16x32_bf16 v[112:115], v[230:233], v[154:157], v[112:115]
	v_mfma_f32_16x16x32_bf16 v[100:103], v[222:225], v[182:185], v[100:103]
	v_mfma_f32_16x16x32_bf16 v[96:99], v[230:233], v[182:185], v[96:99]
	v_mfma_f32_16x16x32_bf16 v[84:87], v[222:225], v[190:193], v[84:87]
	v_mfma_f32_16x16x32_bf16 v[80:83], v[230:233], v[190:193], v[80:83]
	v_mfma_f32_16x16x32_bf16 v[68:71], v[222:225], v[214:217], v[68:71]
	v_mfma_f32_16x16x32_bf16 v[64:67], v[230:233], v[214:217], v[64:67]
	v_mfma_f32_16x16x32_bf16 v[116:119], v[226:229], v[174:177], v[116:119]
	v_mfma_f32_16x16x32_bf16 v[112:115], v[234:237], v[174:177], v[112:115]
	v_mfma_f32_16x16x32_bf16 v[100:103], v[226:229], v[186:189], v[100:103]
	v_mfma_f32_16x16x32_bf16 v[96:99], v[234:237], v[186:189], v[96:99]
	v_mfma_f32_16x16x32_bf16 v[84:87], v[226:229], v[194:197], v[84:87]
	v_mfma_f32_16x16x32_bf16 v[80:83], v[234:237], v[194:197], v[80:83]
	v_mfma_f32_16x16x32_bf16 v[68:71], v[226:229], v[218:221], v[68:71]
	v_mfma_f32_16x16x32_bf16 v[64:67], v[234:237], v[218:221], v[64:67]
	s_mov_b32 m0, s41
	v_lshl_add_u64 v[158:159], v[240:241], 0, s[2:3]
	s_barrier
	ds_read_b128 v[154:157], v181 offset:49152
	ds_read_b128 v[174:177], v181 offset:50176
	ds_read_b128 v[182:185], v181 offset:51200
	ds_read_b128 v[186:189], v181 offset:52224
	ds_read_b128 v[190:193], v181 offset:53248
	ds_read_b128 v[194:197], v181 offset:54272
	ds_read_b128 v[214:217], v181 offset:55296
	ds_read_b128 v[218:221], v181 offset:56320
	global_load_lds_dwordx4 v[158:159], off
	v_lshl_add_u64 v[158:159], v[242:243], 0, s[2:3]
	s_mov_b32 m0, s42
	s_nop 0
	global_load_lds_dwordx4 v[158:159], off
	s_barrier
; DEV bf16x8 pack8(f32x4 a, f32x4 b) { u32x4 w; w.x = cvt_pk_bf16(a[0], a[1]); w.y = cvt_pk_bf16(a[2], a[3]); w.z = cvt_pk_bf16(b[0], b[1]); w.w = cvt_pk_bf16(b[2], b[3]); return __builtin_bit_cast(bf16x8, w); }
; #define PG8_WAIT_V(n) asm volatile("s_waitcnt vmcnt(" #n ")" ::: "memory")
; #define PG8_WAIT_L(n) asm volatile("s_waitcnt lgkmcnt(" #n ")" ::: "memory")
; #define PG8_BAR __builtin_amdgcn_s_barrier()
; template <class Epi>
; DEV void gemm_phase(LAS unsigned char* lds, const Gemm g, const StaticOrder& S, const Epi& E) {
;     ...
;             PG8_BAR; PG8_WAIT_L(0); PG8_MMA(1, 0, At, B0); PG8_BAR; PG8_SCHED;
;             PG8_STAGE(PG8_SB(1, 1), b3 + hstep, voffB);
;             PG8_WAIT_V(6); PG8_BAR; PG8_MMA(1, 1, At, B1); PG8_BAR;
;         }
;         E(acc, cur, wr, wc, fr, fq);
;     DEV void operator()(AccRef acc, const pg8::Unit& u, int wr, int wc, int fr, int fq) const {
;         const int row0 = u.pm * 256 + wr * 64 + fr, col0 = u.pn * 256 + wc * 32 + 8 * fq;
; #pragma unroll
;         for (int am = 0; am < 4; ++am) { const int ai = am >> 1, m0 = (am & 1) * 2;
;             f32x4 bv[4][2][2];
; #pragma unroll
;             for (int m = m0; m < m0 + 2; ++m)
; #pragma unroll
;                 for (int bj = 0; bj < 2; ++bj)
; #pragma unroll
;                     for (int n = 0; n < 2; ++n) bv[m][bj][n] = *(const f32x4*)(base + (size_t)(row0 + ai * 128 + m * 16) * 2048 + col0 + bj * 128 + n * 4);
; #pragma unroll
;             for (int m = m0; m < m0 + 2; ++m) { const size_t off = (size_t)(row0 + ai * 128 + m * 16) * 2048 + col0; float sq = 0.f;
; #pragma unroll
;                 for (int bj = 0; bj < 2; ++bj) { const f32x4 o0 = bv[m][bj][0] + scale * acc[ai][bj][m][0], o1 = bv[m][bj][1] + scale * acc[ai][bj][m][1];
;                     *(f32x4*)(out + off + bj * 128) = o0; *(f32x4*)(out + off + bj * 128 + 4) = o1;
;                     if (xb) { *(u32x4*)(xb + off + bj * 128) = __builtin_bit_cast(u32x4, pack8(o0, o1));
;                         sq += (o0[0] * o0[0] + o0[1] * o0[1] + o0[2] * o0[2] + o0[3] * o0[3]) + (o1[0] * o1[0] + o1[1] * o1[1] + o1[2] * o1[2] + o1[3] * o1[3]); } }
;                 if (ssout) { sq += __shfl_xor(sq, 16); sq += __shfl_xor(sq, 32);
;                     if (fq == 0) { if (red) red[(ai * 128 + wr * 64 + m * 16 + fr) * 4 + wc] = sq; else atomicAdd(ssout + (size_t)(row0 + ai * 128 + m * 16) * 8 + u.pn, sq); } } }
	s_waitcnt lgkmcnt(0)
	v_mfma_f32_16x16x32_bf16 v[60:63], v[128:131], v[154:157], v[60:63]
	v_mfma_f32_16x16x32_bf16 v[56:59], v[136:139], v[154:157], v[56:59]
	v_mfma_f32_16x16x32_bf16 v[44:47], v[128:131], v[182:185], v[44:47]
	v_mfma_f32_16x16x32_bf16 v[40:43], v[136:139], v[182:185], v[40:43]
	v_mfma_f32_16x16x32_bf16 v[28:31], v[128:131], v[190:193], v[28:31]
	v_mfma_f32_16x16x32_bf16 v[24:27], v[136:139], v[190:193], v[24:27]
	v_mfma_f32_16x16x32_bf16 v[12:15], v[128:131], v[214:217], v[12:15]
	v_mfma_f32_16x16x32_bf16 v[8:11], v[136:139], v[214:217], v[8:11]
	v_mfma_f32_16x16x32_bf16 v[60:63], v[132:135], v[174:177], v[60:63]
	v_mfma_f32_16x16x32_bf16 v[56:59], v[140:143], v[174:177], v[56:59]
	v_mfma_f32_16x16x32_bf16 v[44:47], v[132:135], v[186:189], v[44:47]
	v_mfma_f32_16x16x32_bf16 v[40:43], v[140:143], v[186:189], v[40:43]
	v_mfma_f32_16x16x32_bf16 v[28:31], v[132:135], v[194:197], v[28:31]
	v_mfma_f32_16x16x32_bf16 v[24:27], v[140:143], v[194:197], v[24:27]
	v_mfma_f32_16x16x32_bf16 v[12:15], v[132:135], v[218:221], v[12:15]
	v_mfma_f32_16x16x32_bf16 v[8:11], v[140:143], v[218:221], v[8:11]
	s_barrier
	s_add_u32 s28, s28, 0x80080
	s_addc_u32 s29, s29, 0
	s_add_i32 s30, s30, s36
	s_mov_b32 m0, s30
	s_nop 0
	global_load_lds_dwordx4 v160, s[28:29]
	s_add_i32 m0, s30, 0x2000
	s_nop 0
	global_load_lds_dwordx4 v148, s[28:29]
	s_waitcnt vmcnt(10)
	s_barrier
	v_mfma_f32_16x16x32_bf16 v[52:55], v[222:225], v[154:157], v[52:55]
	v_mfma_f32_16x16x32_bf16 v[48:51], v[230:233], v[154:157], v[48:51]
	v_mfma_f32_16x16x32_bf16 v[36:39], v[222:225], v[182:185], v[36:39]
	v_mfma_f32_16x16x32_bf16 v[32:35], v[230:233], v[182:185], v[32:35]
	v_mfma_f32_16x16x32_bf16 v[20:23], v[222:225], v[190:193], v[20:23]
	v_mfma_f32_16x16x32_bf16 v[16:19], v[230:233], v[190:193], v[16:19]
	v_mfma_f32_16x16x32_bf16 v[4:7], v[222:225], v[214:217], v[4:7]
	v_mfma_f32_16x16x32_bf16 v[0:3], v[230:233], v[214:217], v[0:3]
	v_mfma_f32_16x16x32_bf16 v[52:55], v[226:229], v[174:177], v[52:55]
	v_mfma_f32_16x16x32_bf16 v[48:51], v[234:237], v[174:177], v[48:51]
	v_mfma_f32_16x16x32_bf16 v[36:39], v[226:229], v[186:189], v[36:39]
	v_mfma_f32_16x16x32_bf16 v[32:35], v[234:237], v[186:189], v[32:35]
	v_mfma_f32_16x16x32_bf16 v[20:23], v[226:229], v[194:197], v[20:23]
	v_mfma_f32_16x16x32_bf16 v[16:19], v[234:237], v[194:197], v[16:19]
	v_mfma_f32_16x16x32_bf16 v[4:7], v[226:229], v[218:221], v[4:7]
	v_mfma_f32_16x16x32_bf16 v[0:3], v[234:237], v[218:221], v[0:3]
	s_add_i32 s48, s48, 2
	s_add_u32 s26, s26, 0x100
	s_addc_u32 s27, s27, 0
	s_add_u32 s46, s46, 0x100
	s_addc_u32 s47, s47, 0
	s_cmp_gt_u32 s48, 29
	s_barrier
	s_cbranch_scc0 .LBB0_61
	v_lshl_add_u32 v156, s24, 8, v167
	v_lshl_or_b32 v154, s14, 8, v179
	v_readlane_b32 s24, v254, 16
	v_ashrrev_i32_e32 v155, 31, v154
	v_readlane_b32 s25, v254, 17
	v_ashrrev_i32_e32 v157, 31, v156
	v_lshlrev_b64 v[128:129], 13, v[156:157]
	v_lshl_add_u64 v[158:159], v[154:155], 2, s[24:25]
	v_lshl_add_u64 v[214:215], v[158:159], 0, v[128:129]
	global_load_dwordx4 v[182:185], v[214:215], off offset:16
	global_load_dwordx4 v[186:189], v[214:215], off
	global_load_dwordx4 v[190:193], v[214:215], off offset:528
	global_load_dwordx4 v[194:197], v[214:215], off offset:512
	v_or_b32_e32 v174, 16, v156
	v_ashrrev_i32_e32 v175, 31, v174
	v_lshlrev_b64 v[128:129], 13, v[174:175]
	v_lshl_add_u64 v[176:177], v[158:159], 0, v[128:129]
	global_load_dwordx4 v[136:139], v[176:177], off offset:16
	global_load_dwordx4 v[140:143], v[176:177], off
	global_load_dwordx4 v[128:131], v[176:177], off offset:528
	global_load_dwordx4 v[132:135], v[176:177], off offset:512
	v_lshlrev_b64 v[216:217], 11, v[156:157]
	v_readlane_b32 s24, v250, 9
	v_lshl_add_u64 v[216:217], v[216:217], 0, v[154:155]
	v_readlane_b32 s25, v250, 10
	v_cmp_lt_i32_e32 vcc, v208, v206
	s_ashr_i32 s15, s14, 31
	s_waitcnt vmcnt(0)
	v_pk_add_f32 v[120:121], v[120:121], v[182:183]
	v_pk_add_f32 v[126:127], v[126:127], v[188:189]
	v_pk_add_f32 v[124:125], v[124:125], v[186:187]
	v_pk_add_f32 v[122:123], v[122:123], v[184:185]
	global_store_dwordx4 v[214:215], v[124:127], off
	global_store_dwordx4 v[214:215], v[120:123], off offset:16
	v_cvt_pk_bf16_f32 v184, v120, v121
	v_cvt_pk_bf16_f32 v182, v124, v125
	v_mul_f32_e32 v121, v121, v121
	v_cvt_pk_bf16_f32 v183, v126, v127
	v_cvt_pk_bf16_f32 v185, v122, v123
	v_lshl_add_u64 v[186:187], v[216:217], 1, s[24:25]
	v_fmac_f32_e32 v121, v120, v120
	v_pk_add_f32 v[118:119], v[118:119], v[196:197]
	v_pk_add_f32 v[116:117], v[116:117], v[194:195]
	v_pk_add_f32 v[112:113], v[112:113], v[190:191]
	global_store_dwordx4 v[186:187], v[182:185], off
	v_mul_f32_e32 v125, v125, v125
	v_fmac_f32_e32 v121, v122, v122
	v_pk_add_f32 v[114:115], v[114:115], v[192:193]
	global_store_dwordx4 v[214:215], v[116:119], off offset:512
	global_store_dwordx4 v[214:215], v[112:115], off offset:528
	v_cvt_pk_bf16_f32 v120, v116, v117
	v_cvt_pk_bf16_f32 v122, v112, v113
	v_mul_f32_e32 v117, v117, v117
	v_mul_f32_e32 v113, v113, v113
	v_fmac_f32_e32 v125, v124, v124
	v_fmac_f32_e32 v117, v116, v116
	v_fmac_f32_e32 v113, v112, v112
	v_fmac_f32_e32 v125, v126, v126
	v_fmac_f32_e32 v117, v118, v118
	v_fmac_f32_e32 v113, v114, v114
	v_fmac_f32_e32 v125, v127, v127
	v_fmac_f32_e32 v121, v123, v123
	v_fmac_f32_e32 v117, v119, v119
	v_fmac_f32_e32 v113, v115, v115
	v_add_f32_e32 v124, v125, v121
	v_add_f32_e32 v112, v117, v113
	v_cndmask_b32_e32 v113, v204, v208, vcc
	v_cvt_pk_bf16_f32 v121, v118, v119
	v_add_f32_e32 v112, v124, v112
	v_lshlrev_b32_e32 v118, 2, v113
	ds_bpermute_b32 v113, v118, v112
	v_cmp_lt_i32_e32 vcc, v207, v206
	v_cvt_pk_bf16_f32 v123, v114, v115
	global_store_dwordx4 v[186:187], v[120:123], off offset:256
	s_waitcnt lgkmcnt(0)
	v_add_f32_e32 v112, v112, v113
	v_cndmask_b32_e32 v113, v204, v207, vcc
	v_lshlrev_b32_e32 v119, 2, v113
	ds_bpermute_b32 v113, v119, v112
	s_and_saveexec_b64 s[24:25], s[6:7]
	s_cbranch_execz .LBB0_67
	s_waitcnt lgkmcnt(0)
	v_add_f32_e32 v112, v112, v113
	s_mov_b64 s[26:27], -1
	s_and_b64 vcc, exec, s[12:13]
	s_cbranch_vccz .LBB0_65
	v_readlane_b32 s26, v250, 37
	v_lshlrev_b64 v[114:115], 5, v[156:157]
	v_readlane_b32 s27, v250, 38
	s_nop 1
	v_lshl_add_u64 v[114:115], s[26:27], 0, v[114:115]
	v_lshl_add_u64 v[114:115], s[14:15], 2, v[114:115]
	global_atomic_add_f32 v[114:115], v112, off
	s_mov_b64 s[26:27], 0

; #define PG8_STAGE(bufoff, gbase, voff) do { _Pragma("unroll") for (int _i = 0; _i < 2; ++_i) \
;         __builtin_amdgcn_global_load_lds((const unsigned*)((const char*)(gbase) + (voff)[_i]), (LAS unsigned*)(lds + (bufoff) + ldsw + _i * 8192), 16, 0, 0); } while (0)
; #define PG8_LDA(dst, b, h) do { _Pragma("unroll") for (int m = 0; m < 4; ++m) _Pragma("unroll") for (int k = 0; k < 2; ++k) dst[m][k] = *(const LAS bf16x8*)(lds + PG8_SA(b, h) + aoff + m * 2048 + k * 1024); } while (0)
; #define PG8_LDB(dst, b, h) do { _Pragma("unroll") for (int n = 0; n < 2; ++n) _Pragma("unroll") for (int k = 0; k < 2; ++k) dst[n][k] = *(const LAS bf16x8*)(lds + PG8_SB(b, h) + boff + n * 2048 + k * 1024); } while (0)
; #define PG8_MMA(ai, bj, At, Bt) do { __builtin_amdgcn_s_setprio(1); _Pragma("unroll") for (int m = 0; m < 4; ++m) _Pragma("unroll") for (int n = 0; n < 2; ++n) _Pragma("unroll") for (int k = 0; k < 2; ++k) \
;         acc[ai][bj][m][n] = __builtin_amdgcn_mfma_f32_16x16x32_bf16(Bt[n][k], At[m][k], acc[ai][bj][m][n], 0, 0, 0); __builtin_amdgcn_s_setprio(0); } while (0)
; #define PG8_WAIT_V(n) asm volatile("s_waitcnt vmcnt(" #n ")" ::: "memory")
; #define PG8_WAIT_L(n) asm volatile("s_waitcnt lgkmcnt(" #n ")" ::: "memory")
; #define PG8_BAR __builtin_amdgcn_s_barrier()
; #define PG8_SCHED __builtin_amdgcn_sched_barrier(0)
; template <class Epi>
; DEV void gemm_phase(LAS unsigned char* lds, const Gemm g, const StaticOrder& S, const Epi& E) {
;     ...
;             PG8_LDB(B0, 0, 0); PG8_SCHED; PG8_LDA(At, 0, 0); PG8_STAGE(PG8_SA(1, 1), a1 + hstep, voffA);
;             PG8_WAIT_L(8); PG8_BAR; PG8_WAIT_L(0); PG8_MMA(0, 0, At, B0); PG8_BAR; PG8_SCHED;
;             PG8_LDB(B1, 0, 1); PG8_STAGE(PG8_SB(0, 0), b2, voffB);
;             PG8_BAR; PG8_WAIT_L(0); PG8_MMA(0, 1, At, B1); PG8_BAR;
;             PG8_LDA(At, 0, 1); PG8_STAGE(PG8_SA(0, 0), a2, voffA);
;             PG8_BAR; PG8_WAIT_L(0); PG8_MMA(1, 0, At, B0); PG8_BAR; PG8_SCHED;
;             PG8_STAGE(PG8_SB(0, 1), b2 + hstep, voffB);
;             PG8_WAIT_V(6); PG8_BAR; PG8_MMA(1, 1, At, B1); PG8_BAR;
;             PG8_LDB(B0, 1, 0); PG8_SCHED; PG8_LDA(At, 1, 0); PG8_STAGE(PG8_SA(0, 1), a2 + hstep, voffA);
.LBB0_152:
	s_add_u32 s20, s18, 0xfff80080
	s_addc_u32 s21, s19, -1
	s_add_i32 s41, 0, 0x10000
	v_add_u32_e32 v140, s41, v176
	ds_read_b128 v[128:131], v140
	ds_read_b128 v[132:135], v140 offset:1024
	ds_read_b128 v[136:139], v140 offset:2048
	ds_read_b128 v[140:143], v140 offset:3072
	s_cmp_eq_u32 s40, 28
	s_cselect_b32 s23, s5, s21
	s_cselect_b32 s22, s11, s20
	s_cselect_b32 s21, s9, s39
	s_cselect_b32 s20, s37, s38
	s_add_i32 m0, s17, 0xc000
	ds_read_b128 v[180:183], v178
	ds_read_b128 v[184:187], v178 offset:1024
	ds_read_b128 v[188:191], v178 offset:2048
	ds_read_b128 v[192:195], v178 offset:3072
	ds_read_b128 v[214:217], v178 offset:4096
	ds_read_b128 v[218:221], v178 offset:5120
	ds_read_b128 v[222:225], v178 offset:6144
	ds_read_b128 v[226:229], v178 offset:7168
	global_load_lds_dwordx4 v154, s[18:19]
	s_add_i32 m0, s17, 0xe000
	s_nop 0
	global_load_lds_dwordx4 v156, s[18:19]
	s_waitcnt lgkmcnt(8)
	s_waitcnt vmcnt(10)
	s_barrier
	s_waitcnt lgkmcnt(0)
	v_mfma_f32_16x16x32_bf16 v[124:127], v[128:131], v[180:183], v[124:127]
	v_mfma_f32_16x16x32_bf16 v[120:123], v[136:139], v[180:183], v[120:123]
	v_mfma_f32_16x16x32_bf16 v[108:111], v[128:131], v[188:191], v[108:111]
	v_mfma_f32_16x16x32_bf16 v[104:107], v[136:139], v[188:191], v[104:107]
	v_mfma_f32_16x16x32_bf16 v[92:95], v[128:131], v[214:217], v[92:95]
	v_mfma_f32_16x16x32_bf16 v[88:91], v[136:139], v[214:217], v[88:91]
	v_mfma_f32_16x16x32_bf16 v[76:79], v[128:131], v[222:225], v[76:79]
	v_mfma_f32_16x16x32_bf16 v[72:75], v[136:139], v[222:225], v[72:75]
	v_mfma_f32_16x16x32_bf16 v[124:127], v[132:135], v[184:187], v[124:127]
	v_mfma_f32_16x16x32_bf16 v[120:123], v[140:143], v[184:187], v[120:123]
	v_mfma_f32_16x16x32_bf16 v[108:111], v[132:135], v[192:195], v[108:111]
	v_mfma_f32_16x16x32_bf16 v[104:107], v[140:143], v[192:195], v[104:107]
	v_mfma_f32_16x16x32_bf16 v[92:95], v[132:135], v[218:221], v[92:95]
	v_mfma_f32_16x16x32_bf16 v[88:91], v[140:143], v[218:221], v[88:91]
	v_mfma_f32_16x16x32_bf16 v[76:79], v[132:135], v[226:229], v[76:79]
	v_mfma_f32_16x16x32_bf16 v[72:75], v[140:143], v[226:229], v[72:75]
	s_barrier
	s_add_i32 s44, 0, 0x14000
	v_add_u32_e32 v158, s44, v176
	s_add_i32 s41, s41, s26
	ds_read_b128 v[230:233], v158
	ds_read_b128 v[234:237], v158 offset:1024
	ds_read_b128 v[238:241], v158 offset:2048
	ds_read_b128 v[242:245], v158 offset:3072
	v_lshl_add_u64 v[158:159], s[20:21], 0, v[160:161]
	s_mov_b32 m0, s41
	v_lshl_add_u64 v[174:175], s[20:21], 0, v[144:145]
	global_load_lds_dwordx4 v160, s[20:21]
	s_add_i32 m0, s41, 0x2000
	s_nop 0
	global_load_lds_dwordx4 v144, s[20:21]
	s_waitcnt vmcnt(10)
	s_barrier
	s_waitcnt lgkmcnt(0)
	v_mfma_f32_16x16x32_bf16 v[116:119], v[230:233], v[180:183], v[116:119]
	v_mfma_f32_16x16x32_bf16 v[112:115], v[238:241], v[180:183], v[112:115]
	v_mfma_f32_16x16x32_bf16 v[100:103], v[230:233], v[188:191], v[100:103]
	v_mfma_f32_16x16x32_bf16 v[96:99], v[238:241], v[188:191], v[96:99]
	v_mfma_f32_16x16x32_bf16 v[84:87], v[230:233], v[214:217], v[84:87]
	v_mfma_f32_16x16x32_bf16 v[80:83], v[238:241], v[214:217], v[80:83]
	v_mfma_f32_16x16x32_bf16 v[68:71], v[230:233], v[222:225], v[68:71]
	v_mfma_f32_16x16x32_bf16 v[64:67], v[238:241], v[222:225], v[64:67]
	v_mfma_f32_16x16x32_bf16 v[116:119], v[234:237], v[184:187], v[116:119]
	v_mfma_f32_16x16x32_bf16 v[112:115], v[242:245], v[184:187], v[112:115]
	v_mfma_f32_16x16x32_bf16 v[100:103], v[234:237], v[192:195], v[100:103]
	v_mfma_f32_16x16x32_bf16 v[96:99], v[242:245], v[192:195], v[96:99]
	v_mfma_f32_16x16x32_bf16 v[84:87], v[234:237], v[218:221], v[84:87]
	v_mfma_f32_16x16x32_bf16 v[80:83], v[242:245], v[218:221], v[80:83]
	v_mfma_f32_16x16x32_bf16 v[68:71], v[234:237], v[226:229], v[68:71]
	v_mfma_f32_16x16x32_bf16 v[64:67], v[242:245], v[226:229], v[64:67]
	s_mov_b32 m0, s17
	v_lshl_add_u64 v[196:197], s[22:23], 0, v[160:161]
	s_barrier
	ds_read_b128 v[180:183], v178 offset:16384
	ds_read_b128 v[184:187], v178 offset:17408
	ds_read_b128 v[188:191], v178 offset:18432
	ds_read_b128 v[192:195], v178 offset:19456
	ds_read_b128 v[214:217], v178 offset:20480
	ds_read_b128 v[218:221], v178 offset:21504
	ds_read_b128 v[222:225], v178 offset:22528
	ds_read_b128 v[226:229], v178 offset:23552
	global_load_lds_dwordx4 v160, s[22:23]
	v_lshl_add_u64 v[246:247], s[22:23], 0, v[144:145]
	s_mov_b32 m0, s27
	s_nop 0
	global_load_lds_dwordx4 v144, s[22:23]
	s_barrier
	s_waitcnt lgkmcnt(0)
	v_mfma_f32_16x16x32_bf16 v[60:63], v[128:131], v[180:183], v[60:63]
	v_mfma_f32_16x16x32_bf16 v[56:59], v[136:139], v[180:183], v[56:59]
	v_mfma_f32_16x16x32_bf16 v[44:47], v[128:131], v[188:191], v[44:47]
	v_mfma_f32_16x16x32_bf16 v[40:43], v[136:139], v[188:191], v[40:43]
	v_mfma_f32_16x16x32_bf16 v[28:31], v[128:131], v[214:217], v[28:31]
	v_mfma_f32_16x16x32_bf16 v[24:27], v[136:139], v[214:217], v[24:27]
	v_mfma_f32_16x16x32_bf16 v[12:15], v[128:131], v[222:225], v[12:15]
	v_mfma_f32_16x16x32_bf16 v[8:11], v[136:139], v[222:225], v[8:11]
	v_mfma_f32_16x16x32_bf16 v[60:63], v[132:135], v[184:187], v[60:63]
	v_mfma_f32_16x16x32_bf16 v[56:59], v[140:143], v[184:187], v[56:59]
	v_mfma_f32_16x16x32_bf16 v[44:47], v[132:135], v[192:195], v[44:47]
	v_mfma_f32_16x16x32_bf16 v[40:43], v[140:143], v[192:195], v[40:43]
	v_mfma_f32_16x16x32_bf16 v[28:31], v[132:135], v[218:221], v[28:31]
	v_mfma_f32_16x16x32_bf16 v[24:27], v[140:143], v[218:221], v[24:27]
	v_mfma_f32_16x16x32_bf16 v[12:15], v[132:135], v[226:229], v[12:15]
	v_mfma_f32_16x16x32_bf16 v[8:11], v[140:143], v[226:229], v[8:11]
	s_barrier
; #define PG8_STAGE(bufoff, gbase, voff) do { _Pragma("unroll") for (int _i = 0; _i < 2; ++_i) \
;         __builtin_amdgcn_global_load_lds((const unsigned*)((const char*)(gbase) + (voff)[_i]), (LAS unsigned*)(lds + (bufoff) + ldsw + _i * 8192), 16, 0, 0); } while (0)
; #define PG8_LDA(dst, b, h) do { _Pragma("unroll") for (int m = 0; m < 4; ++m) _Pragma("unroll") for (int k = 0; k < 2; ++k) dst[m][k] = *(const LAS bf16x8*)(lds + PG8_SA(b, h) + aoff + m * 2048 + k * 1024); } while (0)
; #define PG8_LDB(dst, b, h) do { _Pragma("unroll") for (int n = 0; n < 2; ++n) _Pragma("unroll") for (int k = 0; k < 2; ++k) dst[n][k] = *(const LAS bf16x8*)(lds + PG8_SB(b, h) + boff + n * 2048 + k * 1024); } while (0)
; #define PG8_MMA(ai, bj, At, Bt) do { __builtin_amdgcn_s_setprio(1); _Pragma("unroll") for (int m = 0; m < 4; ++m) _Pragma("unroll") for (int n = 0; n < 2; ++n) _Pragma("unroll") for (int k = 0; k < 2; ++k) \
;         acc[ai][bj][m][n] = __builtin_amdgcn_mfma_f32_16x16x32_bf16(Bt[n][k], At[m][k], acc[ai][bj][m][n], 0, 0, 0); __builtin_amdgcn_s_setprio(0); } while (0)
; #define PG8_WAIT_V(n) asm volatile("s_waitcnt vmcnt(" #n ")" ::: "memory")
; #define PG8_WAIT_L(n) asm volatile("s_waitcnt lgkmcnt(" #n ")" ::: "memory")
; #define PG8_BAR __builtin_amdgcn_s_barrier()
; #define PG8_SCHED __builtin_amdgcn_sched_barrier(0)
; template <class Epi>
; DEV void gemm_phase(LAS unsigned char* lds, const Gemm g, const StaticOrder& S, const Epi& E) {
;     ...
;             PG8_WAIT_V(6); PG8_BAR; PG8_MMA(1, 1, At, B1); PG8_BAR;
;             PG8_LDB(B0, 1, 0); PG8_SCHED; PG8_LDA(At, 1, 0); PG8_STAGE(PG8_SA(0, 1), a2 + hstep, voffA);
;             PG8_WAIT_L(8); PG8_BAR; PG8_WAIT_L(0); PG8_MMA(0, 0, At, B0); PG8_BAR; PG8_SCHED;
;             PG8_LDB(B1, 1, 1); PG8_STAGE(PG8_SB(1, 0), b3, voffB);
;             PG8_BAR; PG8_WAIT_L(0); PG8_MMA(0, 1, At, B1); PG8_BAR;
;             PG8_LDA(At, 1, 1); PG8_STAGE(PG8_SA(1, 0), a3, voffA);
	s_add_u32 s42, s20, 0x80000
	s_addc_u32 s43, s21, 0
	s_add_i32 s41, s44, s26
	s_mov_b32 m0, s41
	s_nop 0
	global_load_lds_dwordx4 v160, s[42:43]
	s_add_i32 m0, s41, 0x2000
	s_nop 0
	global_load_lds_dwordx4 v144, s[42:43]
	s_waitcnt vmcnt(10)
	s_barrier
	v_mfma_f32_16x16x32_bf16 v[52:55], v[230:233], v[180:183], v[52:55]
	v_mfma_f32_16x16x32_bf16 v[48:51], v[238:241], v[180:183], v[48:51]
	v_mfma_f32_16x16x32_bf16 v[36:39], v[230:233], v[188:191], v[36:39]
	v_mfma_f32_16x16x32_bf16 v[32:35], v[238:241], v[188:191], v[32:35]
	v_mfma_f32_16x16x32_bf16 v[20:23], v[230:233], v[214:217], v[20:23]
	v_mfma_f32_16x16x32_bf16 v[16:19], v[238:241], v[214:217], v[16:19]
	v_mfma_f32_16x16x32_bf16 v[4:7], v[230:233], v[222:225], v[4:7]
	v_mfma_f32_16x16x32_bf16 v[0:3], v[238:241], v[222:225], v[0:3]
	v_mfma_f32_16x16x32_bf16 v[52:55], v[234:237], v[184:187], v[52:55]
	v_mfma_f32_16x16x32_bf16 v[48:51], v[242:245], v[184:187], v[48:51]
	v_mfma_f32_16x16x32_bf16 v[36:39], v[234:237], v[192:195], v[36:39]
	v_mfma_f32_16x16x32_bf16 v[32:35], v[242:245], v[192:195], v[32:35]
	v_mfma_f32_16x16x32_bf16 v[20:23], v[234:237], v[218:221], v[20:23]
	v_mfma_f32_16x16x32_bf16 v[16:19], v[242:245], v[218:221], v[16:19]
	v_mfma_f32_16x16x32_bf16 v[4:7], v[234:237], v[226:229], v[4:7]
	v_mfma_f32_16x16x32_bf16 v[0:3], v[242:245], v[226:229], v[0:3]
	s_add_i32 s41, 0, 0x18000
	v_add_u32_e32 v140, s41, v176
	s_barrier
	ds_read_b128 v[128:131], v140
	ds_read_b128 v[132:135], v140 offset:1024
	ds_read_b128 v[136:139], v140 offset:2048
	ds_read_b128 v[140:143], v140 offset:3072
	s_add_u32 s22, s22, 0x80000
	s_addc_u32 s23, s23, 0
	s_mov_b32 m0, s28
	ds_read_b128 v[180:183], v178 offset:32768
	ds_read_b128 v[184:187], v178 offset:33792
	ds_read_b128 v[188:191], v178 offset:34816
	ds_read_b128 v[192:195], v178 offset:35840
	ds_read_b128 v[214:217], v178 offset:36864
	ds_read_b128 v[218:221], v178 offset:37888
	ds_read_b128 v[222:225], v178 offset:38912
	ds_read_b128 v[226:229], v178 offset:39936
	global_load_lds_dwordx4 v160, s[22:23]
	s_mov_b32 m0, s29
	s_nop 0
	global_load_lds_dwordx4 v144, s[22:23]
	s_waitcnt lgkmcnt(8)
	s_waitcnt vmcnt(10)
	s_barrier
	s_waitcnt lgkmcnt(0)
	v_mfma_f32_16x16x32_bf16 v[124:127], v[128:131], v[180:183], v[124:127]
	v_mfma_f32_16x16x32_bf16 v[120:123], v[136:139], v[180:183], v[120:123]
	v_mfma_f32_16x16x32_bf16 v[108:111], v[128:131], v[188:191], v[108:111]
	v_mfma_f32_16x16x32_bf16 v[104:107], v[136:139], v[188:191], v[104:107]
	v_mfma_f32_16x16x32_bf16 v[92:95], v[128:131], v[214:217], v[92:95]
	v_mfma_f32_16x16x32_bf16 v[88:91], v[136:139], v[214:217], v[88:91]
	v_mfma_f32_16x16x32_bf16 v[76:79], v[128:131], v[222:225], v[76:79]
	v_mfma_f32_16x16x32_bf16 v[72:75], v[136:139], v[222:225], v[72:75]
	v_mfma_f32_16x16x32_bf16 v[124:127], v[132:135], v[184:187], v[124:127]
	v_mfma_f32_16x16x32_bf16 v[120:123], v[140:143], v[184:187], v[120:123]
	v_mfma_f32_16x16x32_bf16 v[108:111], v[132:135], v[192:195], v[108:111]
	v_mfma_f32_16x16x32_bf16 v[104:107], v[140:143], v[192:195], v[104:107]
	v_mfma_f32_16x16x32_bf16 v[92:95], v[132:135], v[218:221], v[92:95]
	v_mfma_f32_16x16x32_bf16 v[88:91], v[140:143], v[218:221], v[88:91]
	v_mfma_f32_16x16x32_bf16 v[76:79], v[132:135], v[226:229], v[76:79]
	v_mfma_f32_16x16x32_bf16 v[72:75], v[140:143], v[226:229], v[72:75]
	s_barrier
	s_add_i32 s22, 0, 0x1c000
	s_add_i32 s23, s41, s26
	v_add_u32_e32 v179, s22, v176
	v_lshl_add_u64 v[158:159], v[158:159], 0, s[2:3]
	s_mov_b32 m0, s23
	ds_read_b128 v[230:233], v179
	ds_read_b128 v[234:237], v179 offset:1024
	ds_read_b128 v[238:241], v179 offset:2048
	ds_read_b128 v[242:245], v179 offset:3072
	global_load_lds_dwordx4 v[158:159], off
	v_lshl_add_u64 v[158:159], v[174:175], 0, s[2:3]
	s_add_i32 m0, s23, 0x2000
	s_nop 0
	global_load_lds_dwordx4 v[158:159], off
	s_waitcnt vmcnt(10)
	s_barrier
	s_waitcnt lgkmcnt(0)
	v_mfma_f32_16x16x32_bf16 v[116:119], v[230:233], v[180:183], v[116:119]
	v_mfma_f32_16x16x32_bf16 v[112:115], v[238:241], v[180:183], v[112:115]
	v_mfma_f32_16x16x32_bf16 v[100:103], v[230:233], v[188:191], v[100:103]
	v_mfma_f32_16x16x32_bf16 v[96:99], v[238:241], v[188:191], v[96:99]
	v_mfma_f32_16x16x32_bf16 v[84:87], v[230:233], v[214:217], v[84:87]
	v_mfma_f32_16x16x32_bf16 v[80:83], v[238:241], v[214:217], v[80:83]
	v_mfma_f32_16x16x32_bf16 v[68:71], v[230:233], v[222:225], v[68:71]
	v_mfma_f32_16x16x32_bf16 v[64:67], v[238:241], v[222:225], v[64:67]
	v_mfma_f32_16x16x32_bf16 v[116:119], v[234:237], v[184:187], v[116:119]
	v_mfma_f32_16x16x32_bf16 v[112:115], v[242:245], v[184:187], v[112:115]
	v_mfma_f32_16x16x32_bf16 v[100:103], v[234:237], v[192:195], v[100:103]
	v_mfma_f32_16x16x32_bf16 v[96:99], v[242:245], v[192:195], v[96:99]
	v_mfma_f32_16x16x32_bf16 v[84:87], v[234:237], v[218:221], v[84:87]
	v_mfma_f32_16x16x32_bf16 v[80:83], v[242:245], v[218:221], v[80:83]
	v_mfma_f32_16x16x32_bf16 v[68:71], v[234:237], v[226:229], v[68:71]
	v_mfma_f32_16x16x32_bf16 v[64:67], v[242:245], v[226:229], v[64:67]
	s_mov_b32 m0, s30
	v_lshl_add_u64 v[158:159], v[196:197], 0, s[2:3]
	s_barrier
; #define PG8_STAGE(bufoff, gbase, voff) do { _Pragma("unroll") for (int _i = 0; _i < 2; ++_i) \
;         __builtin_amdgcn_global_load_lds((const unsigned*)((const char*)(gbase) + (voff)[_i]), (LAS unsigned*)(lds + (bufoff) + ldsw + _i * 8192), 16, 0, 0); } while (0)
; #define PG8_LDA(dst, b, h) do { _Pragma("unroll") for (int m = 0; m < 4; ++m) _Pragma("unroll") for (int k = 0; k < 2; ++k) dst[m][k] = *(const LAS bf16x8*)(lds + PG8_SA(b, h) + aoff + m * 2048 + k * 1024); } while (0)
; #define PG8_LDB(dst, b, h) do { _Pragma("unroll") for (int n = 0; n < 2; ++n) _Pragma("unroll") for (int k = 0; k < 2; ++k) dst[n][k] = *(const LAS bf16x8*)(lds + PG8_SB(b, h) + boff + n * 2048 + k * 1024); } while (0)
; #define PG8_WAIT_V(n) asm volatile("s_waitcnt vmcnt(" #n ")" ::: "memory")
; #define PG8_WAIT_L(n) asm volatile("s_waitcnt lgkmcnt(" #n ")" ::: "memory")
; template <class Epi>
; DEV void gemm_phase(LAS unsigned char* lds, const Gemm g, const StaticOrder& S, const Epi& E) {
;     ...
;             PG8_LDB(B0, 1, 0); PG8_SCHED; PG8_LDA(At, 1, 0); PG8_STAGE(PG8_SA(0, 1), a2 + hstep, voffA);
;             PG8_WAIT_L(8); PG8_BAR; PG8_WAIT_L(0); PG8_MMA(0, 0, At, B0); PG8_BAR; PG8_SCHED;
;             PG8_LDB(B1, 1, 1); PG8_STAGE(PG8_SB(1, 0), b3, voffB);
;             PG8_BAR; PG8_WAIT_L(0); PG8_MMA(0, 1, At, B1); PG8_BAR;
;             PG8_LDA(At, 1, 1); PG8_STAGE(PG8_SA(1, 0), a3, voffA);
;             PG8_BAR; PG8_WAIT_L(0); PG8_MMA(1, 0, At, B0); PG8_BAR; PG8_SCHED;
;             PG8_STAGE(PG8_SB(1, 1), b3 + hstep, voffB);
;             PG8_WAIT_V(6); PG8_BAR; PG8_MMA(1, 1, At, B1); PG8_BAR;
;         }
;         E(acc, cur, wr, wc, fr, fq);
;     DEV void operator()(AccRef acc, const pg8::Unit& u, int wr, int wc, int fr, int fq) const {
;         const int row0 = u.pm * 256 + wr * 64 + fr, col0 = u.pn * 256 + wc * 32 + 4 * fq;
;         const bool rope = (u.pn < 9) && ((wc & 1) == 0);
; #pragma unroll
;         for (int ai = 0; ai < 2; ++ai)
; #pragma unroll
;             for (int m = 0; m < 4; ++m) { const int row = row0 + ai * 128 + m * 16; u16* rowp = O + (size_t)row * 2560 + col0; const float rs = rowscale(ss, row);
;                 f32x4 cs = (f32x4){1.f, 1.f, 1.f, 1.f}, sn = (f32x4){0.f, 0.f, 0.f, 0.f};
;                 if (rope) { cs = *(const f32x4*)(cosT + row * 8 + 4 * (fq & 1)); sn = *(const f32x4*)(sinT + row * 8 + 4 * (fq & 1)); }
	ds_read_b128 v[180:183], v178 offset:49152
	ds_read_b128 v[184:187], v178 offset:50176
	ds_read_b128 v[188:191], v178 offset:51200
	ds_read_b128 v[192:195], v178 offset:52224
	ds_read_b128 v[214:217], v178 offset:53248
	ds_read_b128 v[218:221], v178 offset:54272
	ds_read_b128 v[222:225], v178 offset:55296
	ds_read_b128 v[226:229], v178 offset:56320
	global_load_lds_dwordx4 v[158:159], off
	v_lshl_add_u64 v[158:159], v[246:247], 0, s[2:3]
	s_mov_b32 m0, s31
	s_nop 0
	global_load_lds_dwordx4 v[158:159], off
	s_barrier
	s_waitcnt lgkmcnt(0)
	v_mfma_f32_16x16x32_bf16 v[60:63], v[128:131], v[180:183], v[60:63]
	v_mfma_f32_16x16x32_bf16 v[56:59], v[136:139], v[180:183], v[56:59]
	v_mfma_f32_16x16x32_bf16 v[44:47], v[128:131], v[188:191], v[44:47]
	v_mfma_f32_16x16x32_bf16 v[40:43], v[136:139], v[188:191], v[40:43]
	v_mfma_f32_16x16x32_bf16 v[28:31], v[128:131], v[214:217], v[28:31]
	v_mfma_f32_16x16x32_bf16 v[24:27], v[136:139], v[214:217], v[24:27]
	v_mfma_f32_16x16x32_bf16 v[12:15], v[128:131], v[222:225], v[12:15]
	v_mfma_f32_16x16x32_bf16 v[8:11], v[136:139], v[222:225], v[8:11]
	v_mfma_f32_16x16x32_bf16 v[60:63], v[132:135], v[184:187], v[60:63]
	v_mfma_f32_16x16x32_bf16 v[56:59], v[140:143], v[184:187], v[56:59]
	v_mfma_f32_16x16x32_bf16 v[44:47], v[132:135], v[192:195], v[44:47]
	v_mfma_f32_16x16x32_bf16 v[40:43], v[140:143], v[192:195], v[40:43]
	v_mfma_f32_16x16x32_bf16 v[28:31], v[132:135], v[218:221], v[28:31]
	v_mfma_f32_16x16x32_bf16 v[24:27], v[140:143], v[218:221], v[24:27]
	v_mfma_f32_16x16x32_bf16 v[12:15], v[132:135], v[226:229], v[12:15]
	v_mfma_f32_16x16x32_bf16 v[8:11], v[140:143], v[226:229], v[8:11]
	s_barrier
	s_add_u32 s20, s20, 0x80080
	s_addc_u32 s21, s21, 0
	s_add_i32 s22, s22, s26
	s_mov_b32 m0, s22
	s_nop 0
	global_load_lds_dwordx4 v160, s[20:21]
	s_add_i32 m0, s22, 0x2000
	s_nop 0
	global_load_lds_dwordx4 v144, s[20:21]
	s_waitcnt vmcnt(10)
	s_barrier
	v_mfma_f32_16x16x32_bf16 v[52:55], v[230:233], v[180:183], v[52:55]
	v_mfma_f32_16x16x32_bf16 v[48:51], v[238:241], v[180:183], v[48:51]
	v_mfma_f32_16x16x32_bf16 v[36:39], v[230:233], v[188:191], v[36:39]
	v_mfma_f32_16x16x32_bf16 v[32:35], v[238:241], v[188:191], v[32:35]
	v_mfma_f32_16x16x32_bf16 v[20:23], v[230:233], v[214:217], v[20:23]
	v_mfma_f32_16x16x32_bf16 v[16:19], v[238:241], v[214:217], v[16:19]
	v_mfma_f32_16x16x32_bf16 v[4:7], v[230:233], v[222:225], v[4:7]
	v_mfma_f32_16x16x32_bf16 v[0:3], v[238:241], v[222:225], v[0:3]
	v_mfma_f32_16x16x32_bf16 v[52:55], v[234:237], v[184:187], v[52:55]
	v_mfma_f32_16x16x32_bf16 v[48:51], v[242:245], v[184:187], v[48:51]
	v_mfma_f32_16x16x32_bf16 v[36:39], v[234:237], v[192:195], v[36:39]
	v_mfma_f32_16x16x32_bf16 v[32:35], v[242:245], v[192:195], v[32:35]
	v_mfma_f32_16x16x32_bf16 v[20:23], v[234:237], v[218:221], v[20:23]
	v_mfma_f32_16x16x32_bf16 v[16:19], v[242:245], v[218:221], v[16:19]
	v_mfma_f32_16x16x32_bf16 v[4:7], v[234:237], v[226:229], v[4:7]
	v_mfma_f32_16x16x32_bf16 v[0:3], v[242:245], v[226:229], v[0:3]
	s_add_i32 s40, s40, 2
	s_add_u32 s18, s18, 0x100
	s_addc_u32 s19, s19, 0
	s_add_u32 s38, s38, 0x100
	s_addc_u32 s39, s39, 0
	s_cmp_gt_u32 s40, 29
	s_barrier
	s_cbranch_scc0 .LBB0_152
	v_lshl_add_u32 v174, s4, 8, v167
	v_ashrrev_i32_e32 v175, 31, v174
	v_readlane_b32 s20, v250, 47
	v_lshlrev_b64 v[128:129], 5, v[174:175]
	v_readlane_b32 s21, v250, 48
	s_cmp_lt_i32 s16, 9
	s_cselect_b64 s[4:5], -1, 0
	v_lshl_add_u64 v[128:129], s[20:21], 0, v[128:129]
	global_load_dwordx4 v[136:139], v[128:129], off offset:16
	global_load_dwordx4 v[140:143], v[128:129], off
	s_and_b64 s[18:19], s[6:7], s[4:5]
	v_cndmask_b32_e64 v128, 0, 1, s[18:19]
	v_cmp_ne_u32_e64 s[4:5], 1, v128
	s_andn2_b64 vcc, exec, s[18:19]
	s_cbranch_vccnz .LBB0_155
	v_lshlrev_b32_e32 v128, 3, v174
	v_ashrrev_i32_e32 v129, 31, v128
	v_lshlrev_b64 v[128:129], 2, v[128:129]
	v_lshl_add_u64 v[130:131], v[152:153], 0, v[128:129]
	v_lshl_add_u64 v[132:133], v[150:151], 0, v[128:129]
	global_load_dwordx4 v[128:131], v[130:131], off
	s_nop 0
	global_load_dwordx4 v[132:135], v[132:133], off
	s_branch .LBB0_156

; #define PG8_STAGE(bufoff, gbase, voff) do { _Pragma("unroll") for (int _i = 0; _i < 2; ++_i) \
;         __builtin_amdgcn_global_load_lds((const unsigned*)((const char*)(gbase) + (voff)[_i]), (LAS unsigned*)(lds + (bufoff) + ldsw + _i * 8192), 16, 0, 0); } while (0)
; #define PG8_LDA(dst, b, h) do { _Pragma("unroll") for (int m = 0; m < 4; ++m) _Pragma("unroll") for (int k = 0; k < 2; ++k) dst[m][k] = *(const LAS bf16x8*)(lds + PG8_SA(b, h) + aoff + m * 2048 + k * 1024); } while (0)
; #define PG8_LDB(dst, b, h) do { _Pragma("unroll") for (int n = 0; n < 2; ++n) _Pragma("unroll") for (int k = 0; k < 2; ++k) dst[n][k] = *(const LAS bf16x8*)(lds + PG8_SB(b, h) + boff + n * 2048 + k * 1024); } while (0)
; #define PG8_MMA(ai, bj, At, Bt) do { __builtin_amdgcn_s_setprio(1); _Pragma("unroll") for (int m = 0; m < 4; ++m) _Pragma("unroll") for (int n = 0; n < 2; ++n) _Pragma("unroll") for (int k = 0; k < 2; ++k) \
;         acc[ai][bj][m][n] = __builtin_amdgcn_mfma_f32_16x16x32_bf16(Bt[n][k], At[m][k], acc[ai][bj][m][n], 0, 0, 0); __builtin_amdgcn_s_setprio(0); } while (0)
; #define PG8_WAIT_V(n) asm volatile("s_waitcnt vmcnt(" #n ")" ::: "memory")
; #define PG8_WAIT_L(n) asm volatile("s_waitcnt lgkmcnt(" #n ")" ::: "memory")
; #define PG8_BAR __builtin_amdgcn_s_barrier()
; #define PG8_SCHED __builtin_amdgcn_sched_barrier(0)
; template <class Epi>
; DEV void gemm_phase(LAS unsigned char* lds, const Gemm g, const StaticOrder& S, const Epi& E) {
;     ...
;             PG8_LDB(B0, 0, 0); PG8_SCHED; PG8_LDA(At, 0, 0); PG8_STAGE(PG8_SA(1, 1), a1 + hstep, voffA);
;             PG8_WAIT_L(8); PG8_BAR; PG8_WAIT_L(0); PG8_MMA(0, 0, At, B0); PG8_BAR; PG8_SCHED;
;             PG8_LDB(B1, 0, 1); PG8_STAGE(PG8_SB(0, 0), b2, voffB);
;             PG8_BAR; PG8_WAIT_L(0); PG8_MMA(0, 1, At, B1); PG8_BAR;
;             PG8_LDA(At, 0, 1); PG8_STAGE(PG8_SA(0, 0), a2, voffA);
;             PG8_BAR; PG8_WAIT_L(0); PG8_MMA(1, 0, At, B0); PG8_BAR; PG8_SCHED;
;             PG8_STAGE(PG8_SB(0, 1), b2 + hstep, voffB);
;             PG8_WAIT_V(6); PG8_BAR; PG8_MMA(1, 1, At, B1); PG8_BAR;
;             PG8_LDB(B0, 1, 0); PG8_SCHED; PG8_LDA(At, 1, 0); PG8_STAGE(PG8_SA(0, 1), a2 + hstep, voffA);
.LBB0_260:
	s_add_u32 s34, s30, 0xfffe0080
	s_addc_u32 s35, s31, -1
	s_add_i32 s55, 0, 0x10000
	v_add_u32_e32 v140, s55, v178
	ds_read_b128 v[128:131], v140
	ds_read_b128 v[132:135], v140 offset:1024
	ds_read_b128 v[136:139], v140 offset:2048
	ds_read_b128 v[140:143], v140 offset:3072
	s_cmp_eq_u32 s54, 4
	s_cselect_b32 s37, s19, s35
	s_cselect_b32 s36, s23, s34
	s_cselect_b32 s35, s21, s53
	s_cselect_b32 s34, s29, s52
	s_add_i32 m0, s43, 0xc000
	ds_read_b128 v[154:157], v181
	ds_read_b128 v[174:177], v181 offset:1024
	ds_read_b128 v[182:185], v181 offset:2048
	ds_read_b128 v[186:189], v181 offset:3072
	ds_read_b128 v[190:193], v181 offset:4096
	ds_read_b128 v[194:197], v181 offset:5120
	ds_read_b128 v[214:217], v181 offset:6144
	ds_read_b128 v[218:221], v181 offset:7168
	global_load_lds_dwordx4 v150, s[30:31]
	s_add_i32 m0, s43, 0xe000
	s_nop 0
	global_load_lds_dwordx4 v152, s[30:31]
	s_waitcnt lgkmcnt(8)
	s_waitcnt vmcnt(10)
	s_barrier
	s_waitcnt lgkmcnt(0)
	v_mfma_f32_16x16x32_bf16 v[124:127], v[128:131], v[154:157], v[124:127]
	v_mfma_f32_16x16x32_bf16 v[120:123], v[136:139], v[154:157], v[120:123]
	v_mfma_f32_16x16x32_bf16 v[108:111], v[128:131], v[182:185], v[108:111]
	v_mfma_f32_16x16x32_bf16 v[104:107], v[136:139], v[182:185], v[104:107]
	v_mfma_f32_16x16x32_bf16 v[92:95], v[128:131], v[190:193], v[92:95]
	v_mfma_f32_16x16x32_bf16 v[88:91], v[136:139], v[190:193], v[88:91]
	v_mfma_f32_16x16x32_bf16 v[76:79], v[128:131], v[214:217], v[76:79]
	v_mfma_f32_16x16x32_bf16 v[72:75], v[136:139], v[214:217], v[72:75]
	v_mfma_f32_16x16x32_bf16 v[124:127], v[132:135], v[174:177], v[124:127]
	v_mfma_f32_16x16x32_bf16 v[120:123], v[140:143], v[174:177], v[120:123]
	v_mfma_f32_16x16x32_bf16 v[108:111], v[132:135], v[186:189], v[108:111]
	v_mfma_f32_16x16x32_bf16 v[104:107], v[140:143], v[186:189], v[104:107]
	v_mfma_f32_16x16x32_bf16 v[92:95], v[132:135], v[194:197], v[92:95]
	v_mfma_f32_16x16x32_bf16 v[88:91], v[140:143], v[194:197], v[88:91]
	v_mfma_f32_16x16x32_bf16 v[76:79], v[132:135], v[218:221], v[76:79]
	v_mfma_f32_16x16x32_bf16 v[72:75], v[140:143], v[218:221], v[72:75]
	s_barrier
	s_add_i32 s58, 0, 0x14000
	v_add_u32_e32 v158, s58, v178
	s_add_i32 s55, s55, s42
	ds_read_b128 v[222:225], v158
	ds_read_b128 v[226:229], v158 offset:1024
	ds_read_b128 v[230:233], v158 offset:2048
	ds_read_b128 v[234:237], v158 offset:3072
	v_lshl_add_u64 v[158:159], s[34:35], 0, v[160:161]
	s_mov_b32 m0, s55
	v_lshl_add_u64 v[238:239], s[34:35], 0, v[148:149]
	global_load_lds_dwordx4 v160, s[34:35]
	s_add_i32 m0, s55, 0x2000
	s_nop 0
	global_load_lds_dwordx4 v148, s[34:35]
	s_waitcnt vmcnt(10)
	s_barrier
	s_waitcnt lgkmcnt(0)
	v_mfma_f32_16x16x32_bf16 v[116:119], v[222:225], v[154:157], v[116:119]
	v_mfma_f32_16x16x32_bf16 v[112:115], v[230:233], v[154:157], v[112:115]
	v_mfma_f32_16x16x32_bf16 v[100:103], v[222:225], v[182:185], v[100:103]
	v_mfma_f32_16x16x32_bf16 v[96:99], v[230:233], v[182:185], v[96:99]
	v_mfma_f32_16x16x32_bf16 v[84:87], v[222:225], v[190:193], v[84:87]
	v_mfma_f32_16x16x32_bf16 v[80:83], v[230:233], v[190:193], v[80:83]
	v_mfma_f32_16x16x32_bf16 v[68:71], v[222:225], v[214:217], v[68:71]
	v_mfma_f32_16x16x32_bf16 v[64:67], v[230:233], v[214:217], v[64:67]
	v_mfma_f32_16x16x32_bf16 v[116:119], v[226:229], v[174:177], v[116:119]
	v_mfma_f32_16x16x32_bf16 v[112:115], v[234:237], v[174:177], v[112:115]
	v_mfma_f32_16x16x32_bf16 v[100:103], v[226:229], v[186:189], v[100:103]
	v_mfma_f32_16x16x32_bf16 v[96:99], v[234:237], v[186:189], v[96:99]
	v_mfma_f32_16x16x32_bf16 v[84:87], v[226:229], v[194:197], v[84:87]
	v_mfma_f32_16x16x32_bf16 v[80:83], v[234:237], v[194:197], v[80:83]
	v_mfma_f32_16x16x32_bf16 v[68:71], v[226:229], v[218:221], v[68:71]
	v_mfma_f32_16x16x32_bf16 v[64:67], v[234:237], v[218:221], v[64:67]
	s_mov_b32 m0, s43
	v_lshl_add_u64 v[240:241], s[36:37], 0, v[144:145]
	s_barrier
	ds_read_b128 v[154:157], v181 offset:16384
	ds_read_b128 v[174:177], v181 offset:17408
	ds_read_b128 v[182:185], v181 offset:18432
	ds_read_b128 v[186:189], v181 offset:19456
	ds_read_b128 v[190:193], v181 offset:20480
	ds_read_b128 v[194:197], v181 offset:21504
	ds_read_b128 v[214:217], v181 offset:22528
	ds_read_b128 v[218:221], v181 offset:23552
	global_load_lds_dwordx4 v144, s[36:37]
	v_lshl_add_u64 v[242:243], s[36:37], 0, v[146:147]
	s_mov_b32 m0, s44
	s_nop 0
	global_load_lds_dwordx4 v146, s[36:37]
	s_barrier
	s_waitcnt lgkmcnt(0)
	v_mfma_f32_16x16x32_bf16 v[60:63], v[128:131], v[154:157], v[60:63]
	v_mfma_f32_16x16x32_bf16 v[56:59], v[136:139], v[154:157], v[56:59]
	v_mfma_f32_16x16x32_bf16 v[44:47], v[128:131], v[182:185], v[44:47]
	v_mfma_f32_16x16x32_bf16 v[40:43], v[136:139], v[182:185], v[40:43]
	v_mfma_f32_16x16x32_bf16 v[28:31], v[128:131], v[190:193], v[28:31]
	v_mfma_f32_16x16x32_bf16 v[24:27], v[136:139], v[190:193], v[24:27]
	v_mfma_f32_16x16x32_bf16 v[12:15], v[128:131], v[214:217], v[12:15]
	v_mfma_f32_16x16x32_bf16 v[8:11], v[136:139], v[214:217], v[8:11]
	v_mfma_f32_16x16x32_bf16 v[60:63], v[132:135], v[174:177], v[60:63]
	v_mfma_f32_16x16x32_bf16 v[56:59], v[140:143], v[174:177], v[56:59]
	v_mfma_f32_16x16x32_bf16 v[44:47], v[132:135], v[186:189], v[44:47]
	v_mfma_f32_16x16x32_bf16 v[40:43], v[140:143], v[186:189], v[40:43]
	v_mfma_f32_16x16x32_bf16 v[28:31], v[132:135], v[194:197], v[28:31]
	v_mfma_f32_16x16x32_bf16 v[24:27], v[140:143], v[194:197], v[24:27]
	v_mfma_f32_16x16x32_bf16 v[12:15], v[132:135], v[218:221], v[12:15]
	v_mfma_f32_16x16x32_bf16 v[8:11], v[140:143], v[218:221], v[8:11]
	s_barrier
; #define PG8_STAGE(bufoff, gbase, voff) do { _Pragma("unroll") for (int _i = 0; _i < 2; ++_i) \
;         __builtin_amdgcn_global_load_lds((const unsigned*)((const char*)(gbase) + (voff)[_i]), (LAS unsigned*)(lds + (bufoff) + ldsw + _i * 8192), 16, 0, 0); } while (0)
; #define PG8_LDA(dst, b, h) do { _Pragma("unroll") for (int m = 0; m < 4; ++m) _Pragma("unroll") for (int k = 0; k < 2; ++k) dst[m][k] = *(const LAS bf16x8*)(lds + PG8_SA(b, h) + aoff + m * 2048 + k * 1024); } while (0)
; #define PG8_LDB(dst, b, h) do { _Pragma("unroll") for (int n = 0; n < 2; ++n) _Pragma("unroll") for (int k = 0; k < 2; ++k) dst[n][k] = *(const LAS bf16x8*)(lds + PG8_SB(b, h) + boff + n * 2048 + k * 1024); } while (0)
; #define PG8_MMA(ai, bj, At, Bt) do { __builtin_amdgcn_s_setprio(1); _Pragma("unroll") for (int m = 0; m < 4; ++m) _Pragma("unroll") for (int n = 0; n < 2; ++n) _Pragma("unroll") for (int k = 0; k < 2; ++k) \
;         acc[ai][bj][m][n] = __builtin_amdgcn_mfma_f32_16x16x32_bf16(Bt[n][k], At[m][k], acc[ai][bj][m][n], 0, 0, 0); __builtin_amdgcn_s_setprio(0); } while (0)
; #define PG8_WAIT_V(n) asm volatile("s_waitcnt vmcnt(" #n ")" ::: "memory")
; #define PG8_WAIT_L(n) asm volatile("s_waitcnt lgkmcnt(" #n ")" ::: "memory")
; #define PG8_BAR __builtin_amdgcn_s_barrier()
; #define PG8_SCHED __builtin_amdgcn_sched_barrier(0)
; template <class Epi>
; DEV void gemm_phase(LAS unsigned char* lds, const Gemm g, const StaticOrder& S, const Epi& E) {
;     ...
;             PG8_STAGE(PG8_SB(0, 1), b2 + hstep, voffB);
;             PG8_WAIT_V(6); PG8_BAR; PG8_MMA(1, 1, At, B1); PG8_BAR;
;             PG8_LDB(B0, 1, 0); PG8_SCHED; PG8_LDA(At, 1, 0); PG8_STAGE(PG8_SA(0, 1), a2 + hstep, voffA);
;             PG8_WAIT_L(8); PG8_BAR; PG8_WAIT_L(0); PG8_MMA(0, 0, At, B0); PG8_BAR; PG8_SCHED;
;             PG8_LDB(B1, 1, 1); PG8_STAGE(PG8_SB(1, 0), b3, voffB);
;             PG8_BAR; PG8_WAIT_L(0); PG8_MMA(0, 1, At, B1); PG8_BAR;
;             PG8_LDA(At, 1, 1); PG8_STAGE(PG8_SA(1, 0), a3, voffA);
	s_add_u32 s56, s34, 0x20000
	s_addc_u32 s57, s35, 0
	s_add_i32 s55, s58, s42
	s_mov_b32 m0, s55
	s_nop 0
	global_load_lds_dwordx4 v160, s[56:57]
	s_add_i32 m0, s55, 0x2000
	s_nop 0
	global_load_lds_dwordx4 v148, s[56:57]
	s_waitcnt vmcnt(10)
	s_barrier
	v_mfma_f32_16x16x32_bf16 v[52:55], v[222:225], v[154:157], v[52:55]
	v_mfma_f32_16x16x32_bf16 v[48:51], v[230:233], v[154:157], v[48:51]
	v_mfma_f32_16x16x32_bf16 v[36:39], v[222:225], v[182:185], v[36:39]
	v_mfma_f32_16x16x32_bf16 v[32:35], v[230:233], v[182:185], v[32:35]
	v_mfma_f32_16x16x32_bf16 v[20:23], v[222:225], v[190:193], v[20:23]
	v_mfma_f32_16x16x32_bf16 v[16:19], v[230:233], v[190:193], v[16:19]
	v_mfma_f32_16x16x32_bf16 v[4:7], v[222:225], v[214:217], v[4:7]
	v_mfma_f32_16x16x32_bf16 v[0:3], v[230:233], v[214:217], v[0:3]
	v_mfma_f32_16x16x32_bf16 v[52:55], v[226:229], v[174:177], v[52:55]
	v_mfma_f32_16x16x32_bf16 v[48:51], v[234:237], v[174:177], v[48:51]
	v_mfma_f32_16x16x32_bf16 v[36:39], v[226:229], v[186:189], v[36:39]
	v_mfma_f32_16x16x32_bf16 v[32:35], v[234:237], v[186:189], v[32:35]
	v_mfma_f32_16x16x32_bf16 v[20:23], v[226:229], v[194:197], v[20:23]
	v_mfma_f32_16x16x32_bf16 v[16:19], v[234:237], v[194:197], v[16:19]
	v_mfma_f32_16x16x32_bf16 v[4:7], v[226:229], v[218:221], v[4:7]
	v_mfma_f32_16x16x32_bf16 v[0:3], v[234:237], v[218:221], v[0:3]
	s_add_i32 s55, 0, 0x18000
	v_add_u32_e32 v140, s55, v178
	s_barrier
	ds_read_b128 v[128:131], v140
	ds_read_b128 v[132:135], v140 offset:1024
	ds_read_b128 v[136:139], v140 offset:2048
	ds_read_b128 v[140:143], v140 offset:3072
	s_add_u32 s36, s36, 0x20000
	s_addc_u32 s37, s37, 0
	s_mov_b32 m0, s45
	ds_read_b128 v[154:157], v181 offset:32768
	ds_read_b128 v[174:177], v181 offset:33792
	ds_read_b128 v[182:185], v181 offset:34816
	ds_read_b128 v[186:189], v181 offset:35840
	ds_read_b128 v[190:193], v181 offset:36864
	ds_read_b128 v[194:197], v181 offset:37888
	ds_read_b128 v[214:217], v181 offset:38912
	ds_read_b128 v[218:221], v181 offset:39936
	global_load_lds_dwordx4 v144, s[36:37]
	s_mov_b32 m0, s46
	s_nop 0
	global_load_lds_dwordx4 v146, s[36:37]
	s_waitcnt lgkmcnt(8)
	s_waitcnt vmcnt(10)
	s_barrier
	s_waitcnt lgkmcnt(0)
	v_mfma_f32_16x16x32_bf16 v[124:127], v[128:131], v[154:157], v[124:127]
	v_mfma_f32_16x16x32_bf16 v[120:123], v[136:139], v[154:157], v[120:123]
	v_mfma_f32_16x16x32_bf16 v[108:111], v[128:131], v[182:185], v[108:111]
	v_mfma_f32_16x16x32_bf16 v[104:107], v[136:139], v[182:185], v[104:107]
	v_mfma_f32_16x16x32_bf16 v[92:95], v[128:131], v[190:193], v[92:95]
	v_mfma_f32_16x16x32_bf16 v[88:91], v[136:139], v[190:193], v[88:91]
	v_mfma_f32_16x16x32_bf16 v[76:79], v[128:131], v[214:217], v[76:79]
	v_mfma_f32_16x16x32_bf16 v[72:75], v[136:139], v[214:217], v[72:75]
	v_mfma_f32_16x16x32_bf16 v[124:127], v[132:135], v[174:177], v[124:127]
	v_mfma_f32_16x16x32_bf16 v[120:123], v[140:143], v[174:177], v[120:123]
	v_mfma_f32_16x16x32_bf16 v[108:111], v[132:135], v[186:189], v[108:111]
	v_mfma_f32_16x16x32_bf16 v[104:107], v[140:143], v[186:189], v[104:107]
	v_mfma_f32_16x16x32_bf16 v[92:95], v[132:135], v[194:197], v[92:95]
	v_mfma_f32_16x16x32_bf16 v[88:91], v[140:143], v[194:197], v[88:91]
	v_mfma_f32_16x16x32_bf16 v[76:79], v[132:135], v[218:221], v[76:79]
	v_mfma_f32_16x16x32_bf16 v[72:75], v[140:143], v[218:221], v[72:75]
	s_barrier
	s_add_i32 s36, 0, 0x1c000
	s_add_i32 s37, s55, s42
	v_add_u32_e32 v234, s36, v178
	v_lshl_add_u64 v[158:159], v[158:159], 0, s[2:3]
	s_mov_b32 m0, s37
	ds_read_b128 v[222:225], v234
	ds_read_b128 v[226:229], v234 offset:1024
	ds_read_b128 v[230:233], v234 offset:2048
	ds_read_b128 v[234:237], v234 offset:3072
	global_load_lds_dwordx4 v[158:159], off
	v_lshl_add_u64 v[158:159], v[238:239], 0, s[2:3]
	s_add_i32 m0, s37, 0x2000
	s_nop 0
	global_load_lds_dwordx4 v[158:159], off
	s_waitcnt vmcnt(10)
	s_barrier
	s_waitcnt lgkmcnt(0)
	v_mfma_f32_16x16x32_bf16 v[116:119], v[222:225], v[154:157], v[116:119]
	v_mfma_f32_16x16x32_bf16 v[112:115], v[230:233], v[154:157], v[112:115]
	v_mfma_f32_16x16x32_bf16 v[100:103], v[222:225], v[182:185], v[100:103]
	v_mfma_f32_16x16x32_bf16 v[96:99], v[230:233], v[182:185], v[96:99]
	v_mfma_f32_16x16x32_bf16 v[84:87], v[222:225], v[190:193], v[84:87]
	v_mfma_f32_16x16x32_bf16 v[80:83], v[230:233], v[190:193], v[80:83]
	v_mfma_f32_16x16x32_bf16 v[68:71], v[222:225], v[214:217], v[68:71]
	v_mfma_f32_16x16x32_bf16 v[64:67], v[230:233], v[214:217], v[64:67]
	v_mfma_f32_16x16x32_bf16 v[116:119], v[226:229], v[174:177], v[116:119]
	v_mfma_f32_16x16x32_bf16 v[112:115], v[234:237], v[174:177], v[112:115]
	v_mfma_f32_16x16x32_bf16 v[100:103], v[226:229], v[186:189], v[100:103]
	v_mfma_f32_16x16x32_bf16 v[96:99], v[234:237], v[186:189], v[96:99]
	v_mfma_f32_16x16x32_bf16 v[84:87], v[226:229], v[194:197], v[84:87]
	v_mfma_f32_16x16x32_bf16 v[80:83], v[234:237], v[194:197], v[80:83]
	v_mfma_f32_16x16x32_bf16 v[68:71], v[226:229], v[218:221], v[68:71]
	v_mfma_f32_16x16x32_bf16 v[64:67], v[234:237], v[218:221], v[64:67]
	s_mov_b32 m0, s47
	v_lshl_add_u64 v[158:159], v[240:241], 0, s[2:3]
	s_barrier
	ds_read_b128 v[154:157], v181 offset:49152
	ds_read_b128 v[174:177], v181 offset:50176
	ds_read_b128 v[182:185], v181 offset:51200
	ds_read_b128 v[186:189], v181 offset:52224
	ds_read_b128 v[190:193], v181 offset:53248
	ds_read_b128 v[194:197], v181 offset:54272
	ds_read_b128 v[214:217], v181 offset:55296
	ds_read_b128 v[218:221], v181 offset:56320
	global_load_lds_dwordx4 v[158:159], off
	v_lshl_add_u64 v[158:159], v[242:243], 0, s[2:3]
	s_mov_b32 m0, s48
	s_nop 0
	global_load_lds_dwordx4 v[158:159], off
	s_barrier
; DEV bf16x8 pack8(f32x4 a, f32x4 b) { u32x4 w; w.x = cvt_pk_bf16(a[0], a[1]); w.y = cvt_pk_bf16(a[2], a[3]); w.z = cvt_pk_bf16(b[0], b[1]); w.w = cvt_pk_bf16(b[2], b[3]); return __builtin_bit_cast(bf16x8, w); }
; #define PG8_WAIT_V(n) asm volatile("s_waitcnt vmcnt(" #n ")" ::: "memory")
; #define PG8_WAIT_L(n) asm volatile("s_waitcnt lgkmcnt(" #n ")" ::: "memory")
; #define PG8_BAR __builtin_amdgcn_s_barrier()
; #define PG8_SCHED __builtin_amdgcn_sched_barrier(0)
; template <class Epi>
; DEV void gemm_phase(LAS unsigned char* lds, const Gemm g, const StaticOrder& S, const Epi& E) {
;     ...
;             PG8_BAR; PG8_WAIT_L(0); PG8_MMA(1, 0, At, B0); PG8_BAR; PG8_SCHED;
;             PG8_STAGE(PG8_SB(1, 1), b3 + hstep, voffB);
;             PG8_WAIT_V(6); PG8_BAR; PG8_MMA(1, 1, At, B1); PG8_BAR;
;     DEV void operator()(AccRef acc, const pg8::Unit& u, int wr, int wc, int fr, int fq) const {
;         const int row0 = u.pm * 256 + wr * 64 + fr, col0 = u.pn * 256 + wc * 32 + 8 * fq;
; #pragma unroll
;         for (int am = 0; am < 4; ++am) { const int ai = am >> 1, m0 = (am & 1) * 2;
;             f32x4 bv[4][2][2];
; #pragma unroll
;             for (int m = m0; m < m0 + 2; ++m)
; #pragma unroll
;                 for (int bj = 0; bj < 2; ++bj)
; #pragma unroll
;                     for (int n = 0; n < 2; ++n) bv[m][bj][n] = *(const f32x4*)(base + (size_t)(row0 + ai * 128 + m * 16) * 2048 + col0 + bj * 128 + n * 4);
; #pragma unroll
;             for (int m = m0; m < m0 + 2; ++m) { const size_t off = (size_t)(row0 + ai * 128 + m * 16) * 2048 + col0; float sq = 0.f;
; #pragma unroll
;                 for (int bj = 0; bj < 2; ++bj) { const f32x4 o0 = bv[m][bj][0] + scale * acc[ai][bj][m][0], o1 = bv[m][bj][1] + scale * acc[ai][bj][m][1];
;                     *(f32x4*)(out + off + bj * 128) = o0; *(f32x4*)(out + off + bj * 128 + 4) = o1;
;                     if (xb) { *(u32x4*)(xb + off + bj * 128) = __builtin_bit_cast(u32x4, pack8(o0, o1));
;                         sq += (o0[0] * o0[0] + o0[1] * o0[1] + o0[2] * o0[2] + o0[3] * o0[3]) + (o1[0] * o1[0] + o1[1] * o1[1] + o1[2] * o1[2] + o1[3] * o1[3]); } }
;                 if (ssout) { sq += __shfl_xor(sq, 16); sq += __shfl_xor(sq, 32);
;                     if (fq == 0) { if (red) red[(ai * 128 + wr * 64 + m * 16 + fr) * 4 + wc] = sq; else atomicAdd(ssout + (size_t)(row0 + ai * 128 + m * 16) * 8 + u.pn, sq); } } }
	s_waitcnt lgkmcnt(0)
	v_mfma_f32_16x16x32_bf16 v[60:63], v[128:131], v[154:157], v[60:63]
	v_mfma_f32_16x16x32_bf16 v[56:59], v[136:139], v[154:157], v[56:59]
	v_mfma_f32_16x16x32_bf16 v[44:47], v[128:131], v[182:185], v[44:47]
	v_mfma_f32_16x16x32_bf16 v[40:43], v[136:139], v[182:185], v[40:43]
	v_mfma_f32_16x16x32_bf16 v[28:31], v[128:131], v[190:193], v[28:31]
	v_mfma_f32_16x16x32_bf16 v[24:27], v[136:139], v[190:193], v[24:27]
	v_mfma_f32_16x16x32_bf16 v[12:15], v[128:131], v[214:217], v[12:15]
	v_mfma_f32_16x16x32_bf16 v[8:11], v[136:139], v[214:217], v[8:11]
	v_mfma_f32_16x16x32_bf16 v[60:63], v[132:135], v[174:177], v[60:63]
	v_mfma_f32_16x16x32_bf16 v[56:59], v[140:143], v[174:177], v[56:59]
	v_mfma_f32_16x16x32_bf16 v[44:47], v[132:135], v[186:189], v[44:47]
	v_mfma_f32_16x16x32_bf16 v[40:43], v[140:143], v[186:189], v[40:43]
	v_mfma_f32_16x16x32_bf16 v[28:31], v[132:135], v[194:197], v[28:31]
	v_mfma_f32_16x16x32_bf16 v[24:27], v[140:143], v[194:197], v[24:27]
	v_mfma_f32_16x16x32_bf16 v[12:15], v[132:135], v[218:221], v[12:15]
	v_mfma_f32_16x16x32_bf16 v[8:11], v[140:143], v[218:221], v[8:11]
	s_barrier
	s_add_u32 s34, s34, 0x20080
	s_addc_u32 s35, s35, 0
	s_add_i32 s36, s36, s42
	s_mov_b32 m0, s36
	s_nop 0
	global_load_lds_dwordx4 v160, s[34:35]
	s_add_i32 m0, s36, 0x2000
	s_nop 0
	global_load_lds_dwordx4 v148, s[34:35]
	s_waitcnt vmcnt(10)
	s_barrier
	v_mfma_f32_16x16x32_bf16 v[52:55], v[222:225], v[154:157], v[52:55]
	v_mfma_f32_16x16x32_bf16 v[48:51], v[230:233], v[154:157], v[48:51]
	v_mfma_f32_16x16x32_bf16 v[36:39], v[222:225], v[182:185], v[36:39]
	v_mfma_f32_16x16x32_bf16 v[32:35], v[230:233], v[182:185], v[32:35]
	v_mfma_f32_16x16x32_bf16 v[20:23], v[222:225], v[190:193], v[20:23]
	v_mfma_f32_16x16x32_bf16 v[16:19], v[230:233], v[190:193], v[16:19]
	v_mfma_f32_16x16x32_bf16 v[4:7], v[222:225], v[214:217], v[4:7]
	v_mfma_f32_16x16x32_bf16 v[0:3], v[230:233], v[214:217], v[0:3]
	v_mfma_f32_16x16x32_bf16 v[52:55], v[226:229], v[174:177], v[52:55]
	v_mfma_f32_16x16x32_bf16 v[48:51], v[234:237], v[174:177], v[48:51]
	v_mfma_f32_16x16x32_bf16 v[36:39], v[226:229], v[186:189], v[36:39]
	v_mfma_f32_16x16x32_bf16 v[32:35], v[234:237], v[186:189], v[32:35]
	v_mfma_f32_16x16x32_bf16 v[20:23], v[226:229], v[194:197], v[20:23]
	v_mfma_f32_16x16x32_bf16 v[16:19], v[234:237], v[194:197], v[16:19]
	v_mfma_f32_16x16x32_bf16 v[4:7], v[226:229], v[218:221], v[4:7]
	v_mfma_f32_16x16x32_bf16 v[0:3], v[234:237], v[218:221], v[0:3]
	s_add_i32 s54, s54, 2
	s_add_u32 s30, s30, 0x100
	s_addc_u32 s31, s31, 0
	s_add_u32 s52, s52, 0x100
	s_addc_u32 s53, s53, 0
	s_cmp_gt_u32 s54, 5
	s_barrier
	s_cbranch_scc0 .LBB0_260
	v_lshl_add_u32 v156, s28, 8, v167
	v_lshl_or_b32 v154, s18, 8, v179
	v_readlane_b32 s28, v254, 16
	v_ashrrev_i32_e32 v155, 31, v154
	v_readlane_b32 s29, v254, 17
	v_ashrrev_i32_e32 v157, 31, v156
	v_lshlrev_b64 v[128:129], 13, v[156:157]
	v_lshl_add_u64 v[158:159], v[154:155], 2, s[28:29]
	v_lshl_add_u64 v[214:215], v[158:159], 0, v[128:129]
	global_load_dwordx4 v[182:185], v[214:215], off offset:16
	global_load_dwordx4 v[186:189], v[214:215], off
	global_load_dwordx4 v[190:193], v[214:215], off offset:528
	global_load_dwordx4 v[194:197], v[214:215], off offset:512
	v_or_b32_e32 v174, 16, v156
	v_ashrrev_i32_e32 v175, 31, v174
	v_lshlrev_b64 v[128:129], 13, v[174:175]
	v_lshl_add_u64 v[176:177], v[158:159], 0, v[128:129]
	global_load_dwordx4 v[136:139], v[176:177], off offset:16
	global_load_dwordx4 v[140:143], v[176:177], off
	global_load_dwordx4 v[128:131], v[176:177], off offset:528
	global_load_dwordx4 v[132:135], v[176:177], off offset:512
	v_lshlrev_b64 v[216:217], 11, v[156:157]
	v_readlane_b32 s28, v250, 9
	v_lshl_add_u64 v[216:217], v[216:217], 0, v[154:155]
	v_readlane_b32 s29, v250, 10
	v_cmp_lt_i32_e32 vcc, v208, v206
	s_ashr_i32 s19, s18, 31
	s_waitcnt vmcnt(0)
	v_pk_add_f32 v[120:121], v[120:121], v[182:183]
	v_pk_add_f32 v[126:127], v[126:127], v[188:189]
	v_pk_add_f32 v[124:125], v[124:125], v[186:187]
	v_pk_add_f32 v[122:123], v[122:123], v[184:185]
	global_store_dwordx4 v[214:215], v[124:127], off
	global_store_dwordx4 v[214:215], v[120:123], off offset:16
	v_cvt_pk_bf16_f32 v184, v120, v121
	v_cvt_pk_bf16_f32 v182, v124, v125
	v_mul_f32_e32 v121, v121, v121
	v_cvt_pk_bf16_f32 v183, v126, v127
	v_cvt_pk_bf16_f32 v185, v122, v123
	v_lshl_add_u64 v[186:187], v[216:217], 1, s[28:29]
	v_fmac_f32_e32 v121, v120, v120
	v_pk_add_f32 v[118:119], v[118:119], v[196:197]
	v_pk_add_f32 v[116:117], v[116:117], v[194:195]
	v_pk_add_f32 v[112:113], v[112:113], v[190:191]
	global_store_dwordx4 v[186:187], v[182:185], off
	v_mul_f32_e32 v125, v125, v125
	v_fmac_f32_e32 v121, v122, v122
	v_pk_add_f32 v[114:115], v[114:115], v[192:193]
	global_store_dwordx4 v[214:215], v[116:119], off offset:512
	global_store_dwordx4 v[214:215], v[112:115], off offset:528
	v_cvt_pk_bf16_f32 v120, v116, v117
	v_cvt_pk_bf16_f32 v122, v112, v113
	v_mul_f32_e32 v117, v117, v117
	v_mul_f32_e32 v113, v113, v113
	v_fmac_f32_e32 v125, v124, v124
	v_fmac_f32_e32 v117, v116, v116
	v_fmac_f32_e32 v113, v112, v112
	v_fmac_f32_e32 v125, v126, v126
	v_fmac_f32_e32 v117, v118, v118
	v_fmac_f32_e32 v113, v114, v114
	v_fmac_f32_e32 v125, v127, v127
	v_fmac_f32_e32 v121, v123, v123
	v_fmac_f32_e32 v117, v119, v119
	v_fmac_f32_e32 v113, v115, v115
	v_add_f32_e32 v124, v125, v121
	v_add_f32_e32 v112, v117, v113
	v_cndmask_b32_e32 v113, v204, v208, vcc
	v_cvt_pk_bf16_f32 v121, v118, v119
	v_add_f32_e32 v112, v124, v112
	v_lshlrev_b32_e32 v118, 2, v113
	ds_bpermute_b32 v113, v118, v112
	v_cmp_lt_i32_e32 vcc, v207, v206
	v_cvt_pk_bf16_f32 v123, v114, v115
	global_store_dwordx4 v[186:187], v[120:123], off offset:256
	s_waitcnt lgkmcnt(0)
	v_add_f32_e32 v112, v112, v113
	v_cndmask_b32_e32 v113, v204, v207, vcc
	v_lshlrev_b32_e32 v119, 2, v113
	ds_bpermute_b32 v113, v119, v112
	s_and_saveexec_b64 s[28:29], s[6:7]
	s_cbranch_execz .LBB0_266
	s_waitcnt lgkmcnt(0)
	v_add_f32_e32 v112, v112, v113
	s_mov_b64 s[30:31], -1
	s_and_b64 vcc, exec, s[16:17]
	s_cbranch_vccz .LBB0_264
	v_lshlrev_b64 v[114:115], 5, v[156:157]
	v_lshl_add_u64 v[114:115], s[12:13], 0, v[114:115]
	v_lshl_add_u64 v[114:115], s[18:19], 2, v[114:115]
	global_atomic_add_f32 v[114:115], v112, off
	s_mov_b64 s[30:31], 0

; #define PG8_STAGE(bufoff, gbase, voff) do { _Pragma("unroll") for (int _i = 0; _i < 2; ++_i) \
;         __builtin_amdgcn_global_load_lds((const unsigned*)((const char*)(gbase) + (voff)[_i]), (LAS unsigned*)(lds + (bufoff) + ldsw + _i * 8192), 16, 0, 0); } while (0)
; #define PG8_LDA(dst, b, h) do { _Pragma("unroll") for (int m = 0; m < 4; ++m) _Pragma("unroll") for (int k = 0; k < 2; ++k) dst[m][k] = *(const LAS bf16x8*)(lds + PG8_SA(b, h) + aoff + m * 2048 + k * 1024); } while (0)
; #define PG8_LDB(dst, b, h) do { _Pragma("unroll") for (int n = 0; n < 2; ++n) _Pragma("unroll") for (int k = 0; k < 2; ++k) dst[n][k] = *(const LAS bf16x8*)(lds + PG8_SB(b, h) + boff + n * 2048 + k * 1024); } while (0)
; #define PG8_MMA(ai, bj, At, Bt) do { __builtin_amdgcn_s_setprio(1); _Pragma("unroll") for (int m = 0; m < 4; ++m) _Pragma("unroll") for (int n = 0; n < 2; ++n) _Pragma("unroll") for (int k = 0; k < 2; ++k) \
;         acc[ai][bj][m][n] = __builtin_amdgcn_mfma_f32_16x16x32_bf16(Bt[n][k], At[m][k], acc[ai][bj][m][n], 0, 0, 0); __builtin_amdgcn_s_setprio(0); } while (0)
; #define PG8_WAIT_L(n) asm volatile("s_waitcnt lgkmcnt(" #n ")" ::: "memory")
; #define PG8_BAR __builtin_amdgcn_s_barrier()
; #define PG8_SCHED __builtin_amdgcn_sched_barrier(0)
; template <class Epi>
; DEV void gemm_phase(LAS unsigned char* lds, const Gemm g, const StaticOrder& S, const Epi& E) {
;     ...
;             const bool last = (t == nt - 2);
;             const char* a1 = cA + (size_t)(t + 1) * kstep;
;             const char* a2 = last ? nA : cA + (size_t)(t + 2) * kstep; const char* b2 = last ? nB : cB + (size_t)(t + 2) * kstep;
;             const char* a3 = a2 + kstep; const char* b3 = b2 + kstep;
;             PG8_LDB(B0, 0, 0); PG8_SCHED; PG8_LDA(At, 0, 0); PG8_STAGE(PG8_SA(1, 1), a1 + hstep, voffA);
;             PG8_WAIT_L(8); PG8_BAR; PG8_WAIT_L(0); PG8_MMA(0, 0, At, B0); PG8_BAR; PG8_SCHED;
;             PG8_LDB(B1, 0, 1); PG8_STAGE(PG8_SB(0, 0), b2, voffB);
;             PG8_BAR; PG8_WAIT_L(0); PG8_MMA(0, 1, At, B1); PG8_BAR;
;             PG8_LDA(At, 0, 1); PG8_STAGE(PG8_SA(0, 0), a2, voffA);
;             PG8_BAR; PG8_WAIT_L(0); PG8_MMA(1, 0, At, B0); PG8_BAR; PG8_SCHED;
.LBB0_344:
	s_add_u32 s20, s18, 0xfff80080
	s_addc_u32 s21, s19, -1
	s_add_i32 s45, 0, 0x10000
	v_add_u32_e32 v146, s45, v149
	ds_read_b128 v[128:131], v146
	ds_read_b128 v[132:135], v146 offset:1024
	ds_read_b128 v[142:145], v146 offset:2048
	ds_read_b128 v[150:153], v146 offset:3072
	s_cmp_eq_u32 s44, 28
	s_cselect_b32 s23, s1, s21
	s_cselect_b32 s22, s13, s20
	s_cselect_b32 s21, s11, s43
	s_cselect_b32 s20, s41, s42
	s_add_i32 m0, s30, 0xc000
	ds_read_b128 v[174:177], v159
	ds_read_b128 v[178:181], v159 offset:1024
	ds_read_b128 v[182:185], v159 offset:2048
	ds_read_b128 v[186:189], v159 offset:3072
	ds_read_b128 v[190:193], v159 offset:4096
	ds_read_b128 v[194:197], v159 offset:5120
	ds_read_b128 v[214:217], v159 offset:6144
	ds_read_b128 v[218:221], v159 offset:7168
	global_load_lds_dwordx4 v138, s[18:19]
	s_add_i32 m0, s30, 0xe000
	s_nop 0
	global_load_lds_dwordx4 v140, s[18:19]
	s_waitcnt lgkmcnt(8)
	s_waitcnt vmcnt(10)
	s_barrier
	s_waitcnt lgkmcnt(0)
	v_mfma_f32_16x16x32_bf16 v[124:127], v[128:131], v[174:177], v[124:127]
	v_mfma_f32_16x16x32_bf16 v[120:123], v[142:145], v[174:177], v[120:123]
	v_mfma_f32_16x16x32_bf16 v[116:119], v[128:131], v[182:185], v[116:119]
	v_mfma_f32_16x16x32_bf16 v[108:111], v[142:145], v[182:185], v[108:111]
	v_mfma_f32_16x16x32_bf16 v[100:103], v[128:131], v[190:193], v[100:103]
	v_mfma_f32_16x16x32_bf16 v[92:95], v[142:145], v[190:193], v[92:95]
	v_mfma_f32_16x16x32_bf16 v[84:87], v[128:131], v[214:217], v[84:87]
	v_mfma_f32_16x16x32_bf16 v[76:79], v[142:145], v[214:217], v[76:79]
	v_mfma_f32_16x16x32_bf16 v[124:127], v[132:135], v[178:181], v[124:127]
	v_mfma_f32_16x16x32_bf16 v[120:123], v[150:153], v[178:181], v[120:123]
	v_mfma_f32_16x16x32_bf16 v[116:119], v[132:135], v[186:189], v[116:119]
	v_mfma_f32_16x16x32_bf16 v[108:111], v[150:153], v[186:189], v[108:111]
	v_mfma_f32_16x16x32_bf16 v[100:103], v[132:135], v[194:197], v[100:103]
	v_mfma_f32_16x16x32_bf16 v[92:95], v[150:153], v[194:197], v[92:95]
	v_mfma_f32_16x16x32_bf16 v[84:87], v[132:135], v[218:221], v[84:87]
	v_mfma_f32_16x16x32_bf16 v[76:79], v[150:153], v[218:221], v[76:79]
	s_barrier
	s_add_i32 s48, 0, 0x14000
	s_add_i32 s45, s45, s29
	v_add_u32_e32 v146, s48, v149
	v_lshl_add_u64 v[154:155], s[20:21], 0, v[160:161]
	s_mov_b32 m0, s45
	ds_read_b128 v[222:225], v146
	ds_read_b128 v[226:229], v146 offset:1024
	ds_read_b128 v[230:233], v146 offset:2048
	ds_read_b128 v[234:237], v146 offset:3072
	global_load_lds_dwordx4 v160, s[20:21]
	v_lshl_add_u64 v[238:239], s[20:21], 0, v[136:137]
	s_add_i32 m0, s45, 0x2000
	s_nop 0
	global_load_lds_dwordx4 v136, s[20:21]
	s_waitcnt vmcnt(10)
	s_barrier
	s_waitcnt lgkmcnt(0)
	v_mfma_f32_16x16x32_bf16 v[112:115], v[222:225], v[174:177], v[112:115]
	v_mfma_f32_16x16x32_bf16 v[104:107], v[230:233], v[174:177], v[104:107]
	v_mfma_f32_16x16x32_bf16 v[96:99], v[222:225], v[182:185], v[96:99]
	v_mfma_f32_16x16x32_bf16 v[88:91], v[230:233], v[182:185], v[88:91]
	v_mfma_f32_16x16x32_bf16 v[80:83], v[222:225], v[190:193], v[80:83]
	v_mfma_f32_16x16x32_bf16 v[72:75], v[230:233], v[190:193], v[72:75]
	v_mfma_f32_16x16x32_bf16 v[68:71], v[222:225], v[214:217], v[68:71]
	v_mfma_f32_16x16x32_bf16 v[64:67], v[230:233], v[214:217], v[64:67]
	v_mfma_f32_16x16x32_bf16 v[112:115], v[226:229], v[178:181], v[112:115]
	v_mfma_f32_16x16x32_bf16 v[104:107], v[234:237], v[178:181], v[104:107]
	v_mfma_f32_16x16x32_bf16 v[96:99], v[226:229], v[186:189], v[96:99]
	v_mfma_f32_16x16x32_bf16 v[88:91], v[234:237], v[186:189], v[88:91]
	v_mfma_f32_16x16x32_bf16 v[80:83], v[226:229], v[194:197], v[80:83]
	v_mfma_f32_16x16x32_bf16 v[72:75], v[234:237], v[194:197], v[72:75]
	v_mfma_f32_16x16x32_bf16 v[68:71], v[226:229], v[218:221], v[68:71]
	v_mfma_f32_16x16x32_bf16 v[64:67], v[234:237], v[218:221], v[64:67]
	s_mov_b32 m0, s30
	v_lshl_add_u64 v[240:241], s[22:23], 0, v[160:161]
	s_barrier
	ds_read_b128 v[174:177], v159 offset:16384
	ds_read_b128 v[178:181], v159 offset:17408
	ds_read_b128 v[182:185], v159 offset:18432
	ds_read_b128 v[186:189], v159 offset:19456
	ds_read_b128 v[190:193], v159 offset:20480
	ds_read_b128 v[194:197], v159 offset:21504
	ds_read_b128 v[214:217], v159 offset:22528
	ds_read_b128 v[218:221], v159 offset:23552
	global_load_lds_dwordx4 v160, s[22:23]
	v_lshl_add_u64 v[242:243], s[22:23], 0, v[136:137]
	s_mov_b32 m0, s31
	s_nop 0
	global_load_lds_dwordx4 v136, s[22:23]
	s_barrier
	s_waitcnt lgkmcnt(0)
	v_mfma_f32_16x16x32_bf16 v[60:63], v[128:131], v[174:177], v[60:63]
	v_mfma_f32_16x16x32_bf16 v[56:59], v[142:145], v[174:177], v[56:59]
	v_mfma_f32_16x16x32_bf16 v[52:55], v[128:131], v[182:185], v[52:55]
	v_mfma_f32_16x16x32_bf16 v[44:47], v[142:145], v[182:185], v[44:47]
	v_mfma_f32_16x16x32_bf16 v[36:39], v[128:131], v[190:193], v[36:39]
	v_mfma_f32_16x16x32_bf16 v[28:31], v[142:145], v[190:193], v[28:31]
	v_mfma_f32_16x16x32_bf16 v[20:23], v[128:131], v[214:217], v[20:23]
	v_mfma_f32_16x16x32_bf16 v[12:15], v[142:145], v[214:217], v[12:15]
	v_mfma_f32_16x16x32_bf16 v[60:63], v[132:135], v[178:181], v[60:63]
	v_mfma_f32_16x16x32_bf16 v[56:59], v[150:153], v[178:181], v[56:59]
	v_mfma_f32_16x16x32_bf16 v[52:55], v[132:135], v[186:189], v[52:55]
	v_mfma_f32_16x16x32_bf16 v[44:47], v[150:153], v[186:189], v[44:47]
	v_mfma_f32_16x16x32_bf16 v[36:39], v[132:135], v[194:197], v[36:39]
	v_mfma_f32_16x16x32_bf16 v[28:31], v[150:153], v[194:197], v[28:31]
	v_mfma_f32_16x16x32_bf16 v[20:23], v[132:135], v[218:221], v[20:23]
	v_mfma_f32_16x16x32_bf16 v[12:15], v[150:153], v[218:221], v[12:15]
	s_barrier
; #define PG8_STAGE(bufoff, gbase, voff) do { _Pragma("unroll") for (int _i = 0; _i < 2; ++_i) \
;         __builtin_amdgcn_global_load_lds((const unsigned*)((const char*)(gbase) + (voff)[_i]), (LAS unsigned*)(lds + (bufoff) + ldsw + _i * 8192), 16, 0, 0); } while (0)
; #define PG8_LDA(dst, b, h) do { _Pragma("unroll") for (int m = 0; m < 4; ++m) _Pragma("unroll") for (int k = 0; k < 2; ++k) dst[m][k] = *(const LAS bf16x8*)(lds + PG8_SA(b, h) + aoff + m * 2048 + k * 1024); } while (0)
; #define PG8_LDB(dst, b, h) do { _Pragma("unroll") for (int n = 0; n < 2; ++n) _Pragma("unroll") for (int k = 0; k < 2; ++k) dst[n][k] = *(const LAS bf16x8*)(lds + PG8_SB(b, h) + boff + n * 2048 + k * 1024); } while (0)
; #define PG8_MMA(ai, bj, At, Bt) do { __builtin_amdgcn_s_setprio(1); _Pragma("unroll") for (int m = 0; m < 4; ++m) _Pragma("unroll") for (int n = 0; n < 2; ++n) _Pragma("unroll") for (int k = 0; k < 2; ++k) \
;         acc[ai][bj][m][n] = __builtin_amdgcn_mfma_f32_16x16x32_bf16(Bt[n][k], At[m][k], acc[ai][bj][m][n], 0, 0, 0); __builtin_amdgcn_s_setprio(0); } while (0)
; #define PG8_WAIT_V(n) asm volatile("s_waitcnt vmcnt(" #n ")" ::: "memory")
; #define PG8_WAIT_L(n) asm volatile("s_waitcnt lgkmcnt(" #n ")" ::: "memory")
; #define PG8_BAR __builtin_amdgcn_s_barrier()
; #define PG8_SCHED __builtin_amdgcn_sched_barrier(0)
; template <class Epi>
; DEV void gemm_phase(LAS unsigned char* lds, const Gemm g, const StaticOrder& S, const Epi& E) {
;     ...
;             PG8_STAGE(PG8_SB(0, 1), b2 + hstep, voffB);
;             PG8_WAIT_V(6); PG8_BAR; PG8_MMA(1, 1, At, B1); PG8_BAR;
;             PG8_LDB(B0, 1, 0); PG8_SCHED; PG8_LDA(At, 1, 0); PG8_STAGE(PG8_SA(0, 1), a2 + hstep, voffA);
;             PG8_WAIT_L(8); PG8_BAR; PG8_WAIT_L(0); PG8_MMA(0, 0, At, B0); PG8_BAR; PG8_SCHED;
;             PG8_LDB(B1, 1, 1); PG8_STAGE(PG8_SB(1, 0), b3, voffB);
;             PG8_BAR; PG8_WAIT_L(0); PG8_MMA(0, 1, At, B1); PG8_BAR;
;             PG8_LDA(At, 1, 1); PG8_STAGE(PG8_SA(1, 0), a3, voffA);
	s_add_u32 s46, s20, 0x80000
	s_addc_u32 s47, s21, 0
	s_add_i32 s45, s48, s29
	s_mov_b32 m0, s45
	s_nop 0
	global_load_lds_dwordx4 v160, s[46:47]
	s_add_i32 m0, s45, 0x2000
	s_nop 0
	global_load_lds_dwordx4 v136, s[46:47]
	s_waitcnt vmcnt(10)
	s_barrier
	v_mfma_f32_16x16x32_bf16 v[48:51], v[222:225], v[174:177], v[48:51]
	v_mfma_f32_16x16x32_bf16 v[40:43], v[230:233], v[174:177], v[40:43]
	v_mfma_f32_16x16x32_bf16 v[32:35], v[222:225], v[182:185], v[32:35]
	v_mfma_f32_16x16x32_bf16 v[24:27], v[230:233], v[182:185], v[24:27]
	v_mfma_f32_16x16x32_bf16 v[16:19], v[222:225], v[190:193], v[16:19]
	v_mfma_f32_16x16x32_bf16 v[8:11], v[230:233], v[190:193], v[8:11]
	v_mfma_f32_16x16x32_bf16 v[4:7], v[222:225], v[214:217], v[4:7]
	v_mfma_f32_16x16x32_bf16 v[0:3], v[230:233], v[214:217], v[0:3]
	v_mfma_f32_16x16x32_bf16 v[48:51], v[226:229], v[178:181], v[48:51]
	v_mfma_f32_16x16x32_bf16 v[40:43], v[234:237], v[178:181], v[40:43]
	v_mfma_f32_16x16x32_bf16 v[32:35], v[226:229], v[186:189], v[32:35]
	v_mfma_f32_16x16x32_bf16 v[24:27], v[234:237], v[186:189], v[24:27]
	v_mfma_f32_16x16x32_bf16 v[16:19], v[226:229], v[194:197], v[16:19]
	v_mfma_f32_16x16x32_bf16 v[8:11], v[234:237], v[194:197], v[8:11]
	v_mfma_f32_16x16x32_bf16 v[4:7], v[226:229], v[218:221], v[4:7]
	v_mfma_f32_16x16x32_bf16 v[0:3], v[234:237], v[218:221], v[0:3]
	s_add_i32 s45, 0, 0x18000
	v_add_u32_e32 v146, s45, v149
	s_barrier
	ds_read_b128 v[128:131], v146
	ds_read_b128 v[132:135], v146 offset:1024
	ds_read_b128 v[142:145], v146 offset:2048
	ds_read_b128 v[150:153], v146 offset:3072
	s_add_u32 s22, s22, 0x80000
	s_addc_u32 s23, s23, 0
	s_mov_b32 m0, s34
	ds_read_b128 v[174:177], v159 offset:32768
	ds_read_b128 v[178:181], v159 offset:33792
	ds_read_b128 v[182:185], v159 offset:34816
	ds_read_b128 v[186:189], v159 offset:35840
	ds_read_b128 v[190:193], v159 offset:36864
	ds_read_b128 v[194:197], v159 offset:37888
	ds_read_b128 v[214:217], v159 offset:38912
	ds_read_b128 v[218:221], v159 offset:39936
	global_load_lds_dwordx4 v160, s[22:23]
	s_mov_b32 m0, s35
	s_nop 0
	global_load_lds_dwordx4 v136, s[22:23]
	s_waitcnt lgkmcnt(8)
	s_waitcnt vmcnt(10)
	s_barrier
	s_waitcnt lgkmcnt(0)
	v_mfma_f32_16x16x32_bf16 v[124:127], v[128:131], v[174:177], v[124:127]
	v_mfma_f32_16x16x32_bf16 v[120:123], v[142:145], v[174:177], v[120:123]
	v_mfma_f32_16x16x32_bf16 v[116:119], v[128:131], v[182:185], v[116:119]
	v_mfma_f32_16x16x32_bf16 v[108:111], v[142:145], v[182:185], v[108:111]
	v_mfma_f32_16x16x32_bf16 v[100:103], v[128:131], v[190:193], v[100:103]
	v_mfma_f32_16x16x32_bf16 v[92:95], v[142:145], v[190:193], v[92:95]
	v_mfma_f32_16x16x32_bf16 v[84:87], v[128:131], v[214:217], v[84:87]
	v_mfma_f32_16x16x32_bf16 v[76:79], v[142:145], v[214:217], v[76:79]
	v_mfma_f32_16x16x32_bf16 v[124:127], v[132:135], v[178:181], v[124:127]
	v_mfma_f32_16x16x32_bf16 v[120:123], v[150:153], v[178:181], v[120:123]
	v_mfma_f32_16x16x32_bf16 v[116:119], v[132:135], v[186:189], v[116:119]
	v_mfma_f32_16x16x32_bf16 v[108:111], v[150:153], v[186:189], v[108:111]
	v_mfma_f32_16x16x32_bf16 v[100:103], v[132:135], v[194:197], v[100:103]
	v_mfma_f32_16x16x32_bf16 v[92:95], v[150:153], v[194:197], v[92:95]
	v_mfma_f32_16x16x32_bf16 v[84:87], v[132:135], v[218:221], v[84:87]
	v_mfma_f32_16x16x32_bf16 v[76:79], v[150:153], v[218:221], v[76:79]
	s_barrier
	s_add_i32 s22, 0, 0x1c000
	s_add_i32 s23, s45, s29
	v_add_u32_e32 v146, s22, v149
	v_lshl_add_u64 v[154:155], v[154:155], 0, s[2:3]
	s_mov_b32 m0, s23
	ds_read_b128 v[222:225], v146
	ds_read_b128 v[226:229], v146 offset:1024
	ds_read_b128 v[230:233], v146 offset:2048
	ds_read_b128 v[234:237], v146 offset:3072
	global_load_lds_dwordx4 v[154:155], off
	v_lshl_add_u64 v[154:155], v[238:239], 0, s[2:3]
	s_add_i32 m0, s23, 0x2000
	s_nop 0
	global_load_lds_dwordx4 v[154:155], off
	s_waitcnt vmcnt(10)
	s_barrier
	s_waitcnt lgkmcnt(0)
	v_mfma_f32_16x16x32_bf16 v[112:115], v[222:225], v[174:177], v[112:115]
	v_mfma_f32_16x16x32_bf16 v[104:107], v[230:233], v[174:177], v[104:107]
	v_mfma_f32_16x16x32_bf16 v[96:99], v[222:225], v[182:185], v[96:99]
	v_mfma_f32_16x16x32_bf16 v[88:91], v[230:233], v[182:185], v[88:91]
	v_mfma_f32_16x16x32_bf16 v[80:83], v[222:225], v[190:193], v[80:83]
	v_mfma_f32_16x16x32_bf16 v[72:75], v[230:233], v[190:193], v[72:75]
	v_mfma_f32_16x16x32_bf16 v[68:71], v[222:225], v[214:217], v[68:71]
	v_mfma_f32_16x16x32_bf16 v[64:67], v[230:233], v[214:217], v[64:67]
	v_mfma_f32_16x16x32_bf16 v[112:115], v[226:229], v[178:181], v[112:115]
	v_mfma_f32_16x16x32_bf16 v[104:107], v[234:237], v[178:181], v[104:107]
	v_mfma_f32_16x16x32_bf16 v[96:99], v[226:229], v[186:189], v[96:99]
	v_mfma_f32_16x16x32_bf16 v[88:91], v[234:237], v[186:189], v[88:91]
	v_mfma_f32_16x16x32_bf16 v[80:83], v[226:229], v[194:197], v[80:83]
	v_mfma_f32_16x16x32_bf16 v[72:75], v[234:237], v[194:197], v[72:75]
	v_mfma_f32_16x16x32_bf16 v[68:71], v[226:229], v[218:221], v[68:71]
	v_mfma_f32_16x16x32_bf16 v[64:67], v[234:237], v[218:221], v[64:67]
	s_mov_b32 m0, s37
	v_lshl_add_u64 v[154:155], v[240:241], 0, s[2:3]
	s_barrier
	ds_read_b128 v[174:177], v159 offset:49152
	ds_read_b128 v[178:181], v159 offset:50176
	ds_read_b128 v[182:185], v159 offset:51200
	ds_read_b128 v[186:189], v159 offset:52224
	ds_read_b128 v[190:193], v159 offset:53248
	ds_read_b128 v[194:197], v159 offset:54272
	ds_read_b128 v[214:217], v159 offset:55296
	ds_read_b128 v[218:221], v159 offset:56320
	global_load_lds_dwordx4 v[154:155], off
	v_lshl_add_u64 v[154:155], v[242:243], 0, s[2:3]
	s_mov_b32 m0, s38
	s_nop 0
	global_load_lds_dwordx4 v[154:155], off
	s_barrier
; DEV bf16x8 pack8(f32x4 a, f32x4 b) { u32x4 w; w.x = cvt_pk_bf16(a[0], a[1]); w.y = cvt_pk_bf16(a[2], a[3]); w.z = cvt_pk_bf16(b[0], b[1]); w.w = cvt_pk_bf16(b[2], b[3]); return __builtin_bit_cast(bf16x8, w); }
; DEV u32x2 pack4(f32x4 a) { u32x2 w; w.x = cvt_pk_bf16(a[0], a[1]); w.y = cvt_pk_bf16(a[2], a[3]); return w; }
; DEV f32x4 gelu4(f32x4 v) { f32x2 a = gelu_pk((f32x2){v[0], v[1]}), b = gelu_pk((f32x2){v[2], v[3]}); return (f32x4){a.x, a.y, b.x, b.y}; }
; #define PG8_STAGE(bufoff, gbase, voff) do { _Pragma("unroll") for (int _i = 0; _i < 2; ++_i) \
;         __builtin_amdgcn_global_load_lds((const unsigned*)((const char*)(gbase) + (voff)[_i]), (LAS unsigned*)(lds + (bufoff) + ldsw + _i * 8192), 16, 0, 0); } while (0)
; #define PG8_MMA(ai, bj, At, Bt) do { __builtin_amdgcn_s_setprio(1); _Pragma("unroll") for (int m = 0; m < 4; ++m) _Pragma("unroll") for (int n = 0; n < 2; ++n) _Pragma("unroll") for (int k = 0; k < 2; ++k) \
;         acc[ai][bj][m][n] = __builtin_amdgcn_mfma_f32_16x16x32_bf16(Bt[n][k], At[m][k], acc[ai][bj][m][n], 0, 0, 0); __builtin_amdgcn_s_setprio(0); } while (0)
; template <class Epi>
; DEV void gemm_phase(LAS unsigned char* lds, const Gemm g, const StaticOrder& S, const Epi& E) {
;     ...
;             PG8_BAR; PG8_WAIT_L(0); PG8_MMA(1, 0, At, B0); PG8_BAR; PG8_SCHED;
;             PG8_STAGE(PG8_SB(1, 1), b3 + hstep, voffB);
;             PG8_WAIT_V(6); PG8_BAR; PG8_MMA(1, 1, At, B1); PG8_BAR;
; template <int ACT, bool PERM>
; DEV void store_bf16_tile(AccRef acc, u16* O, int ld, int row0, int col0, const float* ss) {
;     float rsv[2][4];
; #pragma unroll
;     for (int ai = 0; ai < 2; ++ai)
; #pragma unroll
;         for (int m = 0; m < 4; ++m) rsv[ai][m] = ss ? rowscale(ss, row0 + ai * 128 + m * 16) : 1.0f;
; #pragma unroll
;     for (int ai = 0; ai < 2; ++ai)
; #pragma unroll
;         for (int m = 0; m < 4; ++m) { u16* rowp = O + (size_t)(row0 + ai * 128 + m * 16) * ld + col0; const float rs = rsv[ai][m];
; #pragma unroll
;             for (int bj = 0; bj < 2; ++bj) { f32x4 v0 = acc[ai][bj][m][0] * rs, v1 = acc[ai][bj][m][1] * rs; if (ACT == 1) { v0 = gelu4(v0); v1 = gelu4(v1); }
;                 if (PERM) *(u32x4*)(rowp + bj * 128) = __builtin_bit_cast(u32x4, pack8(v0, v1));
;                 else { *(u32x2*)(rowp + bj * 128) = pack4(v0); *(u32x2*)(rowp + bj * 128 + 16) = pack4(v1); } } }
	s_waitcnt lgkmcnt(0)
	v_mfma_f32_16x16x32_bf16 v[60:63], v[128:131], v[174:177], v[60:63]
	v_mfma_f32_16x16x32_bf16 v[56:59], v[142:145], v[174:177], v[56:59]
	v_mfma_f32_16x16x32_bf16 v[52:55], v[128:131], v[182:185], v[52:55]
	v_mfma_f32_16x16x32_bf16 v[44:47], v[142:145], v[182:185], v[44:47]
	v_mfma_f32_16x16x32_bf16 v[36:39], v[128:131], v[190:193], v[36:39]
	v_mfma_f32_16x16x32_bf16 v[28:31], v[142:145], v[190:193], v[28:31]
	v_mfma_f32_16x16x32_bf16 v[20:23], v[128:131], v[214:217], v[20:23]
	v_mfma_f32_16x16x32_bf16 v[12:15], v[142:145], v[214:217], v[12:15]
	v_mfma_f32_16x16x32_bf16 v[60:63], v[132:135], v[178:181], v[60:63]
	v_mfma_f32_16x16x32_bf16 v[56:59], v[150:153], v[178:181], v[56:59]
	v_mfma_f32_16x16x32_bf16 v[52:55], v[132:135], v[186:189], v[52:55]
	v_mfma_f32_16x16x32_bf16 v[44:47], v[150:153], v[186:189], v[44:47]
	v_mfma_f32_16x16x32_bf16 v[36:39], v[132:135], v[194:197], v[36:39]
	v_mfma_f32_16x16x32_bf16 v[28:31], v[150:153], v[194:197], v[28:31]
	v_mfma_f32_16x16x32_bf16 v[20:23], v[132:135], v[218:221], v[20:23]
	v_mfma_f32_16x16x32_bf16 v[12:15], v[150:153], v[218:221], v[12:15]
	s_barrier
	s_add_u32 s20, s20, 0x80080
	s_addc_u32 s21, s21, 0
	s_add_i32 s22, s22, s29
	s_mov_b32 m0, s22
	s_nop 0
	global_load_lds_dwordx4 v160, s[20:21]
	s_add_i32 m0, s22, 0x2000
	s_nop 0
	global_load_lds_dwordx4 v136, s[20:21]
	s_waitcnt vmcnt(10)
	s_barrier
	v_mfma_f32_16x16x32_bf16 v[48:51], v[222:225], v[174:177], v[48:51]
	v_mfma_f32_16x16x32_bf16 v[40:43], v[230:233], v[174:177], v[40:43]
	v_mfma_f32_16x16x32_bf16 v[32:35], v[222:225], v[182:185], v[32:35]
	v_mfma_f32_16x16x32_bf16 v[24:27], v[230:233], v[182:185], v[24:27]
	v_mfma_f32_16x16x32_bf16 v[16:19], v[222:225], v[190:193], v[16:19]
	v_mfma_f32_16x16x32_bf16 v[8:11], v[230:233], v[190:193], v[8:11]
	v_mfma_f32_16x16x32_bf16 v[4:7], v[222:225], v[214:217], v[4:7]
	v_mfma_f32_16x16x32_bf16 v[0:3], v[230:233], v[214:217], v[0:3]
	v_mfma_f32_16x16x32_bf16 v[48:51], v[226:229], v[178:181], v[48:51]
	v_mfma_f32_16x16x32_bf16 v[40:43], v[234:237], v[178:181], v[40:43]
	v_mfma_f32_16x16x32_bf16 v[32:35], v[226:229], v[186:189], v[32:35]
	v_mfma_f32_16x16x32_bf16 v[24:27], v[234:237], v[186:189], v[24:27]
	v_mfma_f32_16x16x32_bf16 v[16:19], v[226:229], v[194:197], v[16:19]
	v_mfma_f32_16x16x32_bf16 v[8:11], v[234:237], v[194:197], v[8:11]
	v_mfma_f32_16x16x32_bf16 v[4:7], v[226:229], v[218:221], v[4:7]
	v_mfma_f32_16x16x32_bf16 v[0:3], v[234:237], v[218:221], v[0:3]
	s_add_i32 s44, s44, 2
	s_add_u32 s18, s18, 0x100
	s_addc_u32 s19, s19, 0
	s_add_u32 s42, s42, 0x100
	s_addc_u32 s43, s43, 0
	s_cmp_gt_u32 s44, 29
	s_barrier
	s_cbranch_scc0 .LBB0_344
	v_lshl_add_u32 v142, s0, 8, v147
	v_ashrrev_i32_e32 v143, 31, v142
	v_lshlrev_b64 v[128:129], 5, v[142:143]
	v_lshl_add_u64 v[132:133], s[4:5], 0, v[128:129]
	global_load_dwordx4 v[128:131], v[132:133], off offset:16
	s_nop 0
	global_load_dwordx4 v[132:135], v[132:133], off
	s_mov_b32 s0, 0x3727c5ac
	s_mov_b32 s18, 0x3a000000
	s_mov_b32 s11, 0x800000
	s_mov_b64 s[20:21], s[16:17]
	s_waitcnt vmcnt(0)
	v_mov_b32_e32 v144, v133
	v_mov_b32_e32 v145, v134
	v_mov_b32_e32 v133, v135
	v_pk_add_f32 v[150:151], v[144:145], v[132:133]
	v_or_b32_e32 v144, 16, v142
	v_mov_b32_e32 v132, v130
	v_mov_b32_e32 v133, v128
	v_mov_b32_e32 v128, v131
	v_ashrrev_i32_e32 v145, 31, v144
	v_pk_add_f32 v[152:153], v[132:133], v[128:129]
	v_lshlrev_b64 v[128:129], 5, v[144:145]
	v_lshl_add_u64 v[132:133], s[4:5], 0, v[128:129]
	global_load_dwordx4 v[128:131], v[132:133], off offset:16
	s_nop 0
	global_load_dwordx4 v[132:135], v[132:133], off
	s_waitcnt vmcnt(0)
	v_mov_b32_e32 v154, v133
	v_mov_b32_e32 v155, v134
	v_mov_b32_e32 v133, v135
	v_pk_add_f32 v[132:133], v[154:155], v[132:133]
	v_mov_b32_e32 v134, v130
	v_mov_b32_e32 v135, v128
	v_mov_b32_e32 v128, v131
	v_pk_add_f32 v[128:129], v[134:135], v[128:129]
	v_mov_b32_e32 v130, v132
	v_mov_b32_e32 v131, v150
	v_mov_b32_e32 v150, v133
	v_pk_add_f32 v[130:131], v[130:131], v[150:151]
	v_mov_b32_e32 v132, v129
	v_mov_b32_e32 v133, v153
	v_pk_add_f32 v[130:131], v[130:131], v[132:133]
	v_mov_b32_e32 v129, v152
	v_pk_add_f32 v[128:129], v[128:129], v[130:131]
	v_mov_b64_e32 v[150:151], s[0:1]
	v_pk_fma_f32 v[128:129], v[128:129], s[18:19], v[150:151] op_sel_hi:[1,0,0]
	v_or_b32_e32 v152, 32, v142
	v_mul_f32_e32 v130, 0x4b800000, v129
	v_cmp_gt_f32_e64 s[0:1], s11, v129
	v_cmp_gt_f32_e32 vcc, s11, v128
	v_ashrrev_i32_e32 v153, 31, v152
	v_cndmask_b32_e64 v129, v129, v130, s[0:1]
	v_rsq_f32_e32 v129, v129
	s_nop 0
	v_mul_f32_e32 v130, 0x45800000, v129
	v_cndmask_b32_e64 v148, v129, v130, s[0:1]
	v_mul_f32_e32 v129, 0x4b800000, v128
	v_cndmask_b32_e32 v128, v128, v129, vcc
	v_rsq_f32_e32 v128, v128
	v_pk_mul_f32 v[106:107], v[106:107], v[148:149] op_sel_hi:[1,0]
	v_pk_mul_f32 v[104:105], v[104:105], v[148:149] op_sel_hi:[1,0]
	v_pk_mul_f32 v[114:115], v[114:115], v[148:149] op_sel_hi:[1,0]
	v_mul_f32_e32 v129, 0x45800000, v128
	v_cndmask_b32_e32 v146, v128, v129, vcc
	v_lshlrev_b64 v[128:129], 5, v[152:153]
	v_lshl_add_u64 v[132:133], s[4:5], 0, v[128:129]
	global_load_dwordx4 v[128:131], v[132:133], off offset:16
	s_nop 0
	global_load_dwordx4 v[132:135], v[132:133], off
	v_cvt_pk_bf16_f32 v104, v104, v105
	v_cvt_pk_bf16_f32 v105, v106, v107
	v_pk_mul_f32 v[90:91], v[90:91], v[146:147] op_sel_hi:[1,0]
	v_pk_mul_f32 v[88:89], v[88:89], v[146:147] op_sel_hi:[1,0]
	v_pk_mul_f32 v[112:113], v[112:113], v[148:149] op_sel_hi:[1,0]
	v_cvt_pk_bf16_f32 v88, v88, v89
	v_cvt_pk_bf16_f32 v89, v90, v91
	v_pk_mul_f32 v[98:99], v[98:99], v[146:147] op_sel_hi:[1,0]
	v_pk_mul_f32 v[96:97], v[96:97], v[146:147] op_sel_hi:[1,0]
	v_cvt_pk_bf16_f32 v112, v112, v113
	v_cvt_pk_bf16_f32 v113, v114, v115
	v_cvt_pk_bf16_f32 v96, v96, v97
	v_cvt_pk_bf16_f32 v97, v98, v99
	v_pk_mul_f32 v[126:127], v[126:127], v[148:149] op_sel_hi:[1,0]
	v_pk_mul_f32 v[124:125], v[124:125], v[148:149] op_sel_hi:[1,0]
	v_pk_mul_f32 v[122:123], v[122:123], v[148:149] op_sel_hi:[1,0]
	v_pk_mul_f32 v[120:121], v[120:121], v[148:149] op_sel_hi:[1,0]
	v_pk_mul_f32 v[106:107], v[118:119], v[146:147] op_sel_hi:[1,0]
	v_pk_mul_f32 v[110:111], v[110:111], v[146:147] op_sel_hi:[1,0]
	v_pk_mul_f32 v[108:109], v[108:109], v[146:147] op_sel_hi:[1,0]
	v_cvt_pk_bf16_f32 v124, v124, v125
	v_cvt_pk_bf16_f32 v125, v126, v127
	v_cvt_pk_bf16_f32 v120, v120, v121
	v_cvt_pk_bf16_f32 v121, v122, v123
	s_waitcnt vmcnt(0)
; DEV bf16x8 pack8(f32x4 a, f32x4 b) { u32x4 w; w.x = cvt_pk_bf16(a[0], a[1]); w.y = cvt_pk_bf16(a[2], a[3]); w.z = cvt_pk_bf16(b[0], b[1]); w.w = cvt_pk_bf16(b[2], b[3]); return __builtin_bit_cast(bf16x8, w); }
; DEV u32x2 pack4(f32x4 a) { u32x2 w; w.x = cvt_pk_bf16(a[0], a[1]); w.y = cvt_pk_bf16(a[2], a[3]); return w; }
; DEV f32x4 gelu4(f32x4 v) { f32x2 a = gelu_pk((f32x2){v[0], v[1]}), b = gelu_pk((f32x2){v[2], v[3]}); return (f32x4){a.x, a.y, b.x, b.y}; }
; DEV float rowscale(const float* ss, int row) { const f32x4 a = *(const f32x4*)(ss + (size_t)row * 8), b = *(const f32x4*)(ss + (size_t)row * 8 + 4);
;     return rsqrtf(((a[0] + a[1]) + (a[2] + a[3]) + (b[0] + b[1]) + (b[2] + b[3])) * (1.0f / 2048.0f) + EPS); }
; template <int ACT, bool PERM>
; DEV void store_bf16_tile(AccRef acc, u16* O, int ld, int row0, int col0, const float* ss) {
;     float rsv[2][4];
; #pragma unroll
;     for (int ai = 0; ai < 2; ++ai)
; #pragma unroll
;         for (int m = 0; m < 4; ++m) rsv[ai][m] = ss ? rowscale(ss, row0 + ai * 128 + m * 16) : 1.0f;
; #pragma unroll
;     for (int ai = 0; ai < 2; ++ai)
; #pragma unroll
;         for (int m = 0; m < 4; ++m) { u16* rowp = O + (size_t)(row0 + ai * 128 + m * 16) * ld + col0; const float rs = rsv[ai][m];
; #pragma unroll
;             for (int bj = 0; bj < 2; ++bj) { f32x4 v0 = acc[ai][bj][m][0] * rs, v1 = acc[ai][bj][m][1] * rs; if (ACT == 1) { v0 = gelu4(v0); v1 = gelu4(v1); }
;                 if (PERM) *(u32x4*)(rowp + bj * 128) = __builtin_bit_cast(u32x4, pack8(v0, v1));
;                 else { *(u32x2*)(rowp + bj * 128) = pack4(v0); *(u32x2*)(rowp + bj * 128 + 16) = pack4(v1); } } }
	v_mov_b32_e32 v154, v133
	v_mov_b32_e32 v155, v134
	v_mov_b32_e32 v133, v135
	v_pk_add_f32 v[174:175], v[154:155], v[132:133]
	v_or_b32_e32 v154, 48, v142
	v_mov_b32_e32 v132, v130
	v_mov_b32_e32 v133, v128
	v_mov_b32_e32 v128, v131
	v_ashrrev_i32_e32 v155, 31, v154
	v_pk_add_f32 v[176:177], v[132:133], v[128:129]
	v_lshlrev_b64 v[128:129], 5, v[154:155]
	v_lshl_add_u64 v[132:133], s[4:5], 0, v[128:129]
	global_load_dwordx4 v[128:131], v[132:133], off offset:16
	s_nop 0
	global_load_dwordx4 v[132:135], v[132:133], off
	s_waitcnt vmcnt(0)
	v_mov_b32_e32 v178, v133
	v_mov_b32_e32 v179, v134
	v_mov_b32_e32 v133, v135
	v_pk_add_f32 v[132:133], v[178:179], v[132:133]
	v_mov_b32_e32 v134, v130
	v_mov_b32_e32 v135, v128
	v_mov_b32_e32 v128, v131
	v_pk_add_f32 v[128:129], v[134:135], v[128:129]
	v_mov_b32_e32 v130, v132
	v_mov_b32_e32 v131, v174
	v_mov_b32_e32 v174, v133
	v_pk_add_f32 v[130:131], v[130:131], v[174:175]
	v_mov_b32_e32 v132, v129
	v_mov_b32_e32 v133, v177
	v_pk_add_f32 v[130:131], v[130:131], v[132:133]
	v_mov_b32_e32 v129, v176
	v_pk_add_f32 v[128:129], v[128:129], v[130:131]
	v_add_u32_e32 v174, 0x80, v142
	v_pk_fma_f32 v[128:129], v[128:129], s[18:19], v[150:151] op_sel_hi:[1,0,0]
	v_ashrrev_i32_e32 v175, 31, v174
	v_mul_f32_e32 v130, 0x4b800000, v129
	v_cmp_gt_f32_e64 s[0:1], s11, v129
	v_cmp_gt_f32_e32 vcc, s11, v128
	s_nop 0
	v_cndmask_b32_e64 v129, v129, v130, s[0:1]
	v_rsq_f32_e32 v129, v129
	s_nop 0
	v_mul_f32_e32 v130, 0x45800000, v129
	v_cndmask_b32_e64 v158, v129, v130, s[0:1]
	v_mul_f32_e32 v129, 0x4b800000, v128
	v_cndmask_b32_e32 v128, v128, v129, vcc
	v_rsq_f32_e32 v128, v128
	v_pk_mul_f32 v[74:75], v[74:75], v[158:159] op_sel_hi:[1,0]
	v_pk_mul_f32 v[72:73], v[72:73], v[158:159] op_sel_hi:[1,0]
	v_pk_mul_f32 v[82:83], v[82:83], v[158:159] op_sel_hi:[1,0]
	v_mul_f32_e32 v129, 0x45800000, v128
	v_cndmask_b32_e32 v156, v128, v129, vcc
	v_lshlrev_b64 v[128:129], 5, v[174:175]
	v_lshl_add_u64 v[132:133], s[4:5], 0, v[128:129]
	global_load_dwordx4 v[128:131], v[132:133], off offset:16
	s_nop 0
	global_load_dwordx4 v[132:135], v[132:133], off
	v_cvt_pk_bf16_f32 v72, v72, v73
	v_cvt_pk_bf16_f32 v73, v74, v75
	v_pk_mul_f32 v[66:67], v[66:67], v[156:157] op_sel_hi:[1,0]
	v_pk_mul_f32 v[64:65], v[64:65], v[156:157] op_sel_hi:[1,0]
	v_pk_mul_f32 v[80:81], v[80:81], v[158:159] op_sel_hi:[1,0]
	v_cvt_pk_bf16_f32 v64, v64, v65
	v_cvt_pk_bf16_f32 v65, v66, v67
	v_cvt_pk_bf16_f32 v80, v80, v81
	v_cvt_pk_bf16_f32 v81, v82, v83
	v_pk_mul_f32 v[90:91], v[102:103], v[158:159] op_sel_hi:[1,0]
	v_pk_mul_f32 v[94:95], v[94:95], v[158:159] op_sel_hi:[1,0]
	v_pk_mul_f32 v[92:93], v[92:93], v[158:159] op_sel_hi:[1,0]
	v_pk_mul_f32 v[74:75], v[86:87], v[156:157] op_sel_hi:[1,0]
	v_pk_mul_f32 v[78:79], v[78:79], v[156:157] op_sel_hi:[1,0]
	v_pk_mul_f32 v[76:77], v[76:77], v[156:157] op_sel_hi:[1,0]
	v_pk_mul_f32 v[70:71], v[70:71], v[156:157] op_sel_hi:[1,0]
	v_pk_mul_f32 v[68:69], v[68:69], v[156:157] op_sel_hi:[1,0]
	s_waitcnt vmcnt(0)
	v_mov_b32_e32 v176, v133
	v_mov_b32_e32 v177, v134
	v_mov_b32_e32 v133, v135
	v_pk_add_f32 v[178:179], v[176:177], v[132:133]
	v_add_u32_e32 v176, 0x90, v142
	v_mov_b32_e32 v132, v130
	v_mov_b32_e32 v133, v128
	v_mov_b32_e32 v128, v131
	v_ashrrev_i32_e32 v177, 31, v176
	v_pk_add_f32 v[180:181], v[132:133], v[128:129]
	v_lshlrev_b64 v[128:129], 5, v[176:177]
	v_lshl_add_u64 v[132:133], s[4:5], 0, v[128:129]
	global_load_dwordx4 v[128:131], v[132:133], off offset:16
	s_nop 0
	global_load_dwordx4 v[132:135], v[132:133], off
	v_cvt_pk_bf16_f32 v68, v68, v69
	v_cvt_pk_bf16_f32 v69, v70, v71
	s_waitcnt vmcnt(0)
	v_mov_b32_e32 v182, v133
	v_mov_b32_e32 v183, v134
	v_mov_b32_e32 v133, v135
	v_pk_add_f32 v[132:133], v[182:183], v[132:133]
	v_mov_b32_e32 v134, v130
	v_mov_b32_e32 v135, v128
	v_mov_b32_e32 v128, v131
	v_pk_add_f32 v[128:129], v[134:135], v[128:129]
	v_mov_b32_e32 v130, v132
	v_mov_b32_e32 v131, v178
	v_mov_b32_e32 v178, v133
	v_pk_add_f32 v[130:131], v[130:131], v[178:179]
	v_mov_b32_e32 v132, v129
	v_mov_b32_e32 v133, v181
	v_pk_add_f32 v[130:131], v[130:131], v[132:133]
	v_mov_b32_e32 v129, v180
	v_pk_add_f32 v[128:129], v[128:129], v[130:131]
	v_add_u32_e32 v182, 0xa0, v142
	v_pk_fma_f32 v[128:129], v[128:129], s[18:19], v[150:151] op_sel_hi:[1,0,0]
	v_ashrrev_i32_e32 v183, 31, v182
	v_mul_f32_e32 v130, 0x4b800000, v129
	v_cmp_gt_f32_e64 s[0:1], s11, v129
	v_cmp_gt_f32_e32 vcc, s11, v128
	s_nop 0
	v_cndmask_b32_e64 v129, v129, v130, s[0:1]
	v_rsq_f32_e32 v129, v129
	s_nop 0
	v_mul_f32_e32 v130, 0x45800000, v129
	v_cndmask_b32_e64 v180, v129, v130, s[0:1]
	v_mul_f32_e32 v129, 0x4b800000, v128
	v_cndmask_b32_e32 v128, v128, v129, vcc
	v_rsq_f32_e32 v128, v128
	v_pk_mul_f32 v[42:43], v[42:43], v[180:181] op_sel_hi:[1,0]
	v_pk_mul_f32 v[40:41], v[40:41], v[180:181] op_sel_hi:[1,0]
	v_pk_mul_f32 v[50:51], v[50:51], v[180:181] op_sel_hi:[1,0]
	v_mul_f32_e32 v129, 0x45800000, v128
	v_cndmask_b32_e32 v178, v128, v129, vcc
	v_lshlrev_b64 v[128:129], 5, v[182:183]
	v_lshl_add_u64 v[132:133], s[4:5], 0, v[128:129]
	global_load_dwordx4 v[128:131], v[132:133], off offset:16
	s_nop 0
	global_load_dwordx4 v[132:135], v[132:133], off
	v_cvt_pk_bf16_f32 v40, v40, v41
	v_cvt_pk_bf16_f32 v41, v42, v43
	v_pk_mul_f32 v[26:27], v[26:27], v[178:179] op_sel_hi:[1,0]
	v_pk_mul_f32 v[24:25], v[24:25], v[178:179] op_sel_hi:[1,0]
	v_pk_mul_f32 v[48:49], v[48:49], v[180:181] op_sel_hi:[1,0]
	v_cvt_pk_bf16_f32 v24, v24, v25
	v_cvt_pk_bf16_f32 v25, v26, v27
	v_pk_mul_f32 v[34:35], v[34:35], v[178:179] op_sel_hi:[1,0]
	v_pk_mul_f32 v[32:33], v[32:33], v[178:179] op_sel_hi:[1,0]
	v_cvt_pk_bf16_f32 v48, v48, v49
	v_cvt_pk_bf16_f32 v49, v50, v51
	v_cvt_pk_bf16_f32 v32, v32, v33
	v_cvt_pk_bf16_f32 v33, v34, v35
	v_pk_mul_f32 v[62:63], v[62:63], v[180:181] op_sel_hi:[1,0]
	v_pk_mul_f32 v[60:61], v[60:61], v[180:181] op_sel_hi:[1,0]
	v_pk_mul_f32 v[58:59], v[58:59], v[180:181] op_sel_hi:[1,0]
	v_pk_mul_f32 v[56:57], v[56:57], v[180:181] op_sel_hi:[1,0]
	v_pk_mul_f32 v[42:43], v[54:55], v[178:179] op_sel_hi:[1,0]
	v_pk_mul_f32 v[46:47], v[46:47], v[178:179] op_sel_hi:[1,0]
	v_pk_mul_f32 v[44:45], v[44:45], v[178:179] op_sel_hi:[1,0]
	v_cvt_pk_bf16_f32 v60, v60, v61
	v_cvt_pk_bf16_f32 v61, v62, v63
	v_cvt_pk_bf16_f32 v56, v56, v57
	v_cvt_pk_bf16_f32 v57, v58, v59
	s_waitcnt vmcnt(0)
; DEV bf16x8 pack8(f32x4 a, f32x4 b) { u32x4 w; w.x = cvt_pk_bf16(a[0], a[1]); w.y = cvt_pk_bf16(a[2], a[3]); w.z = cvt_pk_bf16(b[0], b[1]); w.w = cvt_pk_bf16(b[2], b[3]); return __builtin_bit_cast(bf16x8, w); }
; DEV u32x2 pack4(f32x4 a) { u32x2 w; w.x = cvt_pk_bf16(a[0], a[1]); w.y = cvt_pk_bf16(a[2], a[3]); return w; }
; DEV f32x4 gelu4(f32x4 v) { f32x2 a = gelu_pk((f32x2){v[0], v[1]}), b = gelu_pk((f32x2){v[2], v[3]}); return (f32x4){a.x, a.y, b.x, b.y}; }
; #define PG8_WAIT_V(n) asm volatile("s_waitcnt vmcnt(" #n ")" ::: "memory")
; #define PG8_BAR __builtin_amdgcn_s_barrier()
; template <class Epi>
; DEV void gemm_phase(LAS unsigned char* lds, const Gemm g, const StaticOrder& S, const Epi& E) {
;     ...
;         E(acc, cur, wr, wc, fr, fq);
;         if (!has_next) break;
; #pragma unroll
;         for (int a = 0; a < 2; ++a)
; #pragma unroll
;             for (int b = 0; b < 2; ++b)
; #pragma unroll
;                 for (int m = 0; m < 4; ++m)
; #pragma unroll
;                     for (int n = 0; n < 2; ++n) acc[a][b][m][n] = (f32x4){0.f, 0.f, 0.f, 0.f};
;         cur = nxt; cA = nA; cB = nB; ++ui;
;     }
;     PG8_WAIT_V(0);
;     if (wr == 0) PG8_BAR;
;     PG8_BAR;
; template <int ACT, bool PERM>
; DEV void store_bf16_tile(AccRef acc, u16* O, int ld, int row0, int col0, const float* ss) {
;     float rsv[2][4];
; #pragma unroll
;     for (int ai = 0; ai < 2; ++ai)
; #pragma unroll
;         for (int m = 0; m < 4; ++m) rsv[ai][m] = ss ? rowscale(ss, row0 + ai * 128 + m * 16) : 1.0f;
; #pragma unroll
;     for (int ai = 0; ai < 2; ++ai)
; #pragma unroll
;         for (int m = 0; m < 4; ++m) { u16* rowp = O + (size_t)(row0 + ai * 128 + m * 16) * ld + col0; const float rs = rsv[ai][m];
; #pragma unroll
;             for (int bj = 0; bj < 2; ++bj) { f32x4 v0 = acc[ai][bj][m][0] * rs, v1 = acc[ai][bj][m][1] * rs; if (ACT == 1) { v0 = gelu4(v0); v1 = gelu4(v1); }
;                 if (PERM) *(u32x4*)(rowp + bj * 128) = __builtin_bit_cast(u32x4, pack8(v0, v1));
;                 else { *(u32x2*)(rowp + bj * 128) = pack4(v0); *(u32x2*)(rowp + bj * 128 + 16) = pack4(v1); } } }
	v_mov_b32_e32 v184, v133
	v_mov_b32_e32 v185, v134
	v_mov_b32_e32 v133, v135
	v_pk_add_f32 v[188:189], v[184:185], v[132:133]
	v_add_u32_e32 v184, 0xb0, v142
	v_mov_b32_e32 v132, v130
	v_mov_b32_e32 v133, v128
	v_mov_b32_e32 v128, v131
	v_ashrrev_i32_e32 v185, 31, v184
	v_pk_add_f32 v[186:187], v[132:133], v[128:129]
	v_lshlrev_b64 v[128:129], 5, v[184:185]
	v_lshl_add_u64 v[132:133], s[4:5], 0, v[128:129]
	global_load_dwordx4 v[128:131], v[132:133], off offset:16
	s_nop 0
	global_load_dwordx4 v[132:135], v[132:133], off
	s_waitcnt vmcnt(0)
	v_mov_b32_e32 v190, v133
	v_mov_b32_e32 v191, v134
	v_mov_b32_e32 v133, v135
	v_pk_add_f32 v[132:133], v[190:191], v[132:133]
	v_mov_b32_e32 v134, v130
	v_mov_b32_e32 v135, v128
	v_mov_b32_e32 v128, v131
	v_pk_add_f32 v[128:129], v[134:135], v[128:129]
	v_mov_b32_e32 v130, v132
	v_mov_b32_e32 v131, v188
	v_mov_b32_e32 v188, v133
	v_pk_add_f32 v[130:131], v[130:131], v[188:189]
	v_mov_b32_e32 v132, v129
	v_mov_b32_e32 v133, v187
	v_pk_add_f32 v[130:131], v[130:131], v[132:133]
	v_mov_b32_e32 v129, v186
	v_pk_add_f32 v[128:129], v[128:129], v[130:131]
	v_lshl_or_b32 v132, s40, 8, v157
	v_pk_fma_f32 v[128:129], v[128:129], s[18:19], v[150:151] op_sel_hi:[1,0,0]
	v_ashrrev_i32_e32 v133, 31, v132
	v_mul_f32_e32 v130, 0x4b800000, v129
	v_cmp_gt_f32_e64 s[0:1], s11, v129
	v_lshlrev_b64 v[134:135], 10, v[142:143]
	v_cmp_gt_f32_e32 vcc, s11, v128
	v_cndmask_b32_e64 v129, v129, v130, s[0:1]
	v_rsq_f32_e32 v129, v129
	s_mov_b32 s40, s10
	s_mov_b64 s[18:19], s[14:15]
	v_mul_f32_e32 v130, 0x45800000, v129
	v_cndmask_b32_e64 v130, v129, v130, s[0:1]
	v_readlane_b32 s0, v250, 11
	v_readlane_b32 s1, v250, 12
	v_mul_f32_e32 v129, 0x4b800000, v128
	v_cndmask_b32_e32 v128, v128, v129, vcc
	v_lshl_add_u64 v[132:133], v[132:133], 1, s[0:1]
	v_lshl_add_u64 v[134:135], v[132:133], 0, v[134:135]
	global_store_dwordx2 v[134:135], v[104:105], off offset:288
	v_lshlrev_b64 v[104:105], 10, v[144:145]
	v_lshl_add_u64 v[104:105], v[132:133], 0, v[104:105]
	global_store_dwordx2 v[104:105], v[88:89], off offset:288
	v_lshlrev_b64 v[88:89], 10, v[152:153]
	v_lshl_add_u64 v[88:89], v[132:133], 0, v[88:89]
	global_store_dwordx2 v[88:89], v[72:73], off offset:288
	v_lshlrev_b64 v[72:73], 10, v[154:155]
	v_lshl_add_u64 v[72:73], v[132:133], 0, v[72:73]
	v_rsq_f32_e32 v128, v128
	global_store_dwordx2 v[72:73], v[64:65], off offset:288
	v_lshlrev_b64 v[64:65], 10, v[174:175]
	v_lshl_add_u64 v[64:65], v[132:133], 0, v[64:65]
	global_store_dwordx2 v[64:65], v[40:41], off offset:288
	v_lshlrev_b64 v[40:41], 10, v[176:177]
	v_lshl_add_u64 v[40:41], v[132:133], 0, v[40:41]
	v_mul_f32_e32 v129, 0x45800000, v128
	global_store_dwordx2 v[40:41], v[24:25], off offset:288
	v_lshlrev_b64 v[24:25], 10, v[182:183]
	v_pk_mul_f32 v[18:19], v[18:19], v[130:131] op_sel_hi:[1,0]
	v_pk_mul_f32 v[16:17], v[16:17], v[130:131] op_sel_hi:[1,0]
	v_pk_mul_f32 v[10:11], v[10:11], v[130:131] op_sel_hi:[1,0]
	v_pk_mul_f32 v[8:9], v[8:9], v[130:131] op_sel_hi:[1,0]
	v_cndmask_b32_e32 v128, v128, v129, vcc
	v_lshl_add_u64 v[24:25], v[132:133], 0, v[24:25]
	v_cvt_pk_bf16_f32 v16, v16, v17
	v_cvt_pk_bf16_f32 v17, v18, v19
	v_cvt_pk_bf16_f32 v8, v8, v9
	v_cvt_pk_bf16_f32 v9, v10, v11
	global_store_dwordx2 v[134:135], v[112:113], off offset:256
	v_pk_mul_f32 v[112:113], v[116:117], v[146:147] op_sel_hi:[1,0]
	global_store_dwordx2 v[104:105], v[96:97], off offset:256
	v_pk_mul_f32 v[96:97], v[100:101], v[158:159] op_sel_hi:[1,0]
	global_store_dwordx2 v[88:89], v[80:81], off offset:256
	v_pk_mul_f32 v[80:81], v[84:85], v[156:157] op_sel_hi:[1,0]
	global_store_dwordx2 v[64:65], v[48:49], off offset:256
	v_pk_mul_f32 v[48:49], v[52:53], v[178:179] op_sel_hi:[1,0]
	global_store_dwordx2 v[40:41], v[32:33], off offset:256
	v_pk_mul_f32 v[26:27], v[38:39], v[130:131] op_sel_hi:[1,0]
	v_pk_mul_f32 v[32:33], v[36:37], v[130:131] op_sel_hi:[1,0]
	v_pk_mul_f32 v[30:31], v[30:31], v[130:131] op_sel_hi:[1,0]
	v_pk_mul_f32 v[28:29], v[28:29], v[130:131] op_sel_hi:[1,0]
	global_store_dwordx2 v[24:25], v[16:17], off offset:256
	global_store_dwordx2 v[24:25], v[8:9], off offset:288
	v_lshlrev_b64 v[8:9], 10, v[184:185]
	v_pk_mul_f32 v[10:11], v[22:23], v[128:129] op_sel_hi:[1,0]
	v_pk_mul_f32 v[16:17], v[20:21], v[128:129] op_sel_hi:[1,0]
	v_pk_mul_f32 v[14:15], v[14:15], v[128:129] op_sel_hi:[1,0]
	v_pk_mul_f32 v[12:13], v[12:13], v[128:129] op_sel_hi:[1,0]
	v_pk_mul_f32 v[6:7], v[6:7], v[128:129] op_sel_hi:[1,0]
	v_pk_mul_f32 v[4:5], v[4:5], v[128:129] op_sel_hi:[1,0]
	v_pk_mul_f32 v[2:3], v[2:3], v[128:129] op_sel_hi:[1,0]
	v_pk_mul_f32 v[0:1], v[0:1], v[128:129] op_sel_hi:[1,0]
	v_cvt_pk_bf16_f32 v112, v112, v113
	v_cvt_pk_bf16_f32 v113, v106, v107
	v_cvt_pk_bf16_f32 v106, v108, v109
	v_cvt_pk_bf16_f32 v107, v110, v111
	v_cvt_pk_bf16_f32 v96, v96, v97
	v_cvt_pk_bf16_f32 v97, v90, v91
	v_cvt_pk_bf16_f32 v90, v92, v93
	v_cvt_pk_bf16_f32 v91, v94, v95
	v_cvt_pk_bf16_f32 v80, v80, v81
	v_cvt_pk_bf16_f32 v81, v74, v75
	v_cvt_pk_bf16_f32 v74, v76, v77
	v_cvt_pk_bf16_f32 v75, v78, v79
	v_cvt_pk_bf16_f32 v48, v48, v49
	v_cvt_pk_bf16_f32 v49, v42, v43
	v_cvt_pk_bf16_f32 v42, v44, v45
	v_cvt_pk_bf16_f32 v43, v46, v47
	v_cvt_pk_bf16_f32 v32, v32, v33
	v_cvt_pk_bf16_f32 v33, v26, v27
	v_cvt_pk_bf16_f32 v26, v28, v29
	v_cvt_pk_bf16_f32 v27, v30, v31
	v_lshl_add_u64 v[8:9], v[132:133], 0, v[8:9]
	v_cvt_pk_bf16_f32 v16, v16, v17
	v_cvt_pk_bf16_f32 v17, v10, v11
	v_cvt_pk_bf16_f32 v10, v12, v13
	v_cvt_pk_bf16_f32 v11, v14, v15
	v_cvt_pk_bf16_f32 v4, v4, v5
	v_cvt_pk_bf16_f32 v5, v6, v7
	v_cvt_pk_bf16_f32 v0, v0, v1
	v_cvt_pk_bf16_f32 v1, v2, v3
	s_and_b64 vcc, exec, s[6:7]
	s_mov_b32 s0, s12
	global_store_dwordx2 v[134:135], v[124:125], off
	global_store_dwordx2 v[134:135], v[120:121], off offset:32
	global_store_dwordx2 v[104:105], v[112:113], off
	global_store_dwordx2 v[104:105], v[106:107], off offset:32
	global_store_dwordx2 v[88:89], v[96:97], off
	global_store_dwordx2 v[88:89], v[90:91], off offset:32
	global_store_dwordx2 v[72:73], v[80:81], off
	global_store_dwordx2 v[72:73], v[74:75], off offset:32
	global_store_dwordx2 v[72:73], v[68:69], off offset:256
	global_store_dwordx2 v[64:65], v[60:61], off
	global_store_dwordx2 v[64:65], v[56:57], off offset:32
	global_store_dwordx2 v[40:41], v[48:49], off
	global_store_dwordx2 v[40:41], v[42:43], off offset:32
	global_store_dwordx2 v[24:25], v[32:33], off
	global_store_dwordx2 v[24:25], v[26:27], off offset:32
	global_store_dwordx2 v[8:9], v[16:17], off
	global_store_dwordx2 v[8:9], v[10:11], off offset:32
	global_store_dwordx2 v[8:9], v[4:5], off offset:256
	global_store_dwordx2 v[8:9], v[0:1], off offset:288
	s_cbranch_vccz .LBB0_337
	s_waitcnt vmcnt(0)
	s_cmpk_gt_u32 s25, 0xff
	s_cbranch_scc1 .LBB0_348
	s_barrier

; #define PG8_STAGE(bufoff, gbase, voff) do { _Pragma("unroll") for (int _i = 0; _i < 2; ++_i) \
;         __builtin_amdgcn_global_load_lds((const unsigned*)((const char*)(gbase) + (voff)[_i]), (LAS unsigned*)(lds + (bufoff) + ldsw + _i * 8192), 16, 0, 0); } while (0)
; #define PG8_LDA(dst, b, h) do { _Pragma("unroll") for (int m = 0; m < 4; ++m) _Pragma("unroll") for (int k = 0; k < 2; ++k) dst[m][k] = *(const LAS bf16x8*)(lds + PG8_SA(b, h) + aoff + m * 2048 + k * 1024); } while (0)
; #define PG8_LDB(dst, b, h) do { _Pragma("unroll") for (int n = 0; n < 2; ++n) _Pragma("unroll") for (int k = 0; k < 2; ++k) dst[n][k] = *(const LAS bf16x8*)(lds + PG8_SB(b, h) + boff + n * 2048 + k * 1024); } while (0)
; #define PG8_MMA(ai, bj, At, Bt) do { __builtin_amdgcn_s_setprio(1); _Pragma("unroll") for (int m = 0; m < 4; ++m) _Pragma("unroll") for (int n = 0; n < 2; ++n) _Pragma("unroll") for (int k = 0; k < 2; ++k) \
;         acc[ai][bj][m][n] = __builtin_amdgcn_mfma_f32_16x16x32_bf16(Bt[n][k], At[m][k], acc[ai][bj][m][n], 0, 0, 0); __builtin_amdgcn_s_setprio(0); } while (0)
; #define PG8_WAIT_L(n) asm volatile("s_waitcnt lgkmcnt(" #n ")" ::: "memory")
; #define PG8_BAR __builtin_amdgcn_s_barrier()
; #define PG8_SCHED __builtin_amdgcn_sched_barrier(0)
; template <class Epi>
; DEV void gemm_phase(LAS unsigned char* lds, const Gemm g, const StaticOrder& S, const Epi& E) {
;     ...
;             const bool last = (t == nt - 2);
;             const char* a1 = cA + (size_t)(t + 1) * kstep;
;             const char* a2 = last ? nA : cA + (size_t)(t + 2) * kstep; const char* b2 = last ? nB : cB + (size_t)(t + 2) * kstep;
;             const char* a3 = a2 + kstep; const char* b3 = b2 + kstep;
;             PG8_LDB(B0, 0, 0); PG8_SCHED; PG8_LDA(At, 0, 0); PG8_STAGE(PG8_SA(1, 1), a1 + hstep, voffA);
;             PG8_WAIT_L(8); PG8_BAR; PG8_WAIT_L(0); PG8_MMA(0, 0, At, B0); PG8_BAR; PG8_SCHED;
;             PG8_LDB(B1, 0, 1); PG8_STAGE(PG8_SB(0, 0), b2, voffB);
;             PG8_BAR; PG8_WAIT_L(0); PG8_MMA(0, 1, At, B1); PG8_BAR;
;             PG8_LDA(At, 0, 1); PG8_STAGE(PG8_SA(0, 0), a2, voffA);
;             PG8_BAR; PG8_WAIT_L(0); PG8_MMA(1, 0, At, B0); PG8_BAR; PG8_SCHED;
.LBB0_362:
	s_add_u32 s26, s24, 0xfff80080
	s_addc_u32 s27, s25, -1
	s_add_i32 s56, 0, 0x10000
	v_add_u32_e32 v150, s56, v135
	ds_read_b128 v[138:141], v150
	ds_read_b128 v[142:145], v150 offset:1024
	ds_read_b128 v[146:149], v150 offset:2048
	ds_read_b128 v[150:153], v150 offset:3072
	s_cmp_eq_u32 s55, 28
	s_cselect_b32 s29, s19, s27
	s_cselect_b32 s28, s51, s26
	s_cselect_b32 s27, s17, s54
	s_cselect_b32 s26, s52, s53
	s_add_i32 m0, s13, 0xc000
	ds_read_b128 v[154:157], v137
	ds_read_b128 v[174:177], v137 offset:1024
	ds_read_b128 v[178:181], v137 offset:2048
	ds_read_b128 v[182:185], v137 offset:3072
	ds_read_b128 v[186:189], v137 offset:4096
	ds_read_b128 v[190:193], v137 offset:5120
	ds_read_b128 v[194:197], v137 offset:6144
	ds_read_b128 v[214:217], v137 offset:7168
	global_load_lds_dwordx4 v130, s[24:25]
	s_add_i32 m0, s13, 0xe000
	s_nop 0
	global_load_lds_dwordx4 v132, s[24:25]
	s_waitcnt lgkmcnt(8)
	s_waitcnt vmcnt(10)
	s_barrier
	s_waitcnt lgkmcnt(0)
	v_mfma_f32_16x16x32_bf16 v[124:127], v[138:141], v[154:157], v[124:127]
	v_mfma_f32_16x16x32_bf16 v[120:123], v[146:149], v[154:157], v[120:123]
	v_mfma_f32_16x16x32_bf16 v[116:119], v[138:141], v[178:181], v[116:119]
	v_mfma_f32_16x16x32_bf16 v[108:111], v[146:149], v[178:181], v[108:111]
	v_mfma_f32_16x16x32_bf16 v[100:103], v[138:141], v[186:189], v[100:103]
	v_mfma_f32_16x16x32_bf16 v[92:95], v[146:149], v[186:189], v[92:95]
	v_mfma_f32_16x16x32_bf16 v[84:87], v[138:141], v[194:197], v[84:87]
	v_mfma_f32_16x16x32_bf16 v[76:79], v[146:149], v[194:197], v[76:79]
	v_mfma_f32_16x16x32_bf16 v[124:127], v[142:145], v[174:177], v[124:127]
	v_mfma_f32_16x16x32_bf16 v[120:123], v[150:153], v[174:177], v[120:123]
	v_mfma_f32_16x16x32_bf16 v[116:119], v[142:145], v[182:185], v[116:119]
	v_mfma_f32_16x16x32_bf16 v[108:111], v[150:153], v[182:185], v[108:111]
	v_mfma_f32_16x16x32_bf16 v[100:103], v[142:145], v[190:193], v[100:103]
	v_mfma_f32_16x16x32_bf16 v[92:95], v[150:153], v[190:193], v[92:95]
	v_mfma_f32_16x16x32_bf16 v[84:87], v[142:145], v[214:217], v[84:87]
	v_mfma_f32_16x16x32_bf16 v[76:79], v[150:153], v[214:217], v[76:79]
	s_barrier
	s_add_i32 s58, 0, 0x14000
	v_add_u32_e32 v158, s58, v135
	s_add_i32 s56, s56, s41
	ds_read_b128 v[218:221], v158
	ds_read_b128 v[222:225], v158 offset:1024
	ds_read_b128 v[226:229], v158 offset:2048
	ds_read_b128 v[230:233], v158 offset:3072
	v_lshl_add_u64 v[158:159], s[26:27], 0, v[160:161]
	s_mov_b32 m0, s56
	v_lshl_add_u64 v[234:235], s[26:27], 0, v[128:129]
	global_load_lds_dwordx4 v160, s[26:27]
	s_add_i32 m0, s56, 0x2000
	s_nop 0
	global_load_lds_dwordx4 v128, s[26:27]
	s_waitcnt vmcnt(10)
	s_barrier
	s_waitcnt lgkmcnt(0)
	v_mfma_f32_16x16x32_bf16 v[112:115], v[218:221], v[154:157], v[112:115]
	v_mfma_f32_16x16x32_bf16 v[104:107], v[226:229], v[154:157], v[104:107]
	v_mfma_f32_16x16x32_bf16 v[96:99], v[218:221], v[178:181], v[96:99]
	v_mfma_f32_16x16x32_bf16 v[88:91], v[226:229], v[178:181], v[88:91]
	v_mfma_f32_16x16x32_bf16 v[80:83], v[218:221], v[186:189], v[80:83]
	v_mfma_f32_16x16x32_bf16 v[72:75], v[226:229], v[186:189], v[72:75]
	v_mfma_f32_16x16x32_bf16 v[68:71], v[218:221], v[194:197], v[68:71]
	v_mfma_f32_16x16x32_bf16 v[64:67], v[226:229], v[194:197], v[64:67]
	v_mfma_f32_16x16x32_bf16 v[112:115], v[222:225], v[174:177], v[112:115]
	v_mfma_f32_16x16x32_bf16 v[104:107], v[230:233], v[174:177], v[104:107]
	v_mfma_f32_16x16x32_bf16 v[96:99], v[222:225], v[182:185], v[96:99]
	v_mfma_f32_16x16x32_bf16 v[88:91], v[230:233], v[182:185], v[88:91]
	v_mfma_f32_16x16x32_bf16 v[80:83], v[222:225], v[190:193], v[80:83]
	v_mfma_f32_16x16x32_bf16 v[72:75], v[230:233], v[190:193], v[72:75]
	v_mfma_f32_16x16x32_bf16 v[68:71], v[222:225], v[214:217], v[68:71]
	v_mfma_f32_16x16x32_bf16 v[64:67], v[230:233], v[214:217], v[64:67]
	s_mov_b32 m0, s13
	v_lshl_add_u64 v[236:237], s[28:29], 0, v[160:161]
	s_barrier
	ds_read_b128 v[154:157], v137 offset:16384
	ds_read_b128 v[174:177], v137 offset:17408
	ds_read_b128 v[178:181], v137 offset:18432
	ds_read_b128 v[182:185], v137 offset:19456
	ds_read_b128 v[186:189], v137 offset:20480
	ds_read_b128 v[190:193], v137 offset:21504
	ds_read_b128 v[194:197], v137 offset:22528
	ds_read_b128 v[214:217], v137 offset:23552
	global_load_lds_dwordx4 v160, s[28:29]
	v_lshl_add_u64 v[238:239], s[28:29], 0, v[128:129]
	s_mov_b32 m0, s43
	s_nop 0
	global_load_lds_dwordx4 v128, s[28:29]
	s_barrier
	s_waitcnt lgkmcnt(0)
	v_mfma_f32_16x16x32_bf16 v[60:63], v[138:141], v[154:157], v[60:63]
	v_mfma_f32_16x16x32_bf16 v[56:59], v[146:149], v[154:157], v[56:59]
	v_mfma_f32_16x16x32_bf16 v[52:55], v[138:141], v[178:181], v[52:55]
	v_mfma_f32_16x16x32_bf16 v[44:47], v[146:149], v[178:181], v[44:47]
	v_mfma_f32_16x16x32_bf16 v[36:39], v[138:141], v[186:189], v[36:39]
	v_mfma_f32_16x16x32_bf16 v[28:31], v[146:149], v[186:189], v[28:31]
	v_mfma_f32_16x16x32_bf16 v[20:23], v[138:141], v[194:197], v[20:23]
	v_mfma_f32_16x16x32_bf16 v[12:15], v[146:149], v[194:197], v[12:15]
	v_mfma_f32_16x16x32_bf16 v[60:63], v[142:145], v[174:177], v[60:63]
	v_mfma_f32_16x16x32_bf16 v[56:59], v[150:153], v[174:177], v[56:59]
	v_mfma_f32_16x16x32_bf16 v[52:55], v[142:145], v[182:185], v[52:55]
	v_mfma_f32_16x16x32_bf16 v[44:47], v[150:153], v[182:185], v[44:47]
	v_mfma_f32_16x16x32_bf16 v[36:39], v[142:145], v[190:193], v[36:39]
	v_mfma_f32_16x16x32_bf16 v[28:31], v[150:153], v[190:193], v[28:31]
	v_mfma_f32_16x16x32_bf16 v[20:23], v[142:145], v[214:217], v[20:23]
	v_mfma_f32_16x16x32_bf16 v[12:15], v[150:153], v[214:217], v[12:15]
	s_barrier
; #define PG8_STAGE(bufoff, gbase, voff) do { _Pragma("unroll") for (int _i = 0; _i < 2; ++_i) \
;         __builtin_amdgcn_global_load_lds((const unsigned*)((const char*)(gbase) + (voff)[_i]), (LAS unsigned*)(lds + (bufoff) + ldsw + _i * 8192), 16, 0, 0); } while (0)
; #define PG8_LDA(dst, b, h) do { _Pragma("unroll") for (int m = 0; m < 4; ++m) _Pragma("unroll") for (int k = 0; k < 2; ++k) dst[m][k] = *(const LAS bf16x8*)(lds + PG8_SA(b, h) + aoff + m * 2048 + k * 1024); } while (0)
; #define PG8_LDB(dst, b, h) do { _Pragma("unroll") for (int n = 0; n < 2; ++n) _Pragma("unroll") for (int k = 0; k < 2; ++k) dst[n][k] = *(const LAS bf16x8*)(lds + PG8_SB(b, h) + boff + n * 2048 + k * 1024); } while (0)
; #define PG8_MMA(ai, bj, At, Bt) do { __builtin_amdgcn_s_setprio(1); _Pragma("unroll") for (int m = 0; m < 4; ++m) _Pragma("unroll") for (int n = 0; n < 2; ++n) _Pragma("unroll") for (int k = 0; k < 2; ++k) \
;         acc[ai][bj][m][n] = __builtin_amdgcn_mfma_f32_16x16x32_bf16(Bt[n][k], At[m][k], acc[ai][bj][m][n], 0, 0, 0); __builtin_amdgcn_s_setprio(0); } while (0)
; #define PG8_WAIT_V(n) asm volatile("s_waitcnt vmcnt(" #n ")" ::: "memory")
; #define PG8_WAIT_L(n) asm volatile("s_waitcnt lgkmcnt(" #n ")" ::: "memory")
; #define PG8_BAR __builtin_amdgcn_s_barrier()
; #define PG8_SCHED __builtin_amdgcn_sched_barrier(0)
; template <class Epi>
; DEV void gemm_phase(LAS unsigned char* lds, const Gemm g, const StaticOrder& S, const Epi& E) {
;     ...
;             PG8_STAGE(PG8_SB(0, 1), b2 + hstep, voffB);
;             PG8_WAIT_V(6); PG8_BAR; PG8_MMA(1, 1, At, B1); PG8_BAR;
;             PG8_LDB(B0, 1, 0); PG8_SCHED; PG8_LDA(At, 1, 0); PG8_STAGE(PG8_SA(0, 1), a2 + hstep, voffA);
;             PG8_WAIT_L(8); PG8_BAR; PG8_WAIT_L(0); PG8_MMA(0, 0, At, B0); PG8_BAR; PG8_SCHED;
;             PG8_LDB(B1, 1, 1); PG8_STAGE(PG8_SB(1, 0), b3, voffB);
;             PG8_BAR; PG8_WAIT_L(0); PG8_MMA(0, 1, At, B1); PG8_BAR;
;             PG8_LDA(At, 1, 1); PG8_STAGE(PG8_SA(1, 0), a3, voffA);
	s_add_u32 s56, s26, 0x80000
	s_addc_u32 s57, s27, 0
	s_add_i32 s58, s58, s41
	s_mov_b32 m0, s58
	s_nop 0
	global_load_lds_dwordx4 v160, s[56:57]
	s_add_i32 m0, s58, 0x2000
	s_nop 0
	global_load_lds_dwordx4 v128, s[56:57]
	s_waitcnt vmcnt(10)
	s_barrier
	v_mfma_f32_16x16x32_bf16 v[48:51], v[218:221], v[154:157], v[48:51]
	v_mfma_f32_16x16x32_bf16 v[40:43], v[226:229], v[154:157], v[40:43]
	v_mfma_f32_16x16x32_bf16 v[32:35], v[218:221], v[178:181], v[32:35]
	v_mfma_f32_16x16x32_bf16 v[24:27], v[226:229], v[178:181], v[24:27]
	v_mfma_f32_16x16x32_bf16 v[16:19], v[218:221], v[186:189], v[16:19]
	v_mfma_f32_16x16x32_bf16 v[8:11], v[226:229], v[186:189], v[8:11]
	v_mfma_f32_16x16x32_bf16 v[4:7], v[218:221], v[194:197], v[4:7]
	v_mfma_f32_16x16x32_bf16 v[0:3], v[226:229], v[194:197], v[0:3]
	v_mfma_f32_16x16x32_bf16 v[48:51], v[222:225], v[174:177], v[48:51]
	v_mfma_f32_16x16x32_bf16 v[40:43], v[230:233], v[174:177], v[40:43]
	v_mfma_f32_16x16x32_bf16 v[32:35], v[222:225], v[182:185], v[32:35]
	v_mfma_f32_16x16x32_bf16 v[24:27], v[230:233], v[182:185], v[24:27]
	v_mfma_f32_16x16x32_bf16 v[16:19], v[222:225], v[190:193], v[16:19]
	v_mfma_f32_16x16x32_bf16 v[8:11], v[230:233], v[190:193], v[8:11]
	v_mfma_f32_16x16x32_bf16 v[4:7], v[222:225], v[214:217], v[4:7]
	v_mfma_f32_16x16x32_bf16 v[0:3], v[230:233], v[214:217], v[0:3]
	s_add_i32 s56, 0, 0x18000
	v_add_u32_e32 v150, s56, v135
	s_barrier
	ds_read_b128 v[138:141], v150
	ds_read_b128 v[142:145], v150 offset:1024
	ds_read_b128 v[146:149], v150 offset:2048
	ds_read_b128 v[150:153], v150 offset:3072
	s_add_u32 s28, s28, 0x80000
	s_addc_u32 s29, s29, 0
	s_mov_b32 m0, s44
	ds_read_b128 v[154:157], v137 offset:32768
	ds_read_b128 v[174:177], v137 offset:33792
	ds_read_b128 v[178:181], v137 offset:34816
	ds_read_b128 v[182:185], v137 offset:35840
	ds_read_b128 v[186:189], v137 offset:36864
	ds_read_b128 v[190:193], v137 offset:37888
	ds_read_b128 v[194:197], v137 offset:38912
	ds_read_b128 v[214:217], v137 offset:39936
	global_load_lds_dwordx4 v160, s[28:29]
	s_mov_b32 m0, s45
	s_nop 0
	global_load_lds_dwordx4 v128, s[28:29]
	s_waitcnt lgkmcnt(8)
	s_waitcnt vmcnt(10)
	s_barrier
	s_waitcnt lgkmcnt(0)
	v_mfma_f32_16x16x32_bf16 v[124:127], v[138:141], v[154:157], v[124:127]
	v_mfma_f32_16x16x32_bf16 v[120:123], v[146:149], v[154:157], v[120:123]
	v_mfma_f32_16x16x32_bf16 v[116:119], v[138:141], v[178:181], v[116:119]
	v_mfma_f32_16x16x32_bf16 v[108:111], v[146:149], v[178:181], v[108:111]
	v_mfma_f32_16x16x32_bf16 v[100:103], v[138:141], v[186:189], v[100:103]
	v_mfma_f32_16x16x32_bf16 v[92:95], v[146:149], v[186:189], v[92:95]
	v_mfma_f32_16x16x32_bf16 v[84:87], v[138:141], v[194:197], v[84:87]
	v_mfma_f32_16x16x32_bf16 v[76:79], v[146:149], v[194:197], v[76:79]
	v_mfma_f32_16x16x32_bf16 v[124:127], v[142:145], v[174:177], v[124:127]
	v_mfma_f32_16x16x32_bf16 v[120:123], v[150:153], v[174:177], v[120:123]
	v_mfma_f32_16x16x32_bf16 v[116:119], v[142:145], v[182:185], v[116:119]
	v_mfma_f32_16x16x32_bf16 v[108:111], v[150:153], v[182:185], v[108:111]
	v_mfma_f32_16x16x32_bf16 v[100:103], v[142:145], v[190:193], v[100:103]
	v_mfma_f32_16x16x32_bf16 v[92:95], v[150:153], v[190:193], v[92:95]
	v_mfma_f32_16x16x32_bf16 v[84:87], v[142:145], v[214:217], v[84:87]
	v_mfma_f32_16x16x32_bf16 v[76:79], v[150:153], v[214:217], v[76:79]
	s_barrier
	s_add_i32 s28, 0, 0x1c000
	s_add_i32 s29, s56, s41
	v_add_u32_e32 v167, s28, v135
	v_lshl_add_u64 v[158:159], v[158:159], 0, s[2:3]
	s_mov_b32 m0, s29
	ds_read_b128 v[218:221], v167
	ds_read_b128 v[222:225], v167 offset:1024
	ds_read_b128 v[226:229], v167 offset:2048
	ds_read_b128 v[230:233], v167 offset:3072
	global_load_lds_dwordx4 v[158:159], off
	v_lshl_add_u64 v[158:159], v[234:235], 0, s[2:3]
	s_add_i32 m0, s29, 0x2000
	s_nop 0
	global_load_lds_dwordx4 v[158:159], off
	s_waitcnt vmcnt(10)
	s_barrier
	s_waitcnt lgkmcnt(0)
	v_mfma_f32_16x16x32_bf16 v[112:115], v[218:221], v[154:157], v[112:115]
	v_mfma_f32_16x16x32_bf16 v[104:107], v[226:229], v[154:157], v[104:107]
	v_mfma_f32_16x16x32_bf16 v[96:99], v[218:221], v[178:181], v[96:99]
	v_mfma_f32_16x16x32_bf16 v[88:91], v[226:229], v[178:181], v[88:91]
	v_mfma_f32_16x16x32_bf16 v[80:83], v[218:221], v[186:189], v[80:83]
	v_mfma_f32_16x16x32_bf16 v[72:75], v[226:229], v[186:189], v[72:75]
	v_mfma_f32_16x16x32_bf16 v[68:71], v[218:221], v[194:197], v[68:71]
	v_mfma_f32_16x16x32_bf16 v[64:67], v[226:229], v[194:197], v[64:67]
	v_mfma_f32_16x16x32_bf16 v[112:115], v[222:225], v[174:177], v[112:115]
	v_mfma_f32_16x16x32_bf16 v[104:107], v[230:233], v[174:177], v[104:107]
	v_mfma_f32_16x16x32_bf16 v[96:99], v[222:225], v[182:185], v[96:99]
	v_mfma_f32_16x16x32_bf16 v[88:91], v[230:233], v[182:185], v[88:91]
	v_mfma_f32_16x16x32_bf16 v[80:83], v[222:225], v[190:193], v[80:83]
	v_mfma_f32_16x16x32_bf16 v[72:75], v[230:233], v[190:193], v[72:75]
	v_mfma_f32_16x16x32_bf16 v[68:71], v[222:225], v[214:217], v[68:71]
	v_mfma_f32_16x16x32_bf16 v[64:67], v[230:233], v[214:217], v[64:67]
	s_mov_b32 m0, s46
	v_lshl_add_u64 v[158:159], v[236:237], 0, s[2:3]
	s_barrier
	ds_read_b128 v[154:157], v137 offset:49152
	ds_read_b128 v[174:177], v137 offset:50176
	ds_read_b128 v[178:181], v137 offset:51200
	ds_read_b128 v[182:185], v137 offset:52224
	ds_read_b128 v[186:189], v137 offset:53248
	ds_read_b128 v[190:193], v137 offset:54272
	ds_read_b128 v[194:197], v137 offset:55296
	ds_read_b128 v[214:217], v137 offset:56320
	global_load_lds_dwordx4 v[158:159], off
	v_lshl_add_u64 v[158:159], v[238:239], 0, s[2:3]
	s_mov_b32 m0, s47
	s_nop 0
	global_load_lds_dwordx4 v[158:159], off
	s_barrier
; #define PG8_STAGE(bufoff, gbase, voff) do { _Pragma("unroll") for (int _i = 0; _i < 2; ++_i) \
;         __builtin_amdgcn_global_load_lds((const unsigned*)((const char*)(gbase) + (voff)[_i]), (LAS unsigned*)(lds + (bufoff) + ldsw + _i * 8192), 16, 0, 0); } while (0)
; #define PG8_MMA(ai, bj, At, Bt) do { __builtin_amdgcn_s_setprio(1); _Pragma("unroll") for (int m = 0; m < 4; ++m) _Pragma("unroll") for (int n = 0; n < 2; ++n) _Pragma("unroll") for (int k = 0; k < 2; ++k) \
;         acc[ai][bj][m][n] = __builtin_amdgcn_mfma_f32_16x16x32_bf16(Bt[n][k], At[m][k], acc[ai][bj][m][n], 0, 0, 0); __builtin_amdgcn_s_setprio(0); } while (0)
; #define PG8_WAIT_V(n) asm volatile("s_waitcnt vmcnt(" #n ")" ::: "memory")
; #define PG8_WAIT_L(n) asm volatile("s_waitcnt lgkmcnt(" #n ")" ::: "memory")
; #define PG8_BAR __builtin_amdgcn_s_barrier()
; #define PG8_SCHED __builtin_amdgcn_sched_barrier(0)
; template <class Epi>
; DEV void gemm_phase(LAS unsigned char* lds, const Gemm g, const StaticOrder& S, const Epi& E) {
;     ...
;             PG8_BAR; PG8_WAIT_L(0); PG8_MMA(1, 0, At, B0); PG8_BAR; PG8_SCHED;
;             PG8_STAGE(PG8_SB(1, 1), b3 + hstep, voffB);
;             PG8_WAIT_V(6); PG8_BAR; PG8_MMA(1, 1, At, B1); PG8_BAR;
	s_waitcnt lgkmcnt(0)
	v_mfma_f32_16x16x32_bf16 v[60:63], v[138:141], v[154:157], v[60:63]
	v_mfma_f32_16x16x32_bf16 v[56:59], v[146:149], v[154:157], v[56:59]
	v_mfma_f32_16x16x32_bf16 v[52:55], v[138:141], v[178:181], v[52:55]
	v_mfma_f32_16x16x32_bf16 v[44:47], v[146:149], v[178:181], v[44:47]
	v_mfma_f32_16x16x32_bf16 v[36:39], v[138:141], v[186:189], v[36:39]
	v_mfma_f32_16x16x32_bf16 v[28:31], v[146:149], v[186:189], v[28:31]
	v_mfma_f32_16x16x32_bf16 v[20:23], v[138:141], v[194:197], v[20:23]
	v_mfma_f32_16x16x32_bf16 v[12:15], v[146:149], v[194:197], v[12:15]
	v_mfma_f32_16x16x32_bf16 v[60:63], v[142:145], v[174:177], v[60:63]
	v_mfma_f32_16x16x32_bf16 v[56:59], v[150:153], v[174:177], v[56:59]
	v_mfma_f32_16x16x32_bf16 v[52:55], v[142:145], v[182:185], v[52:55]
	v_mfma_f32_16x16x32_bf16 v[44:47], v[150:153], v[182:185], v[44:47]
	v_mfma_f32_16x16x32_bf16 v[36:39], v[142:145], v[190:193], v[36:39]
	v_mfma_f32_16x16x32_bf16 v[28:31], v[150:153], v[190:193], v[28:31]
	v_mfma_f32_16x16x32_bf16 v[20:23], v[142:145], v[214:217], v[20:23]
	v_mfma_f32_16x16x32_bf16 v[12:15], v[150:153], v[214:217], v[12:15]
	s_barrier
	s_add_u32 s26, s26, 0x80080
	s_addc_u32 s27, s27, 0
	s_add_i32 s28, s28, s41
	s_mov_b32 m0, s28
	s_nop 0
	global_load_lds_dwordx4 v160, s[26:27]
	s_add_i32 m0, s28, 0x2000
	s_nop 0
	global_load_lds_dwordx4 v128, s[26:27]
	s_waitcnt vmcnt(10)
	s_barrier
	v_mfma_f32_16x16x32_bf16 v[48:51], v[218:221], v[154:157], v[48:51]
	v_mfma_f32_16x16x32_bf16 v[40:43], v[226:229], v[154:157], v[40:43]
	v_mfma_f32_16x16x32_bf16 v[32:35], v[218:221], v[178:181], v[32:35]
	v_mfma_f32_16x16x32_bf16 v[24:27], v[226:229], v[178:181], v[24:27]
	v_mfma_f32_16x16x32_bf16 v[16:19], v[218:221], v[186:189], v[16:19]
	v_mfma_f32_16x16x32_bf16 v[8:11], v[226:229], v[186:189], v[8:11]
	v_mfma_f32_16x16x32_bf16 v[4:7], v[218:221], v[194:197], v[4:7]
	v_mfma_f32_16x16x32_bf16 v[0:3], v[226:229], v[194:197], v[0:3]
	v_mfma_f32_16x16x32_bf16 v[48:51], v[222:225], v[174:177], v[48:51]
	v_mfma_f32_16x16x32_bf16 v[40:43], v[230:233], v[174:177], v[40:43]
	v_mfma_f32_16x16x32_bf16 v[32:35], v[222:225], v[182:185], v[32:35]
	v_mfma_f32_16x16x32_bf16 v[24:27], v[230:233], v[182:185], v[24:27]
	v_mfma_f32_16x16x32_bf16 v[16:19], v[222:225], v[190:193], v[16:19]
	v_mfma_f32_16x16x32_bf16 v[8:11], v[230:233], v[190:193], v[8:11]
	v_mfma_f32_16x16x32_bf16 v[4:7], v[222:225], v[214:217], v[4:7]
	v_mfma_f32_16x16x32_bf16 v[0:3], v[230:233], v[214:217], v[0:3]
	s_add_i32 s55, s55, 2
	s_add_u32 s24, s24, 0x100
	s_addc_u32 s25, s25, 0
	s_add_u32 s53, s53, 0x100
	s_addc_u32 s54, s54, 0
	s_cmp_gt_u32 s55, 29
	s_barrier
	s_cbranch_scc0 .LBB0_362
; DEV bf16x8 pack8(f32x4 a, f32x4 b) { u32x4 w; w.x = cvt_pk_bf16(a[0], a[1]); w.y = cvt_pk_bf16(a[2], a[3]); w.z = cvt_pk_bf16(b[0], b[1]); w.w = cvt_pk_bf16(b[2], b[3]); return __builtin_bit_cast(bf16x8, w); }
; DEV u32x2 pack4(f32x4 a) { u32x2 w; w.x = cvt_pk_bf16(a[0], a[1]); w.y = cvt_pk_bf16(a[2], a[3]); return w; }
; DEV f32x4 gelu4(f32x4 v) { f32x2 a = gelu_pk((f32x2){v[0], v[1]}), b = gelu_pk((f32x2){v[2], v[3]}); return (f32x4){a.x, a.y, b.x, b.y}; }
; #define PG8_WAIT_V(n) asm volatile("s_waitcnt vmcnt(" #n ")" ::: "memory")
; #define PG8_BAR __builtin_amdgcn_s_barrier()
; template <class Epi>
; DEV void gemm_phase(LAS unsigned char* lds, const Gemm g, const StaticOrder& S, const Epi& E) {
;     ...
;         E(acc, cur, wr, wc, fr, fq);
;         if (!has_next) break;
; #pragma unroll
;         for (int a = 0; a < 2; ++a)
; #pragma unroll
;             for (int b = 0; b < 2; ++b)
; #pragma unroll
;                 for (int m = 0; m < 4; ++m)
; #pragma unroll
;                     for (int n = 0; n < 2; ++n) acc[a][b][m][n] = (f32x4){0.f, 0.f, 0.f, 0.f};
;         cur = nxt; cA = nA; cB = nB; ++ui;
;     }
;     PG8_WAIT_V(0);
;     if (wr == 0) PG8_BAR;
;     PG8_BAR;
; template <int ACT, bool PERM>
; DEV void store_bf16_tile(AccRef acc, u16* O, int ld, int row0, int col0, const float* ss) {
;     ...
;         for (int m = 0; m < 4; ++m) { u16* rowp = O + (size_t)(row0 + ai * 128 + m * 16) * ld + col0; const float rs = rsv[ai][m];
; #pragma unroll
;             for (int bj = 0; bj < 2; ++bj) { f32x4 v0 = acc[ai][bj][m][0] * rs, v1 = acc[ai][bj][m][1] * rs; if (ACT == 1) { v0 = gelu4(v0); v1 = gelu4(v1); }
;                 if (PERM) *(u32x4*)(rowp + bj * 128) = __builtin_bit_cast(u32x4, pack8(v0, v1));
;                 else { *(u32x2*)(rowp + bj * 128) = pack4(v0); *(u32x2*)(rowp + bj * 128 + 16) = pack4(v1); } } }
	v_lshl_add_u32 v138, s12, 8, v134
	v_lshl_or_b32 v140, s50, 8, v136
	v_ashrrev_i32_e32 v141, 31, v140
	v_ashrrev_i32_e32 v139, 31, v138
	v_lshl_add_u64 v[140:141], v[140:141], 1, s[10:11]
	v_lshlrev_b64 v[142:143], 11, v[138:139]
	v_lshl_add_u64 v[142:143], v[140:141], 0, v[142:143]
	v_cvt_pk_bf16_f32 v104, v104, v105
	v_cvt_pk_bf16_f32 v105, v106, v107
	global_store_dwordx2 v[142:143], v[104:105], off offset:288
	v_or_b32_e32 v104, 16, v138
	v_ashrrev_i32_e32 v105, 31, v104
	v_lshlrev_b64 v[104:105], 11, v[104:105]
	v_lshl_add_u64 v[104:105], v[140:141], 0, v[104:105]
	v_cvt_pk_bf16_f32 v88, v88, v89
	v_cvt_pk_bf16_f32 v89, v90, v91
	global_store_dwordx2 v[104:105], v[88:89], off offset:288
	v_or_b32_e32 v88, 32, v138
	v_ashrrev_i32_e32 v89, 31, v88
	v_lshlrev_b64 v[88:89], 11, v[88:89]
	v_lshl_add_u64 v[88:89], v[140:141], 0, v[88:89]
	v_cvt_pk_bf16_f32 v72, v72, v73
	v_cvt_pk_bf16_f32 v73, v74, v75
	global_store_dwordx2 v[88:89], v[72:73], off offset:288
	v_or_b32_e32 v72, 48, v138
	v_ashrrev_i32_e32 v73, 31, v72
	v_lshlrev_b64 v[72:73], 11, v[72:73]
	s_mov_b32 s12, 0x40000
	v_lshl_add_u64 v[72:73], v[140:141], 0, v[72:73]
	v_cvt_pk_bf16_f32 v64, v64, v65
	v_cvt_pk_bf16_f32 v65, v66, v67
	s_mov_b64 s[24:25], 0x40000
	v_cvt_pk_bf16_f32 v60, v60, v61
	v_cvt_pk_bf16_f32 v61, v62, v63
	v_add_co_u32_e32 v62, vcc, s12, v142
	global_store_dwordx2 v[72:73], v[64:65], off offset:288
	v_lshl_add_u64 v[64:65], v[142:143], 0, s[24:25]
	v_addc_co_u32_e32 v63, vcc, 0, v143, vcc
	v_cvt_pk_bf16_f32 v48, v48, v49
	v_cvt_pk_bf16_f32 v49, v50, v51
	s_mov_b32 s12, 0x48000
	global_store_dwordx2 v[64:65], v[48:49], off offset:256
	v_cvt_pk_bf16_f32 v40, v40, v41
	v_cvt_pk_bf16_f32 v41, v42, v43
	s_mov_b64 s[24:25], 0x48000
	v_add_co_u32_e32 v48, vcc, s12, v142
	global_store_dwordx2 v[64:65], v[40:41], off offset:288
	v_lshl_add_u64 v[40:41], v[142:143], 0, s[24:25]
	v_addc_co_u32_e32 v49, vcc, 0, v143, vcc
	v_cvt_pk_bf16_f32 v32, v32, v33
	v_cvt_pk_bf16_f32 v33, v34, v35
	s_mov_b32 s12, 0x50000
	global_store_dwordx2 v[40:41], v[32:33], off offset:256
	v_cvt_pk_bf16_f32 v24, v24, v25
	v_cvt_pk_bf16_f32 v25, v26, v27
	s_mov_b64 s[24:25], 0x50000
	v_add_co_u32_e32 v32, vcc, s12, v142
	global_store_dwordx2 v[40:41], v[24:25], off offset:288
	v_lshl_add_u64 v[24:25], v[142:143], 0, s[24:25]
	v_addc_co_u32_e32 v33, vcc, 0, v143, vcc
	v_cvt_pk_bf16_f32 v16, v16, v17
	v_cvt_pk_bf16_f32 v17, v18, v19
	global_store_dwordx2 v[24:25], v[16:17], off offset:256
	v_add_co_u32_e32 v16, vcc, s59, v142
	v_cvt_pk_bf16_f32 v106, v116, v117
	v_cvt_pk_bf16_f32 v107, v118, v119
	v_cvt_pk_bf16_f32 v90, v100, v101
	v_cvt_pk_bf16_f32 v91, v102, v103
	v_cvt_pk_bf16_f32 v74, v84, v85
	v_cvt_pk_bf16_f32 v75, v86, v87
	v_cvt_pk_bf16_f32 v42, v52, v53
	v_cvt_pk_bf16_f32 v43, v54, v55
	v_cvt_pk_bf16_f32 v26, v36, v37
	v_cvt_pk_bf16_f32 v27, v38, v39
	v_cvt_pk_bf16_f32 v8, v8, v9
	v_cvt_pk_bf16_f32 v9, v10, v11
	s_mov_b64 s[24:25], 0x58000
	v_cvt_pk_bf16_f32 v10, v20, v21
	v_cvt_pk_bf16_f32 v11, v22, v23
	v_addc_co_u32_e32 v17, vcc, 0, v143, vcc
	v_cvt_pk_bf16_f32 v124, v124, v125
	v_cvt_pk_bf16_f32 v125, v126, v127
	v_cvt_pk_bf16_f32 v120, v120, v121
	v_cvt_pk_bf16_f32 v121, v122, v123
	v_cvt_pk_bf16_f32 v112, v112, v113
	v_cvt_pk_bf16_f32 v113, v114, v115
	global_store_dwordx2 v[104:105], v[106:107], off
	v_cvt_pk_bf16_f32 v106, v108, v109
	v_cvt_pk_bf16_f32 v107, v110, v111
	v_cvt_pk_bf16_f32 v96, v96, v97
	v_cvt_pk_bf16_f32 v97, v98, v99
	global_store_dwordx2 v[88:89], v[90:91], off
	v_cvt_pk_bf16_f32 v90, v92, v93
	v_cvt_pk_bf16_f32 v91, v94, v95
	v_cvt_pk_bf16_f32 v80, v80, v81
	v_cvt_pk_bf16_f32 v81, v82, v83
	global_store_dwordx2 v[72:73], v[74:75], off
	v_cvt_pk_bf16_f32 v74, v76, v77
	v_cvt_pk_bf16_f32 v75, v78, v79
	v_cvt_pk_bf16_f32 v68, v68, v69
	v_cvt_pk_bf16_f32 v69, v70, v71
	v_cvt_pk_bf16_f32 v56, v56, v57
	v_cvt_pk_bf16_f32 v57, v58, v59
	global_store_dwordx2 v[48:49], v[42:43], off
	v_cvt_pk_bf16_f32 v42, v44, v45
	v_cvt_pk_bf16_f32 v43, v46, v47
	global_store_dwordx2 v[32:33], v[26:27], off
	v_cvt_pk_bf16_f32 v26, v28, v29
	v_cvt_pk_bf16_f32 v27, v30, v31
	global_store_dwordx2 v[24:25], v[8:9], off offset:288
	v_lshl_add_u64 v[8:9], v[142:143], 0, s[24:25]
	global_store_dwordx2 v[16:17], v[10:11], off
	v_cvt_pk_bf16_f32 v10, v12, v13
	v_cvt_pk_bf16_f32 v11, v14, v15
	v_cvt_pk_bf16_f32 v4, v4, v5
	v_cvt_pk_bf16_f32 v5, v6, v7
	v_cvt_pk_bf16_f32 v0, v0, v1
	v_cvt_pk_bf16_f32 v1, v2, v3
	s_and_b64 vcc, exec, s[14:15]
	s_mov_b32 s50, s16
	s_mov_b32 s12, s18
	s_mov_b64 s[26:27], s[22:23]
	s_mov_b64 s[24:25], s[20:21]
	global_store_dwordx2 v[142:143], v[124:125], off
	global_store_dwordx2 v[142:143], v[120:121], off offset:32
	global_store_dwordx2 v[142:143], v[112:113], off offset:256
	global_store_dwordx2 v[104:105], v[106:107], off offset:32
	global_store_dwordx2 v[104:105], v[96:97], off offset:256
	global_store_dwordx2 v[88:89], v[90:91], off offset:32
	global_store_dwordx2 v[88:89], v[80:81], off offset:256
	global_store_dwordx2 v[72:73], v[74:75], off offset:32
	global_store_dwordx2 v[72:73], v[68:69], off offset:256
	global_store_dwordx2 v[62:63], v[60:61], off
	global_store_dwordx2 v[64:65], v[56:57], off offset:32
	global_store_dwordx2 v[40:41], v[42:43], off offset:32
	global_store_dwordx2 v[24:25], v[26:27], off offset:32
	global_store_dwordx2 v[8:9], v[10:11], off offset:32
	global_store_dwordx2 v[8:9], v[4:5], off offset:256
	global_store_dwordx2 v[8:9], v[0:1], off offset:288
	s_cbranch_vccz .LBB0_359
	s_waitcnt vmcnt(0)
	s_cmpk_gt_u32 s36, 0xff
	s_cbranch_scc1 .LBB0_353
	s_barrier
	s_branch .LBB0_353

; #define PG8_STAGE(bufoff, gbase, voff) do { _Pragma("unroll") for (int _i = 0; _i < 2; ++_i) \
;         __builtin_amdgcn_global_load_lds((const unsigned*)((const char*)(gbase) + (voff)[_i]), (LAS unsigned*)(lds + (bufoff) + ldsw + _i * 8192), 16, 0, 0); } while (0)
; #define PG8_LDA(dst, b, h) do { _Pragma("unroll") for (int m = 0; m < 4; ++m) _Pragma("unroll") for (int k = 0; k < 2; ++k) dst[m][k] = *(const LAS bf16x8*)(lds + PG8_SA(b, h) + aoff + m * 2048 + k * 1024); } while (0)
; #define PG8_LDB(dst, b, h) do { _Pragma("unroll") for (int n = 0; n < 2; ++n) _Pragma("unroll") for (int k = 0; k < 2; ++k) dst[n][k] = *(const LAS bf16x8*)(lds + PG8_SB(b, h) + boff + n * 2048 + k * 1024); } while (0)
; #define PG8_MMA(ai, bj, At, Bt) do { __builtin_amdgcn_s_setprio(1); _Pragma("unroll") for (int m = 0; m < 4; ++m) _Pragma("unroll") for (int n = 0; n < 2; ++n) _Pragma("unroll") for (int k = 0; k < 2; ++k) \
;         acc[ai][bj][m][n] = __builtin_amdgcn_mfma_f32_16x16x32_bf16(Bt[n][k], At[m][k], acc[ai][bj][m][n], 0, 0, 0); __builtin_amdgcn_s_setprio(0); } while (0)
; #define PG8_WAIT_L(n) asm volatile("s_waitcnt lgkmcnt(" #n ")" ::: "memory")
; #define PG8_BAR __builtin_amdgcn_s_barrier()
; #define PG8_SCHED __builtin_amdgcn_sched_barrier(0)
; template <class Epi>
; DEV void gemm_phase(LAS unsigned char* lds, const Gemm g, const StaticOrder& S, const Epi& E) {
;     ...
;             const bool last = (t == nt - 2);
;             const char* a1 = cA + (size_t)(t + 1) * kstep;
;             const char* a2 = last ? nA : cA + (size_t)(t + 2) * kstep; const char* b2 = last ? nB : cB + (size_t)(t + 2) * kstep;
;             const char* a3 = a2 + kstep; const char* b3 = b2 + kstep;
;             PG8_LDB(B0, 0, 0); PG8_SCHED; PG8_LDA(At, 0, 0); PG8_STAGE(PG8_SA(1, 1), a1 + hstep, voffA);
;             PG8_WAIT_L(8); PG8_BAR; PG8_WAIT_L(0); PG8_MMA(0, 0, At, B0); PG8_BAR; PG8_SCHED;
;             PG8_LDB(B1, 0, 1); PG8_STAGE(PG8_SB(0, 0), b2, voffB);
;             PG8_BAR; PG8_WAIT_L(0); PG8_MMA(0, 1, At, B1); PG8_BAR;
;             PG8_LDA(At, 0, 1); PG8_STAGE(PG8_SA(0, 0), a2, voffA);
;             PG8_BAR; PG8_WAIT_L(0); PG8_MMA(1, 0, At, B0); PG8_BAR; PG8_SCHED;
.LBB0_404:
	s_add_u32 s28, s26, 0xfff00080
	s_addc_u32 s29, s27, -1
	s_add_i32 s49, 0, 0x10000
	v_add_u32_e32 v140, s49, v178
	ds_read_b128 v[128:131], v140
	ds_read_b128 v[132:135], v140 offset:1024
	ds_read_b128 v[136:139], v140 offset:2048
	ds_read_b128 v[140:143], v140 offset:3072
	s_cmp_eq_u32 s48, 60
	s_cselect_b32 s31, s15, s29
	s_cselect_b32 s30, s19, s28
	s_cselect_b32 s29, s17, s47
	s_cselect_b32 s28, s25, s46
	s_add_i32 m0, s37, 0xc000
	ds_read_b128 v[154:157], v181
	ds_read_b128 v[174:177], v181 offset:1024
	ds_read_b128 v[182:185], v181 offset:2048
	ds_read_b128 v[186:189], v181 offset:3072
	ds_read_b128 v[190:193], v181 offset:4096
	ds_read_b128 v[194:197], v181 offset:5120
	ds_read_b128 v[214:217], v181 offset:6144
	ds_read_b128 v[218:221], v181 offset:7168
	global_load_lds_dwordx4 v150, s[26:27]
	s_add_i32 m0, s37, 0xe000
	s_nop 0
	global_load_lds_dwordx4 v152, s[26:27]
	s_waitcnt lgkmcnt(8)
	s_waitcnt vmcnt(10)
	s_barrier
	s_waitcnt lgkmcnt(0)
	v_mfma_f32_16x16x32_bf16 v[124:127], v[128:131], v[154:157], v[124:127]
	v_mfma_f32_16x16x32_bf16 v[120:123], v[136:139], v[154:157], v[120:123]
	v_mfma_f32_16x16x32_bf16 v[108:111], v[128:131], v[182:185], v[108:111]
	v_mfma_f32_16x16x32_bf16 v[104:107], v[136:139], v[182:185], v[104:107]
	v_mfma_f32_16x16x32_bf16 v[92:95], v[128:131], v[190:193], v[92:95]
	v_mfma_f32_16x16x32_bf16 v[88:91], v[136:139], v[190:193], v[88:91]
	v_mfma_f32_16x16x32_bf16 v[76:79], v[128:131], v[214:217], v[76:79]
	v_mfma_f32_16x16x32_bf16 v[72:75], v[136:139], v[214:217], v[72:75]
	v_mfma_f32_16x16x32_bf16 v[124:127], v[132:135], v[174:177], v[124:127]
	v_mfma_f32_16x16x32_bf16 v[120:123], v[140:143], v[174:177], v[120:123]
	v_mfma_f32_16x16x32_bf16 v[108:111], v[132:135], v[186:189], v[108:111]
	v_mfma_f32_16x16x32_bf16 v[104:107], v[140:143], v[186:189], v[104:107]
	v_mfma_f32_16x16x32_bf16 v[92:95], v[132:135], v[194:197], v[92:95]
	v_mfma_f32_16x16x32_bf16 v[88:91], v[140:143], v[194:197], v[88:91]
	v_mfma_f32_16x16x32_bf16 v[76:79], v[132:135], v[218:221], v[76:79]
	v_mfma_f32_16x16x32_bf16 v[72:75], v[140:143], v[218:221], v[72:75]
	s_barrier
	s_add_i32 s52, 0, 0x14000
	v_add_u32_e32 v158, s52, v178
	s_add_i32 s49, s49, s36
	ds_read_b128 v[222:225], v158
	ds_read_b128 v[226:229], v158 offset:1024
	ds_read_b128 v[230:233], v158 offset:2048
	ds_read_b128 v[234:237], v158 offset:3072
	v_lshl_add_u64 v[158:159], s[28:29], 0, v[160:161]
	s_mov_b32 m0, s49
	v_lshl_add_u64 v[238:239], s[28:29], 0, v[148:149]
	global_load_lds_dwordx4 v160, s[28:29]
	s_add_i32 m0, s49, 0x2000
	s_nop 0
	global_load_lds_dwordx4 v148, s[28:29]
	s_waitcnt vmcnt(10)
	s_barrier
	s_waitcnt lgkmcnt(0)
	v_mfma_f32_16x16x32_bf16 v[116:119], v[222:225], v[154:157], v[116:119]
	v_mfma_f32_16x16x32_bf16 v[112:115], v[230:233], v[154:157], v[112:115]
	v_mfma_f32_16x16x32_bf16 v[100:103], v[222:225], v[182:185], v[100:103]
	v_mfma_f32_16x16x32_bf16 v[96:99], v[230:233], v[182:185], v[96:99]
	v_mfma_f32_16x16x32_bf16 v[84:87], v[222:225], v[190:193], v[84:87]
	v_mfma_f32_16x16x32_bf16 v[80:83], v[230:233], v[190:193], v[80:83]
	v_mfma_f32_16x16x32_bf16 v[68:71], v[222:225], v[214:217], v[68:71]
	v_mfma_f32_16x16x32_bf16 v[64:67], v[230:233], v[214:217], v[64:67]
	v_mfma_f32_16x16x32_bf16 v[116:119], v[226:229], v[174:177], v[116:119]
	v_mfma_f32_16x16x32_bf16 v[112:115], v[234:237], v[174:177], v[112:115]
	v_mfma_f32_16x16x32_bf16 v[100:103], v[226:229], v[186:189], v[100:103]
	v_mfma_f32_16x16x32_bf16 v[96:99], v[234:237], v[186:189], v[96:99]
	v_mfma_f32_16x16x32_bf16 v[84:87], v[226:229], v[194:197], v[84:87]
	v_mfma_f32_16x16x32_bf16 v[80:83], v[234:237], v[194:197], v[80:83]
	v_mfma_f32_16x16x32_bf16 v[68:71], v[226:229], v[218:221], v[68:71]
	v_mfma_f32_16x16x32_bf16 v[64:67], v[234:237], v[218:221], v[64:67]
	s_mov_b32 m0, s37
	v_lshl_add_u64 v[240:241], s[30:31], 0, v[144:145]
	s_barrier
	ds_read_b128 v[154:157], v181 offset:16384
	ds_read_b128 v[174:177], v181 offset:17408
	ds_read_b128 v[182:185], v181 offset:18432
	ds_read_b128 v[186:189], v181 offset:19456
	ds_read_b128 v[190:193], v181 offset:20480
	ds_read_b128 v[194:197], v181 offset:21504
	ds_read_b128 v[214:217], v181 offset:22528
	ds_read_b128 v[218:221], v181 offset:23552
	global_load_lds_dwordx4 v144, s[30:31]
	v_lshl_add_u64 v[242:243], s[30:31], 0, v[146:147]
	s_mov_b32 m0, s38
	s_nop 0
	global_load_lds_dwordx4 v146, s[30:31]
	s_barrier
	s_waitcnt lgkmcnt(0)
	v_mfma_f32_16x16x32_bf16 v[60:63], v[128:131], v[154:157], v[60:63]
	v_mfma_f32_16x16x32_bf16 v[56:59], v[136:139], v[154:157], v[56:59]
	v_mfma_f32_16x16x32_bf16 v[44:47], v[128:131], v[182:185], v[44:47]
	v_mfma_f32_16x16x32_bf16 v[40:43], v[136:139], v[182:185], v[40:43]
	v_mfma_f32_16x16x32_bf16 v[28:31], v[128:131], v[190:193], v[28:31]
	v_mfma_f32_16x16x32_bf16 v[24:27], v[136:139], v[190:193], v[24:27]
	v_mfma_f32_16x16x32_bf16 v[12:15], v[128:131], v[214:217], v[12:15]
	v_mfma_f32_16x16x32_bf16 v[8:11], v[136:139], v[214:217], v[8:11]
	v_mfma_f32_16x16x32_bf16 v[60:63], v[132:135], v[174:177], v[60:63]
	v_mfma_f32_16x16x32_bf16 v[56:59], v[140:143], v[174:177], v[56:59]
	v_mfma_f32_16x16x32_bf16 v[44:47], v[132:135], v[186:189], v[44:47]
	v_mfma_f32_16x16x32_bf16 v[40:43], v[140:143], v[186:189], v[40:43]
	v_mfma_f32_16x16x32_bf16 v[28:31], v[132:135], v[194:197], v[28:31]
	v_mfma_f32_16x16x32_bf16 v[24:27], v[140:143], v[194:197], v[24:27]
	v_mfma_f32_16x16x32_bf16 v[12:15], v[132:135], v[218:221], v[12:15]
	v_mfma_f32_16x16x32_bf16 v[8:11], v[140:143], v[218:221], v[8:11]
	s_barrier
; #define PG8_STAGE(bufoff, gbase, voff) do { _Pragma("unroll") for (int _i = 0; _i < 2; ++_i) \
;         __builtin_amdgcn_global_load_lds((const unsigned*)((const char*)(gbase) + (voff)[_i]), (LAS unsigned*)(lds + (bufoff) + ldsw + _i * 8192), 16, 0, 0); } while (0)
; #define PG8_LDA(dst, b, h) do { _Pragma("unroll") for (int m = 0; m < 4; ++m) _Pragma("unroll") for (int k = 0; k < 2; ++k) dst[m][k] = *(const LAS bf16x8*)(lds + PG8_SA(b, h) + aoff + m * 2048 + k * 1024); } while (0)
; #define PG8_LDB(dst, b, h) do { _Pragma("unroll") for (int n = 0; n < 2; ++n) _Pragma("unroll") for (int k = 0; k < 2; ++k) dst[n][k] = *(const LAS bf16x8*)(lds + PG8_SB(b, h) + boff + n * 2048 + k * 1024); } while (0)
; #define PG8_MMA(ai, bj, At, Bt) do { __builtin_amdgcn_s_setprio(1); _Pragma("unroll") for (int m = 0; m < 4; ++m) _Pragma("unroll") for (int n = 0; n < 2; ++n) _Pragma("unroll") for (int k = 0; k < 2; ++k) \
;         acc[ai][bj][m][n] = __builtin_amdgcn_mfma_f32_16x16x32_bf16(Bt[n][k], At[m][k], acc[ai][bj][m][n], 0, 0, 0); __builtin_amdgcn_s_setprio(0); } while (0)
; #define PG8_WAIT_V(n) asm volatile("s_waitcnt vmcnt(" #n ")" ::: "memory")
; #define PG8_WAIT_L(n) asm volatile("s_waitcnt lgkmcnt(" #n ")" ::: "memory")
; #define PG8_BAR __builtin_amdgcn_s_barrier()
; #define PG8_SCHED __builtin_amdgcn_sched_barrier(0)
; template <class Epi>
; DEV void gemm_phase(LAS unsigned char* lds, const Gemm g, const StaticOrder& S, const Epi& E) {
;     ...
;             PG8_STAGE(PG8_SB(0, 1), b2 + hstep, voffB);
;             PG8_WAIT_V(6); PG8_BAR; PG8_MMA(1, 1, At, B1); PG8_BAR;
;             PG8_LDB(B0, 1, 0); PG8_SCHED; PG8_LDA(At, 1, 0); PG8_STAGE(PG8_SA(0, 1), a2 + hstep, voffA);
;             PG8_WAIT_L(8); PG8_BAR; PG8_WAIT_L(0); PG8_MMA(0, 0, At, B0); PG8_BAR; PG8_SCHED;
;             PG8_LDB(B1, 1, 1); PG8_STAGE(PG8_SB(1, 0), b3, voffB);
;             PG8_BAR; PG8_WAIT_L(0); PG8_MMA(0, 1, At, B1); PG8_BAR;
;             PG8_LDA(At, 1, 1); PG8_STAGE(PG8_SA(1, 0), a3, voffA);
	s_add_u32 s50, s28, 0x100000
	s_addc_u32 s51, s29, 0
	s_add_i32 s49, s52, s36
	s_mov_b32 m0, s49
	s_nop 0
	global_load_lds_dwordx4 v160, s[50:51]
	s_add_i32 m0, s49, 0x2000
	s_nop 0
	global_load_lds_dwordx4 v148, s[50:51]
	s_waitcnt vmcnt(10)
	s_barrier
	v_mfma_f32_16x16x32_bf16 v[52:55], v[222:225], v[154:157], v[52:55]
	v_mfma_f32_16x16x32_bf16 v[48:51], v[230:233], v[154:157], v[48:51]
	v_mfma_f32_16x16x32_bf16 v[36:39], v[222:225], v[182:185], v[36:39]
	v_mfma_f32_16x16x32_bf16 v[32:35], v[230:233], v[182:185], v[32:35]
	v_mfma_f32_16x16x32_bf16 v[20:23], v[222:225], v[190:193], v[20:23]
	v_mfma_f32_16x16x32_bf16 v[16:19], v[230:233], v[190:193], v[16:19]
	v_mfma_f32_16x16x32_bf16 v[4:7], v[222:225], v[214:217], v[4:7]
	v_mfma_f32_16x16x32_bf16 v[0:3], v[230:233], v[214:217], v[0:3]
	v_mfma_f32_16x16x32_bf16 v[52:55], v[226:229], v[174:177], v[52:55]
	v_mfma_f32_16x16x32_bf16 v[48:51], v[234:237], v[174:177], v[48:51]
	v_mfma_f32_16x16x32_bf16 v[36:39], v[226:229], v[186:189], v[36:39]
	v_mfma_f32_16x16x32_bf16 v[32:35], v[234:237], v[186:189], v[32:35]
	v_mfma_f32_16x16x32_bf16 v[20:23], v[226:229], v[194:197], v[20:23]
	v_mfma_f32_16x16x32_bf16 v[16:19], v[234:237], v[194:197], v[16:19]
	v_mfma_f32_16x16x32_bf16 v[4:7], v[226:229], v[218:221], v[4:7]
	v_mfma_f32_16x16x32_bf16 v[0:3], v[234:237], v[218:221], v[0:3]
	s_add_i32 s49, 0, 0x18000
	v_add_u32_e32 v140, s49, v178
	s_barrier
	ds_read_b128 v[128:131], v140
	ds_read_b128 v[132:135], v140 offset:1024
	ds_read_b128 v[136:139], v140 offset:2048
	ds_read_b128 v[140:143], v140 offset:3072
	s_add_u32 s30, s30, 0x100000
	s_addc_u32 s31, s31, 0
	s_mov_b32 m0, s39
	ds_read_b128 v[154:157], v181 offset:32768
	ds_read_b128 v[174:177], v181 offset:33792
	ds_read_b128 v[182:185], v181 offset:34816
	ds_read_b128 v[186:189], v181 offset:35840
	ds_read_b128 v[190:193], v181 offset:36864
	ds_read_b128 v[194:197], v181 offset:37888
	ds_read_b128 v[214:217], v181 offset:38912
	ds_read_b128 v[218:221], v181 offset:39936
	global_load_lds_dwordx4 v144, s[30:31]
	s_mov_b32 m0, s40
	s_nop 0
	global_load_lds_dwordx4 v146, s[30:31]
	s_waitcnt lgkmcnt(8)
	s_waitcnt vmcnt(10)
	s_barrier
	s_waitcnt lgkmcnt(0)
	v_mfma_f32_16x16x32_bf16 v[124:127], v[128:131], v[154:157], v[124:127]
	v_mfma_f32_16x16x32_bf16 v[120:123], v[136:139], v[154:157], v[120:123]
	v_mfma_f32_16x16x32_bf16 v[108:111], v[128:131], v[182:185], v[108:111]
	v_mfma_f32_16x16x32_bf16 v[104:107], v[136:139], v[182:185], v[104:107]
	v_mfma_f32_16x16x32_bf16 v[92:95], v[128:131], v[190:193], v[92:95]
	v_mfma_f32_16x16x32_bf16 v[88:91], v[136:139], v[190:193], v[88:91]
	v_mfma_f32_16x16x32_bf16 v[76:79], v[128:131], v[214:217], v[76:79]
	v_mfma_f32_16x16x32_bf16 v[72:75], v[136:139], v[214:217], v[72:75]
	v_mfma_f32_16x16x32_bf16 v[124:127], v[132:135], v[174:177], v[124:127]
	v_mfma_f32_16x16x32_bf16 v[120:123], v[140:143], v[174:177], v[120:123]
	v_mfma_f32_16x16x32_bf16 v[108:111], v[132:135], v[186:189], v[108:111]
	v_mfma_f32_16x16x32_bf16 v[104:107], v[140:143], v[186:189], v[104:107]
	v_mfma_f32_16x16x32_bf16 v[92:95], v[132:135], v[194:197], v[92:95]
	v_mfma_f32_16x16x32_bf16 v[88:91], v[140:143], v[194:197], v[88:91]
	v_mfma_f32_16x16x32_bf16 v[76:79], v[132:135], v[218:221], v[76:79]
	v_mfma_f32_16x16x32_bf16 v[72:75], v[140:143], v[218:221], v[72:75]
	s_barrier
	s_add_i32 s30, 0, 0x1c000
	s_add_i32 s31, s49, s36
	v_add_u32_e32 v234, s30, v178
	v_lshl_add_u64 v[158:159], v[158:159], 0, s[2:3]
	s_mov_b32 m0, s31
	ds_read_b128 v[222:225], v234
	ds_read_b128 v[226:229], v234 offset:1024
	ds_read_b128 v[230:233], v234 offset:2048
	ds_read_b128 v[234:237], v234 offset:3072
	global_load_lds_dwordx4 v[158:159], off
	v_lshl_add_u64 v[158:159], v[238:239], 0, s[2:3]
	s_add_i32 m0, s31, 0x2000
	s_nop 0
	global_load_lds_dwordx4 v[158:159], off
	s_waitcnt vmcnt(10)
	s_barrier
	s_waitcnt lgkmcnt(0)
	v_mfma_f32_16x16x32_bf16 v[116:119], v[222:225], v[154:157], v[116:119]
	v_mfma_f32_16x16x32_bf16 v[112:115], v[230:233], v[154:157], v[112:115]
	v_mfma_f32_16x16x32_bf16 v[100:103], v[222:225], v[182:185], v[100:103]
	v_mfma_f32_16x16x32_bf16 v[96:99], v[230:233], v[182:185], v[96:99]
	v_mfma_f32_16x16x32_bf16 v[84:87], v[222:225], v[190:193], v[84:87]
	v_mfma_f32_16x16x32_bf16 v[80:83], v[230:233], v[190:193], v[80:83]
	v_mfma_f32_16x16x32_bf16 v[68:71], v[222:225], v[214:217], v[68:71]
	v_mfma_f32_16x16x32_bf16 v[64:67], v[230:233], v[214:217], v[64:67]
	v_mfma_f32_16x16x32_bf16 v[116:119], v[226:229], v[174:177], v[116:119]
	v_mfma_f32_16x16x32_bf16 v[112:115], v[234:237], v[174:177], v[112:115]
	v_mfma_f32_16x16x32_bf16 v[100:103], v[226:229], v[186:189], v[100:103]
	v_mfma_f32_16x16x32_bf16 v[96:99], v[234:237], v[186:189], v[96:99]
	v_mfma_f32_16x16x32_bf16 v[84:87], v[226:229], v[194:197], v[84:87]
	v_mfma_f32_16x16x32_bf16 v[80:83], v[234:237], v[194:197], v[80:83]
	v_mfma_f32_16x16x32_bf16 v[68:71], v[226:229], v[218:221], v[68:71]
	v_mfma_f32_16x16x32_bf16 v[64:67], v[234:237], v[218:221], v[64:67]
	s_mov_b32 m0, s41
	v_lshl_add_u64 v[158:159], v[240:241], 0, s[2:3]
	s_barrier
	ds_read_b128 v[154:157], v181 offset:49152
	ds_read_b128 v[174:177], v181 offset:50176
	ds_read_b128 v[182:185], v181 offset:51200
	ds_read_b128 v[186:189], v181 offset:52224
	ds_read_b128 v[190:193], v181 offset:53248
	ds_read_b128 v[194:197], v181 offset:54272
	ds_read_b128 v[214:217], v181 offset:55296
	ds_read_b128 v[218:221], v181 offset:56320
	global_load_lds_dwordx4 v[158:159], off
	v_lshl_add_u64 v[158:159], v[242:243], 0, s[2:3]
	s_mov_b32 m0, s42
	s_nop 0
	global_load_lds_dwordx4 v[158:159], off
	s_barrier
; DEV bf16x8 pack8(f32x4 a, f32x4 b) { u32x4 w; w.x = cvt_pk_bf16(a[0], a[1]); w.y = cvt_pk_bf16(a[2], a[3]); w.z = cvt_pk_bf16(b[0], b[1]); w.w = cvt_pk_bf16(b[2], b[3]); return __builtin_bit_cast(bf16x8, w); }
; #define PG8_WAIT_V(n) asm volatile("s_waitcnt vmcnt(" #n ")" ::: "memory")
; #define PG8_WAIT_L(n) asm volatile("s_waitcnt lgkmcnt(" #n ")" ::: "memory")
; #define PG8_BAR __builtin_amdgcn_s_barrier()
; #define PG8_SCHED __builtin_amdgcn_sched_barrier(0)
; template <class Epi>
; DEV void gemm_phase(LAS unsigned char* lds, const Gemm g, const StaticOrder& S, const Epi& E) {
;     ...
;             PG8_BAR; PG8_WAIT_L(0); PG8_MMA(1, 0, At, B0); PG8_BAR; PG8_SCHED;
;             PG8_STAGE(PG8_SB(1, 1), b3 + hstep, voffB);
;             PG8_WAIT_V(6); PG8_BAR; PG8_MMA(1, 1, At, B1); PG8_BAR;
;     DEV void operator()(AccRef acc, const pg8::Unit& u, int wr, int wc, int fr, int fq) const {
;         const int row0 = u.pm * 256 + wr * 64 + fr, col0 = u.pn * 256 + wc * 32 + 8 * fq;
; #pragma unroll
;         for (int am = 0; am < 4; ++am) { const int ai = am >> 1, m0 = (am & 1) * 2;
;             f32x4 bv[4][2][2];
; #pragma unroll
;             for (int m = m0; m < m0 + 2; ++m)
; #pragma unroll
;                 for (int bj = 0; bj < 2; ++bj)
; #pragma unroll
;                     for (int n = 0; n < 2; ++n) bv[m][bj][n] = *(const f32x4*)(base + (size_t)(row0 + ai * 128 + m * 16) * 2048 + col0 + bj * 128 + n * 4);
; #pragma unroll
;             for (int m = m0; m < m0 + 2; ++m) { const size_t off = (size_t)(row0 + ai * 128 + m * 16) * 2048 + col0; float sq = 0.f;
; #pragma unroll
;                 for (int bj = 0; bj < 2; ++bj) { const f32x4 o0 = bv[m][bj][0] + scale * acc[ai][bj][m][0], o1 = bv[m][bj][1] + scale * acc[ai][bj][m][1];
;                     *(f32x4*)(out + off + bj * 128) = o0; *(f32x4*)(out + off + bj * 128 + 4) = o1;
;                     if (xb) { *(u32x4*)(xb + off + bj * 128) = __builtin_bit_cast(u32x4, pack8(o0, o1));
;                         sq += (o0[0] * o0[0] + o0[1] * o0[1] + o0[2] * o0[2] + o0[3] * o0[3]) + (o1[0] * o1[0] + o1[1] * o1[1] + o1[2] * o1[2] + o1[3] * o1[3]); } }
;                 if (ssout) { sq += __shfl_xor(sq, 16); sq += __shfl_xor(sq, 32);
;                     if (fq == 0) { if (red) red[(ai * 128 + wr * 64 + m * 16 + fr) * 4 + wc] = sq; else atomicAdd(ssout + (size_t)(row0 + ai * 128 + m * 16) * 8 + u.pn, sq); } } }
	s_waitcnt lgkmcnt(0)
	v_mfma_f32_16x16x32_bf16 v[60:63], v[128:131], v[154:157], v[60:63]
	v_mfma_f32_16x16x32_bf16 v[56:59], v[136:139], v[154:157], v[56:59]
	v_mfma_f32_16x16x32_bf16 v[44:47], v[128:131], v[182:185], v[44:47]
	v_mfma_f32_16x16x32_bf16 v[40:43], v[136:139], v[182:185], v[40:43]
	v_mfma_f32_16x16x32_bf16 v[28:31], v[128:131], v[190:193], v[28:31]
	v_mfma_f32_16x16x32_bf16 v[24:27], v[136:139], v[190:193], v[24:27]
	v_mfma_f32_16x16x32_bf16 v[12:15], v[128:131], v[214:217], v[12:15]
	v_mfma_f32_16x16x32_bf16 v[8:11], v[136:139], v[214:217], v[8:11]
	v_mfma_f32_16x16x32_bf16 v[60:63], v[132:135], v[174:177], v[60:63]
	v_mfma_f32_16x16x32_bf16 v[56:59], v[140:143], v[174:177], v[56:59]
	v_mfma_f32_16x16x32_bf16 v[44:47], v[132:135], v[186:189], v[44:47]
	v_mfma_f32_16x16x32_bf16 v[40:43], v[140:143], v[186:189], v[40:43]
	v_mfma_f32_16x16x32_bf16 v[28:31], v[132:135], v[194:197], v[28:31]
	v_mfma_f32_16x16x32_bf16 v[24:27], v[140:143], v[194:197], v[24:27]
	v_mfma_f32_16x16x32_bf16 v[12:15], v[132:135], v[218:221], v[12:15]
	v_mfma_f32_16x16x32_bf16 v[8:11], v[140:143], v[218:221], v[8:11]
	s_barrier
	s_add_u32 s28, s28, 0x100080
	s_addc_u32 s29, s29, 0
	s_add_i32 s30, s30, s36
	s_mov_b32 m0, s30
	s_nop 0
	global_load_lds_dwordx4 v160, s[28:29]
	s_add_i32 m0, s30, 0x2000
	s_nop 0
	global_load_lds_dwordx4 v148, s[28:29]
	s_waitcnt vmcnt(10)
	s_barrier
	v_mfma_f32_16x16x32_bf16 v[52:55], v[222:225], v[154:157], v[52:55]
	v_mfma_f32_16x16x32_bf16 v[48:51], v[230:233], v[154:157], v[48:51]
	v_mfma_f32_16x16x32_bf16 v[36:39], v[222:225], v[182:185], v[36:39]
	v_mfma_f32_16x16x32_bf16 v[32:35], v[230:233], v[182:185], v[32:35]
	v_mfma_f32_16x16x32_bf16 v[20:23], v[222:225], v[190:193], v[20:23]
	v_mfma_f32_16x16x32_bf16 v[16:19], v[230:233], v[190:193], v[16:19]
	v_mfma_f32_16x16x32_bf16 v[4:7], v[222:225], v[214:217], v[4:7]
	v_mfma_f32_16x16x32_bf16 v[0:3], v[230:233], v[214:217], v[0:3]
	v_mfma_f32_16x16x32_bf16 v[52:55], v[226:229], v[174:177], v[52:55]
	v_mfma_f32_16x16x32_bf16 v[48:51], v[234:237], v[174:177], v[48:51]
	v_mfma_f32_16x16x32_bf16 v[36:39], v[226:229], v[186:189], v[36:39]
	v_mfma_f32_16x16x32_bf16 v[32:35], v[234:237], v[186:189], v[32:35]
	v_mfma_f32_16x16x32_bf16 v[20:23], v[226:229], v[194:197], v[20:23]
	v_mfma_f32_16x16x32_bf16 v[16:19], v[234:237], v[194:197], v[16:19]
	v_mfma_f32_16x16x32_bf16 v[4:7], v[226:229], v[218:221], v[4:7]
	v_mfma_f32_16x16x32_bf16 v[0:3], v[234:237], v[218:221], v[0:3]
	s_add_i32 s48, s48, 2
	s_add_u32 s26, s26, 0x100
	s_addc_u32 s27, s27, 0
	s_add_u32 s46, s46, 0x100
	s_addc_u32 s47, s47, 0
	s_cmp_gt_u32 s48, 61
	s_barrier
	s_cbranch_scc0 .LBB0_404
	v_lshl_add_u32 v156, s24, 8, v167
	v_lshl_or_b32 v154, s14, 8, v179
	v_readlane_b32 s24, v254, 16
	v_ashrrev_i32_e32 v155, 31, v154
	v_readlane_b32 s25, v254, 17
	v_ashrrev_i32_e32 v157, 31, v156
	v_lshlrev_b64 v[128:129], 13, v[156:157]
	v_lshl_add_u64 v[158:159], v[154:155], 2, s[24:25]
	v_lshl_add_u64 v[214:215], v[158:159], 0, v[128:129]
	global_load_dwordx4 v[182:185], v[214:215], off offset:16
	global_load_dwordx4 v[186:189], v[214:215], off
	global_load_dwordx4 v[190:193], v[214:215], off offset:528
	global_load_dwordx4 v[194:197], v[214:215], off offset:512
	v_or_b32_e32 v174, 16, v156
	v_ashrrev_i32_e32 v175, 31, v174
	v_lshlrev_b64 v[128:129], 13, v[174:175]
	v_lshl_add_u64 v[176:177], v[158:159], 0, v[128:129]
	global_load_dwordx4 v[136:139], v[176:177], off offset:16
	global_load_dwordx4 v[140:143], v[176:177], off
	global_load_dwordx4 v[128:131], v[176:177], off offset:528
	global_load_dwordx4 v[132:135], v[176:177], off offset:512
	v_lshlrev_b64 v[216:217], 11, v[156:157]
	v_readlane_b32 s24, v250, 9
	v_lshl_add_u64 v[216:217], v[216:217], 0, v[154:155]
	v_readlane_b32 s25, v250, 10
	v_cmp_lt_i32_e32 vcc, v208, v206
	s_ashr_i32 s15, s14, 31
	s_waitcnt vmcnt(0)
	v_pk_add_f32 v[120:121], v[120:121], v[182:183]
	v_pk_add_f32 v[126:127], v[126:127], v[188:189]
	v_pk_add_f32 v[124:125], v[124:125], v[186:187]
	v_pk_add_f32 v[122:123], v[122:123], v[184:185]
	global_store_dwordx4 v[214:215], v[124:127], off
	global_store_dwordx4 v[214:215], v[120:123], off offset:16
	v_cvt_pk_bf16_f32 v184, v120, v121
	v_cvt_pk_bf16_f32 v182, v124, v125
	v_mul_f32_e32 v121, v121, v121
	v_cvt_pk_bf16_f32 v183, v126, v127
	v_cvt_pk_bf16_f32 v185, v122, v123
	v_lshl_add_u64 v[186:187], v[216:217], 1, s[24:25]
	v_fmac_f32_e32 v121, v120, v120
	v_pk_add_f32 v[118:119], v[118:119], v[196:197]
	v_pk_add_f32 v[116:117], v[116:117], v[194:195]
	v_pk_add_f32 v[112:113], v[112:113], v[190:191]
	global_store_dwordx4 v[186:187], v[182:185], off
	v_mul_f32_e32 v125, v125, v125
	v_fmac_f32_e32 v121, v122, v122
	v_pk_add_f32 v[114:115], v[114:115], v[192:193]
	global_store_dwordx4 v[214:215], v[116:119], off offset:512
	global_store_dwordx4 v[214:215], v[112:115], off offset:528
	v_cvt_pk_bf16_f32 v120, v116, v117
	v_cvt_pk_bf16_f32 v122, v112, v113
	v_mul_f32_e32 v117, v117, v117
	v_mul_f32_e32 v113, v113, v113
	v_fmac_f32_e32 v125, v124, v124
	v_fmac_f32_e32 v117, v116, v116
	v_fmac_f32_e32 v113, v112, v112
	v_fmac_f32_e32 v125, v126, v126
	v_fmac_f32_e32 v117, v118, v118
	v_fmac_f32_e32 v113, v114, v114
	v_fmac_f32_e32 v125, v127, v127
	v_fmac_f32_e32 v121, v123, v123
	v_fmac_f32_e32 v117, v119, v119
	v_fmac_f32_e32 v113, v115, v115
	v_add_f32_e32 v124, v125, v121
	v_add_f32_e32 v112, v117, v113
	v_cndmask_b32_e32 v113, v204, v208, vcc
	v_cvt_pk_bf16_f32 v121, v118, v119
	v_add_f32_e32 v112, v124, v112
	v_lshlrev_b32_e32 v118, 2, v113
	ds_bpermute_b32 v113, v118, v112
	v_cmp_lt_i32_e32 vcc, v207, v206
	v_cvt_pk_bf16_f32 v123, v114, v115
	global_store_dwordx4 v[186:187], v[120:123], off offset:256
	s_waitcnt lgkmcnt(0)
	v_add_f32_e32 v112, v112, v113
	v_cndmask_b32_e32 v113, v204, v207, vcc
	v_lshlrev_b32_e32 v119, 2, v113
	ds_bpermute_b32 v113, v119, v112
	s_and_saveexec_b64 s[24:25], s[6:7]
	s_cbranch_execz .LBB0_410
	s_waitcnt lgkmcnt(0)
	v_add_f32_e32 v112, v112, v113
	s_mov_b64 s[26:27], -1
	s_and_b64 vcc, exec, s[12:13]
	s_cbranch_vccz .LBB0_408
	v_readlane_b32 s26, v250, 59
	v_lshlrev_b64 v[114:115], 5, v[156:157]
	v_readlane_b32 s27, v250, 60
	s_nop 1
	v_lshl_add_u64 v[114:115], s[26:27], 0, v[114:115]
	v_lshl_add_u64 v[114:115], s[14:15], 2, v[114:115]
	global_atomic_add_f32 v[114:115], v112, off
	s_mov_b64 s[26:27], 0

; #define PG8_STAGE(bufoff, gbase, voff) do { _Pragma("unroll") for (int _i = 0; _i < 2; ++_i) \
;         __builtin_amdgcn_global_load_lds((const unsigned*)((const char*)(gbase) + (voff)[_i]), (LAS unsigned*)(lds + (bufoff) + ldsw + _i * 8192), 16, 0, 0); } while (0)
; #define PG8_LDA(dst, b, h) do { _Pragma("unroll") for (int m = 0; m < 4; ++m) _Pragma("unroll") for (int k = 0; k < 2; ++k) dst[m][k] = *(const LAS bf16x8*)(lds + PG8_SA(b, h) + aoff + m * 2048 + k * 1024); } while (0)
; #define PG8_LDB(dst, b, h) do { _Pragma("unroll") for (int n = 0; n < 2; ++n) _Pragma("unroll") for (int k = 0; k < 2; ++k) dst[n][k] = *(const LAS bf16x8*)(lds + PG8_SB(b, h) + boff + n * 2048 + k * 1024); } while (0)
; #define PG8_MMA(ai, bj, At, Bt) do { __builtin_amdgcn_s_setprio(1); _Pragma("unroll") for (int m = 0; m < 4; ++m) _Pragma("unroll") for (int n = 0; n < 2; ++n) _Pragma("unroll") for (int k = 0; k < 2; ++k) \
;         acc[ai][bj][m][n] = __builtin_amdgcn_mfma_f32_16x16x32_bf16(Bt[n][k], At[m][k], acc[ai][bj][m][n], 0, 0, 0); __builtin_amdgcn_s_setprio(0); } while (0)
; #define PG8_WAIT_L(n) asm volatile("s_waitcnt lgkmcnt(" #n ")" ::: "memory")
; #define PG8_BAR __builtin_amdgcn_s_barrier()
; #define PG8_SCHED __builtin_amdgcn_sched_barrier(0)
; template <class Epi>
; DEV void gemm_phase(LAS unsigned char* lds, const Gemm g, const StaticOrder& S, const Epi& E) {
;     ...
;             const bool last = (t == nt - 2);
;             const char* a1 = cA + (size_t)(t + 1) * kstep;
;             const char* a2 = last ? nA : cA + (size_t)(t + 2) * kstep; const char* b2 = last ? nB : cB + (size_t)(t + 2) * kstep;
;             const char* a3 = a2 + kstep; const char* b3 = b2 + kstep;
;             PG8_LDB(B0, 0, 0); PG8_SCHED; PG8_LDA(At, 0, 0); PG8_STAGE(PG8_SA(1, 1), a1 + hstep, voffA);
;             PG8_WAIT_L(8); PG8_BAR; PG8_WAIT_L(0); PG8_MMA(0, 0, At, B0); PG8_BAR; PG8_SCHED;
;             PG8_LDB(B1, 0, 1); PG8_STAGE(PG8_SB(0, 0), b2, voffB);
;             PG8_BAR; PG8_WAIT_L(0); PG8_MMA(0, 1, At, B1); PG8_BAR;
;             PG8_LDA(At, 0, 1); PG8_STAGE(PG8_SA(0, 0), a2, voffA);
;             PG8_BAR; PG8_WAIT_L(0); PG8_MMA(1, 0, At, B0); PG8_BAR; PG8_SCHED;
.LBB0_588:
	s_add_u32 s16, s14, 0xfff80080
	s_addc_u32 s17, s15, -1
	s_add_i32 s41, 0, 0x10000
	v_add_u32_e32 v154, s41, v167
	ds_read_b128 v[128:131], v154
	ds_read_b128 v[132:135], v154 offset:1024
	ds_read_b128 v[150:153], v154 offset:2048
	ds_read_b128 v[174:177], v154 offset:3072
	s_cmp_eq_u32 s40, 28
	s_cselect_b32 s19, s1, s17
	s_cselect_b32 s18, s9, s16
	s_cselect_b32 s17, s7, s37
	s_cselect_b32 s16, s35, s36
	s_add_i32 m0, s24, 0xc000
	ds_read_b128 v[182:185], v219
	ds_read_b128 v[190:193], v219 offset:1024
	ds_read_b128 v[194:197], v219 offset:2048
	ds_read_b128 v[220:223], v219 offset:3072
	ds_read_b128 v[224:227], v219 offset:4096
	ds_read_b128 v[228:231], v219 offset:5120
	ds_read_b128 v[232:235], v219 offset:6144
	ds_read_b128 v[236:239], v219 offset:7168
	global_load_lds_dwordx4 v146, s[14:15]
	s_add_i32 m0, s24, 0xe000
	s_nop 0
	global_load_lds_dwordx4 v148, s[14:15]
	s_waitcnt lgkmcnt(8)
	s_waitcnt vmcnt(10)
	s_barrier
	s_waitcnt lgkmcnt(0)
	v_mfma_f32_16x16x32_bf16 v[124:127], v[128:131], v[182:185], v[124:127]
	v_mfma_f32_16x16x32_bf16 v[120:123], v[150:153], v[182:185], v[120:123]
	v_mfma_f32_16x16x32_bf16 v[108:111], v[128:131], v[194:197], v[108:111]
	v_mfma_f32_16x16x32_bf16 v[104:107], v[150:153], v[194:197], v[104:107]
	v_mfma_f32_16x16x32_bf16 v[92:95], v[128:131], v[224:227], v[92:95]
	v_mfma_f32_16x16x32_bf16 v[88:91], v[150:153], v[224:227], v[88:91]
	v_mfma_f32_16x16x32_bf16 v[76:79], v[128:131], v[232:235], v[76:79]
	v_mfma_f32_16x16x32_bf16 v[72:75], v[150:153], v[232:235], v[72:75]
	v_mfma_f32_16x16x32_bf16 v[124:127], v[132:135], v[190:193], v[124:127]
	v_mfma_f32_16x16x32_bf16 v[120:123], v[174:177], v[190:193], v[120:123]
	v_mfma_f32_16x16x32_bf16 v[108:111], v[132:135], v[220:223], v[108:111]
	v_mfma_f32_16x16x32_bf16 v[104:107], v[174:177], v[220:223], v[104:107]
	v_mfma_f32_16x16x32_bf16 v[92:95], v[132:135], v[228:231], v[92:95]
	v_mfma_f32_16x16x32_bf16 v[88:91], v[174:177], v[228:231], v[88:91]
	v_mfma_f32_16x16x32_bf16 v[76:79], v[132:135], v[236:239], v[76:79]
	v_mfma_f32_16x16x32_bf16 v[72:75], v[174:177], v[236:239], v[72:75]
	s_barrier
	s_add_i32 s44, 0, 0x14000
	v_add_u32_e32 v154, s44, v167
	s_add_i32 s41, s41, s22
	ds_read_b128 v[240:243], v154
	ds_read_b128 v[244:247], v154 offset:1024
	ds_read_b128 v[186:189], v154 offset:2048
	ds_read_b128 v[214:217], v154 offset:3072
	v_lshl_add_u64 v[154:155], s[16:17], 0, v[140:141]
	s_mov_b32 m0, s41
	v_lshl_add_u64 v[158:159], s[16:17], 0, v[136:137]
	global_load_lds_dwordx4 v140, s[16:17]
	s_add_i32 m0, s41, 0x2000
	s_nop 0
	global_load_lds_dwordx4 v136, s[16:17]
	s_waitcnt vmcnt(10)
	s_barrier
	s_waitcnt lgkmcnt(0)
	v_mfma_f32_16x16x32_bf16 v[116:119], v[240:243], v[182:185], v[116:119]
	v_mfma_f32_16x16x32_bf16 v[112:115], v[186:189], v[182:185], v[112:115]
	v_mfma_f32_16x16x32_bf16 v[100:103], v[240:243], v[194:197], v[100:103]
	v_mfma_f32_16x16x32_bf16 v[96:99], v[186:189], v[194:197], v[96:99]
	v_mfma_f32_16x16x32_bf16 v[84:87], v[240:243], v[224:227], v[84:87]
	v_mfma_f32_16x16x32_bf16 v[80:83], v[186:189], v[224:227], v[80:83]
	v_mfma_f32_16x16x32_bf16 v[68:71], v[240:243], v[232:235], v[68:71]
	v_mfma_f32_16x16x32_bf16 v[64:67], v[186:189], v[232:235], v[64:67]
	v_mfma_f32_16x16x32_bf16 v[116:119], v[244:247], v[190:193], v[116:119]
	v_mfma_f32_16x16x32_bf16 v[112:115], v[214:217], v[190:193], v[112:115]
	v_mfma_f32_16x16x32_bf16 v[100:103], v[244:247], v[220:223], v[100:103]
	v_mfma_f32_16x16x32_bf16 v[96:99], v[214:217], v[220:223], v[96:99]
	v_mfma_f32_16x16x32_bf16 v[84:87], v[244:247], v[228:231], v[84:87]
	v_mfma_f32_16x16x32_bf16 v[80:83], v[214:217], v[228:231], v[80:83]
	v_mfma_f32_16x16x32_bf16 v[68:71], v[244:247], v[236:239], v[68:71]
	v_mfma_f32_16x16x32_bf16 v[64:67], v[214:217], v[236:239], v[64:67]
	s_mov_b32 m0, s24
	v_lshl_add_u64 v[178:179], s[18:19], 0, v[142:143]
	s_barrier
	ds_read_b128 v[182:185], v219 offset:16384
	ds_read_b128 v[190:193], v219 offset:17408
	ds_read_b128 v[194:197], v219 offset:18432
	ds_read_b128 v[220:223], v219 offset:19456
	ds_read_b128 v[224:227], v219 offset:20480
	ds_read_b128 v[228:231], v219 offset:21504
	ds_read_b128 v[232:235], v219 offset:22528
	ds_read_b128 v[236:239], v219 offset:23552
	global_load_lds_dwordx4 v142, s[18:19]
	v_lshl_add_u64 v[248:249], s[18:19], 0, v[138:139]
	s_mov_b32 m0, s25
	s_nop 0
	global_load_lds_dwordx4 v138, s[18:19]
	s_barrier
	s_waitcnt lgkmcnt(0)
	v_mfma_f32_16x16x32_bf16 v[60:63], v[128:131], v[182:185], v[60:63]
	v_mfma_f32_16x16x32_bf16 v[56:59], v[150:153], v[182:185], v[56:59]
	v_mfma_f32_16x16x32_bf16 v[44:47], v[128:131], v[194:197], v[44:47]
	v_mfma_f32_16x16x32_bf16 v[40:43], v[150:153], v[194:197], v[40:43]
	v_mfma_f32_16x16x32_bf16 v[28:31], v[128:131], v[224:227], v[28:31]
	v_mfma_f32_16x16x32_bf16 v[24:27], v[150:153], v[224:227], v[24:27]
	v_mfma_f32_16x16x32_bf16 v[12:15], v[128:131], v[232:235], v[12:15]
	v_mfma_f32_16x16x32_bf16 v[8:11], v[150:153], v[232:235], v[8:11]
	v_mfma_f32_16x16x32_bf16 v[60:63], v[132:135], v[190:193], v[60:63]
	v_mfma_f32_16x16x32_bf16 v[56:59], v[174:177], v[190:193], v[56:59]
	v_mfma_f32_16x16x32_bf16 v[44:47], v[132:135], v[220:223], v[44:47]
	v_mfma_f32_16x16x32_bf16 v[40:43], v[174:177], v[220:223], v[40:43]
	v_mfma_f32_16x16x32_bf16 v[28:31], v[132:135], v[228:231], v[28:31]
	v_mfma_f32_16x16x32_bf16 v[24:27], v[174:177], v[228:231], v[24:27]
	v_mfma_f32_16x16x32_bf16 v[12:15], v[132:135], v[236:239], v[12:15]
	v_mfma_f32_16x16x32_bf16 v[8:11], v[174:177], v[236:239], v[8:11]
	s_barrier
; #define PG8_STAGE(bufoff, gbase, voff) do { _Pragma("unroll") for (int _i = 0; _i < 2; ++_i) \
;         __builtin_amdgcn_global_load_lds((const unsigned*)((const char*)(gbase) + (voff)[_i]), (LAS unsigned*)(lds + (bufoff) + ldsw + _i * 8192), 16, 0, 0); } while (0)
; #define PG8_LDA(dst, b, h) do { _Pragma("unroll") for (int m = 0; m < 4; ++m) _Pragma("unroll") for (int k = 0; k < 2; ++k) dst[m][k] = *(const LAS bf16x8*)(lds + PG8_SA(b, h) + aoff + m * 2048 + k * 1024); } while (0)
; #define PG8_LDB(dst, b, h) do { _Pragma("unroll") for (int n = 0; n < 2; ++n) _Pragma("unroll") for (int k = 0; k < 2; ++k) dst[n][k] = *(const LAS bf16x8*)(lds + PG8_SB(b, h) + boff + n * 2048 + k * 1024); } while (0)
; #define PG8_MMA(ai, bj, At, Bt) do { __builtin_amdgcn_s_setprio(1); _Pragma("unroll") for (int m = 0; m < 4; ++m) _Pragma("unroll") for (int n = 0; n < 2; ++n) _Pragma("unroll") for (int k = 0; k < 2; ++k) \
;         acc[ai][bj][m][n] = __builtin_amdgcn_mfma_f32_16x16x32_bf16(Bt[n][k], At[m][k], acc[ai][bj][m][n], 0, 0, 0); __builtin_amdgcn_s_setprio(0); } while (0)
; #define PG8_WAIT_V(n) asm volatile("s_waitcnt vmcnt(" #n ")" ::: "memory")
; #define PG8_WAIT_L(n) asm volatile("s_waitcnt lgkmcnt(" #n ")" ::: "memory")
; #define PG8_BAR __builtin_amdgcn_s_barrier()
; #define PG8_SCHED __builtin_amdgcn_sched_barrier(0)
; template <class Epi>
; DEV void gemm_phase(LAS unsigned char* lds, const Gemm g, const StaticOrder& S, const Epi& E) {
;     ...
;             PG8_STAGE(PG8_SB(0, 1), b2 + hstep, voffB);
;             PG8_WAIT_V(6); PG8_BAR; PG8_MMA(1, 1, At, B1); PG8_BAR;
;             PG8_LDB(B0, 1, 0); PG8_SCHED; PG8_LDA(At, 1, 0); PG8_STAGE(PG8_SA(0, 1), a2 + hstep, voffA);
;             PG8_WAIT_L(8); PG8_BAR; PG8_WAIT_L(0); PG8_MMA(0, 0, At, B0); PG8_BAR; PG8_SCHED;
;             PG8_LDB(B1, 1, 1); PG8_STAGE(PG8_SB(1, 0), b3, voffB);
;             PG8_BAR; PG8_WAIT_L(0); PG8_MMA(0, 1, At, B1); PG8_BAR;
;             PG8_LDA(At, 1, 1); PG8_STAGE(PG8_SA(1, 0), a3, voffA);
	s_add_u32 s42, s16, 0x80000
	s_addc_u32 s43, s17, 0
	s_add_i32 s41, s44, s22
	s_mov_b32 m0, s41
	s_nop 0
	global_load_lds_dwordx4 v140, s[42:43]
	s_add_i32 m0, s41, 0x2000
	s_nop 0
	global_load_lds_dwordx4 v136, s[42:43]
	s_waitcnt vmcnt(10)
	s_barrier
	v_mfma_f32_16x16x32_bf16 v[52:55], v[240:243], v[182:185], v[52:55]
	v_mfma_f32_16x16x32_bf16 v[48:51], v[186:189], v[182:185], v[48:51]
	v_mfma_f32_16x16x32_bf16 v[36:39], v[240:243], v[194:197], v[36:39]
	v_mfma_f32_16x16x32_bf16 v[32:35], v[186:189], v[194:197], v[32:35]
	v_mfma_f32_16x16x32_bf16 v[20:23], v[240:243], v[224:227], v[20:23]
	v_mfma_f32_16x16x32_bf16 v[16:19], v[186:189], v[224:227], v[16:19]
	v_mfma_f32_16x16x32_bf16 v[4:7], v[240:243], v[232:235], v[4:7]
	v_mfma_f32_16x16x32_bf16 v[0:3], v[186:189], v[232:235], v[0:3]
	v_mfma_f32_16x16x32_bf16 v[52:55], v[244:247], v[190:193], v[52:55]
	v_mfma_f32_16x16x32_bf16 v[48:51], v[214:217], v[190:193], v[48:51]
	v_mfma_f32_16x16x32_bf16 v[36:39], v[244:247], v[220:223], v[36:39]
	v_mfma_f32_16x16x32_bf16 v[32:35], v[214:217], v[220:223], v[32:35]
	v_mfma_f32_16x16x32_bf16 v[20:23], v[244:247], v[228:231], v[20:23]
	v_mfma_f32_16x16x32_bf16 v[16:19], v[214:217], v[228:231], v[16:19]
	v_mfma_f32_16x16x32_bf16 v[4:7], v[244:247], v[236:239], v[4:7]
	v_mfma_f32_16x16x32_bf16 v[0:3], v[214:217], v[236:239], v[0:3]
	s_add_i32 s41, 0, 0x18000
	v_add_u32_e32 v156, s41, v167
	s_barrier
	ds_read_b128 v[128:131], v156
	ds_read_b128 v[132:135], v156 offset:1024
	ds_read_b128 v[150:153], v156 offset:2048
	ds_read_b128 v[174:177], v156 offset:3072
	s_add_u32 s18, s18, 0x80000
	s_addc_u32 s19, s19, 0
	s_mov_b32 m0, s26
	ds_read_b128 v[182:185], v219 offset:32768
	ds_read_b128 v[186:189], v219 offset:33792
	ds_read_b128 v[190:193], v219 offset:34816
	ds_read_b128 v[194:197], v219 offset:35840
	ds_read_b128 v[214:217], v219 offset:36864
	ds_read_b128 v[220:223], v219 offset:37888
	ds_read_b128 v[224:227], v219 offset:38912
	ds_read_b128 v[228:231], v219 offset:39936
	global_load_lds_dwordx4 v142, s[18:19]
	s_mov_b32 m0, s27
	s_nop 0
	global_load_lds_dwordx4 v138, s[18:19]
	s_waitcnt lgkmcnt(8)
	s_waitcnt vmcnt(10)
	s_barrier
	s_waitcnt lgkmcnt(0)
	v_mfma_f32_16x16x32_bf16 v[124:127], v[128:131], v[182:185], v[124:127]
	v_mfma_f32_16x16x32_bf16 v[120:123], v[150:153], v[182:185], v[120:123]
	v_mfma_f32_16x16x32_bf16 v[108:111], v[128:131], v[190:193], v[108:111]
	v_mfma_f32_16x16x32_bf16 v[104:107], v[150:153], v[190:193], v[104:107]
	v_mfma_f32_16x16x32_bf16 v[92:95], v[128:131], v[214:217], v[92:95]
	v_mfma_f32_16x16x32_bf16 v[88:91], v[150:153], v[214:217], v[88:91]
	v_mfma_f32_16x16x32_bf16 v[76:79], v[128:131], v[224:227], v[76:79]
	v_mfma_f32_16x16x32_bf16 v[72:75], v[150:153], v[224:227], v[72:75]
	v_mfma_f32_16x16x32_bf16 v[124:127], v[132:135], v[186:189], v[124:127]
	v_mfma_f32_16x16x32_bf16 v[120:123], v[174:177], v[186:189], v[120:123]
	v_mfma_f32_16x16x32_bf16 v[108:111], v[132:135], v[194:197], v[108:111]
	v_mfma_f32_16x16x32_bf16 v[104:107], v[174:177], v[194:197], v[104:107]
	v_mfma_f32_16x16x32_bf16 v[92:95], v[132:135], v[220:223], v[92:95]
	v_mfma_f32_16x16x32_bf16 v[88:91], v[174:177], v[220:223], v[88:91]
	v_mfma_f32_16x16x32_bf16 v[76:79], v[132:135], v[228:231], v[76:79]
	v_mfma_f32_16x16x32_bf16 v[72:75], v[174:177], v[228:231], v[72:75]
	s_barrier
	s_add_i32 s18, 0, 0x1c000
	s_add_i32 s19, s41, s22
	v_add_u32_e32 v156, s18, v167
	v_lshl_add_u64 v[154:155], v[154:155], 0, s[2:3]
	s_mov_b32 m0, s19
	ds_read_b128 v[232:235], v156
	ds_read_b128 v[236:239], v156 offset:1024
	ds_read_b128 v[240:243], v156 offset:2048
	ds_read_b128 v[244:247], v156 offset:3072
	global_load_lds_dwordx4 v[154:155], off
	v_lshl_add_u64 v[154:155], v[158:159], 0, s[2:3]
	s_add_i32 m0, s19, 0x2000
	s_nop 0
	global_load_lds_dwordx4 v[154:155], off
	s_waitcnt vmcnt(10)
	s_barrier
	s_waitcnt lgkmcnt(0)
	v_mfma_f32_16x16x32_bf16 v[116:119], v[232:235], v[182:185], v[116:119]
	v_mfma_f32_16x16x32_bf16 v[112:115], v[240:243], v[182:185], v[112:115]
	v_mfma_f32_16x16x32_bf16 v[100:103], v[232:235], v[190:193], v[100:103]
	v_mfma_f32_16x16x32_bf16 v[96:99], v[240:243], v[190:193], v[96:99]
	v_mfma_f32_16x16x32_bf16 v[84:87], v[232:235], v[214:217], v[84:87]
	v_mfma_f32_16x16x32_bf16 v[80:83], v[240:243], v[214:217], v[80:83]
	v_mfma_f32_16x16x32_bf16 v[68:71], v[232:235], v[224:227], v[68:71]
	v_mfma_f32_16x16x32_bf16 v[64:67], v[240:243], v[224:227], v[64:67]
	v_mfma_f32_16x16x32_bf16 v[116:119], v[236:239], v[186:189], v[116:119]
	v_mfma_f32_16x16x32_bf16 v[112:115], v[244:247], v[186:189], v[112:115]
	v_mfma_f32_16x16x32_bf16 v[100:103], v[236:239], v[194:197], v[100:103]
	v_mfma_f32_16x16x32_bf16 v[96:99], v[244:247], v[194:197], v[96:99]
	v_mfma_f32_16x16x32_bf16 v[84:87], v[236:239], v[220:223], v[84:87]
	v_mfma_f32_16x16x32_bf16 v[80:83], v[244:247], v[220:223], v[80:83]
	v_mfma_f32_16x16x32_bf16 v[68:71], v[236:239], v[228:231], v[68:71]
	v_mfma_f32_16x16x32_bf16 v[64:67], v[244:247], v[228:231], v[64:67]
	s_mov_b32 m0, s28
	v_lshl_add_u64 v[154:155], v[178:179], 0, s[2:3]
	s_barrier
	ds_read_b128 v[182:185], v219 offset:49152
	ds_read_b128 v[186:189], v219 offset:50176
	ds_read_b128 v[190:193], v219 offset:51200
	ds_read_b128 v[194:197], v219 offset:52224
	ds_read_b128 v[214:217], v219 offset:53248
	ds_read_b128 v[220:223], v219 offset:54272
	ds_read_b128 v[224:227], v219 offset:55296
	ds_read_b128 v[228:231], v219 offset:56320
	global_load_lds_dwordx4 v[154:155], off
	v_lshl_add_u64 v[154:155], v[248:249], 0, s[2:3]
	s_mov_b32 m0, s29
	s_nop 0
	global_load_lds_dwordx4 v[154:155], off
	s_barrier
; #define PG8_STAGE(bufoff, gbase, voff) do { _Pragma("unroll") for (int _i = 0; _i < 2; ++_i) \
;         __builtin_amdgcn_global_load_lds((const unsigned*)((const char*)(gbase) + (voff)[_i]), (LAS unsigned*)(lds + (bufoff) + ldsw + _i * 8192), 16, 0, 0); } while (0)
; #define PG8_MMA(ai, bj, At, Bt) do { __builtin_amdgcn_s_setprio(1); _Pragma("unroll") for (int m = 0; m < 4; ++m) _Pragma("unroll") for (int n = 0; n < 2; ++n) _Pragma("unroll") for (int k = 0; k < 2; ++k) \
;         acc[ai][bj][m][n] = __builtin_amdgcn_mfma_f32_16x16x32_bf16(Bt[n][k], At[m][k], acc[ai][bj][m][n], 0, 0, 0); __builtin_amdgcn_s_setprio(0); } while (0)
; #define PG8_WAIT_V(n) asm volatile("s_waitcnt vmcnt(" #n ")" ::: "memory")
; #define PG8_WAIT_L(n) asm volatile("s_waitcnt lgkmcnt(" #n ")" ::: "memory")
; #define PG8_BAR __builtin_amdgcn_s_barrier()
; #define PG8_SCHED __builtin_amdgcn_sched_barrier(0)
;     DEV void operator()(AccRef acc, const pg8::Unit& u, int wr, int wc, int fr, int fq) const { store_bf16_tile<0, false>(acc, O, ld, u.pm * 256 + wr * 64 + fr, u.pn * 256 + wc * 32 + 4 * fq, ss); }
; template <class Epi>
; DEV void gemm_phase(LAS unsigned char* lds, const Gemm g, const StaticOrder& S, const Epi& E) {
;     ...
;             PG8_BAR; PG8_WAIT_L(0); PG8_MMA(1, 0, At, B0); PG8_BAR; PG8_SCHED;
;             PG8_STAGE(PG8_SB(1, 1), b3 + hstep, voffB);
;             PG8_WAIT_V(6); PG8_BAR; PG8_MMA(1, 1, At, B1); PG8_BAR;
;     DEV void operator()(AccRef acc, const pg8::Unit& u, int wr, int wc, int fr, int fq) const {
;         const int ct = u.pn * 256, row0 = u.pm * 256 + wr * 64 + fr, cw = wc * 32 + 8 * fq;
;         if (ct < 4096) store_bf16_tile<1, true>(acc, UV, 4096, row0, ct + cw, ss);
;         else if (ct < 6144) store_bf16_tile<0, true>(acc, Z, 2048, row0, ct - 4096 + cw, ss);
;         else if (ct < 9216) store_bf16_tile<0, true>(acc, XBC, 3072, row0, ct - 6144 + cw, ss);
;         else if (wc == 0) {
; #pragma unroll
;             for (int ai = 0; ai < 2; ++ai)
; #pragma unroll
;                 for (int m = 0; m < 4; ++m) { const float rs = rowscale(ss, row0 + ai * 128 + m * 16);
; #pragma unroll
;                     for (int n = 0; n < 2; ++n) *(f32x4*)(DTR + (size_t)(row0 + ai * 128 + m * 16) * 32 + 8 * fq + 4 * n) = acc[ai][0][m][n] * rs; }
	s_waitcnt lgkmcnt(0)
	v_mfma_f32_16x16x32_bf16 v[60:63], v[128:131], v[182:185], v[60:63]
	v_mfma_f32_16x16x32_bf16 v[56:59], v[150:153], v[182:185], v[56:59]
	v_mfma_f32_16x16x32_bf16 v[44:47], v[128:131], v[190:193], v[44:47]
	v_mfma_f32_16x16x32_bf16 v[40:43], v[150:153], v[190:193], v[40:43]
	v_mfma_f32_16x16x32_bf16 v[28:31], v[128:131], v[214:217], v[28:31]
	v_mfma_f32_16x16x32_bf16 v[24:27], v[150:153], v[214:217], v[24:27]
	v_mfma_f32_16x16x32_bf16 v[12:15], v[128:131], v[224:227], v[12:15]
	v_mfma_f32_16x16x32_bf16 v[8:11], v[150:153], v[224:227], v[8:11]
	v_mfma_f32_16x16x32_bf16 v[60:63], v[132:135], v[186:189], v[60:63]
	v_mfma_f32_16x16x32_bf16 v[56:59], v[174:177], v[186:189], v[56:59]
	v_mfma_f32_16x16x32_bf16 v[44:47], v[132:135], v[194:197], v[44:47]
	v_mfma_f32_16x16x32_bf16 v[40:43], v[174:177], v[194:197], v[40:43]
	v_mfma_f32_16x16x32_bf16 v[28:31], v[132:135], v[220:223], v[28:31]
	v_mfma_f32_16x16x32_bf16 v[24:27], v[174:177], v[220:223], v[24:27]
	v_mfma_f32_16x16x32_bf16 v[12:15], v[132:135], v[228:231], v[12:15]
	v_mfma_f32_16x16x32_bf16 v[8:11], v[174:177], v[228:231], v[8:11]
	s_barrier
	s_add_u32 s16, s16, 0x80080
	s_addc_u32 s17, s17, 0
	s_add_i32 s18, s18, s22
	s_mov_b32 m0, s18
	s_nop 0
	global_load_lds_dwordx4 v140, s[16:17]
	s_add_i32 m0, s18, 0x2000
	s_nop 0
	global_load_lds_dwordx4 v136, s[16:17]
	s_waitcnt vmcnt(10)
	s_barrier
	v_mfma_f32_16x16x32_bf16 v[52:55], v[232:235], v[182:185], v[52:55]
	v_mfma_f32_16x16x32_bf16 v[48:51], v[240:243], v[182:185], v[48:51]
	v_mfma_f32_16x16x32_bf16 v[36:39], v[232:235], v[190:193], v[36:39]
	v_mfma_f32_16x16x32_bf16 v[32:35], v[240:243], v[190:193], v[32:35]
	v_mfma_f32_16x16x32_bf16 v[20:23], v[232:235], v[214:217], v[20:23]
	v_mfma_f32_16x16x32_bf16 v[16:19], v[240:243], v[214:217], v[16:19]
	v_mfma_f32_16x16x32_bf16 v[4:7], v[232:235], v[224:227], v[4:7]
	v_mfma_f32_16x16x32_bf16 v[0:3], v[240:243], v[224:227], v[0:3]
	v_mfma_f32_16x16x32_bf16 v[52:55], v[236:239], v[186:189], v[52:55]
	v_mfma_f32_16x16x32_bf16 v[48:51], v[244:247], v[186:189], v[48:51]
	v_mfma_f32_16x16x32_bf16 v[36:39], v[236:239], v[194:197], v[36:39]
	v_mfma_f32_16x16x32_bf16 v[32:35], v[244:247], v[194:197], v[32:35]
	v_mfma_f32_16x16x32_bf16 v[20:23], v[236:239], v[220:223], v[20:23]
	v_mfma_f32_16x16x32_bf16 v[16:19], v[244:247], v[220:223], v[16:19]
	v_mfma_f32_16x16x32_bf16 v[4:7], v[236:239], v[228:231], v[4:7]
	v_mfma_f32_16x16x32_bf16 v[0:3], v[244:247], v[228:231], v[0:3]
	s_add_i32 s40, s40, 2
	s_add_u32 s14, s14, 0x100
	s_addc_u32 s15, s15, 0
	s_add_u32 s36, s36, 0x100
	s_addc_u32 s37, s37, 0
	s_cmp_gt_u32 s40, 29
	s_barrier
	s_cbranch_scc0 .LBB0_588
	s_lshl_b32 s7, s34, 8
	v_lshl_add_u32 v150, s0, 8, v157
	s_cmp_gt_i32 s34, 15
	s_mov_b64 s[0:1], -1
	s_cbranch_scc0 .LBB0_601
	s_cmp_gt_u32 s34, 23
	s_cbranch_scc0 .LBB0_598
	s_cmp_gt_u32 s34, 35
	s_cbranch_scc0 .LBB0_595
	s_andn2_b64 vcc, exec, s[4:5]
	s_cbranch_vccnz .LBB0_594
	v_ashrrev_i32_e32 v151, 31, v150
	v_readlane_b32 s0, v251, 39
	v_lshlrev_b64 v[128:129], 5, v[150:151]
	v_readlane_b32 s1, v251, 40
	s_mov_b32 s9, 0x800000
	s_nop 0
	v_lshl_add_u64 v[132:133], s[0:1], 0, v[128:129]
	global_load_dwordx4 v[128:131], v[132:133], off offset:16
	s_nop 0
	global_load_dwordx4 v[132:135], v[132:133], off
	s_waitcnt vmcnt(0)
	v_mov_b32_e32 v152, v133
	v_mov_b32_e32 v153, v134
	v_mov_b32_e32 v133, v135
	v_pk_add_f32 v[132:133], v[152:153], v[132:133]
	v_mov_b32_e32 v134, v130
	v_mov_b32_e32 v135, v128
	v_mov_b32_e32 v128, v131
	v_pk_add_f32 v[128:129], v[134:135], v[128:129]
	v_add_f32_e32 v130, v132, v133
	v_add_f32_e32 v129, v130, v129
	v_add_f32_e32 v128, v128, v129
	v_fmamk_f32 v128, v128, 0x3a000000, v199
	v_cmp_gt_f32_e32 vcc, s9, v128
	v_mul_f32_e32 v129, 0x4b800000, v128
	v_lshlrev_b64 v[134:135], 7, v[150:151]
	v_cndmask_b32_e32 v128, v128, v129, vcc
	v_rsq_f32_e32 v128, v128
	v_lshl_add_u64 v[134:135], v[144:145], 0, v[134:135]
	v_or_b32_e32 v152, 16, v150
	v_ashrrev_i32_e32 v153, 31, v152
	v_mul_f32_e32 v129, 0x45800000, v128
	v_cndmask_b32_e32 v132, v128, v129, vcc
	v_pk_mul_f32 v[130:131], v[126:127], v[132:133] op_sel_hi:[1,0]
	v_pk_mul_f32 v[128:129], v[124:125], v[132:133] op_sel_hi:[1,0]
	global_store_dwordx4 v[134:135], v[128:131], off
	s_nop 1
	v_pk_mul_f32 v[130:131], v[122:123], v[132:133] op_sel_hi:[1,0]
	v_pk_mul_f32 v[128:129], v[120:121], v[132:133] op_sel_hi:[1,0]
	global_store_dwordx4 v[134:135], v[128:131], off offset:16
	s_nop 1
	v_lshlrev_b64 v[128:129], 5, v[152:153]
	v_lshl_add_u64 v[132:133], s[0:1], 0, v[128:129]
	global_load_dwordx4 v[128:131], v[132:133], off offset:16
	s_nop 0
	global_load_dwordx4 v[132:135], v[132:133], off
	s_waitcnt vmcnt(0)
	v_mov_b32_e32 v154, v133
	v_mov_b32_e32 v155, v134
	v_mov_b32_e32 v133, v135
	v_pk_add_f32 v[132:133], v[154:155], v[132:133]
	v_mov_b32_e32 v134, v130
	v_mov_b32_e32 v135, v128
	v_mov_b32_e32 v128, v131
	v_pk_add_f32 v[128:129], v[134:135], v[128:129]
	v_add_f32_e32 v130, v132, v133
	v_add_f32_e32 v129, v130, v129
	v_add_f32_e32 v128, v128, v129
	v_fmamk_f32 v128, v128, 0x3a000000, v199
	v_cmp_gt_f32_e32 vcc, s9, v128
	v_mul_f32_e32 v129, 0x4b800000, v128
	v_lshlrev_b64 v[134:135], 7, v[152:153]
	v_cndmask_b32_e32 v128, v128, v129, vcc
	v_rsq_f32_e32 v128, v128
	v_lshl_add_u64 v[134:135], v[144:145], 0, v[134:135]
	v_or_b32_e32 v152, 32, v150
	v_ashrrev_i32_e32 v153, 31, v152
	v_mul_f32_e32 v129, 0x45800000, v128
	v_cndmask_b32_e32 v132, v128, v129, vcc
	v_pk_mul_f32 v[130:131], v[110:111], v[132:133] op_sel_hi:[1,0]
	v_pk_mul_f32 v[128:129], v[108:109], v[132:133] op_sel_hi:[1,0]
	global_store_dwordx4 v[134:135], v[128:131], off
	s_nop 1
	v_pk_mul_f32 v[130:131], v[106:107], v[132:133] op_sel_hi:[1,0]
	v_pk_mul_f32 v[128:129], v[104:105], v[132:133] op_sel_hi:[1,0]
	global_store_dwordx4 v[134:135], v[128:131], off offset:16
	s_nop 1
	v_lshlrev_b64 v[128:129], 5, v[152:153]
	v_lshl_add_u64 v[132:133], s[0:1], 0, v[128:129]
	global_load_dwordx4 v[128:131], v[132:133], off offset:16
	s_nop 0
	global_load_dwordx4 v[132:135], v[132:133], off
	s_waitcnt vmcnt(0)
;     DEV void operator()(AccRef acc, const pg8::Unit& u, int wr, int wc, int fr, int fq) const {
;     ...
;         else if (wc == 0) {
; #pragma unroll
;             for (int ai = 0; ai < 2; ++ai)
; #pragma unroll
;                 for (int m = 0; m < 4; ++m) { const float rs = rowscale(ss, row0 + ai * 128 + m * 16);
; #pragma unroll
;                     for (int n = 0; n < 2; ++n) *(f32x4*)(DTR + (size_t)(row0 + ai * 128 + m * 16) * 32 + 8 * fq + 4 * n) = acc[ai][0][m][n] * rs; }
	v_mov_b32_e32 v154, v133
	v_mov_b32_e32 v155, v134
	v_mov_b32_e32 v133, v135
	v_pk_add_f32 v[132:133], v[154:155], v[132:133]
	v_mov_b32_e32 v134, v130
	v_mov_b32_e32 v135, v128
	v_mov_b32_e32 v128, v131
	v_pk_add_f32 v[128:129], v[134:135], v[128:129]
	v_add_f32_e32 v130, v132, v133
	v_add_f32_e32 v129, v130, v129
	v_add_f32_e32 v128, v128, v129
	v_fmamk_f32 v128, v128, 0x3a000000, v199
	v_cmp_gt_f32_e32 vcc, s9, v128
	v_mul_f32_e32 v129, 0x4b800000, v128
	v_lshlrev_b64 v[134:135], 7, v[152:153]
	v_cndmask_b32_e32 v128, v128, v129, vcc
	v_rsq_f32_e32 v128, v128
	v_lshl_add_u64 v[134:135], v[144:145], 0, v[134:135]
	v_or_b32_e32 v152, 48, v150
	v_ashrrev_i32_e32 v153, 31, v152
	v_mul_f32_e32 v129, 0x45800000, v128
	v_cndmask_b32_e32 v132, v128, v129, vcc
	v_pk_mul_f32 v[130:131], v[94:95], v[132:133] op_sel_hi:[1,0]
	v_pk_mul_f32 v[128:129], v[92:93], v[132:133] op_sel_hi:[1,0]
	global_store_dwordx4 v[134:135], v[128:131], off
	s_nop 1
	v_pk_mul_f32 v[130:131], v[90:91], v[132:133] op_sel_hi:[1,0]
	v_pk_mul_f32 v[128:129], v[88:89], v[132:133] op_sel_hi:[1,0]
	global_store_dwordx4 v[134:135], v[128:131], off offset:16
	s_nop 1
	v_lshlrev_b64 v[128:129], 5, v[152:153]
	v_lshl_add_u64 v[132:133], s[0:1], 0, v[128:129]
	global_load_dwordx4 v[128:131], v[132:133], off offset:16
	s_nop 0
	global_load_dwordx4 v[132:135], v[132:133], off
	s_waitcnt vmcnt(0)
	v_mov_b32_e32 v154, v133
	v_mov_b32_e32 v155, v134
	v_mov_b32_e32 v133, v135
	v_pk_add_f32 v[132:133], v[154:155], v[132:133]
	v_mov_b32_e32 v134, v130
	v_mov_b32_e32 v135, v128
	v_mov_b32_e32 v128, v131
	v_pk_add_f32 v[128:129], v[134:135], v[128:129]
	v_add_f32_e32 v130, v132, v133
	v_add_f32_e32 v129, v130, v129
	v_add_f32_e32 v128, v128, v129
	v_fmamk_f32 v128, v128, 0x3a000000, v199
	v_cmp_gt_f32_e32 vcc, s9, v128
	v_mul_f32_e32 v129, 0x4b800000, v128
	v_lshlrev_b64 v[134:135], 7, v[152:153]
	v_cndmask_b32_e32 v128, v128, v129, vcc
	v_rsq_f32_e32 v128, v128
	v_lshl_add_u64 v[134:135], v[144:145], 0, v[134:135]
	v_add_u32_e32 v152, 0x80, v150
	v_ashrrev_i32_e32 v153, 31, v152
	v_mul_f32_e32 v129, 0x45800000, v128
	v_cndmask_b32_e32 v132, v128, v129, vcc
	v_pk_mul_f32 v[130:131], v[78:79], v[132:133] op_sel_hi:[1,0]
	v_pk_mul_f32 v[128:129], v[76:77], v[132:133] op_sel_hi:[1,0]
	global_store_dwordx4 v[134:135], v[128:131], off
	s_nop 1
	v_pk_mul_f32 v[130:131], v[74:75], v[132:133] op_sel_hi:[1,0]
	v_pk_mul_f32 v[128:129], v[72:73], v[132:133] op_sel_hi:[1,0]
	global_store_dwordx4 v[134:135], v[128:131], off offset:16
	s_nop 1
	v_lshlrev_b64 v[128:129], 5, v[152:153]
	v_lshl_add_u64 v[132:133], s[0:1], 0, v[128:129]
	global_load_dwordx4 v[128:131], v[132:133], off offset:16
	s_nop 0
	global_load_dwordx4 v[132:135], v[132:133], off
	s_waitcnt vmcnt(0)
	v_mov_b32_e32 v154, v133
	v_mov_b32_e32 v155, v134
	v_mov_b32_e32 v133, v135
	v_pk_add_f32 v[132:133], v[154:155], v[132:133]
	v_mov_b32_e32 v134, v130
	v_mov_b32_e32 v135, v128
	v_mov_b32_e32 v128, v131
	v_pk_add_f32 v[128:129], v[134:135], v[128:129]
	v_add_f32_e32 v130, v132, v133
	v_add_f32_e32 v129, v130, v129
	v_add_f32_e32 v128, v128, v129
	v_fmamk_f32 v128, v128, 0x3a000000, v199
	v_cmp_gt_f32_e32 vcc, s9, v128
	v_mul_f32_e32 v129, 0x4b800000, v128
	v_lshlrev_b64 v[134:135], 7, v[152:153]
	v_cndmask_b32_e32 v128, v128, v129, vcc
	v_rsq_f32_e32 v128, v128
	v_lshl_add_u64 v[134:135], v[144:145], 0, v[134:135]
	v_add_u32_e32 v152, 0x90, v150
	v_ashrrev_i32_e32 v153, 31, v152
	v_mul_f32_e32 v129, 0x45800000, v128
	v_cndmask_b32_e32 v132, v128, v129, vcc
	v_pk_mul_f32 v[130:131], v[62:63], v[132:133] op_sel_hi:[1,0]
	v_pk_mul_f32 v[128:129], v[60:61], v[132:133] op_sel_hi:[1,0]
	global_store_dwordx4 v[134:135], v[128:131], off
	s_nop 1
	v_pk_mul_f32 v[130:131], v[58:59], v[132:133] op_sel_hi:[1,0]
	v_pk_mul_f32 v[128:129], v[56:57], v[132:133] op_sel_hi:[1,0]
	global_store_dwordx4 v[134:135], v[128:131], off offset:16
	s_nop 1
	v_lshlrev_b64 v[128:129], 5, v[152:153]
	v_lshl_add_u64 v[132:133], s[0:1], 0, v[128:129]
	global_load_dwordx4 v[128:131], v[132:133], off offset:16
	s_nop 0
	global_load_dwordx4 v[132:135], v[132:133], off
	s_waitcnt vmcnt(0)
;     DEV void operator()(AccRef acc, const pg8::Unit& u, int wr, int wc, int fr, int fq) const {
;     ...
;         else if (wc == 0) {
; #pragma unroll
;             for (int ai = 0; ai < 2; ++ai)
; #pragma unroll
;                 for (int m = 0; m < 4; ++m) { const float rs = rowscale(ss, row0 + ai * 128 + m * 16);
; #pragma unroll
;                     for (int n = 0; n < 2; ++n) *(f32x4*)(DTR + (size_t)(row0 + ai * 128 + m * 16) * 32 + 8 * fq + 4 * n) = acc[ai][0][m][n] * rs; }
	v_mov_b32_e32 v154, v133
	v_mov_b32_e32 v155, v134
	v_mov_b32_e32 v133, v135
	v_pk_add_f32 v[132:133], v[154:155], v[132:133]
	v_mov_b32_e32 v134, v130
	v_mov_b32_e32 v135, v128
	v_mov_b32_e32 v128, v131
	v_pk_add_f32 v[128:129], v[134:135], v[128:129]
	v_add_f32_e32 v130, v132, v133
	v_add_f32_e32 v129, v130, v129
	v_add_f32_e32 v128, v128, v129
	v_fmamk_f32 v128, v128, 0x3a000000, v199
	v_cmp_gt_f32_e32 vcc, s9, v128
	v_mul_f32_e32 v129, 0x4b800000, v128
	v_lshlrev_b64 v[134:135], 7, v[152:153]
	v_cndmask_b32_e32 v128, v128, v129, vcc
	v_rsq_f32_e32 v128, v128
	v_lshl_add_u64 v[134:135], v[144:145], 0, v[134:135]
	v_add_u32_e32 v152, 0xa0, v150
	v_ashrrev_i32_e32 v153, 31, v152
	v_mul_f32_e32 v129, 0x45800000, v128
	v_cndmask_b32_e32 v132, v128, v129, vcc
	v_pk_mul_f32 v[130:131], v[46:47], v[132:133] op_sel_hi:[1,0]
	v_pk_mul_f32 v[128:129], v[44:45], v[132:133] op_sel_hi:[1,0]
	global_store_dwordx4 v[134:135], v[128:131], off
	s_nop 1
	v_pk_mul_f32 v[130:131], v[42:43], v[132:133] op_sel_hi:[1,0]
	v_pk_mul_f32 v[128:129], v[40:41], v[132:133] op_sel_hi:[1,0]
	global_store_dwordx4 v[134:135], v[128:131], off offset:16
	s_nop 1
	v_lshlrev_b64 v[128:129], 5, v[152:153]
	v_lshl_add_u64 v[132:133], s[0:1], 0, v[128:129]
	global_load_dwordx4 v[128:131], v[132:133], off offset:16
	s_nop 0
	global_load_dwordx4 v[132:135], v[132:133], off
	s_waitcnt vmcnt(0)
	v_mov_b32_e32 v154, v133
	v_mov_b32_e32 v155, v134
	v_mov_b32_e32 v133, v135
	v_pk_add_f32 v[132:133], v[154:155], v[132:133]
	v_mov_b32_e32 v134, v130
	v_mov_b32_e32 v135, v128
	v_mov_b32_e32 v128, v131
	v_pk_add_f32 v[128:129], v[134:135], v[128:129]
	v_add_f32_e32 v130, v132, v133
	v_add_f32_e32 v129, v130, v129
	v_add_f32_e32 v128, v128, v129
	v_fmamk_f32 v128, v128, 0x3a000000, v199
	v_cmp_gt_f32_e32 vcc, s9, v128
	v_mul_f32_e32 v129, 0x4b800000, v128
	v_lshlrev_b64 v[134:135], 7, v[152:153]
	v_cndmask_b32_e32 v128, v128, v129, vcc
	v_rsq_f32_e32 v128, v128
	v_lshl_add_u64 v[134:135], v[144:145], 0, v[134:135]
	v_add_u32_e32 v152, 0xb0, v150
	v_ashrrev_i32_e32 v153, 31, v152
	v_mul_f32_e32 v129, 0x45800000, v128
	v_cndmask_b32_e32 v132, v128, v129, vcc
	v_pk_mul_f32 v[130:131], v[30:31], v[132:133] op_sel_hi:[1,0]
	v_pk_mul_f32 v[128:129], v[28:29], v[132:133] op_sel_hi:[1,0]
	global_store_dwordx4 v[134:135], v[128:131], off
	s_nop 1
	v_pk_mul_f32 v[130:131], v[26:27], v[132:133] op_sel_hi:[1,0]
	v_pk_mul_f32 v[128:129], v[24:25], v[132:133] op_sel_hi:[1,0]
	global_store_dwordx4 v[134:135], v[128:131], off offset:16
	s_nop 1
	v_lshlrev_b64 v[128:129], 5, v[152:153]
	v_lshl_add_u64 v[132:133], s[0:1], 0, v[128:129]
	global_load_dwordx4 v[128:131], v[132:133], off offset:16
	s_nop 0
	global_load_dwordx4 v[132:135], v[132:133], off
	s_waitcnt vmcnt(0)
	v_mov_b32_e32 v154, v133
	v_mov_b32_e32 v155, v134
	v_mov_b32_e32 v133, v135
	v_pk_add_f32 v[132:133], v[154:155], v[132:133]
	v_mov_b32_e32 v134, v130
	v_mov_b32_e32 v135, v128
	v_mov_b32_e32 v128, v131
	v_pk_add_f32 v[128:129], v[134:135], v[128:129]
	v_add_f32_e32 v130, v132, v133
	v_add_f32_e32 v129, v130, v129
	v_add_f32_e32 v128, v128, v129
	v_fmamk_f32 v128, v128, 0x3a000000, v199
	v_cmp_gt_f32_e32 vcc, s9, v128
	v_mul_f32_e32 v129, 0x4b800000, v128
	v_lshlrev_b64 v[134:135], 7, v[152:153]
	v_cndmask_b32_e32 v128, v128, v129, vcc
	v_rsq_f32_e32 v128, v128
	v_lshl_add_u64 v[134:135], v[144:145], 0, v[134:135]
	v_mul_f32_e32 v129, 0x45800000, v128
	v_cndmask_b32_e32 v132, v128, v129, vcc
	v_pk_mul_f32 v[130:131], v[14:15], v[132:133] op_sel_hi:[1,0]
	v_pk_mul_f32 v[128:129], v[12:13], v[132:133] op_sel_hi:[1,0]
	global_store_dwordx4 v[134:135], v[128:131], off
	s_nop 1
	v_pk_mul_f32 v[130:131], v[10:11], v[132:133] op_sel_hi:[1,0]
	v_pk_mul_f32 v[128:129], v[8:9], v[132:133] op_sel_hi:[1,0]
	global_store_dwordx4 v[134:135], v[128:131], off offset:16

; #define PG8_STAGE(bufoff, gbase, voff) do { _Pragma("unroll") for (int _i = 0; _i < 2; ++_i) \
;         __builtin_amdgcn_global_load_lds((const unsigned*)((const char*)(gbase) + (voff)[_i]), (LAS unsigned*)(lds + (bufoff) + ldsw + _i * 8192), 16, 0, 0); } while (0)
; #define PG8_LDA(dst, b, h) do { _Pragma("unroll") for (int m = 0; m < 4; ++m) _Pragma("unroll") for (int k = 0; k < 2; ++k) dst[m][k] = *(const LAS bf16x8*)(lds + PG8_SA(b, h) + aoff + m * 2048 + k * 1024); } while (0)
; #define PG8_LDB(dst, b, h) do { _Pragma("unroll") for (int n = 0; n < 2; ++n) _Pragma("unroll") for (int k = 0; k < 2; ++k) dst[n][k] = *(const LAS bf16x8*)(lds + PG8_SB(b, h) + boff + n * 2048 + k * 1024); } while (0)
; #define PG8_MMA(ai, bj, At, Bt) do { __builtin_amdgcn_s_setprio(1); _Pragma("unroll") for (int m = 0; m < 4; ++m) _Pragma("unroll") for (int n = 0; n < 2; ++n) _Pragma("unroll") for (int k = 0; k < 2; ++k) \
;         acc[ai][bj][m][n] = __builtin_amdgcn_mfma_f32_16x16x32_bf16(Bt[n][k], At[m][k], acc[ai][bj][m][n], 0, 0, 0); __builtin_amdgcn_s_setprio(0); } while (0)
; #define PG8_WAIT_L(n) asm volatile("s_waitcnt lgkmcnt(" #n ")" ::: "memory")
; #define PG8_BAR __builtin_amdgcn_s_barrier()
; #define PG8_SCHED __builtin_amdgcn_sched_barrier(0)
; template <class Epi>
; DEV void gemm_phase(LAS unsigned char* lds, const Gemm g, const StaticOrder& S, const Epi& E) {
;     ...
;             const bool last = (t == nt - 2);
;             const char* a1 = cA + (size_t)(t + 1) * kstep;
;             const char* a2 = last ? nA : cA + (size_t)(t + 2) * kstep; const char* b2 = last ? nB : cB + (size_t)(t + 2) * kstep;
;             const char* a3 = a2 + kstep; const char* b3 = b2 + kstep;
;             PG8_LDB(B0, 0, 0); PG8_SCHED; PG8_LDA(At, 0, 0); PG8_STAGE(PG8_SA(1, 1), a1 + hstep, voffA);
;             PG8_WAIT_L(8); PG8_BAR; PG8_WAIT_L(0); PG8_MMA(0, 0, At, B0); PG8_BAR; PG8_SCHED;
;             PG8_LDB(B1, 0, 1); PG8_STAGE(PG8_SB(0, 0), b2, voffB);
;             PG8_BAR; PG8_WAIT_L(0); PG8_MMA(0, 1, At, B1); PG8_BAR;
;             PG8_LDA(At, 0, 1); PG8_STAGE(PG8_SA(0, 0), a2, voffA);
;             PG8_BAR; PG8_WAIT_L(0); PG8_MMA(1, 0, At, B0); PG8_BAR; PG8_SCHED;
.LBB0_657:
	s_add_u32 s6, s28, 0x100
	s_addc_u32 s7, s29, 0
	s_add_i32 s55, 0, 0x10000
	v_add_u32_e32 v140, s55, v196
	ds_read_b128 v[128:131], v140
	ds_read_b128 v[132:135], v140 offset:1024
	ds_read_b128 v[136:139], v140 offset:2048
	ds_read_b128 v[140:143], v140 offset:3072
	s_cmpk_eq_i32 s54, 0x54
	s_cselect_b32 s35, s27, s7
	s_cselect_b32 s34, s26, s6
	s_cselect_b32 s31, s9, s53
	s_cselect_b32 s30, s8, s52
	s_add_i32 m0, s41, 0xc000
	ds_read_b128 v[144:147], v219
	ds_read_b128 v[148:151], v219 offset:1024
	ds_read_b128 v[152:155], v219 offset:2048
	ds_read_b128 v[156:159], v219 offset:3072
	ds_read_b128 v[184:187], v219 offset:4096
	ds_read_b128 v[188:191], v219 offset:5120
	ds_read_b128 v[192:195], v219 offset:6144
	ds_read_b128 v[220:223], v219 offset:7168
	global_load_lds_dwordx4 v180, s[28:29]
	s_add_i32 m0, s41, 0xe000
	s_nop 0
	global_load_lds_dwordx4 v182, s[28:29]
	s_waitcnt lgkmcnt(8)
	s_waitcnt vmcnt(10)
	s_barrier
	s_waitcnt lgkmcnt(0)
	v_mfma_f32_16x16x32_bf16 v[124:127], v[128:131], v[144:147], v[124:127]
	v_mfma_f32_16x16x32_bf16 v[120:123], v[136:139], v[144:147], v[120:123]
	v_mfma_f32_16x16x32_bf16 v[112:115], v[128:131], v[152:155], v[112:115]
	v_mfma_f32_16x16x32_bf16 v[104:107], v[136:139], v[152:155], v[104:107]
	v_mfma_f32_16x16x32_bf16 v[92:95], v[128:131], v[184:187], v[92:95]
	v_mfma_f32_16x16x32_bf16 v[88:91], v[136:139], v[184:187], v[88:91]
	v_mfma_f32_16x16x32_bf16 v[80:83], v[128:131], v[192:195], v[80:83]
	v_mfma_f32_16x16x32_bf16 v[72:75], v[136:139], v[192:195], v[72:75]
	v_mfma_f32_16x16x32_bf16 v[124:127], v[132:135], v[148:151], v[124:127]
	v_mfma_f32_16x16x32_bf16 v[120:123], v[140:143], v[148:151], v[120:123]
	v_mfma_f32_16x16x32_bf16 v[112:115], v[132:135], v[156:159], v[112:115]
	v_mfma_f32_16x16x32_bf16 v[104:107], v[140:143], v[156:159], v[104:107]
	v_mfma_f32_16x16x32_bf16 v[92:95], v[132:135], v[188:191], v[92:95]
	v_mfma_f32_16x16x32_bf16 v[88:91], v[140:143], v[188:191], v[88:91]
	v_mfma_f32_16x16x32_bf16 v[80:83], v[132:135], v[220:223], v[80:83]
	v_mfma_f32_16x16x32_bf16 v[72:75], v[140:143], v[220:223], v[72:75]
	s_barrier
	s_add_i32 s56, 0, 0x14000
	v_add_u32_e32 v214, s56, v196
	s_add_i32 s28, s55, s40
	ds_read_b128 v[224:227], v214
	ds_read_b128 v[228:231], v214 offset:1024
	ds_read_b128 v[232:235], v214 offset:2048
	ds_read_b128 v[236:239], v214 offset:3072
	v_lshl_add_u64 v[214:215], s[30:31], 0, v[160:161]
	s_mov_b32 m0, s28
	v_lshl_add_u64 v[216:217], s[30:31], 0, v[178:179]
	global_load_lds_dwordx4 v160, s[30:31]
	s_add_i32 m0, s28, 0x2000
	s_nop 0
	global_load_lds_dwordx4 v178, s[30:31]
	s_waitcnt vmcnt(10)
	s_barrier
	s_waitcnt lgkmcnt(0)
	v_mfma_f32_16x16x32_bf16 v[116:119], v[224:227], v[144:147], v[116:119]
	v_mfma_f32_16x16x32_bf16 v[108:111], v[232:235], v[144:147], v[108:111]
	v_mfma_f32_16x16x32_bf16 v[100:103], v[224:227], v[152:155], v[100:103]
	v_mfma_f32_16x16x32_bf16 v[96:99], v[232:235], v[152:155], v[96:99]
	v_mfma_f32_16x16x32_bf16 v[84:87], v[224:227], v[184:187], v[84:87]
	v_mfma_f32_16x16x32_bf16 v[76:79], v[232:235], v[184:187], v[76:79]
	v_mfma_f32_16x16x32_bf16 v[68:71], v[224:227], v[192:195], v[68:71]
	v_mfma_f32_16x16x32_bf16 v[64:67], v[232:235], v[192:195], v[64:67]
	v_mfma_f32_16x16x32_bf16 v[116:119], v[228:231], v[148:151], v[116:119]
	v_mfma_f32_16x16x32_bf16 v[108:111], v[236:239], v[148:151], v[108:111]
	v_mfma_f32_16x16x32_bf16 v[100:103], v[228:231], v[156:159], v[100:103]
	v_mfma_f32_16x16x32_bf16 v[96:99], v[236:239], v[156:159], v[96:99]
	v_mfma_f32_16x16x32_bf16 v[84:87], v[228:231], v[188:191], v[84:87]
	v_mfma_f32_16x16x32_bf16 v[76:79], v[236:239], v[188:191], v[76:79]
	v_mfma_f32_16x16x32_bf16 v[68:71], v[228:231], v[220:223], v[68:71]
	v_mfma_f32_16x16x32_bf16 v[64:67], v[236:239], v[220:223], v[64:67]
	s_mov_b32 m0, s41
	v_lshl_add_u64 v[240:241], s[34:35], 0, v[174:175]
	s_barrier
	ds_read_b128 v[144:147], v219 offset:16384
	ds_read_b128 v[148:151], v219 offset:17408
	ds_read_b128 v[152:155], v219 offset:18432
	ds_read_b128 v[156:159], v219 offset:19456
	ds_read_b128 v[184:187], v219 offset:20480
	ds_read_b128 v[188:191], v219 offset:21504
	ds_read_b128 v[192:195], v219 offset:22528
	ds_read_b128 v[220:223], v219 offset:23552
	global_load_lds_dwordx4 v174, s[34:35]
	v_lshl_add_u64 v[242:243], s[34:35], 0, v[176:177]
	s_mov_b32 m0, s42
	s_nop 0
	global_load_lds_dwordx4 v176, s[34:35]
	s_barrier
	s_waitcnt lgkmcnt(0)
	v_mfma_f32_16x16x32_bf16 v[60:63], v[128:131], v[144:147], v[60:63]
	v_mfma_f32_16x16x32_bf16 v[56:59], v[136:139], v[144:147], v[56:59]
	v_mfma_f32_16x16x32_bf16 v[48:51], v[128:131], v[152:155], v[48:51]
	v_mfma_f32_16x16x32_bf16 v[40:43], v[136:139], v[152:155], v[40:43]
	v_mfma_f32_16x16x32_bf16 v[28:31], v[128:131], v[184:187], v[28:31]
	v_mfma_f32_16x16x32_bf16 v[24:27], v[136:139], v[184:187], v[24:27]
	v_mfma_f32_16x16x32_bf16 v[16:19], v[128:131], v[192:195], v[16:19]
	v_mfma_f32_16x16x32_bf16 v[8:11], v[136:139], v[192:195], v[8:11]
	v_mfma_f32_16x16x32_bf16 v[60:63], v[132:135], v[148:151], v[60:63]
	v_mfma_f32_16x16x32_bf16 v[56:59], v[140:143], v[148:151], v[56:59]
	v_mfma_f32_16x16x32_bf16 v[48:51], v[132:135], v[156:159], v[48:51]
	v_mfma_f32_16x16x32_bf16 v[40:43], v[140:143], v[156:159], v[40:43]
	v_mfma_f32_16x16x32_bf16 v[28:31], v[132:135], v[188:191], v[28:31]
	v_mfma_f32_16x16x32_bf16 v[24:27], v[140:143], v[188:191], v[24:27]
	v_mfma_f32_16x16x32_bf16 v[16:19], v[132:135], v[220:223], v[16:19]
	v_mfma_f32_16x16x32_bf16 v[8:11], v[140:143], v[220:223], v[8:11]
	s_barrier
; #define PG8_STAGE(bufoff, gbase, voff) do { _Pragma("unroll") for (int _i = 0; _i < 2; ++_i) \
;         __builtin_amdgcn_global_load_lds((const unsigned*)((const char*)(gbase) + (voff)[_i]), (LAS unsigned*)(lds + (bufoff) + ldsw + _i * 8192), 16, 0, 0); } while (0)
; #define PG8_LDA(dst, b, h) do { _Pragma("unroll") for (int m = 0; m < 4; ++m) _Pragma("unroll") for (int k = 0; k < 2; ++k) dst[m][k] = *(const LAS bf16x8*)(lds + PG8_SA(b, h) + aoff + m * 2048 + k * 1024); } while (0)
; #define PG8_LDB(dst, b, h) do { _Pragma("unroll") for (int n = 0; n < 2; ++n) _Pragma("unroll") for (int k = 0; k < 2; ++k) dst[n][k] = *(const LAS bf16x8*)(lds + PG8_SB(b, h) + boff + n * 2048 + k * 1024); } while (0)
; #define PG8_MMA(ai, bj, At, Bt) do { __builtin_amdgcn_s_setprio(1); _Pragma("unroll") for (int m = 0; m < 4; ++m) _Pragma("unroll") for (int n = 0; n < 2; ++n) _Pragma("unroll") for (int k = 0; k < 2; ++k) \
;         acc[ai][bj][m][n] = __builtin_amdgcn_mfma_f32_16x16x32_bf16(Bt[n][k], At[m][k], acc[ai][bj][m][n], 0, 0, 0); __builtin_amdgcn_s_setprio(0); } while (0)
; #define PG8_WAIT_V(n) asm volatile("s_waitcnt vmcnt(" #n ")" ::: "memory")
; #define PG8_WAIT_L(n) asm volatile("s_waitcnt lgkmcnt(" #n ")" ::: "memory")
; #define PG8_BAR __builtin_amdgcn_s_barrier()
; #define PG8_SCHED __builtin_amdgcn_sched_barrier(0)
; template <class Epi>
; DEV void gemm_phase(LAS unsigned char* lds, const Gemm g, const StaticOrder& S, const Epi& E) {
;     ...
;             PG8_STAGE(PG8_SB(0, 1), b2 + hstep, voffB);
;             PG8_WAIT_V(6); PG8_BAR; PG8_MMA(1, 1, At, B1); PG8_BAR;
;             PG8_LDB(B0, 1, 0); PG8_SCHED; PG8_LDA(At, 1, 0); PG8_STAGE(PG8_SA(0, 1), a2 + hstep, voffA);
;             PG8_WAIT_L(8); PG8_BAR; PG8_WAIT_L(0); PG8_MMA(0, 0, At, B0); PG8_BAR; PG8_SCHED;
;             PG8_LDB(B1, 1, 1); PG8_STAGE(PG8_SB(1, 0), b3, voffB);
;             PG8_BAR; PG8_WAIT_L(0); PG8_MMA(0, 1, At, B1); PG8_BAR;
;             PG8_LDA(At, 1, 1); PG8_STAGE(PG8_SA(1, 0), a3, voffA);
	s_add_u32 s28, s30, 0x160000
	s_addc_u32 s29, s31, 0
	s_add_i32 s55, s56, s40
	s_mov_b32 m0, s55
	s_nop 0
	global_load_lds_dwordx4 v160, s[28:29]
	s_add_i32 m0, s55, 0x2000
	s_nop 0
	global_load_lds_dwordx4 v178, s[28:29]
	s_waitcnt vmcnt(10)
	s_barrier
	v_mfma_f32_16x16x32_bf16 v[52:55], v[224:227], v[144:147], v[52:55]
	v_mfma_f32_16x16x32_bf16 v[44:47], v[232:235], v[144:147], v[44:47]
	v_mfma_f32_16x16x32_bf16 v[36:39], v[224:227], v[152:155], v[36:39]
	v_mfma_f32_16x16x32_bf16 v[32:35], v[232:235], v[152:155], v[32:35]
	v_mfma_f32_16x16x32_bf16 v[20:23], v[224:227], v[184:187], v[20:23]
	v_mfma_f32_16x16x32_bf16 v[12:15], v[232:235], v[184:187], v[12:15]
	v_mfma_f32_16x16x32_bf16 v[4:7], v[224:227], v[192:195], v[4:7]
	v_mfma_f32_16x16x32_bf16 v[0:3], v[232:235], v[192:195], v[0:3]
	v_mfma_f32_16x16x32_bf16 v[52:55], v[228:231], v[148:151], v[52:55]
	v_mfma_f32_16x16x32_bf16 v[44:47], v[236:239], v[148:151], v[44:47]
	v_mfma_f32_16x16x32_bf16 v[36:39], v[228:231], v[156:159], v[36:39]
	v_mfma_f32_16x16x32_bf16 v[32:35], v[236:239], v[156:159], v[32:35]
	v_mfma_f32_16x16x32_bf16 v[20:23], v[228:231], v[188:191], v[20:23]
	v_mfma_f32_16x16x32_bf16 v[12:15], v[236:239], v[188:191], v[12:15]
	v_mfma_f32_16x16x32_bf16 v[4:7], v[228:231], v[220:223], v[4:7]
	v_mfma_f32_16x16x32_bf16 v[0:3], v[236:239], v[220:223], v[0:3]
	s_add_i32 s55, 0, 0x18000
	v_add_u32_e32 v140, s55, v196
	s_barrier
	ds_read_b128 v[128:131], v140
	ds_read_b128 v[132:135], v140 offset:1024
	ds_read_b128 v[136:139], v140 offset:2048
	ds_read_b128 v[140:143], v140 offset:3072
	s_add_u32 s28, s34, 0x160000
	s_addc_u32 s29, s35, 0
	s_mov_b32 m0, s43
	ds_read_b128 v[144:147], v219 offset:32768
	ds_read_b128 v[148:151], v219 offset:33792
	ds_read_b128 v[152:155], v219 offset:34816
	ds_read_b128 v[156:159], v219 offset:35840
	ds_read_b128 v[184:187], v219 offset:36864
	ds_read_b128 v[188:191], v219 offset:37888
	ds_read_b128 v[192:195], v219 offset:38912
	ds_read_b128 v[220:223], v219 offset:39936
	global_load_lds_dwordx4 v174, s[28:29]
	s_mov_b32 m0, s44
	s_nop 0
	global_load_lds_dwordx4 v176, s[28:29]
	s_waitcnt lgkmcnt(8)
	s_waitcnt vmcnt(10)
	s_barrier
	s_waitcnt lgkmcnt(0)
	v_mfma_f32_16x16x32_bf16 v[124:127], v[128:131], v[144:147], v[124:127]
	v_mfma_f32_16x16x32_bf16 v[120:123], v[136:139], v[144:147], v[120:123]
	v_mfma_f32_16x16x32_bf16 v[112:115], v[128:131], v[152:155], v[112:115]
	v_mfma_f32_16x16x32_bf16 v[104:107], v[136:139], v[152:155], v[104:107]
	v_mfma_f32_16x16x32_bf16 v[92:95], v[128:131], v[184:187], v[92:95]
	v_mfma_f32_16x16x32_bf16 v[88:91], v[136:139], v[184:187], v[88:91]
	v_mfma_f32_16x16x32_bf16 v[80:83], v[128:131], v[192:195], v[80:83]
	v_mfma_f32_16x16x32_bf16 v[72:75], v[136:139], v[192:195], v[72:75]
	v_mfma_f32_16x16x32_bf16 v[124:127], v[132:135], v[148:151], v[124:127]
	v_mfma_f32_16x16x32_bf16 v[120:123], v[140:143], v[148:151], v[120:123]
	v_mfma_f32_16x16x32_bf16 v[112:115], v[132:135], v[156:159], v[112:115]
	v_mfma_f32_16x16x32_bf16 v[104:107], v[140:143], v[156:159], v[104:107]
	v_mfma_f32_16x16x32_bf16 v[92:95], v[132:135], v[188:191], v[92:95]
	v_mfma_f32_16x16x32_bf16 v[88:91], v[140:143], v[188:191], v[88:91]
	v_mfma_f32_16x16x32_bf16 v[80:83], v[132:135], v[220:223], v[80:83]
	v_mfma_f32_16x16x32_bf16 v[72:75], v[140:143], v[220:223], v[72:75]
	s_barrier
	s_add_i32 s34, 0, 0x1c000
	s_add_i32 s28, s55, s40
	v_add_u32_e32 v236, s34, v196
	v_lshl_add_u64 v[214:215], v[214:215], 0, s[2:3]
	s_mov_b32 m0, s28
	ds_read_b128 v[224:227], v236
	ds_read_b128 v[228:231], v236 offset:1024
	ds_read_b128 v[232:235], v236 offset:2048
	ds_read_b128 v[236:239], v236 offset:3072
	global_load_lds_dwordx4 v[214:215], off
	v_lshl_add_u64 v[214:215], v[216:217], 0, s[2:3]
	s_add_i32 m0, s28, 0x2000
	s_nop 0
	global_load_lds_dwordx4 v[214:215], off
	s_waitcnt vmcnt(10)
	s_barrier
	s_waitcnt lgkmcnt(0)
	v_mfma_f32_16x16x32_bf16 v[116:119], v[224:227], v[144:147], v[116:119]
	v_mfma_f32_16x16x32_bf16 v[108:111], v[232:235], v[144:147], v[108:111]
	v_mfma_f32_16x16x32_bf16 v[100:103], v[224:227], v[152:155], v[100:103]
	v_mfma_f32_16x16x32_bf16 v[96:99], v[232:235], v[152:155], v[96:99]
	v_mfma_f32_16x16x32_bf16 v[84:87], v[224:227], v[184:187], v[84:87]
	v_mfma_f32_16x16x32_bf16 v[76:79], v[232:235], v[184:187], v[76:79]
	v_mfma_f32_16x16x32_bf16 v[68:71], v[224:227], v[192:195], v[68:71]
	v_mfma_f32_16x16x32_bf16 v[64:67], v[232:235], v[192:195], v[64:67]
	v_mfma_f32_16x16x32_bf16 v[116:119], v[228:231], v[148:151], v[116:119]
	v_mfma_f32_16x16x32_bf16 v[108:111], v[236:239], v[148:151], v[108:111]
	v_mfma_f32_16x16x32_bf16 v[100:103], v[228:231], v[156:159], v[100:103]
	v_mfma_f32_16x16x32_bf16 v[96:99], v[236:239], v[156:159], v[96:99]
	v_mfma_f32_16x16x32_bf16 v[84:87], v[228:231], v[188:191], v[84:87]
	v_mfma_f32_16x16x32_bf16 v[76:79], v[236:239], v[188:191], v[76:79]
	v_mfma_f32_16x16x32_bf16 v[68:71], v[228:231], v[220:223], v[68:71]
	v_mfma_f32_16x16x32_bf16 v[64:67], v[236:239], v[220:223], v[64:67]
	s_mov_b32 m0, s45
	v_lshl_add_u64 v[214:215], v[240:241], 0, s[2:3]
	s_barrier
	ds_read_b128 v[144:147], v219 offset:49152
	ds_read_b128 v[148:151], v219 offset:50176
	ds_read_b128 v[152:155], v219 offset:51200
	ds_read_b128 v[156:159], v219 offset:52224
	ds_read_b128 v[184:187], v219 offset:53248
	ds_read_b128 v[188:191], v219 offset:54272
	ds_read_b128 v[192:195], v219 offset:55296
	ds_read_b128 v[220:223], v219 offset:56320
	global_load_lds_dwordx4 v[214:215], off
	v_lshl_add_u64 v[214:215], v[242:243], 0, s[2:3]
	s_mov_b32 m0, s46
	s_nop 0
	global_load_lds_dwordx4 v[214:215], off
	s_barrier
; DEV bf16x8 pack8(f32x4 a, f32x4 b) { u32x4 w; w.x = cvt_pk_bf16(a[0], a[1]); w.y = cvt_pk_bf16(a[2], a[3]); w.z = cvt_pk_bf16(b[0], b[1]); w.w = cvt_pk_bf16(b[2], b[3]); return __builtin_bit_cast(bf16x8, w); }
; #define PG8_WAIT_V(n) asm volatile("s_waitcnt vmcnt(" #n ")" ::: "memory")
; #define PG8_WAIT_L(n) asm volatile("s_waitcnt lgkmcnt(" #n ")" ::: "memory")
; #define PG8_BAR __builtin_amdgcn_s_barrier()
; #define PG8_SCHED __builtin_amdgcn_sched_barrier(0)
; template <class Epi>
; DEV void gemm_phase(LAS unsigned char* lds, const Gemm g, const StaticOrder& S, const Epi& E) {
;     ...
;             PG8_BAR; PG8_WAIT_L(0); PG8_MMA(1, 0, At, B0); PG8_BAR; PG8_SCHED;
;             PG8_STAGE(PG8_SB(1, 1), b3 + hstep, voffB);
;             PG8_WAIT_V(6); PG8_BAR; PG8_MMA(1, 1, At, B1); PG8_BAR;
;     DEV void operator()(AccRef acc, const pg8::Unit& u, int wr, int wc, int fr, int fq) const {
;         const int row0 = u.pm * 256 + wr * 64 + fr, col0 = u.pn * 256 + wc * 32 + 8 * fq;
; #pragma unroll
;         for (int am = 0; am < 4; ++am) { const int ai = am >> 1, m0 = (am & 1) * 2;
;             f32x4 bv[4][2][2];
; #pragma unroll
;             for (int m = m0; m < m0 + 2; ++m)
; #pragma unroll
;                 for (int bj = 0; bj < 2; ++bj)
; #pragma unroll
;                     for (int n = 0; n < 2; ++n) bv[m][bj][n] = *(const f32x4*)(base + (size_t)(row0 + ai * 128 + m * 16) * 2048 + col0 + bj * 128 + n * 4);
; #pragma unroll
;             for (int m = m0; m < m0 + 2; ++m) { const size_t off = (size_t)(row0 + ai * 128 + m * 16) * 2048 + col0; float sq = 0.f;
; #pragma unroll
;                 for (int bj = 0; bj < 2; ++bj) { const f32x4 o0 = bv[m][bj][0] + scale * acc[ai][bj][m][0], o1 = bv[m][bj][1] + scale * acc[ai][bj][m][1];
;                     *(f32x4*)(out + off + bj * 128) = o0; *(f32x4*)(out + off + bj * 128 + 4) = o1;
;                     if (xb) { *(u32x4*)(xb + off + bj * 128) = __builtin_bit_cast(u32x4, pack8(o0, o1));
;                         sq += (o0[0] * o0[0] + o0[1] * o0[1] + o0[2] * o0[2] + o0[3] * o0[3]) + (o1[0] * o1[0] + o1[1] * o1[1] + o1[2] * o1[2] + o1[3] * o1[3]); } }
;                 if (ssout) { sq += __shfl_xor(sq, 16); sq += __shfl_xor(sq, 32);
;                     if (fq == 0) { if (red) red[(ai * 128 + wr * 64 + m * 16 + fr) * 4 + wc] = sq; else atomicAdd(ssout + (size_t)(row0 + ai * 128 + m * 16) * 8 + u.pn, sq); } } }
	s_waitcnt lgkmcnt(0)
	v_mfma_f32_16x16x32_bf16 v[60:63], v[128:131], v[144:147], v[60:63]
	v_mfma_f32_16x16x32_bf16 v[56:59], v[136:139], v[144:147], v[56:59]
	v_mfma_f32_16x16x32_bf16 v[48:51], v[128:131], v[152:155], v[48:51]
	v_mfma_f32_16x16x32_bf16 v[40:43], v[136:139], v[152:155], v[40:43]
	v_mfma_f32_16x16x32_bf16 v[28:31], v[128:131], v[184:187], v[28:31]
	v_mfma_f32_16x16x32_bf16 v[24:27], v[136:139], v[184:187], v[24:27]
	v_mfma_f32_16x16x32_bf16 v[16:19], v[128:131], v[192:195], v[16:19]
	v_mfma_f32_16x16x32_bf16 v[8:11], v[136:139], v[192:195], v[8:11]
	v_mfma_f32_16x16x32_bf16 v[60:63], v[132:135], v[148:151], v[60:63]
	v_mfma_f32_16x16x32_bf16 v[56:59], v[140:143], v[148:151], v[56:59]
	v_mfma_f32_16x16x32_bf16 v[48:51], v[132:135], v[156:159], v[48:51]
	v_mfma_f32_16x16x32_bf16 v[40:43], v[140:143], v[156:159], v[40:43]
	v_mfma_f32_16x16x32_bf16 v[28:31], v[132:135], v[188:191], v[28:31]
	v_mfma_f32_16x16x32_bf16 v[24:27], v[140:143], v[188:191], v[24:27]
	v_mfma_f32_16x16x32_bf16 v[16:19], v[132:135], v[220:223], v[16:19]
	v_mfma_f32_16x16x32_bf16 v[8:11], v[140:143], v[220:223], v[8:11]
	s_barrier
	s_add_u32 s28, s30, 0x160080
	s_addc_u32 s29, s31, 0
	s_add_i32 s30, s34, s40
	s_mov_b32 m0, s30
	s_nop 0
	global_load_lds_dwordx4 v160, s[28:29]
	s_add_i32 m0, s30, 0x2000
	s_nop 0
	global_load_lds_dwordx4 v178, s[28:29]
	s_waitcnt vmcnt(10)
	s_barrier
	v_mfma_f32_16x16x32_bf16 v[52:55], v[224:227], v[144:147], v[52:55]
	v_mfma_f32_16x16x32_bf16 v[44:47], v[232:235], v[144:147], v[44:47]
	v_mfma_f32_16x16x32_bf16 v[36:39], v[224:227], v[152:155], v[36:39]
	v_mfma_f32_16x16x32_bf16 v[32:35], v[232:235], v[152:155], v[32:35]
	v_mfma_f32_16x16x32_bf16 v[20:23], v[224:227], v[184:187], v[20:23]
	v_mfma_f32_16x16x32_bf16 v[12:15], v[232:235], v[184:187], v[12:15]
	v_mfma_f32_16x16x32_bf16 v[4:7], v[224:227], v[192:195], v[4:7]
	v_mfma_f32_16x16x32_bf16 v[0:3], v[232:235], v[192:195], v[0:3]
	v_mfma_f32_16x16x32_bf16 v[52:55], v[228:231], v[148:151], v[52:55]
	v_mfma_f32_16x16x32_bf16 v[44:47], v[236:239], v[148:151], v[44:47]
	v_mfma_f32_16x16x32_bf16 v[36:39], v[228:231], v[156:159], v[36:39]
	v_mfma_f32_16x16x32_bf16 v[32:35], v[236:239], v[156:159], v[32:35]
	v_mfma_f32_16x16x32_bf16 v[20:23], v[228:231], v[188:191], v[20:23]
	v_mfma_f32_16x16x32_bf16 v[12:15], v[236:239], v[188:191], v[12:15]
	v_mfma_f32_16x16x32_bf16 v[4:7], v[228:231], v[220:223], v[4:7]
	v_mfma_f32_16x16x32_bf16 v[0:3], v[236:239], v[220:223], v[0:3]
	s_add_i32 s54, s54, 2
	s_add_u32 s52, s52, 0x100
	s_addc_u32 s53, s53, 0
	s_cmpk_gt_u32 s54, 0x55
	s_mov_b64 s[28:29], s[6:7]
	s_barrier
	s_cbranch_scc0 .LBB0_657
	v_lshl_add_u32 v186, s23, 8, v167
	v_lshl_or_b32 v184, s22, 8, v197
	v_ashrrev_i32_e32 v185, 31, v184
	v_ashrrev_i32_e32 v187, 31, v186
	v_lshl_add_u64 v[188:189], v[184:185], 2, s[24:25]
	v_lshlrev_b64 v[128:129], 13, v[186:187]
	v_or_b32_e32 v190, 16, v186
	v_lshl_add_u64 v[128:129], v[188:189], 0, v[128:129]
	v_ashrrev_i32_e32 v191, 31, v190
	global_load_dwordx4 v[152:155], v[128:129], off offset:16
	global_load_dwordx4 v[156:159], v[128:129], off
	global_load_dwordx4 v[144:147], v[128:129], off offset:528
	global_load_dwordx4 v[148:151], v[128:129], off offset:512
	v_lshlrev_b64 v[128:129], 13, v[190:191]
	v_lshl_add_u64 v[132:133], v[188:189], 0, v[128:129]
	global_load_dwordx4 v[136:139], v[132:133], off offset:16
	global_load_dwordx4 v[140:143], v[132:133], off
	global_load_dwordx4 v[128:131], v[132:133], off offset:528
	s_nop 0
	global_load_dwordx4 v[132:135], v[132:133], off offset:512
	v_lshlrev_b64 v[192:193], 11, v[186:187]
	v_lshl_add_u64 v[194:195], v[192:193], 0, v[184:185]
	s_ashr_i32 s23, s22, 31
	v_lshl_add_u64 v[192:193], v[194:195], 2, s[68:69]
	s_mov_b64 s[28:29], -1
	s_andn2_b64 vcc, exec, s[18:19]
	s_waitcnt vmcnt(0)
	v_pk_fma_f32 v[152:153], v[120:121], 0.5, v[152:153] op_sel_hi:[1,0,1]
	v_cndmask_b32_e64 v120, 0, 1, s[18:19]
	v_pk_fma_f32 v[158:159], v[126:127], 0.5, v[158:159] op_sel_hi:[1,0,1]
	v_pk_fma_f32 v[156:157], v[124:125], 0.5, v[156:157] op_sel_hi:[1,0,1]
	v_pk_fma_f32 v[154:155], v[122:123], 0.5, v[154:155] op_sel_hi:[1,0,1]
	v_cmp_ne_u32_e64 s[6:7], 1, v120
	v_pk_fma_f32 v[120:121], v[116:117], 0.5, v[148:149] op_sel_hi:[1,0,1]
	v_pk_fma_f32 v[124:125], v[108:109], 0.5, v[144:145] op_sel_hi:[1,0,1]
	global_store_dwordx4 v[192:193], v[156:159], off
	global_store_dwordx4 v[192:193], v[152:155], off offset:16
	s_cbranch_vccnz .LBB0_665
	v_mul_f32_e32 v108, v157, v157
	v_mul_f32_e32 v109, v153, v153
	v_fmac_f32_e32 v108, v156, v156
	v_fmac_f32_e32 v109, v152, v152
	v_fmac_f32_e32 v108, v158, v158
	v_fmac_f32_e32 v109, v154, v154
	v_fmac_f32_e32 v108, v159, v159
	v_fmac_f32_e32 v109, v155, v155
	v_add_f32_e32 v108, v108, v109
	v_mul_f32_e32 v109, v121, v121
	v_mul_f32_e32 v144, v125, v125
	v_pk_fma_f32 v[122:123], v[118:119], 0.5, v[150:151] op_sel_hi:[1,0,1]
	v_pk_fma_f32 v[126:127], v[110:111], 0.5, v[146:147] op_sel_hi:[1,0,1]
	v_fmac_f32_e32 v109, v120, v120
	v_fmac_f32_e32 v144, v124, v124
	v_fmac_f32_e32 v109, v122, v122
	v_fmac_f32_e32 v144, v126, v126
	v_fmac_f32_e32 v109, v123, v123
	v_fmac_f32_e32 v144, v127, v127
	v_add_f32_e32 v109, v109, v144
	v_cmp_lt_i32_e32 vcc, v208, v206
	v_add_f32_e32 v108, v108, v109
	v_readlane_b32 s28, v250, 9
	v_cndmask_b32_e32 v109, v204, v208, vcc
	v_lshlrev_b32_e32 v109, 2, v109
	ds_bpermute_b32 v109, v109, v108
	v_cmp_lt_i32_e32 vcc, v207, v206
	v_readlane_b32 s29, v250, 10
	v_cvt_pk_bf16_f32 v220, v156, v157
	v_cvt_pk_bf16_f32 v221, v158, v159
	s_waitcnt lgkmcnt(0)
	v_add_f32_e32 v108, v108, v109
	v_cndmask_b32_e32 v109, v204, v207, vcc
	v_lshlrev_b32_e32 v109, 2, v109
	ds_bpermute_b32 v109, v109, v108
	v_cvt_pk_bf16_f32 v222, v152, v153
	v_cvt_pk_bf16_f32 v223, v154, v155
	v_lshl_add_u64 v[116:117], v[194:195], 1, s[28:29]
	v_cvt_pk_bf16_f32 v152, v120, v121
	v_cvt_pk_bf16_f32 v153, v122, v123
	v_cvt_pk_bf16_f32 v154, v124, v125
	v_cvt_pk_bf16_f32 v155, v126, v127
	global_store_dwordx4 v[116:117], v[220:223], off
	global_store_dwordx4 v[192:193], v[120:123], off offset:512
	global_store_dwordx4 v[192:193], v[124:127], off offset:528
	global_store_dwordx4 v[116:117], v[152:155], off offset:256
	s_and_saveexec_b64 s[28:29], s[10:11]
	s_cbranch_execz .LBB0_664
	s_waitcnt lgkmcnt(0)
	v_add_f32_e32 v108, v108, v109
	s_andn2_b64 vcc, exec, s[20:21]
	s_mov_b64 s[30:31], -1
	s_cbranch_vccnz .LBB0_662
	s_mov_b64 s[30:31], 0
	ds_write_b32 v218, v108

; #define PG8_STAGE(bufoff, gbase, voff) do { _Pragma("unroll") for (int _i = 0; _i < 2; ++_i) \
;         __builtin_amdgcn_global_load_lds((const unsigned*)((const char*)(gbase) + (voff)[_i]), (LAS unsigned*)(lds + (bufoff) + ldsw + _i * 8192), 16, 0, 0); } while (0)
; #define PG8_LDA(dst, b, h) do { _Pragma("unroll") for (int m = 0; m < 4; ++m) _Pragma("unroll") for (int k = 0; k < 2; ++k) dst[m][k] = *(const LAS bf16x8*)(lds + PG8_SA(b, h) + aoff + m * 2048 + k * 1024); } while (0)
; #define PG8_LDB(dst, b, h) do { _Pragma("unroll") for (int n = 0; n < 2; ++n) _Pragma("unroll") for (int k = 0; k < 2; ++k) dst[n][k] = *(const LAS bf16x8*)(lds + PG8_SB(b, h) + boff + n * 2048 + k * 1024); } while (0)
; #define PG8_MMA(ai, bj, At, Bt) do { __builtin_amdgcn_s_setprio(1); _Pragma("unroll") for (int m = 0; m < 4; ++m) _Pragma("unroll") for (int n = 0; n < 2; ++n) _Pragma("unroll") for (int k = 0; k < 2; ++k) \
;         acc[ai][bj][m][n] = __builtin_amdgcn_mfma_f32_16x16x32_bf16(Bt[n][k], At[m][k], acc[ai][bj][m][n], 0, 0, 0); __builtin_amdgcn_s_setprio(0); } while (0)
; #define PG8_WAIT_V(n) asm volatile("s_waitcnt vmcnt(" #n ")" ::: "memory")
; #define PG8_WAIT_L(n) asm volatile("s_waitcnt lgkmcnt(" #n ")" ::: "memory")
; #define PG8_BAR __builtin_amdgcn_s_barrier()
; template <class Epi>
; DEV void gemm_phase(LAS unsigned char* lds, const Gemm g, const StaticOrder& S, const Epi& E) {
;     ...
;         for (int t = 0; t < nt; t += 2) {
;             const bool last = (t == nt - 2);
;             const char* a1 = cA + (size_t)(t + 1) * kstep;
;             const char* a2 = last ? nA : cA + (size_t)(t + 2) * kstep; const char* b2 = last ? nB : cB + (size_t)(t + 2) * kstep;
;             const char* a3 = a2 + kstep; const char* b3 = b2 + kstep;
;             PG8_LDB(B0, 0, 0); PG8_SCHED; PG8_LDA(At, 0, 0); PG8_STAGE(PG8_SA(1, 1), a1 + hstep, voffA);
;             PG8_WAIT_L(8); PG8_BAR; PG8_WAIT_L(0); PG8_MMA(0, 0, At, B0); PG8_BAR; PG8_SCHED;
;             PG8_LDB(B1, 0, 1); PG8_STAGE(PG8_SB(0, 0), b2, voffB);
;             PG8_BAR; PG8_WAIT_L(0); PG8_MMA(0, 1, At, B1); PG8_BAR;
;             PG8_LDA(At, 0, 1); PG8_STAGE(PG8_SA(0, 0), a2, voffA);
;             PG8_BAR; PG8_WAIT_L(0); PG8_MMA(1, 0, At, B0); PG8_BAR; PG8_SCHED;
;             PG8_STAGE(PG8_SB(0, 1), b2 + hstep, voffB);
;             PG8_WAIT_V(6); PG8_BAR; PG8_MMA(1, 1, At, B1); PG8_BAR;
.LBB0_755:
	s_add_u32 s22, s20, 0xfff80080
	s_addc_u32 s23, s21, -1
	s_add_i32 s47, 0, 0x10000
	v_add_u32_e32 v146, s47, v155
	ds_read_b128 v[128:131], v146
	ds_read_b128 v[132:135], v146 offset:1024
	ds_read_b128 v[150:153], v146 offset:2048
	ds_read_b128 v[174:177], v146 offset:3072
	s_cmp_eq_u32 s46, 28
	s_cselect_b32 s25, s5, s23
	s_cselect_b32 s24, s15, s22
	s_cselect_b32 s23, s11, s45
	s_cselect_b32 s22, s43, s44
	s_add_i32 m0, s34, 0xc000
	ds_read_b128 v[178:181], v167
	ds_read_b128 v[182:185], v167 offset:1024
	ds_read_b128 v[186:189], v167 offset:2048
	ds_read_b128 v[190:193], v167 offset:3072
	ds_read_b128 v[194:197], v167 offset:4096
	ds_read_b128 v[218:221], v167 offset:5120
	ds_read_b128 v[222:225], v167 offset:6144
	ds_read_b128 v[226:229], v167 offset:7168
	global_load_lds_dwordx4 v142, s[20:21]
	s_add_i32 m0, s34, 0xe000
	s_nop 0
	global_load_lds_dwordx4 v144, s[20:21]
	s_waitcnt lgkmcnt(8)
	s_waitcnt vmcnt(10)
	s_barrier
	s_waitcnt lgkmcnt(0)
	v_mfma_f32_16x16x32_bf16 v[124:127], v[128:131], v[178:181], v[124:127]
	v_mfma_f32_16x16x32_bf16 v[116:119], v[150:153], v[178:181], v[116:119]
	v_mfma_f32_16x16x32_bf16 v[108:111], v[128:131], v[186:189], v[108:111]
	v_mfma_f32_16x16x32_bf16 v[100:103], v[150:153], v[186:189], v[100:103]
	v_mfma_f32_16x16x32_bf16 v[92:95], v[128:131], v[194:197], v[92:95]
	v_mfma_f32_16x16x32_bf16 v[84:87], v[150:153], v[194:197], v[84:87]
	v_mfma_f32_16x16x32_bf16 v[76:79], v[128:131], v[222:225], v[76:79]
	v_mfma_f32_16x16x32_bf16 v[68:71], v[150:153], v[222:225], v[68:71]
	v_mfma_f32_16x16x32_bf16 v[124:127], v[132:135], v[182:185], v[124:127]
	v_mfma_f32_16x16x32_bf16 v[116:119], v[174:177], v[182:185], v[116:119]
	v_mfma_f32_16x16x32_bf16 v[108:111], v[132:135], v[190:193], v[108:111]
	v_mfma_f32_16x16x32_bf16 v[100:103], v[174:177], v[190:193], v[100:103]
	v_mfma_f32_16x16x32_bf16 v[92:95], v[132:135], v[218:221], v[92:95]
	v_mfma_f32_16x16x32_bf16 v[84:87], v[174:177], v[218:221], v[84:87]
	v_mfma_f32_16x16x32_bf16 v[76:79], v[132:135], v[226:229], v[76:79]
	v_mfma_f32_16x16x32_bf16 v[68:71], v[174:177], v[226:229], v[68:71]
	s_barrier
	s_add_i32 s50, 0, 0x14000
	v_add_u32_e32 v146, s50, v155
	s_add_i32 s47, s47, s30
	ds_read_b128 v[230:233], v146
	ds_read_b128 v[234:237], v146 offset:1024
	ds_read_b128 v[238:241], v146 offset:2048
	ds_read_b128 v[242:245], v146 offset:3072
	v_lshl_add_u64 v[146:147], s[22:23], 0, v[160:161]
	s_mov_b32 m0, s47
	v_lshl_add_u64 v[158:159], s[22:23], 0, v[136:137]
	global_load_lds_dwordx4 v160, s[22:23]
	s_add_i32 m0, s47, 0x2000
	s_nop 0
	global_load_lds_dwordx4 v136, s[22:23]
	s_waitcnt vmcnt(10)
	s_barrier
	s_waitcnt lgkmcnt(0)
	v_mfma_f32_16x16x32_bf16 v[120:123], v[230:233], v[178:181], v[120:123]
	v_mfma_f32_16x16x32_bf16 v[112:115], v[238:241], v[178:181], v[112:115]
	v_mfma_f32_16x16x32_bf16 v[104:107], v[230:233], v[186:189], v[104:107]
	v_mfma_f32_16x16x32_bf16 v[96:99], v[238:241], v[186:189], v[96:99]
	v_mfma_f32_16x16x32_bf16 v[88:91], v[230:233], v[194:197], v[88:91]
	v_mfma_f32_16x16x32_bf16 v[80:83], v[238:241], v[194:197], v[80:83]
	v_mfma_f32_16x16x32_bf16 v[72:75], v[230:233], v[222:225], v[72:75]
	v_mfma_f32_16x16x32_bf16 v[64:67], v[238:241], v[222:225], v[64:67]
	v_mfma_f32_16x16x32_bf16 v[120:123], v[234:237], v[182:185], v[120:123]
	v_mfma_f32_16x16x32_bf16 v[112:115], v[242:245], v[182:185], v[112:115]
	v_mfma_f32_16x16x32_bf16 v[104:107], v[234:237], v[190:193], v[104:107]
	v_mfma_f32_16x16x32_bf16 v[96:99], v[242:245], v[190:193], v[96:99]
	v_mfma_f32_16x16x32_bf16 v[88:91], v[234:237], v[218:221], v[88:91]
	v_mfma_f32_16x16x32_bf16 v[80:83], v[242:245], v[218:221], v[80:83]
	v_mfma_f32_16x16x32_bf16 v[72:75], v[234:237], v[226:229], v[72:75]
	v_mfma_f32_16x16x32_bf16 v[64:67], v[242:245], v[226:229], v[64:67]
	s_mov_b32 m0, s34
	v_lshl_add_u64 v[214:215], s[24:25], 0, v[140:141]
	s_barrier
	ds_read_b128 v[178:181], v167 offset:16384
	ds_read_b128 v[182:185], v167 offset:17408
	ds_read_b128 v[186:189], v167 offset:18432
	ds_read_b128 v[190:193], v167 offset:19456
	ds_read_b128 v[194:197], v167 offset:20480
	ds_read_b128 v[218:221], v167 offset:21504
	ds_read_b128 v[222:225], v167 offset:22528
	ds_read_b128 v[226:229], v167 offset:23552
	global_load_lds_dwordx4 v140, s[24:25]
	v_lshl_add_u64 v[216:217], s[24:25], 0, v[138:139]
	s_mov_b32 m0, s35
	s_nop 0
	global_load_lds_dwordx4 v138, s[24:25]
	s_barrier
	s_waitcnt lgkmcnt(0)
	v_mfma_f32_16x16x32_bf16 v[60:63], v[128:131], v[178:181], v[60:63]
	v_mfma_f32_16x16x32_bf16 v[52:55], v[150:153], v[178:181], v[52:55]
	v_mfma_f32_16x16x32_bf16 v[44:47], v[128:131], v[186:189], v[44:47]
	v_mfma_f32_16x16x32_bf16 v[36:39], v[150:153], v[186:189], v[36:39]
	v_mfma_f32_16x16x32_bf16 v[28:31], v[128:131], v[194:197], v[28:31]
	v_mfma_f32_16x16x32_bf16 v[20:23], v[150:153], v[194:197], v[20:23]
	v_mfma_f32_16x16x32_bf16 v[12:15], v[128:131], v[222:225], v[12:15]
	v_mfma_f32_16x16x32_bf16 v[4:7], v[150:153], v[222:225], v[4:7]
	v_mfma_f32_16x16x32_bf16 v[60:63], v[132:135], v[182:185], v[60:63]
	v_mfma_f32_16x16x32_bf16 v[52:55], v[174:177], v[182:185], v[52:55]
	v_mfma_f32_16x16x32_bf16 v[44:47], v[132:135], v[190:193], v[44:47]
	v_mfma_f32_16x16x32_bf16 v[36:39], v[174:177], v[190:193], v[36:39]
	v_mfma_f32_16x16x32_bf16 v[28:31], v[132:135], v[218:221], v[28:31]
	v_mfma_f32_16x16x32_bf16 v[20:23], v[174:177], v[218:221], v[20:23]
	v_mfma_f32_16x16x32_bf16 v[12:15], v[132:135], v[226:229], v[12:15]
	v_mfma_f32_16x16x32_bf16 v[4:7], v[174:177], v[226:229], v[4:7]
	s_barrier
; #define PG8_STAGE(bufoff, gbase, voff) do { _Pragma("unroll") for (int _i = 0; _i < 2; ++_i) \
;         __builtin_amdgcn_global_load_lds((const unsigned*)((const char*)(gbase) + (voff)[_i]), (LAS unsigned*)(lds + (bufoff) + ldsw + _i * 8192), 16, 0, 0); } while (0)
; #define PG8_LDA(dst, b, h) do { _Pragma("unroll") for (int m = 0; m < 4; ++m) _Pragma("unroll") for (int k = 0; k < 2; ++k) dst[m][k] = *(const LAS bf16x8*)(lds + PG8_SA(b, h) + aoff + m * 2048 + k * 1024); } while (0)
; #define PG8_LDB(dst, b, h) do { _Pragma("unroll") for (int n = 0; n < 2; ++n) _Pragma("unroll") for (int k = 0; k < 2; ++k) dst[n][k] = *(const LAS bf16x8*)(lds + PG8_SB(b, h) + boff + n * 2048 + k * 1024); } while (0)
; #define PG8_MMA(ai, bj, At, Bt) do { __builtin_amdgcn_s_setprio(1); _Pragma("unroll") for (int m = 0; m < 4; ++m) _Pragma("unroll") for (int n = 0; n < 2; ++n) _Pragma("unroll") for (int k = 0; k < 2; ++k) \
;         acc[ai][bj][m][n] = __builtin_amdgcn_mfma_f32_16x16x32_bf16(Bt[n][k], At[m][k], acc[ai][bj][m][n], 0, 0, 0); __builtin_amdgcn_s_setprio(0); } while (0)
; #define PG8_WAIT_V(n) asm volatile("s_waitcnt vmcnt(" #n ")" ::: "memory")
; #define PG8_WAIT_L(n) asm volatile("s_waitcnt lgkmcnt(" #n ")" ::: "memory")
; #define PG8_BAR __builtin_amdgcn_s_barrier()
; #define PG8_SCHED __builtin_amdgcn_sched_barrier(0)
; template <class Epi>
; DEV void gemm_phase(LAS unsigned char* lds, const Gemm g, const StaticOrder& S, const Epi& E) {
;     ...
;             PG8_BAR; PG8_WAIT_L(0); PG8_MMA(0, 1, At, B1); PG8_BAR;
;             PG8_LDA(At, 0, 1); PG8_STAGE(PG8_SA(0, 0), a2, voffA);
;             PG8_BAR; PG8_WAIT_L(0); PG8_MMA(1, 0, At, B0); PG8_BAR; PG8_SCHED;
;             PG8_STAGE(PG8_SB(0, 1), b2 + hstep, voffB);
;             PG8_WAIT_V(6); PG8_BAR; PG8_MMA(1, 1, At, B1); PG8_BAR;
;             PG8_LDB(B0, 1, 0); PG8_SCHED; PG8_LDA(At, 1, 0); PG8_STAGE(PG8_SA(0, 1), a2 + hstep, voffA);
;             PG8_WAIT_L(8); PG8_BAR; PG8_WAIT_L(0); PG8_MMA(0, 0, At, B0); PG8_BAR; PG8_SCHED;
;             PG8_LDB(B1, 1, 1); PG8_STAGE(PG8_SB(1, 0), b3, voffB);
;             PG8_BAR; PG8_WAIT_L(0); PG8_MMA(0, 1, At, B1); PG8_BAR;
;             PG8_LDA(At, 1, 1); PG8_STAGE(PG8_SA(1, 0), a3, voffA);
;             PG8_BAR; PG8_WAIT_L(0); PG8_MMA(1, 0, At, B0); PG8_BAR; PG8_SCHED;
	s_add_u32 s48, s22, 0x80000
	s_addc_u32 s49, s23, 0
	s_add_i32 s47, s50, s30
	s_mov_b32 m0, s47
	s_nop 0
	global_load_lds_dwordx4 v160, s[48:49]
	s_add_i32 m0, s47, 0x2000
	s_nop 0
	global_load_lds_dwordx4 v136, s[48:49]
	s_waitcnt vmcnt(10)
	s_barrier
	v_mfma_f32_16x16x32_bf16 v[56:59], v[230:233], v[178:181], v[56:59]
	v_mfma_f32_16x16x32_bf16 v[48:51], v[238:241], v[178:181], v[48:51]
	v_mfma_f32_16x16x32_bf16 v[40:43], v[230:233], v[186:189], v[40:43]
	v_mfma_f32_16x16x32_bf16 v[32:35], v[238:241], v[186:189], v[32:35]
	v_mfma_f32_16x16x32_bf16 v[24:27], v[230:233], v[194:197], v[24:27]
	v_mfma_f32_16x16x32_bf16 v[16:19], v[238:241], v[194:197], v[16:19]
	v_mfma_f32_16x16x32_bf16 v[8:11], v[230:233], v[222:225], v[8:11]
	v_mfma_f32_16x16x32_bf16 v[0:3], v[238:241], v[222:225], v[0:3]
	v_mfma_f32_16x16x32_bf16 v[56:59], v[234:237], v[182:185], v[56:59]
	v_mfma_f32_16x16x32_bf16 v[48:51], v[242:245], v[182:185], v[48:51]
	v_mfma_f32_16x16x32_bf16 v[40:43], v[234:237], v[190:193], v[40:43]
	v_mfma_f32_16x16x32_bf16 v[32:35], v[242:245], v[190:193], v[32:35]
	v_mfma_f32_16x16x32_bf16 v[24:27], v[234:237], v[218:221], v[24:27]
	v_mfma_f32_16x16x32_bf16 v[16:19], v[242:245], v[218:221], v[16:19]
	v_mfma_f32_16x16x32_bf16 v[8:11], v[234:237], v[226:229], v[8:11]
	v_mfma_f32_16x16x32_bf16 v[0:3], v[242:245], v[226:229], v[0:3]
	s_add_i32 s47, 0, 0x18000
	v_add_u32_e32 v148, s47, v155
	s_barrier
	ds_read_b128 v[128:131], v148
	ds_read_b128 v[132:135], v148 offset:1024
	ds_read_b128 v[150:153], v148 offset:2048
	ds_read_b128 v[174:177], v148 offset:3072
	s_add_u32 s24, s24, 0x80000
	s_addc_u32 s25, s25, 0
	s_mov_b32 m0, s36
	ds_read_b128 v[178:181], v167 offset:32768
	ds_read_b128 v[182:185], v167 offset:33792
	ds_read_b128 v[186:189], v167 offset:34816
	ds_read_b128 v[190:193], v167 offset:35840
	ds_read_b128 v[194:197], v167 offset:36864
	ds_read_b128 v[218:221], v167 offset:37888
	ds_read_b128 v[222:225], v167 offset:38912
	ds_read_b128 v[226:229], v167 offset:39936
	global_load_lds_dwordx4 v140, s[24:25]
	s_mov_b32 m0, s37
	s_nop 0
	global_load_lds_dwordx4 v138, s[24:25]
	s_waitcnt lgkmcnt(8)
	s_waitcnt vmcnt(10)
	s_barrier
	s_waitcnt lgkmcnt(0)
	v_mfma_f32_16x16x32_bf16 v[124:127], v[128:131], v[178:181], v[124:127]
	v_mfma_f32_16x16x32_bf16 v[116:119], v[150:153], v[178:181], v[116:119]
	v_mfma_f32_16x16x32_bf16 v[108:111], v[128:131], v[186:189], v[108:111]
	v_mfma_f32_16x16x32_bf16 v[100:103], v[150:153], v[186:189], v[100:103]
	v_mfma_f32_16x16x32_bf16 v[92:95], v[128:131], v[194:197], v[92:95]
	v_mfma_f32_16x16x32_bf16 v[84:87], v[150:153], v[194:197], v[84:87]
	v_mfma_f32_16x16x32_bf16 v[76:79], v[128:131], v[222:225], v[76:79]
	v_mfma_f32_16x16x32_bf16 v[68:71], v[150:153], v[222:225], v[68:71]
	v_mfma_f32_16x16x32_bf16 v[124:127], v[132:135], v[182:185], v[124:127]
	v_mfma_f32_16x16x32_bf16 v[116:119], v[174:177], v[182:185], v[116:119]
	v_mfma_f32_16x16x32_bf16 v[108:111], v[132:135], v[190:193], v[108:111]
	v_mfma_f32_16x16x32_bf16 v[100:103], v[174:177], v[190:193], v[100:103]
	v_mfma_f32_16x16x32_bf16 v[92:95], v[132:135], v[218:221], v[92:95]
	v_mfma_f32_16x16x32_bf16 v[84:87], v[174:177], v[218:221], v[84:87]
	v_mfma_f32_16x16x32_bf16 v[76:79], v[132:135], v[226:229], v[76:79]
	v_mfma_f32_16x16x32_bf16 v[68:71], v[174:177], v[226:229], v[68:71]
	s_barrier
	s_add_i32 s24, 0, 0x1c000
	s_add_i32 s25, s47, s30
	v_add_u32_e32 v148, s24, v155
	v_lshl_add_u64 v[146:147], v[146:147], 0, s[2:3]
	s_mov_b32 m0, s25
	ds_read_b128 v[230:233], v148
	ds_read_b128 v[234:237], v148 offset:1024
	ds_read_b128 v[238:241], v148 offset:2048
	ds_read_b128 v[242:245], v148 offset:3072
	global_load_lds_dwordx4 v[146:147], off
	v_lshl_add_u64 v[146:147], v[158:159], 0, s[2:3]
	s_add_i32 m0, s25, 0x2000
	s_nop 0
	global_load_lds_dwordx4 v[146:147], off
	s_waitcnt vmcnt(10)
	s_barrier
	s_waitcnt lgkmcnt(0)
	v_mfma_f32_16x16x32_bf16 v[120:123], v[230:233], v[178:181], v[120:123]
	v_mfma_f32_16x16x32_bf16 v[112:115], v[238:241], v[178:181], v[112:115]
	v_mfma_f32_16x16x32_bf16 v[104:107], v[230:233], v[186:189], v[104:107]
	v_mfma_f32_16x16x32_bf16 v[96:99], v[238:241], v[186:189], v[96:99]
	v_mfma_f32_16x16x32_bf16 v[88:91], v[230:233], v[194:197], v[88:91]
	v_mfma_f32_16x16x32_bf16 v[80:83], v[238:241], v[194:197], v[80:83]
	v_mfma_f32_16x16x32_bf16 v[72:75], v[230:233], v[222:225], v[72:75]
	v_mfma_f32_16x16x32_bf16 v[64:67], v[238:241], v[222:225], v[64:67]
	v_mfma_f32_16x16x32_bf16 v[120:123], v[234:237], v[182:185], v[120:123]
	v_mfma_f32_16x16x32_bf16 v[112:115], v[242:245], v[182:185], v[112:115]
	v_mfma_f32_16x16x32_bf16 v[104:107], v[234:237], v[190:193], v[104:107]
	v_mfma_f32_16x16x32_bf16 v[96:99], v[242:245], v[190:193], v[96:99]
	v_mfma_f32_16x16x32_bf16 v[88:91], v[234:237], v[218:221], v[88:91]
	v_mfma_f32_16x16x32_bf16 v[80:83], v[242:245], v[218:221], v[80:83]
	v_mfma_f32_16x16x32_bf16 v[72:75], v[234:237], v[226:229], v[72:75]
	v_mfma_f32_16x16x32_bf16 v[64:67], v[242:245], v[226:229], v[64:67]
	s_mov_b32 m0, s38
	v_lshl_add_u64 v[146:147], v[214:215], 0, s[2:3]
	s_barrier
	ds_read_b128 v[178:181], v167 offset:49152
	ds_read_b128 v[182:185], v167 offset:50176
	ds_read_b128 v[186:189], v167 offset:51200
	ds_read_b128 v[190:193], v167 offset:52224
	ds_read_b128 v[194:197], v167 offset:53248
	ds_read_b128 v[218:221], v167 offset:54272
	ds_read_b128 v[222:225], v167 offset:55296
	ds_read_b128 v[226:229], v167 offset:56320
	global_load_lds_dwordx4 v[146:147], off
	v_lshl_add_u64 v[146:147], v[216:217], 0, s[2:3]
	s_mov_b32 m0, s39
	s_nop 0
	global_load_lds_dwordx4 v[146:147], off
	s_barrier
; #define PG8_STAGE(bufoff, gbase, voff) do { _Pragma("unroll") for (int _i = 0; _i < 2; ++_i) \
;         __builtin_amdgcn_global_load_lds((const unsigned*)((const char*)(gbase) + (voff)[_i]), (LAS unsigned*)(lds + (bufoff) + ldsw + _i * 8192), 16, 0, 0); } while (0)
; #define PG8_MMA(ai, bj, At, Bt) do { __builtin_amdgcn_s_setprio(1); _Pragma("unroll") for (int m = 0; m < 4; ++m) _Pragma("unroll") for (int n = 0; n < 2; ++n) _Pragma("unroll") for (int k = 0; k < 2; ++k) \
;         acc[ai][bj][m][n] = __builtin_amdgcn_mfma_f32_16x16x32_bf16(Bt[n][k], At[m][k], acc[ai][bj][m][n], 0, 0, 0); __builtin_amdgcn_s_setprio(0); } while (0)
; #define PG8_WAIT_V(n) asm volatile("s_waitcnt vmcnt(" #n ")" ::: "memory")
; #define PG8_WAIT_L(n) asm volatile("s_waitcnt lgkmcnt(" #n ")" ::: "memory")
; #define PG8_BAR __builtin_amdgcn_s_barrier()
; #define PG8_SCHED __builtin_amdgcn_sched_barrier(0)
; template <class Epi>
; DEV void gemm_phase(LAS unsigned char* lds, const Gemm g, const StaticOrder& S, const Epi& E) {
;     ...
;             PG8_BAR; PG8_WAIT_L(0); PG8_MMA(1, 0, At, B0); PG8_BAR; PG8_SCHED;
;             PG8_STAGE(PG8_SB(1, 1), b3 + hstep, voffB);
;             PG8_WAIT_V(6); PG8_BAR; PG8_MMA(1, 1, At, B1); PG8_BAR;
;         }
;         E(acc, cur, wr, wc, fr, fq);
; DEV float rowscale(const float* ss, int row) { const f32x4 a = *(const f32x4*)(ss + (size_t)row * 8), b = *(const f32x4*)(ss + (size_t)row * 8 + 4);
;     return rsqrtf(((a[0] + a[1]) + (a[2] + a[3]) + (b[0] + b[1]) + (b[2] + b[3])) * (1.0f / 2048.0f) + EPS); }
;     DEV void operator()(AccRef acc, const pg8::Unit& u, int wr, int wc, int fr, int fq) const {
;         const int row0 = u.pm * 256 + wr * 64 + fr, col0 = u.pn * 128 + wc * 32 + 8 * fq;
;         float rsv[2][4];
; #pragma unroll
;         for (int ai = 0; ai < 2; ++ai)
; #pragma unroll
;             for (int m = 0; m < 4; ++m) rsv[ai][m] = rowscale(ss, row0 + ai * 128 + m * 16);
; #pragma unroll
;         for (int ai = 0; ai < 2; ++ai)
; #pragma unroll
;             for (int m = 0; m < 4; ++m) { u16* rowp = O + (size_t)(row0 + ai * 128 + m * 16) * 5632 + col0; const float rs = rsv[ai][m]; f32x4 r[2];
; #pragma unroll
;                 for (int n = 0; n < 2; ++n) { const f32x4 g = acc[ai][0][m][n] * rs, uu = acc[ai][1][m][n] * rs;
	s_waitcnt lgkmcnt(0)
	v_mfma_f32_16x16x32_bf16 v[60:63], v[128:131], v[178:181], v[60:63]
	v_mfma_f32_16x16x32_bf16 v[52:55], v[150:153], v[178:181], v[52:55]
	v_mfma_f32_16x16x32_bf16 v[44:47], v[128:131], v[186:189], v[44:47]
	v_mfma_f32_16x16x32_bf16 v[36:39], v[150:153], v[186:189], v[36:39]
	v_mfma_f32_16x16x32_bf16 v[28:31], v[128:131], v[194:197], v[28:31]
	v_mfma_f32_16x16x32_bf16 v[20:23], v[150:153], v[194:197], v[20:23]
	v_mfma_f32_16x16x32_bf16 v[12:15], v[128:131], v[222:225], v[12:15]
	v_mfma_f32_16x16x32_bf16 v[4:7], v[150:153], v[222:225], v[4:7]
	v_mfma_f32_16x16x32_bf16 v[60:63], v[132:135], v[182:185], v[60:63]
	v_mfma_f32_16x16x32_bf16 v[52:55], v[174:177], v[182:185], v[52:55]
	v_mfma_f32_16x16x32_bf16 v[44:47], v[132:135], v[190:193], v[44:47]
	v_mfma_f32_16x16x32_bf16 v[36:39], v[174:177], v[190:193], v[36:39]
	v_mfma_f32_16x16x32_bf16 v[28:31], v[132:135], v[218:221], v[28:31]
	v_mfma_f32_16x16x32_bf16 v[20:23], v[174:177], v[218:221], v[20:23]
	v_mfma_f32_16x16x32_bf16 v[12:15], v[132:135], v[226:229], v[12:15]
	v_mfma_f32_16x16x32_bf16 v[4:7], v[174:177], v[226:229], v[4:7]
	s_barrier
	s_add_u32 s22, s22, 0x80080
	s_addc_u32 s23, s23, 0
	s_add_i32 s24, s24, s30
	s_mov_b32 m0, s24
	s_nop 0
	global_load_lds_dwordx4 v160, s[22:23]
	s_add_i32 m0, s24, 0x2000
	s_nop 0
	global_load_lds_dwordx4 v136, s[22:23]
	s_waitcnt vmcnt(10)
	s_barrier
	v_mfma_f32_16x16x32_bf16 v[56:59], v[230:233], v[178:181], v[56:59]
	v_mfma_f32_16x16x32_bf16 v[48:51], v[238:241], v[178:181], v[48:51]
	v_mfma_f32_16x16x32_bf16 v[40:43], v[230:233], v[186:189], v[40:43]
	v_mfma_f32_16x16x32_bf16 v[32:35], v[238:241], v[186:189], v[32:35]
	v_mfma_f32_16x16x32_bf16 v[24:27], v[230:233], v[194:197], v[24:27]
	v_mfma_f32_16x16x32_bf16 v[16:19], v[238:241], v[194:197], v[16:19]
	v_mfma_f32_16x16x32_bf16 v[8:11], v[230:233], v[222:225], v[8:11]
	v_mfma_f32_16x16x32_bf16 v[0:3], v[238:241], v[222:225], v[0:3]
	v_mfma_f32_16x16x32_bf16 v[56:59], v[234:237], v[182:185], v[56:59]
	v_mfma_f32_16x16x32_bf16 v[48:51], v[242:245], v[182:185], v[48:51]
	v_mfma_f32_16x16x32_bf16 v[40:43], v[234:237], v[190:193], v[40:43]
	v_mfma_f32_16x16x32_bf16 v[32:35], v[242:245], v[190:193], v[32:35]
	v_mfma_f32_16x16x32_bf16 v[24:27], v[234:237], v[218:221], v[24:27]
	v_mfma_f32_16x16x32_bf16 v[16:19], v[242:245], v[218:221], v[16:19]
	v_mfma_f32_16x16x32_bf16 v[8:11], v[234:237], v[226:229], v[8:11]
	v_mfma_f32_16x16x32_bf16 v[0:3], v[242:245], v[226:229], v[0:3]
	s_add_i32 s46, s46, 2
	s_add_u32 s20, s20, 0x100
	s_addc_u32 s21, s21, 0
	s_add_u32 s44, s44, 0x100
	s_addc_u32 s45, s45, 0
	s_cmp_gt_u32 s46, 29
	s_barrier
	s_cbranch_scc0 .LBB0_755
	v_lshl_add_u32 v186, s4, 8, v149
	v_ashrrev_i32_e32 v187, 31, v186
	v_lshlrev_b64 v[146:147], 5, v[186:187]
	v_lshl_add_u64 v[146:147], s[8:9], 0, v[146:147]
	v_add_co_u32_e32 v158, vcc, 0x1000, v146
	global_load_dwordx4 v[218:221], v[146:147], off
	global_load_dwordx4 v[222:225], v[146:147], off offset:16
	v_addc_co_u32_e32 v159, vcc, 0, v147, vcc
	global_load_dwordx4 v[174:177], v[146:147], off offset:512
	global_load_dwordx4 v[230:233], v[146:147], off offset:528
	global_load_dwordx4 v[234:237], v[146:147], off offset:1024
	global_load_dwordx4 v[238:241], v[146:147], off offset:1040
	global_load_dwordx4 v[242:245], v[146:147], off offset:1536
	global_load_dwordx4 v[246:249], v[146:147], off offset:1552
	global_load_dwordx4 v[190:193], v[158:159], off
	global_load_dwordx4 v[194:197], v[158:159], off offset:16
	global_load_dwordx4 v[214:217], v[158:159], off offset:512
	global_load_dwordx4 v[132:135], v[158:159], off offset:528
	global_load_dwordx4 v[150:153], v[158:159], off offset:1024
	global_load_dwordx4 v[128:131], v[158:159], off offset:1040
	global_load_dwordx4 v[226:229], v[158:159], off offset:1536
	global_load_dwordx4 v[180:183], v[158:159], off offset:1552
	s_mov_b32 s12, 0x3a000000
	s_mov_b64 s[22:23], s[18:19]
	s_mov_b64 s[20:21], s[16:17]
	s_movk_i32 s11, 0x2c00
	v_readlane_b32 s4, v250, 11
	v_readlane_b32 s5, v250, 12
	s_waitcnt vmcnt(14)
	v_add_f32_e32 v218, v218, v219
	v_add_f32_e32 v220, v220, v221
	v_add_f32_e32 v222, v222, v223
	v_add_f32_e32 v224, v224, v225
	v_add_f32_e32 v218, v218, v220
	v_add_f32_e32 v218, v218, v222
	v_add_f32_e32 v218, v218, v224
	v_fmamk_f32 v218, v218, 0x3a000000, v199
	v_rsq_f32_e32 v184, v218
	s_waitcnt vmcnt(12)
	v_add_f32_e32 v174, v174, v175
	v_add_f32_e32 v176, v176, v177
	v_add_f32_e32 v230, v230, v231
	v_add_f32_e32 v232, v232, v233
	v_add_f32_e32 v174, v174, v176
	v_add_f32_e32 v174, v174, v230
	v_add_f32_e32 v174, v174, v232
	v_fmamk_f32 v174, v174, 0x3a000000, v199
	v_rsq_f32_e32 v176, v174
	v_pk_mul_f32 v[124:125], v[124:125], v[184:185] op_sel_hi:[1,0]
	v_pk_mul_f32 v[120:121], v[120:121], v[184:185] op_sel_hi:[1,0]
	v_pk_mul_f32 v[122:123], v[122:123], v[184:185] op_sel_hi:[1,0]
	v_pk_mul_f32 v[116:117], v[116:117], v[184:185] op_sel_hi:[1,0]
	v_pk_mul_f32 v[112:113], v[112:113], v[184:185] op_sel_hi:[1,0]
	v_pk_mul_f32 v[114:115], v[114:115], v[184:185] op_sel_hi:[1,0]
	s_waitcnt vmcnt(10)
	v_add_f32_e32 v234, v234, v235
	v_add_f32_e32 v236, v236, v237
	v_add_f32_e32 v238, v238, v239
	v_add_f32_e32 v240, v240, v241
	v_add_f32_e32 v234, v234, v236
	v_add_f32_e32 v234, v234, v238
	v_add_f32_e32 v234, v234, v240
	v_fmamk_f32 v234, v234, 0x3a000000, v199
	v_rsq_f32_e32 v178, v234
	v_pk_mul_f32 v[108:109], v[108:109], v[176:177] op_sel_hi:[1,0]
	v_pk_mul_f32 v[104:105], v[104:105], v[176:177] op_sel_hi:[1,0]
	v_pk_mul_f32 v[106:107], v[106:107], v[176:177] op_sel_hi:[1,0]
	v_pk_mul_f32 v[100:101], v[100:101], v[176:177] op_sel_hi:[1,0]
	v_pk_mul_f32 v[96:97], v[96:97], v[176:177] op_sel_hi:[1,0]
	v_pk_mul_f32 v[98:99], v[98:99], v[176:177] op_sel_hi:[1,0]
	s_waitcnt vmcnt(8)
; DEV bf16x8 pack8(f32x4 a, f32x4 b) { u32x4 w; w.x = cvt_pk_bf16(a[0], a[1]); w.y = cvt_pk_bf16(a[2], a[3]); w.z = cvt_pk_bf16(b[0], b[1]); w.w = cvt_pk_bf16(b[2], b[3]); return __builtin_bit_cast(bf16x8, w); }
;     DEV void operator()(AccRef acc, const pg8::Unit& u, int wr, int wc, int fr, int fq) const { store_bf16_tile<0, false>(acc, O, ld, u.pm * 256 + wr * 64 + fr, u.pn * 256 + wc * 32 + 4 * fq, ss); }
; DEV float siluf(float x) { return x * __builtin_amdgcn_rcpf(1.0f + __builtin_amdgcn_exp2f(x * -1.4426950408889634f)); }
;     DEV void operator()(AccRef acc, const pg8::Unit& u, int wr, int wc, int fr, int fq) const {
;         const int row0 = u.pm * 256 + wr * 64 + fr, col0 = u.pn * 128 + wc * 32 + 8 * fq;
;         float rsv[2][4];
; #pragma unroll
;         for (int ai = 0; ai < 2; ++ai)
; #pragma unroll
;             for (int m = 0; m < 4; ++m) rsv[ai][m] = rowscale(ss, row0 + ai * 128 + m * 16);
; #pragma unroll
;         for (int ai = 0; ai < 2; ++ai)
; #pragma unroll
;             for (int m = 0; m < 4; ++m) { u16* rowp = O + (size_t)(row0 + ai * 128 + m * 16) * 5632 + col0; const float rs = rsv[ai][m]; f32x4 r[2];
; #pragma unroll
;                 for (int n = 0; n < 2; ++n) { const f32x4 g = acc[ai][0][m][n] * rs, uu = acc[ai][1][m][n] * rs;
; #pragma unroll
;                     for (int e = 0; e < 4; ++e) r[n][e] = siluf(g[e]) * uu[e]; }
;                 *(u32x4*)rowp = __builtin_bit_cast(u32x4, pack8(r[0], r[1])); }
	v_add_f32_e32 v242, v242, v243
	v_add_f32_e32 v244, v244, v245
	v_add_f32_e32 v246, v246, v247
	v_add_f32_e32 v248, v248, v249
	v_add_f32_e32 v242, v242, v244
	v_add_f32_e32 v242, v242, v246
	v_add_f32_e32 v242, v242, v248
	v_fmamk_f32 v242, v242, 0x3a000000, v199
	v_rsq_f32_e32 v154, v242
	v_pk_mul_f32 v[92:93], v[92:93], v[178:179] op_sel_hi:[1,0]
	v_pk_mul_f32 v[88:89], v[88:89], v[178:179] op_sel_hi:[1,0]
	v_pk_mul_f32 v[90:91], v[90:91], v[178:179] op_sel_hi:[1,0]
	v_pk_mul_f32 v[84:85], v[84:85], v[178:179] op_sel_hi:[1,0]
	v_pk_mul_f32 v[80:81], v[80:81], v[178:179] op_sel_hi:[1,0]
	v_pk_mul_f32 v[82:83], v[82:83], v[178:179] op_sel_hi:[1,0]
	s_waitcnt vmcnt(6)
	v_add_f32_e32 v190, v190, v191
	v_add_f32_e32 v192, v192, v193
	v_add_f32_e32 v194, v194, v195
	v_add_f32_e32 v196, v196, v197
	v_add_f32_e32 v190, v190, v192
	v_add_f32_e32 v190, v190, v194
	v_add_f32_e32 v190, v190, v196
	v_fmamk_f32 v190, v190, 0x3a000000, v199
	v_rsq_f32_e32 v156, v190
	v_pk_mul_f32 v[76:77], v[76:77], v[154:155] op_sel_hi:[1,0]
	v_pk_mul_f32 v[72:73], v[72:73], v[154:155] op_sel_hi:[1,0]
	v_pk_mul_f32 v[74:75], v[74:75], v[154:155] op_sel_hi:[1,0]
	v_pk_mul_f32 v[68:69], v[68:69], v[154:155] op_sel_hi:[1,0]
	v_pk_mul_f32 v[64:65], v[64:65], v[154:155] op_sel_hi:[1,0]
	v_pk_mul_f32 v[66:67], v[66:67], v[154:155] op_sel_hi:[1,0]
	s_waitcnt vmcnt(4)
	v_add_f32_e32 v214, v214, v215
	v_add_f32_e32 v216, v216, v217
	v_add_f32_e32 v132, v132, v133
	v_add_f32_e32 v134, v134, v135
	v_add_f32_e32 v214, v214, v216
	v_add_f32_e32 v214, v214, v132
	v_add_f32_e32 v214, v214, v134
	v_fmamk_f32 v214, v214, 0x3a000000, v199
	v_rsq_f32_e32 v148, v214
	v_pk_mul_f32 v[60:61], v[60:61], v[156:157] op_sel_hi:[1,0]
	v_pk_mul_f32 v[56:57], v[56:57], v[156:157] op_sel_hi:[1,0]
	v_pk_mul_f32 v[58:59], v[58:59], v[156:157] op_sel_hi:[1,0]
	v_pk_mul_f32 v[52:53], v[52:53], v[156:157] op_sel_hi:[1,0]
	v_pk_mul_f32 v[48:49], v[48:49], v[156:157] op_sel_hi:[1,0]
	v_pk_mul_f32 v[50:51], v[50:51], v[156:157] op_sel_hi:[1,0]
	s_waitcnt vmcnt(2)
	v_add_f32_e32 v150, v150, v151
	v_add_f32_e32 v152, v152, v153
	v_add_f32_e32 v128, v128, v129
	v_add_f32_e32 v130, v130, v131
	v_add_f32_e32 v150, v150, v152
	v_add_f32_e32 v150, v150, v128
	v_add_f32_e32 v150, v150, v130
	v_fmamk_f32 v150, v150, 0x3a000000, v199
	v_rsq_f32_e32 v130, v150
	v_pk_mul_f32 v[44:45], v[44:45], v[148:149] op_sel_hi:[1,0]
	v_pk_mul_f32 v[40:41], v[40:41], v[148:149] op_sel_hi:[1,0]
	v_pk_mul_f32 v[42:43], v[42:43], v[148:149] op_sel_hi:[1,0]
	v_pk_mul_f32 v[36:37], v[36:37], v[148:149] op_sel_hi:[1,0]
	v_pk_mul_f32 v[32:33], v[32:33], v[148:149] op_sel_hi:[1,0]
	v_pk_mul_f32 v[34:35], v[34:35], v[148:149] op_sel_hi:[1,0]
	s_waitcnt vmcnt(0)
	v_add_f32_e32 v226, v226, v227
	v_add_f32_e32 v228, v228, v229
	v_add_f32_e32 v180, v180, v181
	v_add_f32_e32 v182, v182, v183
	v_add_f32_e32 v226, v226, v228
	v_add_f32_e32 v226, v226, v180
	v_add_f32_e32 v226, v226, v182
	v_fmamk_f32 v226, v226, 0x3a000000, v199
	v_rsq_f32_e32 v128, v226
	v_pk_mul_f32 v[28:29], v[28:29], v[130:131] op_sel_hi:[1,0]
	v_or_b32_e32 v182, 16, v186
	v_ashrrev_i32_e32 v183, 31, v182
	v_or_b32_e32 v180, 32, v186
	v_ashrrev_i32_e32 v181, 31, v180
	v_or_b32_e32 v174, 48, v186
	v_ashrrev_i32_e32 v175, 31, v174
	v_add_u32_e32 v158, 0x80, v186
	v_ashrrev_i32_e32 v159, 31, v158
	v_add_u32_e32 v152, 0x90, v186
	v_ashrrev_i32_e32 v153, 31, v152
	v_add_u32_e32 v150, 0xa0, v186
	v_ashrrev_i32_e32 v151, 31, v150
	v_add_u32_e32 v146, 0xb0, v186
	v_ashrrev_i32_e32 v147, 31, v146
	v_lshl_or_b32 v134, s42, 7, v157
	v_ashrrev_i32_e32 v135, 31, v134
	s_mov_b32 s42, s10
	v_mul_f32_e32 v129, 0xbfb8aa3b, v124
	v_exp_f32_e32 v129, v129
	v_mov_b64_e32 v[132:133], s[4:5]
	v_mad_i64_i32 v[186:187], s[4:5], v186, s11, v[132:133]
	v_add_f32_e32 v129, 1.0, v129
	v_rcp_f32_e32 v188, v129
	v_mul_f32_e32 v129, 0xbfb8aa3b, v125
	v_exp_f32_e32 v129, v129
	v_pk_mul_f32 v[24:25], v[24:25], v[130:131] op_sel_hi:[1,0]
	v_pk_mul_f32 v[26:27], v[26:27], v[130:131] op_sel_hi:[1,0]
	v_pk_mul_f32 v[20:21], v[20:21], v[130:131] op_sel_hi:[1,0]
	v_add_f32_e32 v129, 1.0, v129
	v_rcp_f32_e32 v189, v129
	v_pk_mul_f32 v[16:17], v[16:17], v[130:131] op_sel_hi:[1,0]
	v_pk_mul_f32 v[18:19], v[18:19], v[130:131] op_sel_hi:[1,0]
	v_pk_mul_f32 v[12:13], v[12:13], v[128:129] op_sel_hi:[1,0]
	v_pk_mul_f32 v[124:125], v[124:125], v[188:189]
	v_pk_mul_f32 v[8:9], v[8:9], v[128:129] op_sel_hi:[1,0]
	v_pk_mul_f32 v[120:121], v[120:121], v[124:125]
	v_pk_mul_f32 v[124:125], v[126:127], v[184:185] op_sel_hi:[1,0]
	v_pk_mul_f32 v[10:11], v[10:11], v[128:129] op_sel_hi:[1,0]
	v_mul_f32_e32 v126, 0xbfb8aa3b, v124
	v_mul_f32_e32 v127, 0xbfb8aa3b, v125
	v_exp_f32_e32 v126, v126
	v_exp_f32_e32 v127, v127
	v_pk_mul_f32 v[4:5], v[4:5], v[128:129] op_sel_hi:[1,0]
	v_pk_mul_f32 v[0:1], v[0:1], v[128:129] op_sel_hi:[1,0]
	v_add_f32_e32 v126, 1.0, v126
	v_add_f32_e32 v127, 1.0, v127
	v_rcp_f32_e32 v126, v126
	v_rcp_f32_e32 v127, v127
	v_pk_mul_f32 v[2:3], v[2:3], v[128:129] op_sel_hi:[1,0]
	s_and_b64 vcc, exec, s[0:1]
	v_pk_mul_f32 v[124:125], v[124:125], v[126:127]
	s_nop 0
	v_pk_mul_f32 v[122:123], v[122:123], v[124:125]
	v_mul_f32_e32 v124, 0xbfb8aa3b, v116
	v_mul_f32_e32 v125, 0xbfb8aa3b, v117
	v_exp_f32_e32 v124, v124
	v_exp_f32_e32 v125, v125
	v_add_f32_e32 v124, 1.0, v124
	v_add_f32_e32 v125, 1.0, v125
	v_rcp_f32_e32 v124, v124
	v_rcp_f32_e32 v125, v125
	s_nop 0
	v_pk_mul_f32 v[116:117], v[116:117], v[124:125]
	s_nop 0
	v_pk_mul_f32 v[116:117], v[112:113], v[116:117]
	v_pk_mul_f32 v[112:113], v[118:119], v[184:185] op_sel_hi:[1,0]
	v_cvt_pk_bf16_f32 v116, v116, v117
	v_mul_f32_e32 v118, 0xbfb8aa3b, v112
; DEV bf16x8 pack8(f32x4 a, f32x4 b) { u32x4 w; w.x = cvt_pk_bf16(a[0], a[1]); w.y = cvt_pk_bf16(a[2], a[3]); w.z = cvt_pk_bf16(b[0], b[1]); w.w = cvt_pk_bf16(b[2], b[3]); return __builtin_bit_cast(bf16x8, w); }
; DEV float siluf(float x) { return x * __builtin_amdgcn_rcpf(1.0f + __builtin_amdgcn_exp2f(x * -1.4426950408889634f)); }
;     DEV void operator()(AccRef acc, const pg8::Unit& u, int wr, int wc, int fr, int fq) const {
;     ...
;             for (int m = 0; m < 4; ++m) { u16* rowp = O + (size_t)(row0 + ai * 128 + m * 16) * 5632 + col0; const float rs = rsv[ai][m]; f32x4 r[2];
; #pragma unroll
;                 for (int n = 0; n < 2; ++n) { const f32x4 g = acc[ai][0][m][n] * rs, uu = acc[ai][1][m][n] * rs;
; #pragma unroll
;                     for (int e = 0; e < 4; ++e) r[n][e] = siluf(g[e]) * uu[e]; }
;                 *(u32x4*)rowp = __builtin_bit_cast(u32x4, pack8(r[0], r[1])); }
	v_mul_f32_e32 v119, 0xbfb8aa3b, v113
	v_exp_f32_e32 v118, v118
	v_exp_f32_e32 v119, v119
	v_add_f32_e32 v118, 1.0, v118
	v_add_f32_e32 v119, 1.0, v119
	v_rcp_f32_e32 v118, v118
	v_rcp_f32_e32 v119, v119
	s_nop 0
	v_pk_mul_f32 v[112:113], v[112:113], v[118:119]
	s_nop 0
	v_pk_mul_f32 v[118:119], v[114:115], v[112:113]
	v_lshlrev_b64 v[112:113], 1, v[134:135]
	v_lshl_add_u64 v[124:125], v[186:187], 0, v[112:113]
	v_cvt_pk_bf16_f32 v114, v120, v121
	v_cvt_pk_bf16_f32 v115, v122, v123
	v_cvt_pk_bf16_f32 v117, v118, v119
	global_store_dwordx4 v[124:125], v[114:117], off
	s_nop 1
	v_mul_f32_e32 v116, 0xbfb8aa3b, v108
	v_mul_f32_e32 v117, 0xbfb8aa3b, v109
	v_exp_f32_e32 v116, v116
	v_exp_f32_e32 v117, v117
	v_mad_i64_i32 v[114:115], s[4:5], v182, s11, v[132:133]
	v_add_f32_e32 v116, 1.0, v116
	v_add_f32_e32 v117, 1.0, v117
	v_rcp_f32_e32 v116, v116
	v_rcp_f32_e32 v117, v117
	s_nop 0
	v_pk_mul_f32 v[108:109], v[108:109], v[116:117]
	s_nop 0
	v_pk_mul_f32 v[104:105], v[104:105], v[108:109]
	v_pk_mul_f32 v[108:109], v[110:111], v[176:177] op_sel_hi:[1,0]
	s_nop 0
	v_mul_f32_e32 v110, 0xbfb8aa3b, v108
	v_mul_f32_e32 v111, 0xbfb8aa3b, v109
	v_exp_f32_e32 v110, v110
	v_exp_f32_e32 v111, v111
	v_add_f32_e32 v110, 1.0, v110
	v_add_f32_e32 v111, 1.0, v111
	v_rcp_f32_e32 v110, v110
	v_rcp_f32_e32 v111, v111
	s_nop 0
	v_pk_mul_f32 v[108:109], v[108:109], v[110:111]
	s_nop 0
	v_pk_mul_f32 v[106:107], v[106:107], v[108:109]
	v_mul_f32_e32 v108, 0xbfb8aa3b, v100
	v_mul_f32_e32 v109, 0xbfb8aa3b, v101
	v_exp_f32_e32 v108, v108
	v_exp_f32_e32 v109, v109
	v_add_f32_e32 v108, 1.0, v108
	v_add_f32_e32 v109, 1.0, v109
	v_rcp_f32_e32 v108, v108
	v_rcp_f32_e32 v109, v109
	s_nop 0
	v_pk_mul_f32 v[100:101], v[100:101], v[108:109]
	s_nop 0
	v_pk_mul_f32 v[100:101], v[96:97], v[100:101]
	v_pk_mul_f32 v[96:97], v[102:103], v[176:177] op_sel_hi:[1,0]
	v_lshl_add_u64 v[108:109], v[114:115], 0, v[112:113]
	v_mul_f32_e32 v102, 0xbfb8aa3b, v96
	v_mul_f32_e32 v103, 0xbfb8aa3b, v97
	v_exp_f32_e32 v102, v102
	v_exp_f32_e32 v103, v103
	v_add_f32_e32 v102, 1.0, v102
	v_add_f32_e32 v103, 1.0, v103
	v_rcp_f32_e32 v102, v102
	v_rcp_f32_e32 v103, v103
	s_nop 0
	v_pk_mul_f32 v[96:97], v[96:97], v[102:103]
	s_nop 0
	v_pk_mul_f32 v[102:103], v[98:99], v[96:97]
	v_cvt_pk_bf16_f32 v96, v104, v105
	v_cvt_pk_bf16_f32 v97, v106, v107
	v_cvt_pk_bf16_f32 v98, v100, v101
	v_cvt_pk_bf16_f32 v99, v102, v103
	global_store_dwordx4 v[108:109], v[96:99], off
	s_nop 1
	v_mul_f32_e32 v98, 0xbfb8aa3b, v92
	v_mul_f32_e32 v99, 0xbfb8aa3b, v93
	v_exp_f32_e32 v98, v98
	v_exp_f32_e32 v99, v99
	v_mad_i64_i32 v[96:97], s[4:5], v180, s11, v[132:133]
	v_add_f32_e32 v98, 1.0, v98
	v_add_f32_e32 v99, 1.0, v99
	v_rcp_f32_e32 v98, v98
	v_rcp_f32_e32 v99, v99
	s_nop 0
	v_pk_mul_f32 v[92:93], v[92:93], v[98:99]
	s_nop 0
	v_pk_mul_f32 v[88:89], v[88:89], v[92:93]
	v_pk_mul_f32 v[92:93], v[94:95], v[178:179] op_sel_hi:[1,0]
	s_nop 0
	v_mul_f32_e32 v94, 0xbfb8aa3b, v92
	v_mul_f32_e32 v95, 0xbfb8aa3b, v93
	v_exp_f32_e32 v94, v94
	v_exp_f32_e32 v95, v95
	v_add_f32_e32 v94, 1.0, v94
	v_add_f32_e32 v95, 1.0, v95
	v_rcp_f32_e32 v94, v94
	v_rcp_f32_e32 v95, v95
	s_nop 0
	v_pk_mul_f32 v[92:93], v[92:93], v[94:95]
	s_nop 0
	v_pk_mul_f32 v[90:91], v[90:91], v[92:93]
	v_mul_f32_e32 v92, 0xbfb8aa3b, v84
	v_mul_f32_e32 v93, 0xbfb8aa3b, v85
	v_exp_f32_e32 v92, v92
	v_exp_f32_e32 v93, v93
	v_add_f32_e32 v92, 1.0, v92
	v_add_f32_e32 v93, 1.0, v93
	v_rcp_f32_e32 v92, v92
	v_rcp_f32_e32 v93, v93
	s_nop 0
	v_pk_mul_f32 v[84:85], v[84:85], v[92:93]
	s_nop 0
	v_pk_mul_f32 v[84:85], v[80:81], v[84:85]
	v_pk_mul_f32 v[80:81], v[86:87], v[178:179] op_sel_hi:[1,0]
	v_lshl_add_u64 v[92:93], v[96:97], 0, v[112:113]
	v_mul_f32_e32 v86, 0xbfb8aa3b, v80
	v_mul_f32_e32 v87, 0xbfb8aa3b, v81
	v_exp_f32_e32 v86, v86
	v_exp_f32_e32 v87, v87
	v_add_f32_e32 v86, 1.0, v86
	v_add_f32_e32 v87, 1.0, v87
	v_rcp_f32_e32 v86, v86
	v_rcp_f32_e32 v87, v87
	s_nop 0
	v_pk_mul_f32 v[80:81], v[80:81], v[86:87]
	s_nop 0
	v_pk_mul_f32 v[86:87], v[82:83], v[80:81]
	v_cvt_pk_bf16_f32 v80, v88, v89
	v_cvt_pk_bf16_f32 v81, v90, v91
	v_cvt_pk_bf16_f32 v82, v84, v85
	v_cvt_pk_bf16_f32 v83, v86, v87
	global_store_dwordx4 v[92:93], v[80:83], off
	s_nop 1
	v_mul_f32_e32 v82, 0xbfb8aa3b, v76
	v_mul_f32_e32 v83, 0xbfb8aa3b, v77
	v_exp_f32_e32 v82, v82
	v_exp_f32_e32 v83, v83
	v_mad_i64_i32 v[80:81], s[4:5], v174, s11, v[132:133]
	v_add_f32_e32 v82, 1.0, v82
	v_add_f32_e32 v83, 1.0, v83
	v_rcp_f32_e32 v82, v82
	v_rcp_f32_e32 v83, v83
	s_nop 0
	v_pk_mul_f32 v[76:77], v[76:77], v[82:83]
	s_nop 0
	v_pk_mul_f32 v[72:73], v[72:73], v[76:77]
	v_pk_mul_f32 v[76:77], v[78:79], v[154:155] op_sel_hi:[1,0]
	s_nop 0
	v_mul_f32_e32 v78, 0xbfb8aa3b, v76
	v_mul_f32_e32 v79, 0xbfb8aa3b, v77
	v_exp_f32_e32 v78, v78
	v_exp_f32_e32 v79, v79
	v_add_f32_e32 v78, 1.0, v78
	v_add_f32_e32 v79, 1.0, v79
	v_rcp_f32_e32 v78, v78
	v_rcp_f32_e32 v79, v79
	s_nop 0
	v_pk_mul_f32 v[76:77], v[76:77], v[78:79]
	s_nop 0
	v_pk_mul_f32 v[74:75], v[74:75], v[76:77]
	v_mul_f32_e32 v76, 0xbfb8aa3b, v68
	v_mul_f32_e32 v77, 0xbfb8aa3b, v69
	v_exp_f32_e32 v76, v76
	v_exp_f32_e32 v77, v77
	v_add_f32_e32 v76, 1.0, v76
	v_add_f32_e32 v77, 1.0, v77
	v_rcp_f32_e32 v76, v76
	v_rcp_f32_e32 v77, v77
	s_nop 0
	v_pk_mul_f32 v[68:69], v[68:69], v[76:77]
	s_nop 0
	v_pk_mul_f32 v[68:69], v[64:65], v[68:69]
	v_pk_mul_f32 v[64:65], v[70:71], v[154:155] op_sel_hi:[1,0]
	v_lshl_add_u64 v[76:77], v[80:81], 0, v[112:113]
	v_mul_f32_e32 v70, 0xbfb8aa3b, v64
	v_mul_f32_e32 v71, 0xbfb8aa3b, v65
	v_exp_f32_e32 v70, v70
	v_exp_f32_e32 v71, v71
	v_add_f32_e32 v70, 1.0, v70
	v_add_f32_e32 v71, 1.0, v71
	v_rcp_f32_e32 v70, v70
	v_rcp_f32_e32 v71, v71
; DEV bf16x8 pack8(f32x4 a, f32x4 b) { u32x4 w; w.x = cvt_pk_bf16(a[0], a[1]); w.y = cvt_pk_bf16(a[2], a[3]); w.z = cvt_pk_bf16(b[0], b[1]); w.w = cvt_pk_bf16(b[2], b[3]); return __builtin_bit_cast(bf16x8, w); }
; DEV float siluf(float x) { return x * __builtin_amdgcn_rcpf(1.0f + __builtin_amdgcn_exp2f(x * -1.4426950408889634f)); }
;     DEV void operator()(AccRef acc, const pg8::Unit& u, int wr, int wc, int fr, int fq) const {
;     ...
;             for (int m = 0; m < 4; ++m) { u16* rowp = O + (size_t)(row0 + ai * 128 + m * 16) * 5632 + col0; const float rs = rsv[ai][m]; f32x4 r[2];
; #pragma unroll
;                 for (int n = 0; n < 2; ++n) { const f32x4 g = acc[ai][0][m][n] * rs, uu = acc[ai][1][m][n] * rs;
; #pragma unroll
;                     for (int e = 0; e < 4; ++e) r[n][e] = siluf(g[e]) * uu[e]; }
;                 *(u32x4*)rowp = __builtin_bit_cast(u32x4, pack8(r[0], r[1])); }
	s_nop 0
	v_pk_mul_f32 v[64:65], v[64:65], v[70:71]
	s_nop 0
	v_pk_mul_f32 v[70:71], v[66:67], v[64:65]
	v_cvt_pk_bf16_f32 v64, v72, v73
	v_cvt_pk_bf16_f32 v65, v74, v75
	v_cvt_pk_bf16_f32 v66, v68, v69
	v_cvt_pk_bf16_f32 v67, v70, v71
	global_store_dwordx4 v[76:77], v[64:67], off
	s_nop 1
	v_mul_f32_e32 v66, 0xbfb8aa3b, v60
	v_mul_f32_e32 v67, 0xbfb8aa3b, v61
	v_exp_f32_e32 v66, v66
	v_exp_f32_e32 v67, v67
	v_mad_i64_i32 v[64:65], s[4:5], v158, s11, v[132:133]
	v_add_f32_e32 v66, 1.0, v66
	v_add_f32_e32 v67, 1.0, v67
	v_rcp_f32_e32 v66, v66
	v_rcp_f32_e32 v67, v67
	s_nop 0
	v_pk_mul_f32 v[60:61], v[60:61], v[66:67]
	s_nop 0
	v_pk_mul_f32 v[56:57], v[56:57], v[60:61]
	v_pk_mul_f32 v[60:61], v[62:63], v[156:157] op_sel_hi:[1,0]
	s_nop 0
	v_mul_f32_e32 v62, 0xbfb8aa3b, v60
	v_mul_f32_e32 v63, 0xbfb8aa3b, v61
	v_exp_f32_e32 v62, v62
	v_exp_f32_e32 v63, v63
	v_add_f32_e32 v62, 1.0, v62
	v_add_f32_e32 v63, 1.0, v63
	v_rcp_f32_e32 v62, v62
	v_rcp_f32_e32 v63, v63
	s_nop 0
	v_pk_mul_f32 v[60:61], v[60:61], v[62:63]
	s_nop 0
	v_pk_mul_f32 v[58:59], v[58:59], v[60:61]
	v_mul_f32_e32 v60, 0xbfb8aa3b, v52
	v_mul_f32_e32 v61, 0xbfb8aa3b, v53
	v_exp_f32_e32 v60, v60
	v_exp_f32_e32 v61, v61
	v_add_f32_e32 v60, 1.0, v60
	v_add_f32_e32 v61, 1.0, v61
	v_rcp_f32_e32 v60, v60
	v_rcp_f32_e32 v61, v61
	s_nop 0
	v_pk_mul_f32 v[52:53], v[52:53], v[60:61]
	s_nop 0
	v_pk_mul_f32 v[52:53], v[48:49], v[52:53]
	v_pk_mul_f32 v[48:49], v[54:55], v[156:157] op_sel_hi:[1,0]
	v_lshl_add_u64 v[60:61], v[64:65], 0, v[112:113]
	v_mul_f32_e32 v54, 0xbfb8aa3b, v48
	v_mul_f32_e32 v55, 0xbfb8aa3b, v49
	v_exp_f32_e32 v54, v54
	v_exp_f32_e32 v55, v55
	v_add_f32_e32 v54, 1.0, v54
	v_add_f32_e32 v55, 1.0, v55
	v_rcp_f32_e32 v54, v54
	v_rcp_f32_e32 v55, v55
	s_nop 0
	v_pk_mul_f32 v[48:49], v[48:49], v[54:55]
	s_nop 0
	v_pk_mul_f32 v[54:55], v[50:51], v[48:49]
	v_cvt_pk_bf16_f32 v48, v56, v57
	v_cvt_pk_bf16_f32 v49, v58, v59
	v_cvt_pk_bf16_f32 v50, v52, v53
	v_cvt_pk_bf16_f32 v51, v54, v55
	global_store_dwordx4 v[60:61], v[48:51], off
	s_nop 1
	v_mul_f32_e32 v50, 0xbfb8aa3b, v44
	v_mul_f32_e32 v51, 0xbfb8aa3b, v45
	v_exp_f32_e32 v50, v50
	v_exp_f32_e32 v51, v51
	v_mad_i64_i32 v[48:49], s[4:5], v152, s11, v[132:133]
	v_add_f32_e32 v50, 1.0, v50
	v_add_f32_e32 v51, 1.0, v51
	v_rcp_f32_e32 v50, v50
	v_rcp_f32_e32 v51, v51
	s_nop 0
	v_pk_mul_f32 v[44:45], v[44:45], v[50:51]
	s_nop 0
	v_pk_mul_f32 v[40:41], v[40:41], v[44:45]
	v_pk_mul_f32 v[44:45], v[46:47], v[148:149] op_sel_hi:[1,0]
	s_nop 0
	v_mul_f32_e32 v46, 0xbfb8aa3b, v44
	v_mul_f32_e32 v47, 0xbfb8aa3b, v45
	v_exp_f32_e32 v46, v46
	v_exp_f32_e32 v47, v47
	v_add_f32_e32 v46, 1.0, v46
	v_add_f32_e32 v47, 1.0, v47
	v_rcp_f32_e32 v46, v46
	v_rcp_f32_e32 v47, v47
	s_nop 0
	v_pk_mul_f32 v[44:45], v[44:45], v[46:47]
	s_nop 0
	v_pk_mul_f32 v[42:43], v[42:43], v[44:45]
	v_mul_f32_e32 v44, 0xbfb8aa3b, v36
	v_mul_f32_e32 v45, 0xbfb8aa3b, v37
	v_exp_f32_e32 v44, v44
	v_exp_f32_e32 v45, v45
	v_add_f32_e32 v44, 1.0, v44
	v_add_f32_e32 v45, 1.0, v45
	v_rcp_f32_e32 v44, v44
	v_rcp_f32_e32 v45, v45
	s_nop 0
	v_pk_mul_f32 v[36:37], v[36:37], v[44:45]
	s_nop 0
	v_pk_mul_f32 v[36:37], v[32:33], v[36:37]
	v_pk_mul_f32 v[32:33], v[38:39], v[148:149] op_sel_hi:[1,0]
	v_lshl_add_u64 v[44:45], v[48:49], 0, v[112:113]
	v_mul_f32_e32 v38, 0xbfb8aa3b, v32
	v_mul_f32_e32 v39, 0xbfb8aa3b, v33
	v_exp_f32_e32 v38, v38
	v_exp_f32_e32 v39, v39
	v_add_f32_e32 v38, 1.0, v38
	v_add_f32_e32 v39, 1.0, v39
	v_rcp_f32_e32 v38, v38
	v_rcp_f32_e32 v39, v39
	s_nop 0
	v_pk_mul_f32 v[32:33], v[32:33], v[38:39]
	s_nop 0
	v_pk_mul_f32 v[38:39], v[34:35], v[32:33]
	v_cvt_pk_bf16_f32 v32, v40, v41
	v_cvt_pk_bf16_f32 v33, v42, v43
; DEV float siluf(float x) { return x * __builtin_amdgcn_rcpf(1.0f + __builtin_amdgcn_exp2f(x * -1.4426950408889634f)); }
; DEV bf16x8 pack8(f32x4 a, f32x4 b) { u32x4 w; w.x = cvt_pk_bf16(a[0], a[1]); w.y = cvt_pk_bf16(a[2], a[3]); w.z = cvt_pk_bf16(b[0], b[1]); w.w = cvt_pk_bf16(b[2], b[3]); return __builtin_bit_cast(bf16x8, w); }
; #define PG8_WAIT_V(n) asm volatile("s_waitcnt vmcnt(" #n ")" ::: "memory")
; #define PG8_BAR __builtin_amdgcn_s_barrier()
; template <class Epi>
; DEV void gemm_phase(LAS unsigned char* lds, const Gemm g, const StaticOrder& S, const Epi& E) {
;     ...
;         if (!has_next) break;
; #pragma unroll
;         for (int a = 0; a < 2; ++a)
; #pragma unroll
;             for (int b = 0; b < 2; ++b)
; #pragma unroll
;                 for (int m = 0; m < 4; ++m)
; #pragma unroll
;                     for (int n = 0; n < 2; ++n) acc[a][b][m][n] = (f32x4){0.f, 0.f, 0.f, 0.f};
;         cur = nxt; cA = nA; cB = nB; ++ui;
;     }
;     PG8_WAIT_V(0);
;     if (wr == 0) PG8_BAR;
;     PG8_BAR;
;     DEV void operator()(AccRef acc, const pg8::Unit& u, int wr, int wc, int fr, int fq) const {
;     ...
;             for (int m = 0; m < 4; ++m) { u16* rowp = O + (size_t)(row0 + ai * 128 + m * 16) * 5632 + col0; const float rs = rsv[ai][m]; f32x4 r[2];
; #pragma unroll
;                 for (int n = 0; n < 2; ++n) { const f32x4 g = acc[ai][0][m][n] * rs, uu = acc[ai][1][m][n] * rs;
; #pragma unroll
;                     for (int e = 0; e < 4; ++e) r[n][e] = siluf(g[e]) * uu[e]; }
;                 *(u32x4*)rowp = __builtin_bit_cast(u32x4, pack8(r[0], r[1])); }
	v_cvt_pk_bf16_f32 v34, v36, v37
	v_cvt_pk_bf16_f32 v35, v38, v39
	global_store_dwordx4 v[44:45], v[32:35], off
	s_nop 1
	v_mul_f32_e32 v34, 0xbfb8aa3b, v28
	v_mul_f32_e32 v35, 0xbfb8aa3b, v29
	v_exp_f32_e32 v34, v34
	v_exp_f32_e32 v35, v35
	v_mad_i64_i32 v[32:33], s[4:5], v150, s11, v[132:133]
	v_add_f32_e32 v34, 1.0, v34
	v_add_f32_e32 v35, 1.0, v35
	v_rcp_f32_e32 v34, v34
	v_rcp_f32_e32 v35, v35
	s_nop 0
	v_pk_mul_f32 v[28:29], v[28:29], v[34:35]
	s_nop 0
	v_pk_mul_f32 v[24:25], v[24:25], v[28:29]
	v_pk_mul_f32 v[28:29], v[30:31], v[130:131] op_sel_hi:[1,0]
	s_nop 0
	v_mul_f32_e32 v30, 0xbfb8aa3b, v28
	v_mul_f32_e32 v31, 0xbfb8aa3b, v29
	v_exp_f32_e32 v30, v30
	v_exp_f32_e32 v31, v31
	v_add_f32_e32 v30, 1.0, v30
	v_add_f32_e32 v31, 1.0, v31
	v_rcp_f32_e32 v30, v30
	v_rcp_f32_e32 v31, v31
	s_nop 0
	v_pk_mul_f32 v[28:29], v[28:29], v[30:31]
	s_nop 0
	v_pk_mul_f32 v[26:27], v[26:27], v[28:29]
	v_mul_f32_e32 v28, 0xbfb8aa3b, v20
	v_mul_f32_e32 v29, 0xbfb8aa3b, v21
	v_exp_f32_e32 v28, v28
	v_exp_f32_e32 v29, v29
	v_add_f32_e32 v28, 1.0, v28
	v_add_f32_e32 v29, 1.0, v29
	v_rcp_f32_e32 v28, v28
	v_rcp_f32_e32 v29, v29
	s_nop 0
	v_pk_mul_f32 v[20:21], v[20:21], v[28:29]
	s_nop 0
	v_pk_mul_f32 v[20:21], v[16:17], v[20:21]
	v_pk_mul_f32 v[16:17], v[22:23], v[130:131] op_sel_hi:[1,0]
	v_lshl_add_u64 v[28:29], v[32:33], 0, v[112:113]
	v_mul_f32_e32 v22, 0xbfb8aa3b, v16
	v_mul_f32_e32 v23, 0xbfb8aa3b, v17
	v_exp_f32_e32 v22, v22
	v_exp_f32_e32 v23, v23
	v_add_f32_e32 v22, 1.0, v22
	v_add_f32_e32 v23, 1.0, v23
	v_rcp_f32_e32 v22, v22
	v_rcp_f32_e32 v23, v23
	s_nop 0
	v_pk_mul_f32 v[16:17], v[16:17], v[22:23]
	s_nop 0
	v_pk_mul_f32 v[22:23], v[18:19], v[16:17]
	v_cvt_pk_bf16_f32 v16, v24, v25
	v_cvt_pk_bf16_f32 v17, v26, v27
	v_cvt_pk_bf16_f32 v18, v20, v21
	v_cvt_pk_bf16_f32 v19, v22, v23
	global_store_dwordx4 v[28:29], v[16:19], off
	s_nop 1
	v_mul_f32_e32 v18, 0xbfb8aa3b, v12
	v_mul_f32_e32 v19, 0xbfb8aa3b, v13
	v_exp_f32_e32 v18, v18
	v_exp_f32_e32 v19, v19
	v_mad_i64_i32 v[16:17], s[4:5], v146, s11, v[132:133]
	v_add_f32_e32 v18, 1.0, v18
	v_add_f32_e32 v19, 1.0, v19
	v_rcp_f32_e32 v18, v18
	v_rcp_f32_e32 v19, v19
	s_mov_b32 s4, s14
	v_pk_mul_f32 v[12:13], v[12:13], v[18:19]
	s_nop 0
	v_pk_mul_f32 v[8:9], v[8:9], v[12:13]
	v_pk_mul_f32 v[12:13], v[14:15], v[128:129] op_sel_hi:[1,0]
	s_nop 0
	v_mul_f32_e32 v14, 0xbfb8aa3b, v12
	v_mul_f32_e32 v15, 0xbfb8aa3b, v13
	v_exp_f32_e32 v14, v14
	v_exp_f32_e32 v15, v15
	v_add_f32_e32 v14, 1.0, v14
	v_add_f32_e32 v15, 1.0, v15
	v_rcp_f32_e32 v14, v14
	v_rcp_f32_e32 v15, v15
	s_nop 0
	v_pk_mul_f32 v[12:13], v[12:13], v[14:15]
	s_nop 0
	v_pk_mul_f32 v[10:11], v[10:11], v[12:13]
	v_mul_f32_e32 v12, 0xbfb8aa3b, v4
	v_mul_f32_e32 v13, 0xbfb8aa3b, v5
	v_exp_f32_e32 v12, v12
	v_exp_f32_e32 v13, v13
	v_add_f32_e32 v12, 1.0, v12
	v_add_f32_e32 v13, 1.0, v13
	v_rcp_f32_e32 v12, v12
	v_rcp_f32_e32 v13, v13
	s_nop 0
	v_pk_mul_f32 v[4:5], v[4:5], v[12:13]
	s_nop 0
	v_pk_mul_f32 v[4:5], v[0:1], v[4:5]
	v_pk_mul_f32 v[0:1], v[6:7], v[128:129] op_sel_hi:[1,0]
	v_lshl_add_u64 v[12:13], v[16:17], 0, v[112:113]
	v_mul_f32_e32 v6, 0xbfb8aa3b, v0
	v_mul_f32_e32 v7, 0xbfb8aa3b, v1
	v_exp_f32_e32 v6, v6
	v_exp_f32_e32 v7, v7
	v_add_f32_e32 v6, 1.0, v6
	v_add_f32_e32 v7, 1.0, v7
	v_rcp_f32_e32 v6, v6
	v_rcp_f32_e32 v7, v7
	s_nop 0
	v_pk_mul_f32 v[0:1], v[0:1], v[6:7]
	s_nop 0
	v_pk_mul_f32 v[6:7], v[2:3], v[0:1]
	v_cvt_pk_bf16_f32 v0, v8, v9
	v_cvt_pk_bf16_f32 v1, v10, v11
	v_cvt_pk_bf16_f32 v2, v4, v5
	v_cvt_pk_bf16_f32 v3, v6, v7
	global_store_dwordx4 v[12:13], v[0:3], off
	s_cbranch_vccz .LBB0_752
	s_waitcnt vmcnt(0)
	s_cmpk_gt_u32 s27, 0xff
	s_cbranch_scc1 .LBB0_759
	s_barrier
